# peeled first K-iteration: its first two vmcnt waits leave the preceding epilogue's stores/atomics in flight (vmcnt 8+n_epilogue) when the tile follows an epilogue; on top of v11
# baseline (speedup 1.0000x reference)
; #define PG8_STAGE(bufoff, gbase, voff) do { _Pragma("unroll") for (int _i = 0; _i < 2; ++_i) \
;         __builtin_amdgcn_global_load_lds((const unsigned*)((const char*)(gbase) + (voff)[_i]), (PG8_LAS unsigned*)(lds + (bufoff) + ldsw + _i * 8192), 16, 0, 0); } while (0)
; #define PG8_LDA(dst, b, h) do { _Pragma("unroll") for (int m = 0; m < 4; ++m) _Pragma("unroll") for (int k = 0; k < 2; ++k) dst[m][k] = *(const PG8_LAS bf16x8*)(lds + PG8_SA(b, h) + aoff + m * 2048 + k * 1024); } while (0)
; #define PG8_LDB(dst, b, h) do { _Pragma("unroll") for (int n = 0; n < 2; ++n) _Pragma("unroll") for (int k = 0; k < 2; ++k) dst[n][k] = *(const PG8_LAS bf16x8*)(lds + PG8_SB(b, h) + boff + n * 2048 + k * 1024); } while (0)
; #define PG8_SCHED __builtin_amdgcn_sched_barrier(0)
; template <class Epi, class Sched, bool ALIGN_EPI = false, bool SP2 = false>
; __device__ __forceinline__ void gemm_phase(PG8_LAS unsigned char* lds, const Gemm g, const Sched& S, const Epi& E, int tid_in) {
;     ...
;             const bool last = (t == nt - 2);
;             const char* a1 = cA + (size_t)(t + 1) * kstep;
;             const char* a2 = last ? nA : cA + (size_t)(t + 2) * kstep; const char* b2 = last ? nB : cB + (size_t)(t + 2) * kstep;
;             const char* a3 = a2 + kstep; const char* b3 = b2 + kstep;
;             if (last && has_next) S.a_ready(nxt);
;             if constexpr (SP2) {
;             PG8_LDB(B0, 0, 0); PG8_LDB(B1, 0, 1); PG8_SCHED; PG8_LDA(At, 0, 0); PG8_STAGE(PG8_SA(1, 1), a1 + hstep, voffA);
.Lkb_skip_0:
	ds_read_b128 v[156:159], v150
	ds_read_b128 v[160:163], v150 offset:1024
	ds_read_b128 v[164:167], v150 offset:2048
	ds_read_b128 v[168:171], v150 offset:3072
	ds_read_b128 v[172:175], v151
	ds_read_b128 v[176:179], v151 offset:1024
	ds_read_b128 v[180:183], v151 offset:2048
	ds_read_b128 v[184:187], v151 offset:3072
	s_add_u32 s26, s48, 0xfff80080
	s_addc_u32 s27, s49, -1
	s_cmp_eq_u32 s76, 28
	s_cselect_b32 s53, s41, s27
	s_cselect_b32 s52, s70, s26
	s_cselect_b32 s51, s39, s75
	s_cselect_b32 s50, s71, s74
	s_add_i32 m0, s47, 0xc000
	ds_read_b128 v[188:191], v152
	ds_read_b128 v[192:195], v152 offset:1024
	ds_read_b128 v[196:199], v152 offset:2048
	ds_read_b128 v[200:203], v152 offset:3072
	ds_read_b128 v[212:215], v152 offset:4096
	ds_read_b128 v[216:219], v152 offset:5120
	ds_read_b128 v[220:223], v152 offset:6144
	ds_read_b128 v[224:227], v152 offset:7168
	global_load_lds_dwordx4 v138, s[48:49]
	s_add_i32 m0, s47, 0xe000
	s_nop 0
	global_load_lds_dwordx4 v140, s[48:49]
	s_cmp_eq_u32 s99, 0
	s_cbranch_scc1 .Lw1s_0_0
	s_waitcnt vmcnt(24)
	s_branch .Lw1d_0_0
.Lw1s_0_0:
	s_waitcnt vmcnt(8)
.Lw1d_0_0:
	s_waitcnt lgkmcnt(0)
	s_barrier
	s_setprio 1
	s_waitcnt lgkmcnt(0)
	v_mfma_f32_16x16x32_bf16 v[124:127], v[156:159], v[188:191], 0
	v_mfma_f32_16x16x32_bf16 v[120:123], v[164:167], v[188:191], 0
	v_mfma_f32_16x16x32_bf16 v[108:111], v[156:159], v[196:199], 0
	v_mfma_f32_16x16x32_bf16 v[104:107], v[164:167], v[196:199], 0
	v_mfma_f32_16x16x32_bf16 v[92:95], v[156:159], v[212:215], 0
	v_mfma_f32_16x16x32_bf16 v[88:91], v[164:167], v[212:215], 0
	v_mfma_f32_16x16x32_bf16 v[76:79], v[156:159], v[220:223], 0
	v_mfma_f32_16x16x32_bf16 v[72:75], v[164:167], v[220:223], 0
	v_mfma_f32_16x16x32_bf16 v[124:127], v[160:163], v[192:195], v[124:127]
	v_mfma_f32_16x16x32_bf16 v[120:123], v[168:171], v[192:195], v[120:123]
	v_mfma_f32_16x16x32_bf16 v[108:111], v[160:163], v[200:203], v[108:111]
	v_mfma_f32_16x16x32_bf16 v[104:107], v[168:171], v[200:203], v[104:107]
	v_mfma_f32_16x16x32_bf16 v[92:95], v[160:163], v[216:219], v[92:95]
	v_mfma_f32_16x16x32_bf16 v[88:91], v[168:171], v[216:219], v[88:91]
	v_mfma_f32_16x16x32_bf16 v[76:79], v[160:163], v[224:227], v[76:79]
	v_mfma_f32_16x16x32_bf16 v[72:75], v[168:171], v[224:227], v[72:75]
	s_setprio 0
	s_setprio 1
	v_mfma_f32_16x16x32_bf16 v[116:119], v[172:175], v[188:191], 0
	v_mfma_f32_16x16x32_bf16 v[112:115], v[180:183], v[188:191], 0
	v_mfma_f32_16x16x32_bf16 v[100:103], v[172:175], v[196:199], 0
	v_mfma_f32_16x16x32_bf16 v[96:99], v[180:183], v[196:199], 0
	v_mfma_f32_16x16x32_bf16 v[84:87], v[172:175], v[212:215], 0
	v_mfma_f32_16x16x32_bf16 v[80:83], v[180:183], v[212:215], 0
	v_mfma_f32_16x16x32_bf16 v[68:71], v[172:175], v[220:223], 0
	v_mfma_f32_16x16x32_bf16 v[64:67], v[180:183], v[220:223], 0
	v_mfma_f32_16x16x32_bf16 v[116:119], v[176:179], v[192:195], v[116:119]
	v_mfma_f32_16x16x32_bf16 v[112:115], v[184:187], v[192:195], v[112:115]
	v_mfma_f32_16x16x32_bf16 v[100:103], v[176:179], v[200:203], v[100:103]
	v_mfma_f32_16x16x32_bf16 v[96:99], v[184:187], v[200:203], v[96:99]
	v_mfma_f32_16x16x32_bf16 v[84:87], v[176:179], v[216:219], v[84:87]
	v_mfma_f32_16x16x32_bf16 v[80:83], v[184:187], v[216:219], v[80:83]
	v_mfma_f32_16x16x32_bf16 v[68:71], v[176:179], v[224:227], v[68:71]
	v_mfma_f32_16x16x32_bf16 v[64:67], v[184:187], v[224:227], v[64:67]
	s_setprio 0
	s_barrier
	s_add_i32 s26, s67, s54
	s_mov_b32 m0, s26
	ds_read_b128 v[188:191], v152 offset:16384
	ds_read_b128 v[192:195], v152 offset:17408
	ds_read_b128 v[196:199], v152 offset:18432
	ds_read_b128 v[200:203], v152 offset:19456
	ds_read_b128 v[212:215], v152 offset:20480
	ds_read_b128 v[216:219], v152 offset:21504
	ds_read_b128 v[220:223], v152 offset:22528
	ds_read_b128 v[224:227], v152 offset:23552
	global_load_lds_dwordx4 v132, s[50:51]
	s_add_i32 m0, s26, 0x2000
	s_add_u32 s26, s50, 0x20000
	s_addc_u32 s27, s51, 0
	s_add_i32 s33, s68, s54
	global_load_lds_dwordx4 v128, s[50:51]
	s_mov_b32 m0, s33
	s_nop 0
	global_load_lds_dwordx4 v132, s[26:27]
	s_add_i32 m0, s33, 0x2000
	s_nop 0
	global_load_lds_dwordx4 v128, s[26:27]
	s_mov_b32 m0, s47
	s_nop 0
	global_load_lds_dwordx4 v134, s[52:53]
	s_mov_b32 m0, s56
	s_nop 0
	global_load_lds_dwordx4 v130, s[52:53]
	s_cmp_eq_u32 s99, 0
	s_cbranch_scc1 .Lw1s_0_1
	s_waitcnt vmcnt(24)
	s_branch .Lw1d_0_1

; #define PG8_STAGE(bufoff, gbase, voff) do { _Pragma("unroll") for (int _i = 0; _i < 2; ++_i) \
;         __builtin_amdgcn_global_load_lds((const unsigned*)((const char*)(gbase) + (voff)[_i]), (PG8_LAS unsigned*)(lds + (bufoff) + ldsw + _i * 8192), 16, 0, 0); } while (0)
; #define PG8_LDA(dst, b, h) do { _Pragma("unroll") for (int m = 0; m < 4; ++m) _Pragma("unroll") for (int k = 0; k < 2; ++k) dst[m][k] = *(const PG8_LAS bf16x8*)(lds + PG8_SA(b, h) + aoff + m * 2048 + k * 1024); } while (0)
; #define PG8_LDB(dst, b, h) do { _Pragma("unroll") for (int n = 0; n < 2; ++n) _Pragma("unroll") for (int k = 0; k < 2; ++k) dst[n][k] = *(const PG8_LAS bf16x8*)(lds + PG8_SB(b, h) + boff + n * 2048 + k * 1024); } while (0)
; #define PG8_MMA(ai, bj, At, Bt) do { __builtin_amdgcn_s_setprio(1); _Pragma("unroll") for (int m = 0; m < 4; ++m) _Pragma("unroll") for (int n = 0; n < 2; ++n) _Pragma("unroll") for (int k = 0; k < 2; ++k) \
;         acc[ai][bj][m][n] = __builtin_amdgcn_mfma_f32_16x16x32_bf16(Bt[n][k], At[m][k], acc[ai][bj][m][n], 0, 0, 0); __builtin_amdgcn_s_setprio(0); } while (0)
; #define PG8_WAIT_V(n) asm volatile("s_waitcnt vmcnt(" #n ")" ::: "memory")
; #define PG8_WAIT_L(n) asm volatile("s_waitcnt lgkmcnt(" #n ")" ::: "memory")
; #define PG8_BAR __builtin_amdgcn_s_barrier()
; #define PG8_SCHED __builtin_amdgcn_sched_barrier(0)
; template <class Epi, class Sched, bool ALIGN_EPI = false, bool SP2 = false>
; __device__ __forceinline__ void gemm_phase(PG8_LAS unsigned char* lds, const Gemm g, const Sched& S, const Epi& E, int tid_in) {
;     ...
;             PG8_WAIT_V(8); PG8_WAIT_L(0); PG8_BAR; PG8_MMA(0, 0, At, B0); PG8_MMA(0, 1, At, B1); PG8_BAR; PG8_SCHED;
;             PG8_LDA(At, 0, 1); PG8_STAGE(PG8_SB(0, 0), b2, voffB); PG8_STAGE(PG8_SB(0, 1), b2 + hstepB, voffB); PG8_STAGE(PG8_SA(0, 0), a2, voffA);
;             PG8_WAIT_V(8); PG8_WAIT_L(0); PG8_BAR; PG8_MMA(1, 0, At, B0); PG8_MMA(1, 1, At, B1); PG8_BAR; PG8_SCHED;
;             PG8_LDB(B0, 1, 0); PG8_LDB(B1, 1, 1); PG8_SCHED; PG8_LDA(At, 1, 0); PG8_STAGE(PG8_SA(0, 1), a2 + hstep, voffA);
.Lw1d_0_1:
	s_waitcnt lgkmcnt(0)
	s_barrier
	s_setprio 1
	s_waitcnt lgkmcnt(0)
	v_mfma_f32_16x16x32_bf16 v[60:63], v[156:159], v[188:191], 0
	v_mfma_f32_16x16x32_bf16 v[56:59], v[164:167], v[188:191], 0
	v_mfma_f32_16x16x32_bf16 v[44:47], v[156:159], v[196:199], 0
	v_mfma_f32_16x16x32_bf16 v[40:43], v[164:167], v[196:199], 0
	v_mfma_f32_16x16x32_bf16 v[28:31], v[156:159], v[212:215], 0
	v_mfma_f32_16x16x32_bf16 v[24:27], v[164:167], v[212:215], 0
	v_mfma_f32_16x16x32_bf16 v[12:15], v[156:159], v[220:223], 0
	v_mfma_f32_16x16x32_bf16 v[8:11], v[164:167], v[220:223], 0
	v_mfma_f32_16x16x32_bf16 v[60:63], v[160:163], v[192:195], v[60:63]
	v_mfma_f32_16x16x32_bf16 v[56:59], v[168:171], v[192:195], v[56:59]
	v_mfma_f32_16x16x32_bf16 v[44:47], v[160:163], v[200:203], v[44:47]
	v_mfma_f32_16x16x32_bf16 v[40:43], v[168:171], v[200:203], v[40:43]
	v_mfma_f32_16x16x32_bf16 v[28:31], v[160:163], v[216:219], v[28:31]
	v_mfma_f32_16x16x32_bf16 v[24:27], v[168:171], v[216:219], v[24:27]
	v_mfma_f32_16x16x32_bf16 v[12:15], v[160:163], v[224:227], v[12:15]
	v_mfma_f32_16x16x32_bf16 v[8:11], v[168:171], v[224:227], v[8:11]
	s_setprio 0
	s_setprio 1
	v_mfma_f32_16x16x32_bf16 v[52:55], v[172:175], v[188:191], 0
	v_mfma_f32_16x16x32_bf16 v[48:51], v[180:183], v[188:191], 0
	v_mfma_f32_16x16x32_bf16 v[36:39], v[172:175], v[196:199], 0
	v_mfma_f32_16x16x32_bf16 v[32:35], v[180:183], v[196:199], 0
	v_mfma_f32_16x16x32_bf16 v[20:23], v[172:175], v[212:215], 0
	v_mfma_f32_16x16x32_bf16 v[16:19], v[180:183], v[212:215], 0
	v_mfma_f32_16x16x32_bf16 v[4:7], v[172:175], v[220:223], 0
	v_mfma_f32_16x16x32_bf16 v[0:3], v[180:183], v[220:223], 0
	v_mfma_f32_16x16x32_bf16 v[52:55], v[176:179], v[192:195], v[52:55]
	v_mfma_f32_16x16x32_bf16 v[48:51], v[184:187], v[192:195], v[48:51]
	v_mfma_f32_16x16x32_bf16 v[36:39], v[176:179], v[200:203], v[36:39]
	v_mfma_f32_16x16x32_bf16 v[32:35], v[184:187], v[200:203], v[32:35]
	v_mfma_f32_16x16x32_bf16 v[20:23], v[176:179], v[216:219], v[20:23]
	v_mfma_f32_16x16x32_bf16 v[16:19], v[184:187], v[216:219], v[16:19]
	v_mfma_f32_16x16x32_bf16 v[4:7], v[176:179], v[224:227], v[4:7]
	v_mfma_f32_16x16x32_bf16 v[0:3], v[184:187], v[224:227], v[0:3]
	s_setprio 0
	s_barrier
	s_add_i32 s33, 0, 0x18000
	v_add_u32_e32 v155, s33, v146
	s_add_i32 s77, 0, 0x1c000
	ds_read_b128 v[156:159], v155
	ds_read_b128 v[160:163], v155 offset:1024
	ds_read_b128 v[164:167], v155 offset:2048
	ds_read_b128 v[168:171], v155 offset:3072
	v_add_u32_e32 v155, s77, v146
	ds_read_b128 v[172:175], v155
	ds_read_b128 v[176:179], v155 offset:1024
	ds_read_b128 v[180:183], v155 offset:2048
	ds_read_b128 v[184:187], v155 offset:3072
	s_add_u32 s26, s52, 0x80000
	s_addc_u32 s27, s53, 0
	s_mov_b32 m0, s57
	ds_read_b128 v[188:191], v152 offset:32768
	ds_read_b128 v[192:195], v152 offset:33792
	ds_read_b128 v[196:199], v152 offset:34816
	ds_read_b128 v[200:203], v152 offset:35840
	ds_read_b128 v[212:215], v152 offset:36864
	ds_read_b128 v[216:219], v152 offset:37888
	ds_read_b128 v[220:223], v152 offset:38912
	ds_read_b128 v[224:227], v152 offset:39936
	global_load_lds_dwordx4 v134, s[26:27]
	s_mov_b32 m0, s58
	s_nop 0
	global_load_lds_dwordx4 v130, s[26:27]
	s_waitcnt vmcnt(8)
	s_waitcnt lgkmcnt(0)
	s_barrier
	s_setprio 1
	s_waitcnt lgkmcnt(0)
	v_mfma_f32_16x16x32_bf16 v[124:127], v[156:159], v[188:191], v[124:127]
	v_mfma_f32_16x16x32_bf16 v[120:123], v[164:167], v[188:191], v[120:123]
	v_mfma_f32_16x16x32_bf16 v[108:111], v[156:159], v[196:199], v[108:111]
	v_mfma_f32_16x16x32_bf16 v[104:107], v[164:167], v[196:199], v[104:107]
	v_mfma_f32_16x16x32_bf16 v[92:95], v[156:159], v[212:215], v[92:95]
	v_mfma_f32_16x16x32_bf16 v[88:91], v[164:167], v[212:215], v[88:91]
	v_mfma_f32_16x16x32_bf16 v[76:79], v[156:159], v[220:223], v[76:79]
	v_mfma_f32_16x16x32_bf16 v[72:75], v[164:167], v[220:223], v[72:75]
	v_mfma_f32_16x16x32_bf16 v[124:127], v[160:163], v[192:195], v[124:127]
	v_mfma_f32_16x16x32_bf16 v[120:123], v[168:171], v[192:195], v[120:123]
	v_mfma_f32_16x16x32_bf16 v[108:111], v[160:163], v[200:203], v[108:111]
	v_mfma_f32_16x16x32_bf16 v[104:107], v[168:171], v[200:203], v[104:107]
	v_mfma_f32_16x16x32_bf16 v[92:95], v[160:163], v[216:219], v[92:95]
	v_mfma_f32_16x16x32_bf16 v[88:91], v[168:171], v[216:219], v[88:91]
	v_mfma_f32_16x16x32_bf16 v[76:79], v[160:163], v[224:227], v[76:79]
	v_mfma_f32_16x16x32_bf16 v[72:75], v[168:171], v[224:227], v[72:75]
	s_setprio 0
	s_setprio 1
	v_mfma_f32_16x16x32_bf16 v[116:119], v[172:175], v[188:191], v[116:119]
	v_mfma_f32_16x16x32_bf16 v[112:115], v[180:183], v[188:191], v[112:115]
	v_mfma_f32_16x16x32_bf16 v[100:103], v[172:175], v[196:199], v[100:103]
	v_mfma_f32_16x16x32_bf16 v[96:99], v[180:183], v[196:199], v[96:99]
	v_mfma_f32_16x16x32_bf16 v[84:87], v[172:175], v[212:215], v[84:87]
	v_mfma_f32_16x16x32_bf16 v[80:83], v[180:183], v[212:215], v[80:83]
	v_mfma_f32_16x16x32_bf16 v[68:71], v[172:175], v[220:223], v[68:71]
	v_mfma_f32_16x16x32_bf16 v[64:67], v[180:183], v[220:223], v[64:67]
	v_mfma_f32_16x16x32_bf16 v[116:119], v[176:179], v[192:195], v[116:119]
	v_mfma_f32_16x16x32_bf16 v[112:115], v[184:187], v[192:195], v[112:115]
	v_mfma_f32_16x16x32_bf16 v[100:103], v[176:179], v[200:203], v[100:103]
	v_mfma_f32_16x16x32_bf16 v[96:99], v[184:187], v[200:203], v[96:99]
	v_mfma_f32_16x16x32_bf16 v[84:87], v[176:179], v[216:219], v[84:87]
	v_mfma_f32_16x16x32_bf16 v[80:83], v[184:187], v[216:219], v[80:83]
	v_mfma_f32_16x16x32_bf16 v[68:71], v[176:179], v[224:227], v[68:71]
	v_mfma_f32_16x16x32_bf16 v[64:67], v[184:187], v[224:227], v[64:67]
	s_setprio 0
	s_barrier
; #define PG8_STAGE(bufoff, gbase, voff) do { _Pragma("unroll") for (int _i = 0; _i < 2; ++_i) \
;         __builtin_amdgcn_global_load_lds((const unsigned*)((const char*)(gbase) + (voff)[_i]), (PG8_LAS unsigned*)(lds + (bufoff) + ldsw + _i * 8192), 16, 0, 0); } while (0)
; #define PG8_LDA(dst, b, h) do { _Pragma("unroll") for (int m = 0; m < 4; ++m) _Pragma("unroll") for (int k = 0; k < 2; ++k) dst[m][k] = *(const PG8_LAS bf16x8*)(lds + PG8_SA(b, h) + aoff + m * 2048 + k * 1024); } while (0)
; #define PG8_LDB(dst, b, h) do { _Pragma("unroll") for (int n = 0; n < 2; ++n) _Pragma("unroll") for (int k = 0; k < 2; ++k) dst[n][k] = *(const PG8_LAS bf16x8*)(lds + PG8_SB(b, h) + boff + n * 2048 + k * 1024); } while (0)
; #define PG8_MMA(ai, bj, At, Bt) do { __builtin_amdgcn_s_setprio(1); _Pragma("unroll") for (int m = 0; m < 4; ++m) _Pragma("unroll") for (int n = 0; n < 2; ++n) _Pragma("unroll") for (int k = 0; k < 2; ++k) \
;         acc[ai][bj][m][n] = __builtin_amdgcn_mfma_f32_16x16x32_bf16(Bt[n][k], At[m][k], acc[ai][bj][m][n], 0, 0, 0); __builtin_amdgcn_s_setprio(0); } while (0)
; #define PG8_WAIT_V(n) asm volatile("s_waitcnt vmcnt(" #n ")" ::: "memory")
; #define PG8_WAIT_L(n) asm volatile("s_waitcnt lgkmcnt(" #n ")" ::: "memory")
; #define PG8_BAR __builtin_amdgcn_s_barrier()
; #define PG8_SCHED __builtin_amdgcn_sched_barrier(0)
; template <class Epi, class Sched, bool ALIGN_EPI = false, bool SP2 = false>
; __device__ __forceinline__ void gemm_phase(PG8_LAS unsigned char* lds, const Gemm g, const Sched& S, const Epi& E, int tid_in) {
;     ...
;             PG8_LDB(B0, 0, 0); PG8_LDB(B1, 0, 1); PG8_SCHED; PG8_LDA(At, 0, 0); PG8_STAGE(PG8_SA(1, 1), a1 + hstep, voffA);
;             PG8_WAIT_V(8); PG8_WAIT_L(0); PG8_BAR; PG8_MMA(0, 0, At, B0); PG8_MMA(0, 1, At, B1); PG8_BAR; PG8_SCHED;
;     ...
;             PG8_LDA(At, 1, 1); PG8_STAGE(PG8_SB(1, 0), b3, voffB); PG8_STAGE(PG8_SB(1, 1), b3 + hstepB, voffB); PG8_STAGE(PG8_SA(1, 0), a3, voffA);
;             PG8_WAIT_V(8); PG8_WAIT_L(0); PG8_BAR; PG8_MMA(1, 0, At, B0); PG8_MMA(1, 1, At, B1); PG8_BAR; PG8_SCHED;
	s_add_i32 s26, s33, s54
	s_add_i32 m0, s26, 0xffffff80
	ds_read_b128 v[188:191], v152 offset:49152
	ds_read_b128 v[192:195], v152 offset:50176
	ds_read_b128 v[196:199], v152 offset:51200
	ds_read_b128 v[200:203], v152 offset:52224
	ds_read_b128 v[212:215], v152 offset:53248
	ds_read_b128 v[216:219], v152 offset:54272
	ds_read_b128 v[220:223], v152 offset:55296
	ds_read_b128 v[224:227], v152 offset:56320
	global_load_lds_dwordx4 v132, s[50:51] offset:128
	s_add_i32 m0, s26, 0x1f80
	s_add_u32 s26, s50, 0x20080
	s_addc_u32 s27, s51, 0
	s_add_i32 s33, s77, s54
	global_load_lds_dwordx4 v128, s[50:51] offset:128
	s_mov_b32 m0, s33
	s_nop 0
	global_load_lds_dwordx4 v132, s[26:27]
	s_add_i32 m0, s33, 0x2000
	s_nop 0
	global_load_lds_dwordx4 v128, s[26:27]
	s_add_i32 m0, s61, 0xffffff80
	s_nop 0
	global_load_lds_dwordx4 v134, s[52:53] offset:128
	s_add_i32 m0, s62, 0xffffff80
	s_nop 0
	global_load_lds_dwordx4 v130, s[52:53] offset:128
	s_waitcnt vmcnt(8)
	s_waitcnt lgkmcnt(0)
	s_barrier
	s_setprio 1
	s_waitcnt lgkmcnt(0)
	v_mfma_f32_16x16x32_bf16 v[60:63], v[156:159], v[188:191], v[60:63]
	v_mfma_f32_16x16x32_bf16 v[56:59], v[164:167], v[188:191], v[56:59]
	v_mfma_f32_16x16x32_bf16 v[44:47], v[156:159], v[196:199], v[44:47]
	v_mfma_f32_16x16x32_bf16 v[40:43], v[164:167], v[196:199], v[40:43]
	v_mfma_f32_16x16x32_bf16 v[28:31], v[156:159], v[212:215], v[28:31]
	v_mfma_f32_16x16x32_bf16 v[24:27], v[164:167], v[212:215], v[24:27]
	v_mfma_f32_16x16x32_bf16 v[12:15], v[156:159], v[220:223], v[12:15]
	v_mfma_f32_16x16x32_bf16 v[8:11], v[164:167], v[220:223], v[8:11]
	v_mfma_f32_16x16x32_bf16 v[60:63], v[160:163], v[192:195], v[60:63]
	v_mfma_f32_16x16x32_bf16 v[56:59], v[168:171], v[192:195], v[56:59]
	v_mfma_f32_16x16x32_bf16 v[44:47], v[160:163], v[200:203], v[44:47]
	v_mfma_f32_16x16x32_bf16 v[40:43], v[168:171], v[200:203], v[40:43]
	v_mfma_f32_16x16x32_bf16 v[28:31], v[160:163], v[216:219], v[28:31]
	v_mfma_f32_16x16x32_bf16 v[24:27], v[168:171], v[216:219], v[24:27]
	v_mfma_f32_16x16x32_bf16 v[12:15], v[160:163], v[224:227], v[12:15]
	v_mfma_f32_16x16x32_bf16 v[8:11], v[168:171], v[224:227], v[8:11]
	s_setprio 0
	s_setprio 1
	v_mfma_f32_16x16x32_bf16 v[52:55], v[172:175], v[188:191], v[52:55]
	v_mfma_f32_16x16x32_bf16 v[48:51], v[180:183], v[188:191], v[48:51]
	v_mfma_f32_16x16x32_bf16 v[36:39], v[172:175], v[196:199], v[36:39]
	v_mfma_f32_16x16x32_bf16 v[32:35], v[180:183], v[196:199], v[32:35]
	v_mfma_f32_16x16x32_bf16 v[20:23], v[172:175], v[212:215], v[20:23]
	v_mfma_f32_16x16x32_bf16 v[16:19], v[180:183], v[212:215], v[16:19]
	v_mfma_f32_16x16x32_bf16 v[4:7], v[172:175], v[220:223], v[4:7]
	v_mfma_f32_16x16x32_bf16 v[0:3], v[180:183], v[220:223], v[0:3]
	v_mfma_f32_16x16x32_bf16 v[52:55], v[176:179], v[192:195], v[52:55]
	v_mfma_f32_16x16x32_bf16 v[48:51], v[184:187], v[192:195], v[48:51]
	v_mfma_f32_16x16x32_bf16 v[36:39], v[176:179], v[200:203], v[36:39]
	v_mfma_f32_16x16x32_bf16 v[32:35], v[184:187], v[200:203], v[32:35]
	v_mfma_f32_16x16x32_bf16 v[20:23], v[176:179], v[216:219], v[20:23]
	v_mfma_f32_16x16x32_bf16 v[16:19], v[184:187], v[216:219], v[16:19]
	v_mfma_f32_16x16x32_bf16 v[4:7], v[176:179], v[224:227], v[4:7]
	v_mfma_f32_16x16x32_bf16 v[0:3], v[184:187], v[224:227], v[0:3]
	s_setprio 0
	s_barrier
	s_add_i32 s76, s76, 2
	s_add_u32 s48, s48, 0x100
	s_addc_u32 s49, s49, 0
	s_add_u32 s74, s74, 0x100
	s_addc_u32 s75, s75, 0
	s_cmp_gt_u32 s76, 29
.LBB0_80:
	ds_read_b128 v[156:159], v150
	ds_read_b128 v[160:163], v150 offset:1024
	ds_read_b128 v[164:167], v150 offset:2048
	ds_read_b128 v[168:171], v150 offset:3072
	ds_read_b128 v[172:175], v151
	ds_read_b128 v[176:179], v151 offset:1024
	ds_read_b128 v[180:183], v151 offset:2048
	ds_read_b128 v[184:187], v151 offset:3072
	s_add_u32 s26, s48, 0xfff80080
	s_addc_u32 s27, s49, -1
	s_cmp_eq_u32 s76, 28
	s_cselect_b32 s53, s41, s27
	s_cselect_b32 s52, s70, s26
	s_cselect_b32 s51, s39, s75
	s_cselect_b32 s50, s71, s74
	s_add_i32 m0, s47, 0xc000
	ds_read_b128 v[188:191], v152
	ds_read_b128 v[192:195], v152 offset:1024
	ds_read_b128 v[196:199], v152 offset:2048
	ds_read_b128 v[200:203], v152 offset:3072
	ds_read_b128 v[212:215], v152 offset:4096
	ds_read_b128 v[216:219], v152 offset:5120
	ds_read_b128 v[220:223], v152 offset:6144
	ds_read_b128 v[224:227], v152 offset:7168
	global_load_lds_dwordx4 v138, s[48:49]
	s_add_i32 m0, s47, 0xe000
	s_nop 0
	global_load_lds_dwordx4 v140, s[48:49]
	s_waitcnt vmcnt(8)
	s_waitcnt lgkmcnt(0)
	s_barrier
; #define PG8_STAGE(bufoff, gbase, voff) do { _Pragma("unroll") for (int _i = 0; _i < 2; ++_i) \
;         __builtin_amdgcn_global_load_lds((const unsigned*)((const char*)(gbase) + (voff)[_i]), (PG8_LAS unsigned*)(lds + (bufoff) + ldsw + _i * 8192), 16, 0, 0); } while (0)
; #define PG8_LDA(dst, b, h) do { _Pragma("unroll") for (int m = 0; m < 4; ++m) _Pragma("unroll") for (int k = 0; k < 2; ++k) dst[m][k] = *(const PG8_LAS bf16x8*)(lds + PG8_SA(b, h) + aoff + m * 2048 + k * 1024); } while (0)
; #define PG8_LDB(dst, b, h) do { _Pragma("unroll") for (int n = 0; n < 2; ++n) _Pragma("unroll") for (int k = 0; k < 2; ++k) dst[n][k] = *(const PG8_LAS bf16x8*)(lds + PG8_SB(b, h) + boff + n * 2048 + k * 1024); } while (0)
; #define PG8_MMA(ai, bj, At, Bt) do { __builtin_amdgcn_s_setprio(1); _Pragma("unroll") for (int m = 0; m < 4; ++m) _Pragma("unroll") for (int n = 0; n < 2; ++n) _Pragma("unroll") for (int k = 0; k < 2; ++k) \
;         acc[ai][bj][m][n] = __builtin_amdgcn_mfma_f32_16x16x32_bf16(Bt[n][k], At[m][k], acc[ai][bj][m][n], 0, 0, 0); __builtin_amdgcn_s_setprio(0); } while (0)
; #define PG8_WAIT_V(n) asm volatile("s_waitcnt vmcnt(" #n ")" ::: "memory")
; #define PG8_WAIT_L(n) asm volatile("s_waitcnt lgkmcnt(" #n ")" ::: "memory")
; #define PG8_BAR __builtin_amdgcn_s_barrier()
; #define PG8_SCHED __builtin_amdgcn_sched_barrier(0)
; template <class Epi, class Sched, bool ALIGN_EPI = false, bool SP2 = false>
; __device__ __forceinline__ void gemm_phase(PG8_LAS unsigned char* lds, const Gemm g, const Sched& S, const Epi& E, int tid_in) {
;     ...
;             PG8_WAIT_V(8); PG8_WAIT_L(0); PG8_BAR; PG8_MMA(0, 0, At, B0); PG8_MMA(0, 1, At, B1); PG8_BAR; PG8_SCHED;
;             PG8_LDA(At, 0, 1); PG8_STAGE(PG8_SB(0, 0), b2, voffB); PG8_STAGE(PG8_SB(0, 1), b2 + hstepB, voffB); PG8_STAGE(PG8_SA(0, 0), a2, voffA);
;             PG8_WAIT_V(8); PG8_WAIT_L(0); PG8_BAR; PG8_MMA(1, 0, At, B0); PG8_MMA(1, 1, At, B1); PG8_BAR; PG8_SCHED;
;             PG8_LDB(B0, 1, 0); PG8_LDB(B1, 1, 1); PG8_SCHED; PG8_LDA(At, 1, 0); PG8_STAGE(PG8_SA(0, 1), a2 + hstep, voffA);
	s_setprio 1
	s_waitcnt lgkmcnt(0)
	v_mfma_f32_16x16x32_bf16 v[124:127], v[156:159], v[188:191], v[124:127]
	v_mfma_f32_16x16x32_bf16 v[120:123], v[164:167], v[188:191], v[120:123]
	v_mfma_f32_16x16x32_bf16 v[108:111], v[156:159], v[196:199], v[108:111]
	v_mfma_f32_16x16x32_bf16 v[104:107], v[164:167], v[196:199], v[104:107]
	v_mfma_f32_16x16x32_bf16 v[92:95], v[156:159], v[212:215], v[92:95]
	v_mfma_f32_16x16x32_bf16 v[88:91], v[164:167], v[212:215], v[88:91]
	v_mfma_f32_16x16x32_bf16 v[76:79], v[156:159], v[220:223], v[76:79]
	v_mfma_f32_16x16x32_bf16 v[72:75], v[164:167], v[220:223], v[72:75]
	v_mfma_f32_16x16x32_bf16 v[124:127], v[160:163], v[192:195], v[124:127]
	v_mfma_f32_16x16x32_bf16 v[120:123], v[168:171], v[192:195], v[120:123]
	v_mfma_f32_16x16x32_bf16 v[108:111], v[160:163], v[200:203], v[108:111]
	v_mfma_f32_16x16x32_bf16 v[104:107], v[168:171], v[200:203], v[104:107]
	v_mfma_f32_16x16x32_bf16 v[92:95], v[160:163], v[216:219], v[92:95]
	v_mfma_f32_16x16x32_bf16 v[88:91], v[168:171], v[216:219], v[88:91]
	v_mfma_f32_16x16x32_bf16 v[76:79], v[160:163], v[224:227], v[76:79]
	v_mfma_f32_16x16x32_bf16 v[72:75], v[168:171], v[224:227], v[72:75]
	s_setprio 0
	s_setprio 1
	v_mfma_f32_16x16x32_bf16 v[116:119], v[172:175], v[188:191], v[116:119]
	v_mfma_f32_16x16x32_bf16 v[112:115], v[180:183], v[188:191], v[112:115]
	v_mfma_f32_16x16x32_bf16 v[100:103], v[172:175], v[196:199], v[100:103]
	v_mfma_f32_16x16x32_bf16 v[96:99], v[180:183], v[196:199], v[96:99]
	v_mfma_f32_16x16x32_bf16 v[84:87], v[172:175], v[212:215], v[84:87]
	v_mfma_f32_16x16x32_bf16 v[80:83], v[180:183], v[212:215], v[80:83]
	v_mfma_f32_16x16x32_bf16 v[68:71], v[172:175], v[220:223], v[68:71]
	v_mfma_f32_16x16x32_bf16 v[64:67], v[180:183], v[220:223], v[64:67]
	v_mfma_f32_16x16x32_bf16 v[116:119], v[176:179], v[192:195], v[116:119]
	v_mfma_f32_16x16x32_bf16 v[112:115], v[184:187], v[192:195], v[112:115]
	v_mfma_f32_16x16x32_bf16 v[100:103], v[176:179], v[200:203], v[100:103]
	v_mfma_f32_16x16x32_bf16 v[96:99], v[184:187], v[200:203], v[96:99]
	v_mfma_f32_16x16x32_bf16 v[84:87], v[176:179], v[216:219], v[84:87]
	v_mfma_f32_16x16x32_bf16 v[80:83], v[184:187], v[216:219], v[80:83]
	v_mfma_f32_16x16x32_bf16 v[68:71], v[176:179], v[224:227], v[68:71]
	v_mfma_f32_16x16x32_bf16 v[64:67], v[184:187], v[224:227], v[64:67]
	s_setprio 0
	s_barrier
	s_add_i32 s26, s67, s54
	s_mov_b32 m0, s26
	ds_read_b128 v[188:191], v152 offset:16384
	ds_read_b128 v[192:195], v152 offset:17408
	ds_read_b128 v[196:199], v152 offset:18432
	ds_read_b128 v[200:203], v152 offset:19456
	ds_read_b128 v[212:215], v152 offset:20480
	ds_read_b128 v[216:219], v152 offset:21504
	ds_read_b128 v[220:223], v152 offset:22528
	ds_read_b128 v[224:227], v152 offset:23552
	global_load_lds_dwordx4 v132, s[50:51]
	s_add_i32 m0, s26, 0x2000
	s_add_u32 s26, s50, 0x20000
	s_addc_u32 s27, s51, 0
	s_add_i32 s33, s68, s54
	global_load_lds_dwordx4 v128, s[50:51]
	s_mov_b32 m0, s33
	s_nop 0
	global_load_lds_dwordx4 v132, s[26:27]
	s_add_i32 m0, s33, 0x2000
	s_nop 0
	global_load_lds_dwordx4 v128, s[26:27]
	s_mov_b32 m0, s47
	s_nop 0
	global_load_lds_dwordx4 v134, s[52:53]
	s_mov_b32 m0, s56
	s_nop 0
	global_load_lds_dwordx4 v130, s[52:53]
	s_waitcnt vmcnt(8)
	s_waitcnt lgkmcnt(0)
	s_barrier
	s_setprio 1
	s_waitcnt lgkmcnt(0)
	v_mfma_f32_16x16x32_bf16 v[60:63], v[156:159], v[188:191], v[60:63]
	v_mfma_f32_16x16x32_bf16 v[56:59], v[164:167], v[188:191], v[56:59]
	v_mfma_f32_16x16x32_bf16 v[44:47], v[156:159], v[196:199], v[44:47]
	v_mfma_f32_16x16x32_bf16 v[40:43], v[164:167], v[196:199], v[40:43]
	v_mfma_f32_16x16x32_bf16 v[28:31], v[156:159], v[212:215], v[28:31]
	v_mfma_f32_16x16x32_bf16 v[24:27], v[164:167], v[212:215], v[24:27]
	v_mfma_f32_16x16x32_bf16 v[12:15], v[156:159], v[220:223], v[12:15]
	v_mfma_f32_16x16x32_bf16 v[8:11], v[164:167], v[220:223], v[8:11]
	v_mfma_f32_16x16x32_bf16 v[60:63], v[160:163], v[192:195], v[60:63]
	v_mfma_f32_16x16x32_bf16 v[56:59], v[168:171], v[192:195], v[56:59]
	v_mfma_f32_16x16x32_bf16 v[44:47], v[160:163], v[200:203], v[44:47]
	v_mfma_f32_16x16x32_bf16 v[40:43], v[168:171], v[200:203], v[40:43]
	v_mfma_f32_16x16x32_bf16 v[28:31], v[160:163], v[216:219], v[28:31]
	v_mfma_f32_16x16x32_bf16 v[24:27], v[168:171], v[216:219], v[24:27]
	v_mfma_f32_16x16x32_bf16 v[12:15], v[160:163], v[224:227], v[12:15]
	v_mfma_f32_16x16x32_bf16 v[8:11], v[168:171], v[224:227], v[8:11]
	s_setprio 0
	s_setprio 1
	v_mfma_f32_16x16x32_bf16 v[52:55], v[172:175], v[188:191], v[52:55]
	v_mfma_f32_16x16x32_bf16 v[48:51], v[180:183], v[188:191], v[48:51]
	v_mfma_f32_16x16x32_bf16 v[36:39], v[172:175], v[196:199], v[36:39]
	v_mfma_f32_16x16x32_bf16 v[32:35], v[180:183], v[196:199], v[32:35]
	v_mfma_f32_16x16x32_bf16 v[20:23], v[172:175], v[212:215], v[20:23]
	v_mfma_f32_16x16x32_bf16 v[16:19], v[180:183], v[212:215], v[16:19]
	v_mfma_f32_16x16x32_bf16 v[4:7], v[172:175], v[220:223], v[4:7]
	v_mfma_f32_16x16x32_bf16 v[0:3], v[180:183], v[220:223], v[0:3]
	v_mfma_f32_16x16x32_bf16 v[52:55], v[176:179], v[192:195], v[52:55]
	v_mfma_f32_16x16x32_bf16 v[48:51], v[184:187], v[192:195], v[48:51]
	v_mfma_f32_16x16x32_bf16 v[36:39], v[176:179], v[200:203], v[36:39]
	v_mfma_f32_16x16x32_bf16 v[32:35], v[184:187], v[200:203], v[32:35]
	v_mfma_f32_16x16x32_bf16 v[20:23], v[176:179], v[216:219], v[20:23]
	v_mfma_f32_16x16x32_bf16 v[16:19], v[184:187], v[216:219], v[16:19]
	v_mfma_f32_16x16x32_bf16 v[4:7], v[176:179], v[224:227], v[4:7]
	v_mfma_f32_16x16x32_bf16 v[0:3], v[184:187], v[224:227], v[0:3]
	s_setprio 0
	s_barrier
; #define PG8_STAGE(bufoff, gbase, voff) do { _Pragma("unroll") for (int _i = 0; _i < 2; ++_i) \
;         __builtin_amdgcn_global_load_lds((const unsigned*)((const char*)(gbase) + (voff)[_i]), (PG8_LAS unsigned*)(lds + (bufoff) + ldsw + _i * 8192), 16, 0, 0); } while (0)
; #define PG8_LDA(dst, b, h) do { _Pragma("unroll") for (int m = 0; m < 4; ++m) _Pragma("unroll") for (int k = 0; k < 2; ++k) dst[m][k] = *(const PG8_LAS bf16x8*)(lds + PG8_SA(b, h) + aoff + m * 2048 + k * 1024); } while (0)
; #define PG8_MMA(ai, bj, At, Bt) do { __builtin_amdgcn_s_setprio(1); _Pragma("unroll") for (int m = 0; m < 4; ++m) _Pragma("unroll") for (int n = 0; n < 2; ++n) _Pragma("unroll") for (int k = 0; k < 2; ++k) \
;         acc[ai][bj][m][n] = __builtin_amdgcn_mfma_f32_16x16x32_bf16(Bt[n][k], At[m][k], acc[ai][bj][m][n], 0, 0, 0); __builtin_amdgcn_s_setprio(0); } while (0)
; #define PG8_WAIT_V(n) asm volatile("s_waitcnt vmcnt(" #n ")" ::: "memory")
; #define PG8_WAIT_L(n) asm volatile("s_waitcnt lgkmcnt(" #n ")" ::: "memory")
; #define PG8_BAR __builtin_amdgcn_s_barrier()
; #define PG8_SCHED __builtin_amdgcn_sched_barrier(0)
; template <class Epi, class Sched, bool ALIGN_EPI = false, bool SP2 = false>
; __device__ __forceinline__ void gemm_phase(PG8_LAS unsigned char* lds, const Gemm g, const Sched& S, const Epi& E, int tid_in) {
;     ...
;         for (int t = 0; t < nt; t += 2) {
;             const bool last = (t == nt - 2);
;             const char* a1 = cA + (size_t)(t + 1) * kstep;
;             const char* a2 = last ? nA : cA + (size_t)(t + 2) * kstep; const char* b2 = last ? nB : cB + (size_t)(t + 2) * kstep;
;             const char* a3 = a2 + kstep; const char* b3 = b2 + kstep;
;             if (last && has_next) S.a_ready(nxt);
;     ...
;             PG8_WAIT_V(8); PG8_WAIT_L(0); PG8_BAR; PG8_MMA(0, 0, At, B0); PG8_MMA(0, 1, At, B1); PG8_BAR; PG8_SCHED;
;             PG8_LDA(At, 1, 1); PG8_STAGE(PG8_SB(1, 0), b3, voffB); PG8_STAGE(PG8_SB(1, 1), b3 + hstepB, voffB); PG8_STAGE(PG8_SA(1, 0), a3, voffA);
;             PG8_WAIT_V(8); PG8_WAIT_L(0); PG8_BAR; PG8_MMA(1, 0, At, B0); PG8_MMA(1, 1, At, B1); PG8_BAR; PG8_SCHED;
	s_add_i32 s33, 0, 0x18000
	v_add_u32_e32 v155, s33, v146
	s_add_i32 s77, 0, 0x1c000
	ds_read_b128 v[156:159], v155
	ds_read_b128 v[160:163], v155 offset:1024
	ds_read_b128 v[164:167], v155 offset:2048
	ds_read_b128 v[168:171], v155 offset:3072
	v_add_u32_e32 v155, s77, v146
	ds_read_b128 v[172:175], v155
	ds_read_b128 v[176:179], v155 offset:1024
	ds_read_b128 v[180:183], v155 offset:2048
	ds_read_b128 v[184:187], v155 offset:3072
	s_add_u32 s26, s52, 0x80000
	s_addc_u32 s27, s53, 0
	s_mov_b32 m0, s57
	ds_read_b128 v[188:191], v152 offset:32768
	ds_read_b128 v[192:195], v152 offset:33792
	ds_read_b128 v[196:199], v152 offset:34816
	ds_read_b128 v[200:203], v152 offset:35840
	ds_read_b128 v[212:215], v152 offset:36864
	ds_read_b128 v[216:219], v152 offset:37888
	ds_read_b128 v[220:223], v152 offset:38912
	ds_read_b128 v[224:227], v152 offset:39936
	global_load_lds_dwordx4 v134, s[26:27]
	s_mov_b32 m0, s58
	s_nop 0
	global_load_lds_dwordx4 v130, s[26:27]
	s_waitcnt vmcnt(8)
	s_waitcnt lgkmcnt(0)
	s_barrier
	s_setprio 1
	s_waitcnt lgkmcnt(0)
	v_mfma_f32_16x16x32_bf16 v[124:127], v[156:159], v[188:191], v[124:127]
	v_mfma_f32_16x16x32_bf16 v[120:123], v[164:167], v[188:191], v[120:123]
	v_mfma_f32_16x16x32_bf16 v[108:111], v[156:159], v[196:199], v[108:111]
	v_mfma_f32_16x16x32_bf16 v[104:107], v[164:167], v[196:199], v[104:107]
	v_mfma_f32_16x16x32_bf16 v[92:95], v[156:159], v[212:215], v[92:95]
	v_mfma_f32_16x16x32_bf16 v[88:91], v[164:167], v[212:215], v[88:91]
	v_mfma_f32_16x16x32_bf16 v[76:79], v[156:159], v[220:223], v[76:79]
	v_mfma_f32_16x16x32_bf16 v[72:75], v[164:167], v[220:223], v[72:75]
	v_mfma_f32_16x16x32_bf16 v[124:127], v[160:163], v[192:195], v[124:127]
	v_mfma_f32_16x16x32_bf16 v[120:123], v[168:171], v[192:195], v[120:123]
	v_mfma_f32_16x16x32_bf16 v[108:111], v[160:163], v[200:203], v[108:111]
	v_mfma_f32_16x16x32_bf16 v[104:107], v[168:171], v[200:203], v[104:107]
	v_mfma_f32_16x16x32_bf16 v[92:95], v[160:163], v[216:219], v[92:95]
	v_mfma_f32_16x16x32_bf16 v[88:91], v[168:171], v[216:219], v[88:91]
	v_mfma_f32_16x16x32_bf16 v[76:79], v[160:163], v[224:227], v[76:79]
	v_mfma_f32_16x16x32_bf16 v[72:75], v[168:171], v[224:227], v[72:75]
	s_setprio 0
	s_setprio 1
	v_mfma_f32_16x16x32_bf16 v[116:119], v[172:175], v[188:191], v[116:119]
	v_mfma_f32_16x16x32_bf16 v[112:115], v[180:183], v[188:191], v[112:115]
	v_mfma_f32_16x16x32_bf16 v[100:103], v[172:175], v[196:199], v[100:103]
	v_mfma_f32_16x16x32_bf16 v[96:99], v[180:183], v[196:199], v[96:99]
	v_mfma_f32_16x16x32_bf16 v[84:87], v[172:175], v[212:215], v[84:87]
	v_mfma_f32_16x16x32_bf16 v[80:83], v[180:183], v[212:215], v[80:83]
	v_mfma_f32_16x16x32_bf16 v[68:71], v[172:175], v[220:223], v[68:71]
	v_mfma_f32_16x16x32_bf16 v[64:67], v[180:183], v[220:223], v[64:67]
	v_mfma_f32_16x16x32_bf16 v[116:119], v[176:179], v[192:195], v[116:119]
	v_mfma_f32_16x16x32_bf16 v[112:115], v[184:187], v[192:195], v[112:115]
	v_mfma_f32_16x16x32_bf16 v[100:103], v[176:179], v[200:203], v[100:103]
	v_mfma_f32_16x16x32_bf16 v[96:99], v[184:187], v[200:203], v[96:99]
	v_mfma_f32_16x16x32_bf16 v[84:87], v[176:179], v[216:219], v[84:87]
	v_mfma_f32_16x16x32_bf16 v[80:83], v[184:187], v[216:219], v[80:83]
	v_mfma_f32_16x16x32_bf16 v[68:71], v[176:179], v[224:227], v[68:71]
	v_mfma_f32_16x16x32_bf16 v[64:67], v[184:187], v[224:227], v[64:67]
	s_setprio 0
	s_barrier
	s_add_i32 s26, s33, s54
	s_add_i32 m0, s26, 0xffffff80
	ds_read_b128 v[188:191], v152 offset:49152
	ds_read_b128 v[192:195], v152 offset:50176
	ds_read_b128 v[196:199], v152 offset:51200
	ds_read_b128 v[200:203], v152 offset:52224
	ds_read_b128 v[212:215], v152 offset:53248
	ds_read_b128 v[216:219], v152 offset:54272
	ds_read_b128 v[220:223], v152 offset:55296
	ds_read_b128 v[224:227], v152 offset:56320
	global_load_lds_dwordx4 v132, s[50:51] offset:128
	s_add_i32 m0, s26, 0x1f80
	s_add_u32 s26, s50, 0x20080
	s_addc_u32 s27, s51, 0
	s_add_i32 s33, s77, s54
	global_load_lds_dwordx4 v128, s[50:51] offset:128
	s_mov_b32 m0, s33
	s_nop 0
	global_load_lds_dwordx4 v132, s[26:27]
	s_add_i32 m0, s33, 0x2000
	s_nop 0
	global_load_lds_dwordx4 v128, s[26:27]
	s_add_i32 m0, s61, 0xffffff80
	s_nop 0
	global_load_lds_dwordx4 v134, s[52:53] offset:128
	s_add_i32 m0, s62, 0xffffff80
	s_nop 0
	global_load_lds_dwordx4 v130, s[52:53] offset:128
	s_waitcnt vmcnt(8)
	s_waitcnt lgkmcnt(0)
	s_barrier
	s_setprio 1
	s_waitcnt lgkmcnt(0)
	v_mfma_f32_16x16x32_bf16 v[60:63], v[156:159], v[188:191], v[60:63]
	v_mfma_f32_16x16x32_bf16 v[56:59], v[164:167], v[188:191], v[56:59]
	v_mfma_f32_16x16x32_bf16 v[44:47], v[156:159], v[196:199], v[44:47]
	v_mfma_f32_16x16x32_bf16 v[40:43], v[164:167], v[196:199], v[40:43]
	v_mfma_f32_16x16x32_bf16 v[28:31], v[156:159], v[212:215], v[28:31]
	v_mfma_f32_16x16x32_bf16 v[24:27], v[164:167], v[212:215], v[24:27]
	v_mfma_f32_16x16x32_bf16 v[12:15], v[156:159], v[220:223], v[12:15]
	v_mfma_f32_16x16x32_bf16 v[8:11], v[164:167], v[220:223], v[8:11]
	v_mfma_f32_16x16x32_bf16 v[60:63], v[160:163], v[192:195], v[60:63]
	v_mfma_f32_16x16x32_bf16 v[56:59], v[168:171], v[192:195], v[56:59]
	v_mfma_f32_16x16x32_bf16 v[44:47], v[160:163], v[200:203], v[44:47]
	v_mfma_f32_16x16x32_bf16 v[40:43], v[168:171], v[200:203], v[40:43]
	v_mfma_f32_16x16x32_bf16 v[28:31], v[160:163], v[216:219], v[28:31]
	v_mfma_f32_16x16x32_bf16 v[24:27], v[168:171], v[216:219], v[24:27]
	v_mfma_f32_16x16x32_bf16 v[12:15], v[160:163], v[224:227], v[12:15]
	v_mfma_f32_16x16x32_bf16 v[8:11], v[168:171], v[224:227], v[8:11]
	s_setprio 0
	s_setprio 1
	v_mfma_f32_16x16x32_bf16 v[52:55], v[172:175], v[188:191], v[52:55]
	v_mfma_f32_16x16x32_bf16 v[48:51], v[180:183], v[188:191], v[48:51]
	v_mfma_f32_16x16x32_bf16 v[36:39], v[172:175], v[196:199], v[36:39]
	v_mfma_f32_16x16x32_bf16 v[32:35], v[180:183], v[196:199], v[32:35]
	v_mfma_f32_16x16x32_bf16 v[20:23], v[172:175], v[212:215], v[20:23]
	v_mfma_f32_16x16x32_bf16 v[16:19], v[180:183], v[212:215], v[16:19]
	v_mfma_f32_16x16x32_bf16 v[4:7], v[172:175], v[220:223], v[4:7]
	v_mfma_f32_16x16x32_bf16 v[0:3], v[180:183], v[220:223], v[0:3]
	v_mfma_f32_16x16x32_bf16 v[52:55], v[176:179], v[192:195], v[52:55]
	v_mfma_f32_16x16x32_bf16 v[48:51], v[184:187], v[192:195], v[48:51]
	v_mfma_f32_16x16x32_bf16 v[36:39], v[176:179], v[200:203], v[36:39]
	v_mfma_f32_16x16x32_bf16 v[32:35], v[184:187], v[200:203], v[32:35]
	v_mfma_f32_16x16x32_bf16 v[20:23], v[176:179], v[216:219], v[20:23]
	v_mfma_f32_16x16x32_bf16 v[16:19], v[184:187], v[216:219], v[16:19]
	v_mfma_f32_16x16x32_bf16 v[4:7], v[176:179], v[224:227], v[4:7]
	v_mfma_f32_16x16x32_bf16 v[0:3], v[184:187], v[224:227], v[0:3]
	s_setprio 0
	s_barrier
	s_add_i32 s76, s76, 2
	s_add_u32 s48, s48, 0x100
	s_addc_u32 s49, s49, 0
	s_add_u32 s74, s74, 0x100
	s_addc_u32 s75, s75, 0
	s_cmp_gt_u32 s76, 29
	s_cbranch_scc0 .LBB0_80
	s_mov_b32 s99, 1
	s_and_b64 vcc, exec, s[14:15]
	s_cbranch_vccz .LBB0_83
	s_barrier

; #define PG8_STAGE(bufoff, gbase, voff) do { _Pragma("unroll") for (int _i = 0; _i < 2; ++_i) \
;         __builtin_amdgcn_global_load_lds((const unsigned*)((const char*)(gbase) + (voff)[_i]), (PG8_LAS unsigned*)(lds + (bufoff) + ldsw + _i * 8192), 16, 0, 0); } while (0)
; #define PG8_WAIT_V(n) asm volatile("s_waitcnt vmcnt(" #n ")" ::: "memory")
; #define PG8_BAR __builtin_amdgcn_s_barrier()
; template <class Epi, class Sched, bool ALIGN_EPI = false, bool SP2 = false>
; __device__ __forceinline__ void gemm_phase(PG8_LAS unsigned char* lds, const Gemm g, const Sched& S, const Epi& E, int tid_in) {
;     ...
;     for (int i = 0; i < 2; ++i) { int R, C; stage_rc(tid * 16 + i * 8192, R, C); const int Rb = 2 * (R & ~31) + (Epi::PERM ? perm32(R & 31) : (R & 31));
;         voffA[i] = (unsigned)(R * g.lda + C) * 2u; voffB[i] = (unsigned)(Rb * K + C) * 2u; }
;     const size_t kstep = (size_t)(BK * 2);
;     const size_t hstep = (size_t)HALF * g.lda * 2;
;     const size_t hstepB = (size_t)32 * K * 2;
;     const size_t tstep = 2 * hstep, tstepB = (size_t)BM * K * 2;
;     const unsigned ldsw = (unsigned)wid * 1024u;
;     const int aoff = lds_byte(wr * 64 + fr, fq * 8), boff = lds_byte(wc * 32 + fr, fq * 8);
;     ...
;         PG8_WAIT_V(2); PG8_BAR;
;         PG8_STAGE(PG8_SB(1, 0), cB + kstep, voffB); PG8_STAGE(PG8_SA(1, 0), cA + kstep, voffA); PG8_STAGE(PG8_SB(1, 1), cB + hstepB + kstep, voffB);
;         PG8_WAIT_V(6); PG8_BAR;
.LBB0_282:
	s_mov_b64 s[42:43], 0x80
	s_and_b32 s8, s8, 3
	s_add_i32 m0, s57, 0x18000
	v_lshl_add_u64 v[6:7], v[6:7], 0, s[42:43]
	s_lshl_b32 s11, s9, 13
	s_lshl_b32 s33, s8, 12
	s_waitcnt vmcnt(2)
	s_barrier
	global_load_lds_dwordx4 v[6:7], off
	v_lshl_add_u64 v[4:5], v[4:5], 0, s[42:43]
	s_add_i32 m0, s57, 0x1a000
	s_add_i32 s71, s57, 0x8000
	s_add_i32 s72, s57, 0xa000
	global_load_lds_dwordx4 v[4:5], off
	v_lshl_add_u64 v[0:1], v[0:1], 0, s[42:43]
	s_mov_b32 m0, s71
	s_add_u32 s26, s60, 0x20080
	global_load_lds_dwordx4 v[0:1], off
	v_lshl_add_u64 v[0:1], v[2:3], 0, s[42:43]
	s_mov_b32 m0, s72
	s_addc_u32 s27, s61, 0
	global_load_lds_dwordx4 v[0:1], off
	s_add_i32 m0, s57, 0x1c000
	v_lshl_add_u64 v[0:1], s[26:27], 0, v[130:131]
	global_load_lds_dwordx4 v[0:1], off
	v_lshl_add_u64 v[0:1], s[26:27], 0, v[134:135]
	s_add_i32 m0, s57, 0x1e000
	s_cmpk_lt_u32 s10, 0x100
	global_load_lds_dwordx4 v[0:1], off
	s_cselect_b64 s[44:45], -1, 0
	s_lshl_b32 s10, s9, 2
	v_and_b32_e32 v0, 15, v8
	v_and_b32_e32 v1, 48, v8
	v_lshlrev_b32_e32 v3, 2, v8
	s_or_b32 s10, s10, s8
	v_lshl_or_b32 v2, v0, 6, v1
	v_and_b32_e32 v3, 32, v3
	s_mulk_i32 s10, 0x900
	v_bitop3_b32 v4, v2, s11, v3 bitop3:0xde
	v_bitop3_b32 v137, v2, s33, v3 bitop3:0xde
	v_and_b32_e32 v3, 3, v8
	s_add_i32 s10, s10, 0
	v_bfe_u32 v2, v8, 2, 4
	v_lshlrev_b32_e32 v5, 3, v3
	s_add_i32 s10, s10, 0x20000
	v_lshl_or_b32 v150, s9, 6, v2
	v_lshl_or_b32 v136, s8, 6, v5
	v_lshlrev_b32_e32 v5, 5, v3
	v_cmp_eq_u32_e64 s[8:9], 0, v3
	s_movk_i32 s11, 0x90
	v_mov_b32_e32 v3, s10
	v_mad_u32_u24 v0, v0, s11, v3
	v_mad_u32_u24 v2, v2, s11, v3
	v_and_b32_e32 v3, 64, v252
	v_add_u32_e32 v3, 64, v3
	v_cmp_lt_i32_e32 vcc, v254, v3
	s_waitcnt vmcnt(6)
	s_add_i32 s73, 0, 0x10000
	s_add_i32 s74, 0, 0x14000
	v_cndmask_b32_e32 v6, v252, v254, vcc
	v_cmp_lt_i32_e32 vcc, v253, v3
	v_lshlrev_b32_e32 v151, 2, v6
	v_and_b32_e32 v6, 1, v9
	v_cndmask_b32_e32 v3, v252, v253, vcc
	v_lshlrev_b32_e32 v152, 2, v3
	v_lshlrev_b32_e32 v3, 15, v9
	v_and_b32_e32 v3, 0xffff0000, v3
	v_lshl_add_u32 v3, v10, 12, v3
	v_lshl_or_b32 v3, v6, 6, v3
	v_lshl_add_u32 v138, v11, 1, v3
	v_lshlrev_b32_e32 v3, 15, v12
	v_and_b32_e32 v3, 0xffff0000, v3
	v_lshl_add_u32 v3, v13, 12, v3
	v_and_b32_e32 v6, 1, v12
	v_lshl_or_b32 v3, v6, 6, v3
	v_mov_b32_e32 v139, v131
	v_lshl_add_u32 v140, v14, 1, v3
	v_mov_b32_e32 v141, v131
	v_mov_b64_e32 v[142:143], 0x400
	v_mov_b64_e32 v[144:145], 0x3ff
	v_add_u32_e32 v153, s73, v137
	v_add_u32_e32 v154, s74, v137
	v_add_u32_e32 v155, 0, v4
	v_add_u32_e32 v156, v0, v1
	v_add_u32_e32 v157, v2, v5
	s_barrier
	s_mov_b32 s99, 0
	s_branch .LBB0_285

; #define PG8_STAGE(bufoff, gbase, voff) do { _Pragma("unroll") for (int _i = 0; _i < 2; ++_i) \
;         __builtin_amdgcn_global_load_lds((const unsigned*)((const char*)(gbase) + (voff)[_i]), (PG8_LAS unsigned*)(lds + (bufoff) + ldsw + _i * 8192), 16, 0, 0); } while (0)
; #define PG8_LDA(dst, b, h) do { _Pragma("unroll") for (int m = 0; m < 4; ++m) _Pragma("unroll") for (int k = 0; k < 2; ++k) dst[m][k] = *(const PG8_LAS bf16x8*)(lds + PG8_SA(b, h) + aoff + m * 2048 + k * 1024); } while (0)
; #define PG8_LDB(dst, b, h) do { _Pragma("unroll") for (int n = 0; n < 2; ++n) _Pragma("unroll") for (int k = 0; k < 2; ++k) dst[n][k] = *(const PG8_LAS bf16x8*)(lds + PG8_SB(b, h) + boff + n * 2048 + k * 1024); } while (0)
; #define PG8_SCHED __builtin_amdgcn_sched_barrier(0)
; template <class Epi, class Sched, bool ALIGN_EPI = false, bool SP2 = false>
; __device__ __forceinline__ void gemm_phase(PG8_LAS unsigned char* lds, const Gemm g, const Sched& S, const Epi& E, int tid_in) {
;     ...
;             const bool last = (t == nt - 2);
;             const char* a1 = cA + (size_t)(t + 1) * kstep;
;             const char* a2 = last ? nA : cA + (size_t)(t + 2) * kstep; const char* b2 = last ? nB : cB + (size_t)(t + 2) * kstep;
;             const char* a3 = a2 + kstep; const char* b3 = b2 + kstep;
;             if (last && has_next) S.a_ready(nxt);
;             if constexpr (SP2) {
;             PG8_LDB(B0, 0, 0); PG8_LDB(B1, 0, 1); PG8_SCHED; PG8_LDA(At, 0, 0); PG8_STAGE(PG8_SA(1, 1), a1 + hstep, voffA);
.Lkb_skip_1:
	ds_read_b128 v[146:149], v153
	ds_read_b128 v[158:161], v153 offset:1024
	ds_read_b128 v[162:165], v153 offset:2048
	ds_read_b128 v[166:169], v153 offset:3072
	ds_read_b128 v[170:173], v154
	ds_read_b128 v[174:177], v154 offset:1024
	ds_read_b128 v[178:181], v154 offset:2048
	ds_read_b128 v[182:185], v154 offset:3072
	s_add_u32 s26, s58, 0xfff80080
	s_addc_u32 s27, s59, -1
	s_cmp_eq_u32 s79, 28
	s_cselect_b32 s63, s49, s27
	s_cselect_b32 s62, s55, s26
	s_cselect_b32 s61, s47, s77
	s_cselect_b32 s60, s75, s76
	s_add_i32 m0, s57, 0xc000
	ds_read_b128 v[186:189], v155
	ds_read_b128 v[190:193], v155 offset:1024
	ds_read_b128 v[194:197], v155 offset:2048
	ds_read_b128 v[198:201], v155 offset:3072
	ds_read_b128 v[202:205], v155 offset:4096
	ds_read_b128 v[206:209], v155 offset:5120
	ds_read_b128 v[212:215], v155 offset:6144
	ds_read_b128 v[216:219], v155 offset:7168
	global_load_lds_dwordx4 v138, s[58:59]
	s_add_i32 m0, s57, 0xe000
	s_nop 0
	global_load_lds_dwordx4 v140, s[58:59]
	s_cmp_eq_u32 s99, 0
	s_cbranch_scc1 .Lw1s_1_0
	s_waitcnt vmcnt(63)
	s_branch .Lw1d_1_0

; #define PG8_STAGE(bufoff, gbase, voff) do { _Pragma("unroll") for (int _i = 0; _i < 2; ++_i) \
;         __builtin_amdgcn_global_load_lds((const unsigned*)((const char*)(gbase) + (voff)[_i]), (PG8_LAS unsigned*)(lds + (bufoff) + ldsw + _i * 8192), 16, 0, 0); } while (0)
; #define PG8_LDA(dst, b, h) do { _Pragma("unroll") for (int m = 0; m < 4; ++m) _Pragma("unroll") for (int k = 0; k < 2; ++k) dst[m][k] = *(const PG8_LAS bf16x8*)(lds + PG8_SA(b, h) + aoff + m * 2048 + k * 1024); } while (0)
; #define PG8_MMA(ai, bj, At, Bt) do { __builtin_amdgcn_s_setprio(1); _Pragma("unroll") for (int m = 0; m < 4; ++m) _Pragma("unroll") for (int n = 0; n < 2; ++n) _Pragma("unroll") for (int k = 0; k < 2; ++k) \
;         acc[ai][bj][m][n] = __builtin_amdgcn_mfma_f32_16x16x32_bf16(Bt[n][k], At[m][k], acc[ai][bj][m][n], 0, 0, 0); __builtin_amdgcn_s_setprio(0); } while (0)
; #define PG8_WAIT_V(n) asm volatile("s_waitcnt vmcnt(" #n ")" ::: "memory")
; #define PG8_WAIT_L(n) asm volatile("s_waitcnt lgkmcnt(" #n ")" ::: "memory")
; #define PG8_BAR __builtin_amdgcn_s_barrier()
; #define PG8_SCHED __builtin_amdgcn_sched_barrier(0)
; template <class Epi, class Sched, bool ALIGN_EPI = false, bool SP2 = false>
; __device__ __forceinline__ void gemm_phase(PG8_LAS unsigned char* lds, const Gemm g, const Sched& S, const Epi& E, int tid_in) {
;     ...
;             PG8_WAIT_V(8); PG8_WAIT_L(0); PG8_BAR; PG8_MMA(0, 0, At, B0); PG8_MMA(0, 1, At, B1); PG8_BAR; PG8_SCHED;
;             PG8_LDA(At, 0, 1); PG8_STAGE(PG8_SB(0, 0), b2, voffB); PG8_STAGE(PG8_SB(0, 1), b2 + hstepB, voffB); PG8_STAGE(PG8_SA(0, 0), a2, voffA);
.Lw1d_1_0:
	s_waitcnt lgkmcnt(0)
	s_barrier
	s_setprio 1
	s_waitcnt lgkmcnt(0)
	v_mfma_f32_16x16x32_bf16 v[124:127], v[146:149], v[186:189], 0
	v_mfma_f32_16x16x32_bf16 v[120:123], v[162:165], v[186:189], 0
	v_mfma_f32_16x16x32_bf16 v[108:111], v[146:149], v[194:197], 0
	v_mfma_f32_16x16x32_bf16 v[104:107], v[162:165], v[194:197], 0
	v_mfma_f32_16x16x32_bf16 v[92:95], v[146:149], v[202:205], 0
	v_mfma_f32_16x16x32_bf16 v[88:91], v[162:165], v[202:205], 0
	v_mfma_f32_16x16x32_bf16 v[76:79], v[146:149], v[212:215], 0
	v_mfma_f32_16x16x32_bf16 v[72:75], v[162:165], v[212:215], 0
	v_mfma_f32_16x16x32_bf16 v[124:127], v[158:161], v[190:193], v[124:127]
	v_mfma_f32_16x16x32_bf16 v[120:123], v[166:169], v[190:193], v[120:123]
	v_mfma_f32_16x16x32_bf16 v[108:111], v[158:161], v[198:201], v[108:111]
	v_mfma_f32_16x16x32_bf16 v[104:107], v[166:169], v[198:201], v[104:107]
	v_mfma_f32_16x16x32_bf16 v[92:95], v[158:161], v[206:209], v[92:95]
	v_mfma_f32_16x16x32_bf16 v[88:91], v[166:169], v[206:209], v[88:91]
	v_mfma_f32_16x16x32_bf16 v[76:79], v[158:161], v[216:219], v[76:79]
	v_mfma_f32_16x16x32_bf16 v[72:75], v[166:169], v[216:219], v[72:75]
	s_setprio 0
	s_setprio 1
	v_mfma_f32_16x16x32_bf16 v[116:119], v[170:173], v[186:189], 0
	v_mfma_f32_16x16x32_bf16 v[112:115], v[178:181], v[186:189], 0
	v_mfma_f32_16x16x32_bf16 v[100:103], v[170:173], v[194:197], 0
	v_mfma_f32_16x16x32_bf16 v[96:99], v[178:181], v[194:197], 0
	v_mfma_f32_16x16x32_bf16 v[84:87], v[170:173], v[202:205], 0
	v_mfma_f32_16x16x32_bf16 v[80:83], v[178:181], v[202:205], 0
	v_mfma_f32_16x16x32_bf16 v[68:71], v[170:173], v[212:215], 0
	v_mfma_f32_16x16x32_bf16 v[64:67], v[178:181], v[212:215], 0
	v_mfma_f32_16x16x32_bf16 v[116:119], v[174:177], v[190:193], v[116:119]
	v_mfma_f32_16x16x32_bf16 v[112:115], v[182:185], v[190:193], v[112:115]
	v_mfma_f32_16x16x32_bf16 v[100:103], v[174:177], v[198:201], v[100:103]
	v_mfma_f32_16x16x32_bf16 v[96:99], v[182:185], v[198:201], v[96:99]
	v_mfma_f32_16x16x32_bf16 v[84:87], v[174:177], v[206:209], v[84:87]
	v_mfma_f32_16x16x32_bf16 v[80:83], v[182:185], v[206:209], v[80:83]
	v_mfma_f32_16x16x32_bf16 v[68:71], v[174:177], v[216:219], v[68:71]
	v_mfma_f32_16x16x32_bf16 v[64:67], v[182:185], v[216:219], v[64:67]
	s_setprio 0
	s_barrier
	s_add_i32 s26, s73, s66
	s_mov_b32 m0, s26
	ds_read_b128 v[186:189], v155 offset:16384
	ds_read_b128 v[190:193], v155 offset:17408
	ds_read_b128 v[194:197], v155 offset:18432
	ds_read_b128 v[198:201], v155 offset:19456
	ds_read_b128 v[202:205], v155 offset:20480
	ds_read_b128 v[206:209], v155 offset:21504
	ds_read_b128 v[212:215], v155 offset:22528
	ds_read_b128 v[216:219], v155 offset:23552
	global_load_lds_dwordx4 v130, s[60:61]
	s_add_i32 m0, s26, 0x2000
	s_add_u32 s26, s60, 0x20000
	s_addc_u32 s27, s61, 0
	s_add_i32 s33, s74, s66
	global_load_lds_dwordx4 v134, s[60:61]
	s_mov_b32 m0, s33
	s_nop 0
	global_load_lds_dwordx4 v130, s[26:27]
	s_add_i32 m0, s33, 0x2000
	s_nop 0
	global_load_lds_dwordx4 v134, s[26:27]
	s_mov_b32 m0, s57
	s_nop 0
	global_load_lds_dwordx4 v128, s[62:63]
	s_mov_b32 m0, s67
	s_nop 0
	global_load_lds_dwordx4 v132, s[62:63]
	s_cmp_eq_u32 s99, 0
	s_cbranch_scc1 .Lw1s_1_1
	s_waitcnt vmcnt(63)
	s_branch .Lw1d_1_1

; #define PG8_STAGE(bufoff, gbase, voff) do { _Pragma("unroll") for (int _i = 0; _i < 2; ++_i) \
;         __builtin_amdgcn_global_load_lds((const unsigned*)((const char*)(gbase) + (voff)[_i]), (PG8_LAS unsigned*)(lds + (bufoff) + ldsw + _i * 8192), 16, 0, 0); } while (0)
; #define PG8_LDA(dst, b, h) do { _Pragma("unroll") for (int m = 0; m < 4; ++m) _Pragma("unroll") for (int k = 0; k < 2; ++k) dst[m][k] = *(const PG8_LAS bf16x8*)(lds + PG8_SA(b, h) + aoff + m * 2048 + k * 1024); } while (0)
; #define PG8_LDB(dst, b, h) do { _Pragma("unroll") for (int n = 0; n < 2; ++n) _Pragma("unroll") for (int k = 0; k < 2; ++k) dst[n][k] = *(const PG8_LAS bf16x8*)(lds + PG8_SB(b, h) + boff + n * 2048 + k * 1024); } while (0)
; #define PG8_MMA(ai, bj, At, Bt) do { __builtin_amdgcn_s_setprio(1); _Pragma("unroll") for (int m = 0; m < 4; ++m) _Pragma("unroll") for (int n = 0; n < 2; ++n) _Pragma("unroll") for (int k = 0; k < 2; ++k) \
;         acc[ai][bj][m][n] = __builtin_amdgcn_mfma_f32_16x16x32_bf16(Bt[n][k], At[m][k], acc[ai][bj][m][n], 0, 0, 0); __builtin_amdgcn_s_setprio(0); } while (0)
; #define PG8_WAIT_V(n) asm volatile("s_waitcnt vmcnt(" #n ")" ::: "memory")
; #define PG8_WAIT_L(n) asm volatile("s_waitcnt lgkmcnt(" #n ")" ::: "memory")
; #define PG8_BAR __builtin_amdgcn_s_barrier()
; #define PG8_SCHED __builtin_amdgcn_sched_barrier(0)
; template <class Epi, class Sched, bool ALIGN_EPI = false, bool SP2 = false>
; __device__ __forceinline__ void gemm_phase(PG8_LAS unsigned char* lds, const Gemm g, const Sched& S, const Epi& E, int tid_in) {
;     ...
;             PG8_WAIT_V(8); PG8_WAIT_L(0); PG8_BAR; PG8_MMA(1, 0, At, B0); PG8_MMA(1, 1, At, B1); PG8_BAR; PG8_SCHED;
;             PG8_LDB(B0, 1, 0); PG8_LDB(B1, 1, 1); PG8_SCHED; PG8_LDA(At, 1, 0); PG8_STAGE(PG8_SA(0, 1), a2 + hstep, voffA);
;             PG8_WAIT_V(8); PG8_WAIT_L(0); PG8_BAR; PG8_MMA(0, 0, At, B0); PG8_MMA(0, 1, At, B1); PG8_BAR; PG8_SCHED;
.Lw1d_1_1:
	s_waitcnt lgkmcnt(0)
	s_barrier
	s_setprio 1
	s_waitcnt lgkmcnt(0)
	v_mfma_f32_16x16x32_bf16 v[60:63], v[146:149], v[186:189], 0
	v_mfma_f32_16x16x32_bf16 v[56:59], v[162:165], v[186:189], 0
	v_mfma_f32_16x16x32_bf16 v[44:47], v[146:149], v[194:197], 0
	v_mfma_f32_16x16x32_bf16 v[40:43], v[162:165], v[194:197], 0
	v_mfma_f32_16x16x32_bf16 v[28:31], v[146:149], v[202:205], 0
	v_mfma_f32_16x16x32_bf16 v[24:27], v[162:165], v[202:205], 0
	v_mfma_f32_16x16x32_bf16 v[12:15], v[146:149], v[212:215], 0
	v_mfma_f32_16x16x32_bf16 v[8:11], v[162:165], v[212:215], 0
	v_mfma_f32_16x16x32_bf16 v[60:63], v[158:161], v[190:193], v[60:63]
	v_mfma_f32_16x16x32_bf16 v[56:59], v[166:169], v[190:193], v[56:59]
	v_mfma_f32_16x16x32_bf16 v[44:47], v[158:161], v[198:201], v[44:47]
	v_mfma_f32_16x16x32_bf16 v[40:43], v[166:169], v[198:201], v[40:43]
	v_mfma_f32_16x16x32_bf16 v[28:31], v[158:161], v[206:209], v[28:31]
	v_mfma_f32_16x16x32_bf16 v[24:27], v[166:169], v[206:209], v[24:27]
	v_mfma_f32_16x16x32_bf16 v[12:15], v[158:161], v[216:219], v[12:15]
	v_mfma_f32_16x16x32_bf16 v[8:11], v[166:169], v[216:219], v[8:11]
	s_setprio 0
	s_setprio 1
	v_mfma_f32_16x16x32_bf16 v[52:55], v[170:173], v[186:189], 0
	v_mfma_f32_16x16x32_bf16 v[48:51], v[178:181], v[186:189], 0
	v_mfma_f32_16x16x32_bf16 v[36:39], v[170:173], v[194:197], 0
	v_mfma_f32_16x16x32_bf16 v[32:35], v[178:181], v[194:197], 0
	v_mfma_f32_16x16x32_bf16 v[20:23], v[170:173], v[202:205], 0
	v_mfma_f32_16x16x32_bf16 v[16:19], v[178:181], v[202:205], 0
	v_mfma_f32_16x16x32_bf16 v[4:7], v[170:173], v[212:215], 0
	v_mfma_f32_16x16x32_bf16 v[0:3], v[178:181], v[212:215], 0
	v_mfma_f32_16x16x32_bf16 v[52:55], v[174:177], v[190:193], v[52:55]
	v_mfma_f32_16x16x32_bf16 v[48:51], v[182:185], v[190:193], v[48:51]
	v_mfma_f32_16x16x32_bf16 v[36:39], v[174:177], v[198:201], v[36:39]
	v_mfma_f32_16x16x32_bf16 v[32:35], v[182:185], v[198:201], v[32:35]
	v_mfma_f32_16x16x32_bf16 v[20:23], v[174:177], v[206:209], v[20:23]
	v_mfma_f32_16x16x32_bf16 v[16:19], v[182:185], v[206:209], v[16:19]
	v_mfma_f32_16x16x32_bf16 v[4:7], v[174:177], v[216:219], v[4:7]
	v_mfma_f32_16x16x32_bf16 v[0:3], v[182:185], v[216:219], v[0:3]
	s_setprio 0
	s_barrier
	s_add_i32 s33, 0, 0x18000
	s_add_i32 s84, 0, 0x1c000
	v_add_u32_e32 v166, s33, v137
	v_add_u32_e32 v182, s84, v137
	ds_read_b128 v[146:149], v166
	ds_read_b128 v[158:161], v166 offset:1024
	ds_read_b128 v[162:165], v166 offset:2048
	ds_read_b128 v[166:169], v166 offset:3072
	ds_read_b128 v[170:173], v182
	ds_read_b128 v[174:177], v182 offset:1024
	ds_read_b128 v[178:181], v182 offset:2048
	ds_read_b128 v[182:185], v182 offset:3072
	s_add_u32 s26, s62, 0x80000
	s_addc_u32 s27, s63, 0
	s_mov_b32 m0, s68
	ds_read_b128 v[186:189], v155 offset:32768
	ds_read_b128 v[190:193], v155 offset:33792
	ds_read_b128 v[194:197], v155 offset:34816
	ds_read_b128 v[198:201], v155 offset:35840
	ds_read_b128 v[202:205], v155 offset:36864
	ds_read_b128 v[206:209], v155 offset:37888
	ds_read_b128 v[212:215], v155 offset:38912
	ds_read_b128 v[216:219], v155 offset:39936
	global_load_lds_dwordx4 v128, s[26:27]
	s_mov_b32 m0, s69
	s_nop 0
	global_load_lds_dwordx4 v132, s[26:27]
	s_waitcnt vmcnt(8)
	s_waitcnt lgkmcnt(0)
	s_barrier
	s_setprio 1
	s_waitcnt lgkmcnt(0)
	v_mfma_f32_16x16x32_bf16 v[124:127], v[146:149], v[186:189], v[124:127]
	v_mfma_f32_16x16x32_bf16 v[120:123], v[162:165], v[186:189], v[120:123]
	v_mfma_f32_16x16x32_bf16 v[108:111], v[146:149], v[194:197], v[108:111]
	v_mfma_f32_16x16x32_bf16 v[104:107], v[162:165], v[194:197], v[104:107]
	v_mfma_f32_16x16x32_bf16 v[92:95], v[146:149], v[202:205], v[92:95]
	v_mfma_f32_16x16x32_bf16 v[88:91], v[162:165], v[202:205], v[88:91]
	v_mfma_f32_16x16x32_bf16 v[76:79], v[146:149], v[212:215], v[76:79]
	v_mfma_f32_16x16x32_bf16 v[72:75], v[162:165], v[212:215], v[72:75]
	v_mfma_f32_16x16x32_bf16 v[124:127], v[158:161], v[190:193], v[124:127]
	v_mfma_f32_16x16x32_bf16 v[120:123], v[166:169], v[190:193], v[120:123]
	v_mfma_f32_16x16x32_bf16 v[108:111], v[158:161], v[198:201], v[108:111]
	v_mfma_f32_16x16x32_bf16 v[104:107], v[166:169], v[198:201], v[104:107]
	v_mfma_f32_16x16x32_bf16 v[92:95], v[158:161], v[206:209], v[92:95]
	v_mfma_f32_16x16x32_bf16 v[88:91], v[166:169], v[206:209], v[88:91]
	v_mfma_f32_16x16x32_bf16 v[76:79], v[158:161], v[216:219], v[76:79]
	v_mfma_f32_16x16x32_bf16 v[72:75], v[166:169], v[216:219], v[72:75]
	s_setprio 0
	s_setprio 1
	v_mfma_f32_16x16x32_bf16 v[116:119], v[170:173], v[186:189], v[116:119]
	v_mfma_f32_16x16x32_bf16 v[112:115], v[178:181], v[186:189], v[112:115]
	v_mfma_f32_16x16x32_bf16 v[100:103], v[170:173], v[194:197], v[100:103]
	v_mfma_f32_16x16x32_bf16 v[96:99], v[178:181], v[194:197], v[96:99]
	v_mfma_f32_16x16x32_bf16 v[84:87], v[170:173], v[202:205], v[84:87]
	v_mfma_f32_16x16x32_bf16 v[80:83], v[178:181], v[202:205], v[80:83]
	v_mfma_f32_16x16x32_bf16 v[68:71], v[170:173], v[212:215], v[68:71]
	v_mfma_f32_16x16x32_bf16 v[64:67], v[178:181], v[212:215], v[64:67]
	v_mfma_f32_16x16x32_bf16 v[116:119], v[174:177], v[190:193], v[116:119]
	v_mfma_f32_16x16x32_bf16 v[112:115], v[182:185], v[190:193], v[112:115]
	v_mfma_f32_16x16x32_bf16 v[100:103], v[174:177], v[198:201], v[100:103]
	v_mfma_f32_16x16x32_bf16 v[96:99], v[182:185], v[198:201], v[96:99]
	v_mfma_f32_16x16x32_bf16 v[84:87], v[174:177], v[206:209], v[84:87]
	v_mfma_f32_16x16x32_bf16 v[80:83], v[182:185], v[206:209], v[80:83]
	v_mfma_f32_16x16x32_bf16 v[68:71], v[174:177], v[216:219], v[68:71]
	v_mfma_f32_16x16x32_bf16 v[64:67], v[182:185], v[216:219], v[64:67]
	s_setprio 0
	s_barrier
; #define PG8_STAGE(bufoff, gbase, voff) do { _Pragma("unroll") for (int _i = 0; _i < 2; ++_i) \
;         __builtin_amdgcn_global_load_lds((const unsigned*)((const char*)(gbase) + (voff)[_i]), (PG8_LAS unsigned*)(lds + (bufoff) + ldsw + _i * 8192), 16, 0, 0); } while (0)
; #define PG8_LDA(dst, b, h) do { _Pragma("unroll") for (int m = 0; m < 4; ++m) _Pragma("unroll") for (int k = 0; k < 2; ++k) dst[m][k] = *(const PG8_LAS bf16x8*)(lds + PG8_SA(b, h) + aoff + m * 2048 + k * 1024); } while (0)
; #define PG8_LDB(dst, b, h) do { _Pragma("unroll") for (int n = 0; n < 2; ++n) _Pragma("unroll") for (int k = 0; k < 2; ++k) dst[n][k] = *(const PG8_LAS bf16x8*)(lds + PG8_SB(b, h) + boff + n * 2048 + k * 1024); } while (0)
; #define PG8_MMA(ai, bj, At, Bt) do { __builtin_amdgcn_s_setprio(1); _Pragma("unroll") for (int m = 0; m < 4; ++m) _Pragma("unroll") for (int n = 0; n < 2; ++n) _Pragma("unroll") for (int k = 0; k < 2; ++k) \
;         acc[ai][bj][m][n] = __builtin_amdgcn_mfma_f32_16x16x32_bf16(Bt[n][k], At[m][k], acc[ai][bj][m][n], 0, 0, 0); __builtin_amdgcn_s_setprio(0); } while (0)
; #define PG8_WAIT_V(n) asm volatile("s_waitcnt vmcnt(" #n ")" ::: "memory")
; #define PG8_WAIT_L(n) asm volatile("s_waitcnt lgkmcnt(" #n ")" ::: "memory")
; #define PG8_BAR __builtin_amdgcn_s_barrier()
; #define PG8_SCHED __builtin_amdgcn_sched_barrier(0)
; template <class Epi, class Sched, bool ALIGN_EPI = false, bool SP2 = false>
; __device__ __forceinline__ void gemm_phase(PG8_LAS unsigned char* lds, const Gemm g, const Sched& S, const Epi& E, int tid_in) {
;     ...
;             PG8_LDB(B0, 0, 0); PG8_LDB(B1, 0, 1); PG8_SCHED; PG8_LDA(At, 0, 0); PG8_STAGE(PG8_SA(1, 1), a1 + hstep, voffA);
;             PG8_WAIT_V(8); PG8_WAIT_L(0); PG8_BAR; PG8_MMA(0, 0, At, B0); PG8_MMA(0, 1, At, B1); PG8_BAR; PG8_SCHED;
;     ...
;             PG8_LDA(At, 1, 1); PG8_STAGE(PG8_SB(1, 0), b3, voffB); PG8_STAGE(PG8_SB(1, 1), b3 + hstepB, voffB); PG8_STAGE(PG8_SA(1, 0), a3, voffA);
;             PG8_WAIT_V(8); PG8_WAIT_L(0); PG8_BAR; PG8_MMA(1, 0, At, B0); PG8_MMA(1, 1, At, B1); PG8_BAR; PG8_SCHED;
	s_add_i32 s26, s33, s66
	s_add_i32 m0, s26, 0xffffff80
	ds_read_b128 v[186:189], v155 offset:49152
	ds_read_b128 v[190:193], v155 offset:50176
	ds_read_b128 v[194:197], v155 offset:51200
	ds_read_b128 v[198:201], v155 offset:52224
	ds_read_b128 v[202:205], v155 offset:53248
	ds_read_b128 v[206:209], v155 offset:54272
	ds_read_b128 v[212:215], v155 offset:55296
	ds_read_b128 v[216:219], v155 offset:56320
	global_load_lds_dwordx4 v130, s[60:61] offset:128
	s_add_i32 m0, s26, 0x1f80
	s_add_u32 s26, s60, 0x20080
	s_addc_u32 s27, s61, 0
	s_add_i32 s33, s84, s66
	global_load_lds_dwordx4 v134, s[60:61] offset:128
	s_mov_b32 m0, s33
	s_nop 0
	global_load_lds_dwordx4 v130, s[26:27]
	s_add_i32 m0, s33, 0x2000
	s_nop 0
	global_load_lds_dwordx4 v134, s[26:27]
	s_add_i32 m0, s71, 0xffffff80
	s_nop 0
	global_load_lds_dwordx4 v128, s[62:63] offset:128
	s_add_i32 m0, s72, 0xffffff80
	s_nop 0
	global_load_lds_dwordx4 v132, s[62:63] offset:128
	s_waitcnt vmcnt(8)
	s_waitcnt lgkmcnt(0)
	s_barrier
	s_setprio 1
	s_waitcnt lgkmcnt(0)
	v_mfma_f32_16x16x32_bf16 v[60:63], v[146:149], v[186:189], v[60:63]
	v_mfma_f32_16x16x32_bf16 v[56:59], v[162:165], v[186:189], v[56:59]
	v_mfma_f32_16x16x32_bf16 v[44:47], v[146:149], v[194:197], v[44:47]
	v_mfma_f32_16x16x32_bf16 v[40:43], v[162:165], v[194:197], v[40:43]
	v_mfma_f32_16x16x32_bf16 v[28:31], v[146:149], v[202:205], v[28:31]
	v_mfma_f32_16x16x32_bf16 v[24:27], v[162:165], v[202:205], v[24:27]
	v_mfma_f32_16x16x32_bf16 v[12:15], v[146:149], v[212:215], v[12:15]
	v_mfma_f32_16x16x32_bf16 v[8:11], v[162:165], v[212:215], v[8:11]
	v_mfma_f32_16x16x32_bf16 v[60:63], v[158:161], v[190:193], v[60:63]
	v_mfma_f32_16x16x32_bf16 v[56:59], v[166:169], v[190:193], v[56:59]
	v_mfma_f32_16x16x32_bf16 v[44:47], v[158:161], v[198:201], v[44:47]
	v_mfma_f32_16x16x32_bf16 v[40:43], v[166:169], v[198:201], v[40:43]
	v_mfma_f32_16x16x32_bf16 v[28:31], v[158:161], v[206:209], v[28:31]
	v_mfma_f32_16x16x32_bf16 v[24:27], v[166:169], v[206:209], v[24:27]
	v_mfma_f32_16x16x32_bf16 v[12:15], v[158:161], v[216:219], v[12:15]
	v_mfma_f32_16x16x32_bf16 v[8:11], v[166:169], v[216:219], v[8:11]
	s_setprio 0
	s_setprio 1
	v_mfma_f32_16x16x32_bf16 v[52:55], v[170:173], v[186:189], v[52:55]
	v_mfma_f32_16x16x32_bf16 v[48:51], v[178:181], v[186:189], v[48:51]
	v_mfma_f32_16x16x32_bf16 v[36:39], v[170:173], v[194:197], v[36:39]
	v_mfma_f32_16x16x32_bf16 v[32:35], v[178:181], v[194:197], v[32:35]
	v_mfma_f32_16x16x32_bf16 v[20:23], v[170:173], v[202:205], v[20:23]
	v_mfma_f32_16x16x32_bf16 v[16:19], v[178:181], v[202:205], v[16:19]
	v_mfma_f32_16x16x32_bf16 v[4:7], v[170:173], v[212:215], v[4:7]
	v_mfma_f32_16x16x32_bf16 v[0:3], v[178:181], v[212:215], v[0:3]
	v_mfma_f32_16x16x32_bf16 v[52:55], v[174:177], v[190:193], v[52:55]
	v_mfma_f32_16x16x32_bf16 v[48:51], v[182:185], v[190:193], v[48:51]
	v_mfma_f32_16x16x32_bf16 v[36:39], v[174:177], v[198:201], v[36:39]
	v_mfma_f32_16x16x32_bf16 v[32:35], v[182:185], v[198:201], v[32:35]
	v_mfma_f32_16x16x32_bf16 v[20:23], v[174:177], v[206:209], v[20:23]
	v_mfma_f32_16x16x32_bf16 v[16:19], v[182:185], v[206:209], v[16:19]
	v_mfma_f32_16x16x32_bf16 v[4:7], v[174:177], v[216:219], v[4:7]
	v_mfma_f32_16x16x32_bf16 v[0:3], v[182:185], v[216:219], v[0:3]
	s_setprio 0
	s_barrier
	s_add_i32 s79, s79, 2
	s_add_u32 s58, s58, 0x100
	s_addc_u32 s59, s59, 0
	s_add_u32 s76, s76, 0x100
	s_addc_u32 s77, s77, 0
	s_cmp_gt_u32 s79, 29
.LBB0_292:
	ds_read_b128 v[146:149], v153
	ds_read_b128 v[158:161], v153 offset:1024
	ds_read_b128 v[162:165], v153 offset:2048
	ds_read_b128 v[166:169], v153 offset:3072
	ds_read_b128 v[170:173], v154
	ds_read_b128 v[174:177], v154 offset:1024
	ds_read_b128 v[178:181], v154 offset:2048
	ds_read_b128 v[182:185], v154 offset:3072
	s_add_u32 s26, s58, 0xfff80080
	s_addc_u32 s27, s59, -1
	s_cmp_eq_u32 s79, 28
	s_cselect_b32 s63, s49, s27
	s_cselect_b32 s62, s55, s26
	s_cselect_b32 s61, s47, s77
	s_cselect_b32 s60, s75, s76
	s_add_i32 m0, s57, 0xc000
	ds_read_b128 v[186:189], v155
	ds_read_b128 v[190:193], v155 offset:1024
	ds_read_b128 v[194:197], v155 offset:2048
	ds_read_b128 v[198:201], v155 offset:3072
	ds_read_b128 v[202:205], v155 offset:4096
	ds_read_b128 v[206:209], v155 offset:5120
	ds_read_b128 v[212:215], v155 offset:6144
	ds_read_b128 v[216:219], v155 offset:7168
	global_load_lds_dwordx4 v138, s[58:59]
	s_add_i32 m0, s57, 0xe000
	s_nop 0
	global_load_lds_dwordx4 v140, s[58:59]
	s_waitcnt vmcnt(8)
	s_waitcnt lgkmcnt(0)
	s_barrier
; #define PG8_STAGE(bufoff, gbase, voff) do { _Pragma("unroll") for (int _i = 0; _i < 2; ++_i) \
;         __builtin_amdgcn_global_load_lds((const unsigned*)((const char*)(gbase) + (voff)[_i]), (PG8_LAS unsigned*)(lds + (bufoff) + ldsw + _i * 8192), 16, 0, 0); } while (0)
; #define PG8_LDA(dst, b, h) do { _Pragma("unroll") for (int m = 0; m < 4; ++m) _Pragma("unroll") for (int k = 0; k < 2; ++k) dst[m][k] = *(const PG8_LAS bf16x8*)(lds + PG8_SA(b, h) + aoff + m * 2048 + k * 1024); } while (0)
; #define PG8_MMA(ai, bj, At, Bt) do { __builtin_amdgcn_s_setprio(1); _Pragma("unroll") for (int m = 0; m < 4; ++m) _Pragma("unroll") for (int n = 0; n < 2; ++n) _Pragma("unroll") for (int k = 0; k < 2; ++k) \
;         acc[ai][bj][m][n] = __builtin_amdgcn_mfma_f32_16x16x32_bf16(Bt[n][k], At[m][k], acc[ai][bj][m][n], 0, 0, 0); __builtin_amdgcn_s_setprio(0); } while (0)
; #define PG8_WAIT_V(n) asm volatile("s_waitcnt vmcnt(" #n ")" ::: "memory")
; #define PG8_WAIT_L(n) asm volatile("s_waitcnt lgkmcnt(" #n ")" ::: "memory")
; #define PG8_BAR __builtin_amdgcn_s_barrier()
; #define PG8_SCHED __builtin_amdgcn_sched_barrier(0)
; template <class Epi, class Sched, bool ALIGN_EPI = false, bool SP2 = false>
; __device__ __forceinline__ void gemm_phase(PG8_LAS unsigned char* lds, const Gemm g, const Sched& S, const Epi& E, int tid_in) {
;     ...
;             PG8_WAIT_V(8); PG8_WAIT_L(0); PG8_BAR; PG8_MMA(0, 0, At, B0); PG8_MMA(0, 1, At, B1); PG8_BAR; PG8_SCHED;
;             PG8_LDA(At, 0, 1); PG8_STAGE(PG8_SB(0, 0), b2, voffB); PG8_STAGE(PG8_SB(0, 1), b2 + hstepB, voffB); PG8_STAGE(PG8_SA(0, 0), a2, voffA);
;             PG8_WAIT_V(8); PG8_WAIT_L(0); PG8_BAR; PG8_MMA(1, 0, At, B0); PG8_MMA(1, 1, At, B1); PG8_BAR; PG8_SCHED;
	s_setprio 1
	s_waitcnt lgkmcnt(0)
	v_mfma_f32_16x16x32_bf16 v[124:127], v[146:149], v[186:189], v[124:127]
	v_mfma_f32_16x16x32_bf16 v[120:123], v[162:165], v[186:189], v[120:123]
	v_mfma_f32_16x16x32_bf16 v[108:111], v[146:149], v[194:197], v[108:111]
	v_mfma_f32_16x16x32_bf16 v[104:107], v[162:165], v[194:197], v[104:107]
	v_mfma_f32_16x16x32_bf16 v[92:95], v[146:149], v[202:205], v[92:95]
	v_mfma_f32_16x16x32_bf16 v[88:91], v[162:165], v[202:205], v[88:91]
	v_mfma_f32_16x16x32_bf16 v[76:79], v[146:149], v[212:215], v[76:79]
	v_mfma_f32_16x16x32_bf16 v[72:75], v[162:165], v[212:215], v[72:75]
	v_mfma_f32_16x16x32_bf16 v[124:127], v[158:161], v[190:193], v[124:127]
	v_mfma_f32_16x16x32_bf16 v[120:123], v[166:169], v[190:193], v[120:123]
	v_mfma_f32_16x16x32_bf16 v[108:111], v[158:161], v[198:201], v[108:111]
	v_mfma_f32_16x16x32_bf16 v[104:107], v[166:169], v[198:201], v[104:107]
	v_mfma_f32_16x16x32_bf16 v[92:95], v[158:161], v[206:209], v[92:95]
	v_mfma_f32_16x16x32_bf16 v[88:91], v[166:169], v[206:209], v[88:91]
	v_mfma_f32_16x16x32_bf16 v[76:79], v[158:161], v[216:219], v[76:79]
	v_mfma_f32_16x16x32_bf16 v[72:75], v[166:169], v[216:219], v[72:75]
	s_setprio 0
	s_setprio 1
	v_mfma_f32_16x16x32_bf16 v[116:119], v[170:173], v[186:189], v[116:119]
	v_mfma_f32_16x16x32_bf16 v[112:115], v[178:181], v[186:189], v[112:115]
	v_mfma_f32_16x16x32_bf16 v[100:103], v[170:173], v[194:197], v[100:103]
	v_mfma_f32_16x16x32_bf16 v[96:99], v[178:181], v[194:197], v[96:99]
	v_mfma_f32_16x16x32_bf16 v[84:87], v[170:173], v[202:205], v[84:87]
	v_mfma_f32_16x16x32_bf16 v[80:83], v[178:181], v[202:205], v[80:83]
	v_mfma_f32_16x16x32_bf16 v[68:71], v[170:173], v[212:215], v[68:71]
	v_mfma_f32_16x16x32_bf16 v[64:67], v[178:181], v[212:215], v[64:67]
	v_mfma_f32_16x16x32_bf16 v[116:119], v[174:177], v[190:193], v[116:119]
	v_mfma_f32_16x16x32_bf16 v[112:115], v[182:185], v[190:193], v[112:115]
	v_mfma_f32_16x16x32_bf16 v[100:103], v[174:177], v[198:201], v[100:103]
	v_mfma_f32_16x16x32_bf16 v[96:99], v[182:185], v[198:201], v[96:99]
	v_mfma_f32_16x16x32_bf16 v[84:87], v[174:177], v[206:209], v[84:87]
	v_mfma_f32_16x16x32_bf16 v[80:83], v[182:185], v[206:209], v[80:83]
	v_mfma_f32_16x16x32_bf16 v[68:71], v[174:177], v[216:219], v[68:71]
	v_mfma_f32_16x16x32_bf16 v[64:67], v[182:185], v[216:219], v[64:67]
	s_setprio 0
	s_barrier
	s_add_i32 s26, s73, s66
	s_mov_b32 m0, s26
	ds_read_b128 v[186:189], v155 offset:16384
	ds_read_b128 v[190:193], v155 offset:17408
	ds_read_b128 v[194:197], v155 offset:18432
	ds_read_b128 v[198:201], v155 offset:19456
	ds_read_b128 v[202:205], v155 offset:20480
	ds_read_b128 v[206:209], v155 offset:21504
	ds_read_b128 v[212:215], v155 offset:22528
	ds_read_b128 v[216:219], v155 offset:23552
	global_load_lds_dwordx4 v130, s[60:61]
	s_add_i32 m0, s26, 0x2000
	s_add_u32 s26, s60, 0x20000
	s_addc_u32 s27, s61, 0
	s_add_i32 s33, s74, s66
	global_load_lds_dwordx4 v134, s[60:61]
	s_mov_b32 m0, s33
	s_nop 0
	global_load_lds_dwordx4 v130, s[26:27]
	s_add_i32 m0, s33, 0x2000
	s_nop 0
	global_load_lds_dwordx4 v134, s[26:27]
	s_mov_b32 m0, s57
	s_nop 0
	global_load_lds_dwordx4 v128, s[62:63]
	s_mov_b32 m0, s67
	s_nop 0
	global_load_lds_dwordx4 v132, s[62:63]
	s_waitcnt vmcnt(8)
	s_waitcnt lgkmcnt(0)
	s_barrier
	s_setprio 1
	s_waitcnt lgkmcnt(0)
	v_mfma_f32_16x16x32_bf16 v[60:63], v[146:149], v[186:189], v[60:63]
	v_mfma_f32_16x16x32_bf16 v[56:59], v[162:165], v[186:189], v[56:59]
	v_mfma_f32_16x16x32_bf16 v[44:47], v[146:149], v[194:197], v[44:47]
	v_mfma_f32_16x16x32_bf16 v[40:43], v[162:165], v[194:197], v[40:43]
	v_mfma_f32_16x16x32_bf16 v[28:31], v[146:149], v[202:205], v[28:31]
	v_mfma_f32_16x16x32_bf16 v[24:27], v[162:165], v[202:205], v[24:27]
	v_mfma_f32_16x16x32_bf16 v[12:15], v[146:149], v[212:215], v[12:15]
	v_mfma_f32_16x16x32_bf16 v[8:11], v[162:165], v[212:215], v[8:11]
	v_mfma_f32_16x16x32_bf16 v[60:63], v[158:161], v[190:193], v[60:63]
	v_mfma_f32_16x16x32_bf16 v[56:59], v[166:169], v[190:193], v[56:59]
	v_mfma_f32_16x16x32_bf16 v[44:47], v[158:161], v[198:201], v[44:47]
	v_mfma_f32_16x16x32_bf16 v[40:43], v[166:169], v[198:201], v[40:43]
	v_mfma_f32_16x16x32_bf16 v[28:31], v[158:161], v[206:209], v[28:31]
	v_mfma_f32_16x16x32_bf16 v[24:27], v[166:169], v[206:209], v[24:27]
	v_mfma_f32_16x16x32_bf16 v[12:15], v[158:161], v[216:219], v[12:15]
	v_mfma_f32_16x16x32_bf16 v[8:11], v[166:169], v[216:219], v[8:11]
	s_setprio 0
	s_setprio 1
	v_mfma_f32_16x16x32_bf16 v[52:55], v[170:173], v[186:189], v[52:55]
	v_mfma_f32_16x16x32_bf16 v[48:51], v[178:181], v[186:189], v[48:51]
	v_mfma_f32_16x16x32_bf16 v[36:39], v[170:173], v[194:197], v[36:39]
	v_mfma_f32_16x16x32_bf16 v[32:35], v[178:181], v[194:197], v[32:35]
	v_mfma_f32_16x16x32_bf16 v[20:23], v[170:173], v[202:205], v[20:23]
	v_mfma_f32_16x16x32_bf16 v[16:19], v[178:181], v[202:205], v[16:19]
	v_mfma_f32_16x16x32_bf16 v[4:7], v[170:173], v[212:215], v[4:7]
	v_mfma_f32_16x16x32_bf16 v[0:3], v[178:181], v[212:215], v[0:3]
	v_mfma_f32_16x16x32_bf16 v[52:55], v[174:177], v[190:193], v[52:55]
	v_mfma_f32_16x16x32_bf16 v[48:51], v[182:185], v[190:193], v[48:51]
	v_mfma_f32_16x16x32_bf16 v[36:39], v[174:177], v[198:201], v[36:39]
	v_mfma_f32_16x16x32_bf16 v[32:35], v[182:185], v[198:201], v[32:35]
	v_mfma_f32_16x16x32_bf16 v[20:23], v[174:177], v[206:209], v[20:23]
	v_mfma_f32_16x16x32_bf16 v[16:19], v[182:185], v[206:209], v[16:19]
	v_mfma_f32_16x16x32_bf16 v[4:7], v[174:177], v[216:219], v[4:7]
	v_mfma_f32_16x16x32_bf16 v[0:3], v[182:185], v[216:219], v[0:3]
	s_setprio 0
	s_barrier
; #define PG8_STAGE(bufoff, gbase, voff) do { _Pragma("unroll") for (int _i = 0; _i < 2; ++_i) \
;         __builtin_amdgcn_global_load_lds((const unsigned*)((const char*)(gbase) + (voff)[_i]), (PG8_LAS unsigned*)(lds + (bufoff) + ldsw + _i * 8192), 16, 0, 0); } while (0)
; #define PG8_LDA(dst, b, h) do { _Pragma("unroll") for (int m = 0; m < 4; ++m) _Pragma("unroll") for (int k = 0; k < 2; ++k) dst[m][k] = *(const PG8_LAS bf16x8*)(lds + PG8_SA(b, h) + aoff + m * 2048 + k * 1024); } while (0)
; #define PG8_LDB(dst, b, h) do { _Pragma("unroll") for (int n = 0; n < 2; ++n) _Pragma("unroll") for (int k = 0; k < 2; ++k) dst[n][k] = *(const PG8_LAS bf16x8*)(lds + PG8_SB(b, h) + boff + n * 2048 + k * 1024); } while (0)
; #define PG8_MMA(ai, bj, At, Bt) do { __builtin_amdgcn_s_setprio(1); _Pragma("unroll") for (int m = 0; m < 4; ++m) _Pragma("unroll") for (int n = 0; n < 2; ++n) _Pragma("unroll") for (int k = 0; k < 2; ++k) \
;         acc[ai][bj][m][n] = __builtin_amdgcn_mfma_f32_16x16x32_bf16(Bt[n][k], At[m][k], acc[ai][bj][m][n], 0, 0, 0); __builtin_amdgcn_s_setprio(0); } while (0)
; #define PG8_WAIT_V(n) asm volatile("s_waitcnt vmcnt(" #n ")" ::: "memory")
; #define PG8_WAIT_L(n) asm volatile("s_waitcnt lgkmcnt(" #n ")" ::: "memory")
; #define PG8_BAR __builtin_amdgcn_s_barrier()
; #define PG8_SCHED __builtin_amdgcn_sched_barrier(0)
; template <class Epi, class Sched, bool ALIGN_EPI = false, bool SP2 = false>
; __device__ __forceinline__ void gemm_phase(PG8_LAS unsigned char* lds, const Gemm g, const Sched& S, const Epi& E, int tid_in) {
;     ...
;             PG8_LDB(B0, 1, 0); PG8_LDB(B1, 1, 1); PG8_SCHED; PG8_LDA(At, 1, 0); PG8_STAGE(PG8_SA(0, 1), a2 + hstep, voffA);
;             PG8_WAIT_V(8); PG8_WAIT_L(0); PG8_BAR; PG8_MMA(0, 0, At, B0); PG8_MMA(0, 1, At, B1); PG8_BAR; PG8_SCHED;
;             PG8_LDA(At, 1, 1); PG8_STAGE(PG8_SB(1, 0), b3, voffB); PG8_STAGE(PG8_SB(1, 1), b3 + hstepB, voffB); PG8_STAGE(PG8_SA(1, 0), a3, voffA);
	s_add_i32 s33, 0, 0x18000
	s_add_i32 s84, 0, 0x1c000
	v_add_u32_e32 v166, s33, v137
	v_add_u32_e32 v182, s84, v137
	ds_read_b128 v[146:149], v166
	ds_read_b128 v[158:161], v166 offset:1024
	ds_read_b128 v[162:165], v166 offset:2048
	ds_read_b128 v[166:169], v166 offset:3072
	ds_read_b128 v[170:173], v182
	ds_read_b128 v[174:177], v182 offset:1024
	ds_read_b128 v[178:181], v182 offset:2048
	ds_read_b128 v[182:185], v182 offset:3072
	s_add_u32 s26, s62, 0x80000
	s_addc_u32 s27, s63, 0
	s_mov_b32 m0, s68
	ds_read_b128 v[186:189], v155 offset:32768
	ds_read_b128 v[190:193], v155 offset:33792
	ds_read_b128 v[194:197], v155 offset:34816
	ds_read_b128 v[198:201], v155 offset:35840
	ds_read_b128 v[202:205], v155 offset:36864
	ds_read_b128 v[206:209], v155 offset:37888
	ds_read_b128 v[212:215], v155 offset:38912
	ds_read_b128 v[216:219], v155 offset:39936
	global_load_lds_dwordx4 v128, s[26:27]
	s_mov_b32 m0, s69
	s_nop 0
	global_load_lds_dwordx4 v132, s[26:27]
	s_waitcnt vmcnt(8)
	s_waitcnt lgkmcnt(0)
	s_barrier
	s_setprio 1
	s_waitcnt lgkmcnt(0)
	v_mfma_f32_16x16x32_bf16 v[124:127], v[146:149], v[186:189], v[124:127]
	v_mfma_f32_16x16x32_bf16 v[120:123], v[162:165], v[186:189], v[120:123]
	v_mfma_f32_16x16x32_bf16 v[108:111], v[146:149], v[194:197], v[108:111]
	v_mfma_f32_16x16x32_bf16 v[104:107], v[162:165], v[194:197], v[104:107]
	v_mfma_f32_16x16x32_bf16 v[92:95], v[146:149], v[202:205], v[92:95]
	v_mfma_f32_16x16x32_bf16 v[88:91], v[162:165], v[202:205], v[88:91]
	v_mfma_f32_16x16x32_bf16 v[76:79], v[146:149], v[212:215], v[76:79]
	v_mfma_f32_16x16x32_bf16 v[72:75], v[162:165], v[212:215], v[72:75]
	v_mfma_f32_16x16x32_bf16 v[124:127], v[158:161], v[190:193], v[124:127]
	v_mfma_f32_16x16x32_bf16 v[120:123], v[166:169], v[190:193], v[120:123]
	v_mfma_f32_16x16x32_bf16 v[108:111], v[158:161], v[198:201], v[108:111]
	v_mfma_f32_16x16x32_bf16 v[104:107], v[166:169], v[198:201], v[104:107]
	v_mfma_f32_16x16x32_bf16 v[92:95], v[158:161], v[206:209], v[92:95]
	v_mfma_f32_16x16x32_bf16 v[88:91], v[166:169], v[206:209], v[88:91]
	v_mfma_f32_16x16x32_bf16 v[76:79], v[158:161], v[216:219], v[76:79]
	v_mfma_f32_16x16x32_bf16 v[72:75], v[166:169], v[216:219], v[72:75]
	s_setprio 0
	s_setprio 1
	v_mfma_f32_16x16x32_bf16 v[116:119], v[170:173], v[186:189], v[116:119]
	v_mfma_f32_16x16x32_bf16 v[112:115], v[178:181], v[186:189], v[112:115]
	v_mfma_f32_16x16x32_bf16 v[100:103], v[170:173], v[194:197], v[100:103]
	v_mfma_f32_16x16x32_bf16 v[96:99], v[178:181], v[194:197], v[96:99]
	v_mfma_f32_16x16x32_bf16 v[84:87], v[170:173], v[202:205], v[84:87]
	v_mfma_f32_16x16x32_bf16 v[80:83], v[178:181], v[202:205], v[80:83]
	v_mfma_f32_16x16x32_bf16 v[68:71], v[170:173], v[212:215], v[68:71]
	v_mfma_f32_16x16x32_bf16 v[64:67], v[178:181], v[212:215], v[64:67]
	v_mfma_f32_16x16x32_bf16 v[116:119], v[174:177], v[190:193], v[116:119]
	v_mfma_f32_16x16x32_bf16 v[112:115], v[182:185], v[190:193], v[112:115]
	v_mfma_f32_16x16x32_bf16 v[100:103], v[174:177], v[198:201], v[100:103]
	v_mfma_f32_16x16x32_bf16 v[96:99], v[182:185], v[198:201], v[96:99]
	v_mfma_f32_16x16x32_bf16 v[84:87], v[174:177], v[206:209], v[84:87]
	v_mfma_f32_16x16x32_bf16 v[80:83], v[182:185], v[206:209], v[80:83]
	v_mfma_f32_16x16x32_bf16 v[68:71], v[174:177], v[216:219], v[68:71]
	v_mfma_f32_16x16x32_bf16 v[64:67], v[182:185], v[216:219], v[64:67]
	s_setprio 0
	s_barrier
	s_add_i32 s26, s33, s66
	s_add_i32 m0, s26, 0xffffff80
	ds_read_b128 v[186:189], v155 offset:49152
	ds_read_b128 v[190:193], v155 offset:50176
	ds_read_b128 v[194:197], v155 offset:51200
	ds_read_b128 v[198:201], v155 offset:52224
	ds_read_b128 v[202:205], v155 offset:53248
	ds_read_b128 v[206:209], v155 offset:54272
	ds_read_b128 v[212:215], v155 offset:55296
	ds_read_b128 v[216:219], v155 offset:56320
	global_load_lds_dwordx4 v130, s[60:61] offset:128
	s_add_i32 m0, s26, 0x1f80
	s_add_u32 s26, s60, 0x20080
	s_addc_u32 s27, s61, 0
	s_add_i32 s33, s84, s66
	global_load_lds_dwordx4 v134, s[60:61] offset:128
	s_mov_b32 m0, s33
	s_nop 0
	global_load_lds_dwordx4 v130, s[26:27]
	s_add_i32 m0, s33, 0x2000
	s_nop 0
	global_load_lds_dwordx4 v134, s[26:27]
	s_add_i32 m0, s71, 0xffffff80
	s_nop 0
	global_load_lds_dwordx4 v128, s[62:63] offset:128
	s_add_i32 m0, s72, 0xffffff80
	s_nop 0
	global_load_lds_dwordx4 v132, s[62:63] offset:128
	s_waitcnt vmcnt(8)
	s_waitcnt lgkmcnt(0)
	s_barrier
; #define PG8_MMA(ai, bj, At, Bt) do { __builtin_amdgcn_s_setprio(1); _Pragma("unroll") for (int m = 0; m < 4; ++m) _Pragma("unroll") for (int n = 0; n < 2; ++n) _Pragma("unroll") for (int k = 0; k < 2; ++k) \
;         acc[ai][bj][m][n] = __builtin_amdgcn_mfma_f32_16x16x32_bf16(Bt[n][k], At[m][k], acc[ai][bj][m][n], 0, 0, 0); __builtin_amdgcn_s_setprio(0); } while (0)
; #define PG8_WAIT_V(n) asm volatile("s_waitcnt vmcnt(" #n ")" ::: "memory")
; #define PG8_WAIT_L(n) asm volatile("s_waitcnt lgkmcnt(" #n ")" ::: "memory")
; #define PG8_BAR __builtin_amdgcn_s_barrier()
; #define PG8_SCHED __builtin_amdgcn_sched_barrier(0)
; template <class Epi, class Sched, bool ALIGN_EPI = false, bool SP2 = false>
; __device__ __forceinline__ void gemm_phase(PG8_LAS unsigned char* lds, const Gemm g, const Sched& S, const Epi& E, int tid_in) {
;     ...
;             PG8_WAIT_V(8); PG8_WAIT_L(0); PG8_BAR; PG8_MMA(1, 0, At, B0); PG8_MMA(1, 1, At, B1); PG8_BAR; PG8_SCHED;
;     __device__ __forceinline__ void operator()(const f32x4 (&acc)[2][2][4][2], const Unit& u, int wr, int wc, int fr, int fq) const {
;     ...
;                 const int row = u.pm * BM + ai * HALF + wr * 64 + m * 16 + r; float q = 0.f;
; #pragma unroll
;                 for (int bj = 0; bj < 2; ++bj) {
;                     const size_t off = (size_t)row * 2048 + u.pn * BM + wc * 64 + bj * 32 + 8 * p;
;                     f32x4 b0, b1;
;                     if (BASE_F32) { b0 = *(const f32x4*)((const float*)base + off); b1 = *(const f32x4*)((const float*)base + off + 4); }
;                     else { const u32x4 bb = *(const u32x4*)((const bf16_t*)base + off);
	s_setprio 1
	s_waitcnt lgkmcnt(0)
	v_mfma_f32_16x16x32_bf16 v[60:63], v[146:149], v[186:189], v[60:63]
	v_mfma_f32_16x16x32_bf16 v[56:59], v[162:165], v[186:189], v[56:59]
	v_mfma_f32_16x16x32_bf16 v[44:47], v[146:149], v[194:197], v[44:47]
	v_mfma_f32_16x16x32_bf16 v[40:43], v[162:165], v[194:197], v[40:43]
	v_mfma_f32_16x16x32_bf16 v[28:31], v[146:149], v[202:205], v[28:31]
	v_mfma_f32_16x16x32_bf16 v[24:27], v[162:165], v[202:205], v[24:27]
	v_mfma_f32_16x16x32_bf16 v[12:15], v[146:149], v[212:215], v[12:15]
	v_mfma_f32_16x16x32_bf16 v[8:11], v[162:165], v[212:215], v[8:11]
	v_mfma_f32_16x16x32_bf16 v[60:63], v[158:161], v[190:193], v[60:63]
	v_mfma_f32_16x16x32_bf16 v[56:59], v[166:169], v[190:193], v[56:59]
	v_mfma_f32_16x16x32_bf16 v[44:47], v[158:161], v[198:201], v[44:47]
	v_mfma_f32_16x16x32_bf16 v[40:43], v[166:169], v[198:201], v[40:43]
	v_mfma_f32_16x16x32_bf16 v[28:31], v[158:161], v[206:209], v[28:31]
	v_mfma_f32_16x16x32_bf16 v[24:27], v[166:169], v[206:209], v[24:27]
	v_mfma_f32_16x16x32_bf16 v[12:15], v[158:161], v[216:219], v[12:15]
	v_mfma_f32_16x16x32_bf16 v[8:11], v[166:169], v[216:219], v[8:11]
	s_setprio 0
	s_setprio 1
	v_mfma_f32_16x16x32_bf16 v[52:55], v[170:173], v[186:189], v[52:55]
	v_mfma_f32_16x16x32_bf16 v[48:51], v[178:181], v[186:189], v[48:51]
	v_mfma_f32_16x16x32_bf16 v[36:39], v[170:173], v[194:197], v[36:39]
	v_mfma_f32_16x16x32_bf16 v[32:35], v[178:181], v[194:197], v[32:35]
	v_mfma_f32_16x16x32_bf16 v[20:23], v[170:173], v[202:205], v[20:23]
	v_mfma_f32_16x16x32_bf16 v[16:19], v[178:181], v[202:205], v[16:19]
	v_mfma_f32_16x16x32_bf16 v[4:7], v[170:173], v[212:215], v[4:7]
	v_mfma_f32_16x16x32_bf16 v[0:3], v[178:181], v[212:215], v[0:3]
	v_mfma_f32_16x16x32_bf16 v[52:55], v[174:177], v[190:193], v[52:55]
	v_mfma_f32_16x16x32_bf16 v[48:51], v[182:185], v[190:193], v[48:51]
	v_mfma_f32_16x16x32_bf16 v[36:39], v[174:177], v[198:201], v[36:39]
	v_mfma_f32_16x16x32_bf16 v[32:35], v[182:185], v[198:201], v[32:35]
	v_mfma_f32_16x16x32_bf16 v[20:23], v[174:177], v[206:209], v[20:23]
	v_mfma_f32_16x16x32_bf16 v[16:19], v[182:185], v[206:209], v[16:19]
	v_mfma_f32_16x16x32_bf16 v[4:7], v[174:177], v[216:219], v[4:7]
	v_mfma_f32_16x16x32_bf16 v[0:3], v[182:185], v[216:219], v[0:3]
	s_setprio 0
	s_barrier
	s_add_i32 s79, s79, 2
	s_add_u32 s58, s58, 0x100
	s_addc_u32 s59, s59, 0
	s_add_u32 s76, s76, 0x100
	s_addc_u32 s77, s77, 0
	s_cmp_gt_u32 s79, 29
	s_cbranch_scc0 .LBB0_292
	s_mov_b32 s99, 1
	v_lshl_add_u32 v148, s54, 8, v150
	v_lshl_or_b32 v146, s56, 8, v136
	v_lshl_add_u32 v147, v148, 11, v146
	v_lshlrev_b32_e32 v159, 1, v147
	v_lshlrev_b32_e32 v158, 2, v147
	v_lshlrev_b32_e32 v208, 3, v148
	global_load_dwordx4 v[160:163], v158, s[12:13]
	global_load_dwordx4 v[164:167], v158, s[12:13] offset:16
	global_load_dwordx4 v[168:171], v158, s[12:13] offset:128
	global_load_dwordx4 v[172:175], v158, s[12:13] offset:144
	v_add_u32_e32 v149, 0x20000, v158
	global_load_dwordx4 v[176:179], v149, s[12:13]
	global_load_dwordx4 v[180:183], v149, s[12:13] offset:16
	global_load_dwordx4 v[184:187], v149, s[12:13] offset:128
	global_load_dwordx4 v[188:191], v149, s[12:13] offset:144
	v_add_u32_e32 v209, 0x40000, v158
	global_load_dwordx4 v[192:195], v209, s[12:13]
	global_load_dwordx4 v[196:199], v209, s[12:13] offset:16
	global_load_dwordx4 v[200:203], v209, s[12:13] offset:128
	global_load_dwordx4 v[204:207], v209, s[12:13] offset:144
	v_add_u32_e32 v149, 0x60000, v158
	global_load_dwordx4 v[212:215], v149, s[12:13]
	global_load_dwordx4 v[216:219], v149, s[12:13] offset:16
	global_load_dwordx4 v[220:223], v149, s[12:13] offset:128
	global_load_dwordx4 v[224:227], v149, s[12:13] offset:144
	v_add_u32_e32 v209, 0x100000, v158
	global_load_dwordx4 v[228:231], v209, s[12:13]
	global_load_dwordx4 v[232:235], v209, s[12:13] offset:16
	global_load_dwordx4 v[236:239], v209, s[12:13] offset:128
	global_load_dwordx4 v[240:243], v209, s[12:13] offset:144
	s_and_b64 vcc, exec, s[44:45]
	s_cbranch_vccz .LBB0_295
	s_barrier

; #define PG8_STAGE(bufoff, gbase, voff) do { _Pragma("unroll") for (int _i = 0; _i < 2; ++_i) \
;         __builtin_amdgcn_global_load_lds((const unsigned*)((const char*)(gbase) + (voff)[_i]), (PG8_LAS unsigned*)(lds + (bufoff) + ldsw + _i * 8192), 16, 0, 0); } while (0)
; #define PG8_LDA(dst, b, h) do { _Pragma("unroll") for (int m = 0; m < 4; ++m) _Pragma("unroll") for (int k = 0; k < 2; ++k) dst[m][k] = *(const PG8_LAS bf16x8*)(lds + PG8_SA(b, h) + aoff + m * 2048 + k * 1024); } while (0)
; #define PG8_LDB(dst, b, h) do { _Pragma("unroll") for (int n = 0; n < 2; ++n) _Pragma("unroll") for (int k = 0; k < 2; ++k) dst[n][k] = *(const PG8_LAS bf16x8*)(lds + PG8_SB(b, h) + boff + n * 2048 + k * 1024); } while (0)
; #define PG8_SCHED __builtin_amdgcn_sched_barrier(0)
; template <class Epi, class Sched, bool ALIGN_EPI = false, bool SP2 = false>
; __device__ __forceinline__ void gemm_phase(PG8_LAS unsigned char* lds, const Gemm g, const Sched& S, const Epi& E, int tid_in) {
;     ...
;             const bool last = (t == nt - 2);
;             const char* a1 = cA + (size_t)(t + 1) * kstep;
;             const char* a2 = last ? nA : cA + (size_t)(t + 2) * kstep; const char* b2 = last ? nB : cB + (size_t)(t + 2) * kstep;
;             const char* a3 = a2 + kstep; const char* b3 = b2 + kstep;
;             if (last && has_next) S.a_ready(nxt);
;             if constexpr (SP2) {
;             PG8_LDB(B0, 0, 0); PG8_LDB(B1, 0, 1); PG8_SCHED; PG8_LDA(At, 0, 0); PG8_STAGE(PG8_SA(1, 1), a1 + hstep, voffA);
.Lkb_skip_2:
	ds_read_b128 v[156:159], v150
	ds_read_b128 v[160:163], v150 offset:1024
	ds_read_b128 v[164:167], v150 offset:2048
	ds_read_b128 v[168:171], v150 offset:3072
	ds_read_b128 v[172:175], v151
	ds_read_b128 v[176:179], v151 offset:1024
	ds_read_b128 v[180:183], v151 offset:2048
	ds_read_b128 v[184:187], v151 offset:3072
	s_add_u32 s26, s52, 0xfff80080
	s_addc_u32 s27, s53, -1
	s_cmp_eq_u32 s76, 28
	s_cselect_b32 s57, s45, s27
	s_cselect_b32 s56, s72, s26
	s_cselect_b32 s55, s43, s75
	s_cselect_b32 s54, s73, s74
	s_add_i32 m0, s51, 0xc000
	ds_read_b128 v[188:191], v152
	ds_read_b128 v[192:195], v152 offset:1024
	ds_read_b128 v[196:199], v152 offset:2048
	ds_read_b128 v[200:203], v152 offset:3072
	ds_read_b128 v[204:207], v152 offset:4096
	ds_read_b128 v[212:215], v152 offset:5120
	ds_read_b128 v[216:219], v152 offset:6144
	ds_read_b128 v[220:223], v152 offset:7168
	global_load_lds_dwordx4 v138, s[52:53]
	s_add_i32 m0, s51, 0xe000
	s_nop 0
	global_load_lds_dwordx4 v140, s[52:53]
	s_cmp_eq_u32 s99, 0
	s_cbranch_scc1 .Lw1s_2_0
	s_waitcnt vmcnt(24)
	s_branch .Lw1d_2_0

; #define PG8_STAGE(bufoff, gbase, voff) do { _Pragma("unroll") for (int _i = 0; _i < 2; ++_i) \
;         __builtin_amdgcn_global_load_lds((const unsigned*)((const char*)(gbase) + (voff)[_i]), (PG8_LAS unsigned*)(lds + (bufoff) + ldsw + _i * 8192), 16, 0, 0); } while (0)
; #define PG8_LDA(dst, b, h) do { _Pragma("unroll") for (int m = 0; m < 4; ++m) _Pragma("unroll") for (int k = 0; k < 2; ++k) dst[m][k] = *(const PG8_LAS bf16x8*)(lds + PG8_SA(b, h) + aoff + m * 2048 + k * 1024); } while (0)
; #define PG8_MMA(ai, bj, At, Bt) do { __builtin_amdgcn_s_setprio(1); _Pragma("unroll") for (int m = 0; m < 4; ++m) _Pragma("unroll") for (int n = 0; n < 2; ++n) _Pragma("unroll") for (int k = 0; k < 2; ++k) \
;         acc[ai][bj][m][n] = __builtin_amdgcn_mfma_f32_16x16x32_bf16(Bt[n][k], At[m][k], acc[ai][bj][m][n], 0, 0, 0); __builtin_amdgcn_s_setprio(0); } while (0)
; #define PG8_WAIT_V(n) asm volatile("s_waitcnt vmcnt(" #n ")" ::: "memory")
; #define PG8_WAIT_L(n) asm volatile("s_waitcnt lgkmcnt(" #n ")" ::: "memory")
; #define PG8_BAR __builtin_amdgcn_s_barrier()
; #define PG8_SCHED __builtin_amdgcn_sched_barrier(0)
; template <class Epi, class Sched, bool ALIGN_EPI = false, bool SP2 = false>
; __device__ __forceinline__ void gemm_phase(PG8_LAS unsigned char* lds, const Gemm g, const Sched& S, const Epi& E, int tid_in) {
;     ...
;             PG8_WAIT_V(8); PG8_WAIT_L(0); PG8_BAR; PG8_MMA(0, 0, At, B0); PG8_MMA(0, 1, At, B1); PG8_BAR; PG8_SCHED;
;             PG8_LDA(At, 0, 1); PG8_STAGE(PG8_SB(0, 0), b2, voffB); PG8_STAGE(PG8_SB(0, 1), b2 + hstepB, voffB); PG8_STAGE(PG8_SA(0, 0), a2, voffA);
.Lw1d_2_0:
	s_waitcnt lgkmcnt(0)
	s_barrier
	s_setprio 1
	s_waitcnt lgkmcnt(0)
	v_mfma_f32_16x16x32_bf16 v[124:127], v[156:159], v[188:191], 0
	v_mfma_f32_16x16x32_bf16 v[120:123], v[164:167], v[188:191], 0
	v_mfma_f32_16x16x32_bf16 v[108:111], v[156:159], v[196:199], 0
	v_mfma_f32_16x16x32_bf16 v[104:107], v[164:167], v[196:199], 0
	v_mfma_f32_16x16x32_bf16 v[92:95], v[156:159], v[204:207], 0
	v_mfma_f32_16x16x32_bf16 v[88:91], v[164:167], v[204:207], 0
	v_mfma_f32_16x16x32_bf16 v[76:79], v[156:159], v[216:219], 0
	v_mfma_f32_16x16x32_bf16 v[72:75], v[164:167], v[216:219], 0
	v_mfma_f32_16x16x32_bf16 v[124:127], v[160:163], v[192:195], v[124:127]
	v_mfma_f32_16x16x32_bf16 v[120:123], v[168:171], v[192:195], v[120:123]
	v_mfma_f32_16x16x32_bf16 v[108:111], v[160:163], v[200:203], v[108:111]
	v_mfma_f32_16x16x32_bf16 v[104:107], v[168:171], v[200:203], v[104:107]
	v_mfma_f32_16x16x32_bf16 v[92:95], v[160:163], v[212:215], v[92:95]
	v_mfma_f32_16x16x32_bf16 v[88:91], v[168:171], v[212:215], v[88:91]
	v_mfma_f32_16x16x32_bf16 v[76:79], v[160:163], v[220:223], v[76:79]
	v_mfma_f32_16x16x32_bf16 v[72:75], v[168:171], v[220:223], v[72:75]
	s_setprio 0
	s_setprio 1
	v_mfma_f32_16x16x32_bf16 v[116:119], v[172:175], v[188:191], 0
	v_mfma_f32_16x16x32_bf16 v[112:115], v[180:183], v[188:191], 0
	v_mfma_f32_16x16x32_bf16 v[100:103], v[172:175], v[196:199], 0
	v_mfma_f32_16x16x32_bf16 v[96:99], v[180:183], v[196:199], 0
	v_mfma_f32_16x16x32_bf16 v[84:87], v[172:175], v[204:207], 0
	v_mfma_f32_16x16x32_bf16 v[80:83], v[180:183], v[204:207], 0
	v_mfma_f32_16x16x32_bf16 v[68:71], v[172:175], v[216:219], 0
	v_mfma_f32_16x16x32_bf16 v[64:67], v[180:183], v[216:219], 0
	v_mfma_f32_16x16x32_bf16 v[116:119], v[176:179], v[192:195], v[116:119]
	v_mfma_f32_16x16x32_bf16 v[112:115], v[184:187], v[192:195], v[112:115]
	v_mfma_f32_16x16x32_bf16 v[100:103], v[176:179], v[200:203], v[100:103]
	v_mfma_f32_16x16x32_bf16 v[96:99], v[184:187], v[200:203], v[96:99]
	v_mfma_f32_16x16x32_bf16 v[84:87], v[176:179], v[212:215], v[84:87]
	v_mfma_f32_16x16x32_bf16 v[80:83], v[184:187], v[212:215], v[80:83]
	v_mfma_f32_16x16x32_bf16 v[68:71], v[176:179], v[220:223], v[68:71]
	v_mfma_f32_16x16x32_bf16 v[64:67], v[184:187], v[220:223], v[64:67]
	s_setprio 0
	s_barrier
	s_add_i32 s26, s68, s60
	s_mov_b32 m0, s26
	ds_read_b128 v[188:191], v152 offset:16384
	ds_read_b128 v[192:195], v152 offset:17408
	ds_read_b128 v[196:199], v152 offset:18432
	ds_read_b128 v[200:203], v152 offset:19456
	ds_read_b128 v[204:207], v152 offset:20480
	ds_read_b128 v[212:215], v152 offset:21504
	ds_read_b128 v[216:219], v152 offset:22528
	ds_read_b128 v[220:223], v152 offset:23552
	global_load_lds_dwordx4 v130, s[54:55]
	s_add_i32 m0, s26, 0x2000
	s_add_u32 s26, s54, 0x20000
	s_addc_u32 s27, s55, 0
	s_add_i32 s33, s69, s60
	global_load_lds_dwordx4 v134, s[54:55]
	s_mov_b32 m0, s33
	s_nop 0
	global_load_lds_dwordx4 v130, s[26:27]
	s_add_i32 m0, s33, 0x2000
	s_nop 0
	global_load_lds_dwordx4 v134, s[26:27]
	s_mov_b32 m0, s51
	s_nop 0
	global_load_lds_dwordx4 v128, s[56:57]
	s_mov_b32 m0, s61
	s_nop 0
	global_load_lds_dwordx4 v132, s[56:57]
	s_cmp_eq_u32 s99, 0
	s_cbranch_scc1 .Lw1s_2_1
	s_waitcnt vmcnt(24)
	s_branch .Lw1d_2_1

; #define PG8_STAGE(bufoff, gbase, voff) do { _Pragma("unroll") for (int _i = 0; _i < 2; ++_i) \
;         __builtin_amdgcn_global_load_lds((const unsigned*)((const char*)(gbase) + (voff)[_i]), (PG8_LAS unsigned*)(lds + (bufoff) + ldsw + _i * 8192), 16, 0, 0); } while (0)
; #define PG8_LDA(dst, b, h) do { _Pragma("unroll") for (int m = 0; m < 4; ++m) _Pragma("unroll") for (int k = 0; k < 2; ++k) dst[m][k] = *(const PG8_LAS bf16x8*)(lds + PG8_SA(b, h) + aoff + m * 2048 + k * 1024); } while (0)
; #define PG8_LDB(dst, b, h) do { _Pragma("unroll") for (int n = 0; n < 2; ++n) _Pragma("unroll") for (int k = 0; k < 2; ++k) dst[n][k] = *(const PG8_LAS bf16x8*)(lds + PG8_SB(b, h) + boff + n * 2048 + k * 1024); } while (0)
; #define PG8_MMA(ai, bj, At, Bt) do { __builtin_amdgcn_s_setprio(1); _Pragma("unroll") for (int m = 0; m < 4; ++m) _Pragma("unroll") for (int n = 0; n < 2; ++n) _Pragma("unroll") for (int k = 0; k < 2; ++k) \
;         acc[ai][bj][m][n] = __builtin_amdgcn_mfma_f32_16x16x32_bf16(Bt[n][k], At[m][k], acc[ai][bj][m][n], 0, 0, 0); __builtin_amdgcn_s_setprio(0); } while (0)
; #define PG8_WAIT_V(n) asm volatile("s_waitcnt vmcnt(" #n ")" ::: "memory")
; #define PG8_WAIT_L(n) asm volatile("s_waitcnt lgkmcnt(" #n ")" ::: "memory")
; #define PG8_BAR __builtin_amdgcn_s_barrier()
; #define PG8_SCHED __builtin_amdgcn_sched_barrier(0)
; template <class Epi, class Sched, bool ALIGN_EPI = false, bool SP2 = false>
; __device__ __forceinline__ void gemm_phase(PG8_LAS unsigned char* lds, const Gemm g, const Sched& S, const Epi& E, int tid_in) {
;     ...
;             PG8_WAIT_V(8); PG8_WAIT_L(0); PG8_BAR; PG8_MMA(1, 0, At, B0); PG8_MMA(1, 1, At, B1); PG8_BAR; PG8_SCHED;
;             PG8_LDB(B0, 1, 0); PG8_LDB(B1, 1, 1); PG8_SCHED; PG8_LDA(At, 1, 0); PG8_STAGE(PG8_SA(0, 1), a2 + hstep, voffA);
;             PG8_WAIT_V(8); PG8_WAIT_L(0); PG8_BAR; PG8_MMA(0, 0, At, B0); PG8_MMA(0, 1, At, B1); PG8_BAR; PG8_SCHED;
.Lw1d_2_1:
	s_waitcnt lgkmcnt(0)
	s_barrier
	s_setprio 1
	s_waitcnt lgkmcnt(0)
	v_mfma_f32_16x16x32_bf16 v[60:63], v[156:159], v[188:191], 0
	v_mfma_f32_16x16x32_bf16 v[56:59], v[164:167], v[188:191], 0
	v_mfma_f32_16x16x32_bf16 v[44:47], v[156:159], v[196:199], 0
	v_mfma_f32_16x16x32_bf16 v[40:43], v[164:167], v[196:199], 0
	v_mfma_f32_16x16x32_bf16 v[28:31], v[156:159], v[204:207], 0
	v_mfma_f32_16x16x32_bf16 v[24:27], v[164:167], v[204:207], 0
	v_mfma_f32_16x16x32_bf16 v[12:15], v[156:159], v[216:219], 0
	v_mfma_f32_16x16x32_bf16 v[8:11], v[164:167], v[216:219], 0
	v_mfma_f32_16x16x32_bf16 v[60:63], v[160:163], v[192:195], v[60:63]
	v_mfma_f32_16x16x32_bf16 v[56:59], v[168:171], v[192:195], v[56:59]
	v_mfma_f32_16x16x32_bf16 v[44:47], v[160:163], v[200:203], v[44:47]
	v_mfma_f32_16x16x32_bf16 v[40:43], v[168:171], v[200:203], v[40:43]
	v_mfma_f32_16x16x32_bf16 v[28:31], v[160:163], v[212:215], v[28:31]
	v_mfma_f32_16x16x32_bf16 v[24:27], v[168:171], v[212:215], v[24:27]
	v_mfma_f32_16x16x32_bf16 v[12:15], v[160:163], v[220:223], v[12:15]
	v_mfma_f32_16x16x32_bf16 v[8:11], v[168:171], v[220:223], v[8:11]
	s_setprio 0
	s_setprio 1
	v_mfma_f32_16x16x32_bf16 v[52:55], v[172:175], v[188:191], 0
	v_mfma_f32_16x16x32_bf16 v[48:51], v[180:183], v[188:191], 0
	v_mfma_f32_16x16x32_bf16 v[36:39], v[172:175], v[196:199], 0
	v_mfma_f32_16x16x32_bf16 v[32:35], v[180:183], v[196:199], 0
	v_mfma_f32_16x16x32_bf16 v[20:23], v[172:175], v[204:207], 0
	v_mfma_f32_16x16x32_bf16 v[16:19], v[180:183], v[204:207], 0
	v_mfma_f32_16x16x32_bf16 v[4:7], v[172:175], v[216:219], 0
	v_mfma_f32_16x16x32_bf16 v[0:3], v[180:183], v[216:219], 0
	v_mfma_f32_16x16x32_bf16 v[52:55], v[176:179], v[192:195], v[52:55]
	v_mfma_f32_16x16x32_bf16 v[48:51], v[184:187], v[192:195], v[48:51]
	v_mfma_f32_16x16x32_bf16 v[36:39], v[176:179], v[200:203], v[36:39]
	v_mfma_f32_16x16x32_bf16 v[32:35], v[184:187], v[200:203], v[32:35]
	v_mfma_f32_16x16x32_bf16 v[20:23], v[176:179], v[212:215], v[20:23]
	v_mfma_f32_16x16x32_bf16 v[16:19], v[184:187], v[212:215], v[16:19]
	v_mfma_f32_16x16x32_bf16 v[4:7], v[176:179], v[220:223], v[4:7]
	v_mfma_f32_16x16x32_bf16 v[0:3], v[184:187], v[220:223], v[0:3]
	s_setprio 0
	s_barrier
	s_add_i32 s33, 0, 0x18000
	v_add_u32_e32 v155, s33, v146
	s_add_i32 s77, 0, 0x1c000
	ds_read_b128 v[156:159], v155
	ds_read_b128 v[160:163], v155 offset:1024
	ds_read_b128 v[164:167], v155 offset:2048
	ds_read_b128 v[168:171], v155 offset:3072
	v_add_u32_e32 v155, s77, v146
	ds_read_b128 v[172:175], v155
	ds_read_b128 v[176:179], v155 offset:1024
	ds_read_b128 v[180:183], v155 offset:2048
	ds_read_b128 v[184:187], v155 offset:3072
	s_add_u32 s26, s56, 0x80000
	s_addc_u32 s27, s57, 0
	s_mov_b32 m0, s62
	ds_read_b128 v[188:191], v152 offset:32768
	ds_read_b128 v[192:195], v152 offset:33792
	ds_read_b128 v[196:199], v152 offset:34816
	ds_read_b128 v[200:203], v152 offset:35840
	ds_read_b128 v[204:207], v152 offset:36864
	ds_read_b128 v[212:215], v152 offset:37888
	ds_read_b128 v[216:219], v152 offset:38912
	ds_read_b128 v[220:223], v152 offset:39936
	global_load_lds_dwordx4 v128, s[26:27]
	s_mov_b32 m0, s63
	s_nop 0
	global_load_lds_dwordx4 v132, s[26:27]
	s_waitcnt vmcnt(8)
	s_waitcnt lgkmcnt(0)
	s_barrier
	s_setprio 1
	s_waitcnt lgkmcnt(0)
	v_mfma_f32_16x16x32_bf16 v[124:127], v[156:159], v[188:191], v[124:127]
	v_mfma_f32_16x16x32_bf16 v[120:123], v[164:167], v[188:191], v[120:123]
	v_mfma_f32_16x16x32_bf16 v[108:111], v[156:159], v[196:199], v[108:111]
	v_mfma_f32_16x16x32_bf16 v[104:107], v[164:167], v[196:199], v[104:107]
	v_mfma_f32_16x16x32_bf16 v[92:95], v[156:159], v[204:207], v[92:95]
	v_mfma_f32_16x16x32_bf16 v[88:91], v[164:167], v[204:207], v[88:91]
	v_mfma_f32_16x16x32_bf16 v[76:79], v[156:159], v[216:219], v[76:79]
	v_mfma_f32_16x16x32_bf16 v[72:75], v[164:167], v[216:219], v[72:75]
	v_mfma_f32_16x16x32_bf16 v[124:127], v[160:163], v[192:195], v[124:127]
	v_mfma_f32_16x16x32_bf16 v[120:123], v[168:171], v[192:195], v[120:123]
	v_mfma_f32_16x16x32_bf16 v[108:111], v[160:163], v[200:203], v[108:111]
	v_mfma_f32_16x16x32_bf16 v[104:107], v[168:171], v[200:203], v[104:107]
	v_mfma_f32_16x16x32_bf16 v[92:95], v[160:163], v[212:215], v[92:95]
	v_mfma_f32_16x16x32_bf16 v[88:91], v[168:171], v[212:215], v[88:91]
	v_mfma_f32_16x16x32_bf16 v[76:79], v[160:163], v[220:223], v[76:79]
	v_mfma_f32_16x16x32_bf16 v[72:75], v[168:171], v[220:223], v[72:75]
	s_setprio 0
	s_setprio 1
	v_mfma_f32_16x16x32_bf16 v[116:119], v[172:175], v[188:191], v[116:119]
	v_mfma_f32_16x16x32_bf16 v[112:115], v[180:183], v[188:191], v[112:115]
	v_mfma_f32_16x16x32_bf16 v[100:103], v[172:175], v[196:199], v[100:103]
	v_mfma_f32_16x16x32_bf16 v[96:99], v[180:183], v[196:199], v[96:99]
	v_mfma_f32_16x16x32_bf16 v[84:87], v[172:175], v[204:207], v[84:87]
	v_mfma_f32_16x16x32_bf16 v[80:83], v[180:183], v[204:207], v[80:83]
	v_mfma_f32_16x16x32_bf16 v[68:71], v[172:175], v[216:219], v[68:71]
	v_mfma_f32_16x16x32_bf16 v[64:67], v[180:183], v[216:219], v[64:67]
	v_mfma_f32_16x16x32_bf16 v[116:119], v[176:179], v[192:195], v[116:119]
	v_mfma_f32_16x16x32_bf16 v[112:115], v[184:187], v[192:195], v[112:115]
	v_mfma_f32_16x16x32_bf16 v[100:103], v[176:179], v[200:203], v[100:103]
	v_mfma_f32_16x16x32_bf16 v[96:99], v[184:187], v[200:203], v[96:99]
	v_mfma_f32_16x16x32_bf16 v[84:87], v[176:179], v[212:215], v[84:87]
	v_mfma_f32_16x16x32_bf16 v[80:83], v[184:187], v[212:215], v[80:83]
	v_mfma_f32_16x16x32_bf16 v[68:71], v[176:179], v[220:223], v[68:71]
	v_mfma_f32_16x16x32_bf16 v[64:67], v[184:187], v[220:223], v[64:67]
	s_setprio 0
	s_barrier
; #define PG8_STAGE(bufoff, gbase, voff) do { _Pragma("unroll") for (int _i = 0; _i < 2; ++_i) \
;         __builtin_amdgcn_global_load_lds((const unsigned*)((const char*)(gbase) + (voff)[_i]), (PG8_LAS unsigned*)(lds + (bufoff) + ldsw + _i * 8192), 16, 0, 0); } while (0)
; #define PG8_LDA(dst, b, h) do { _Pragma("unroll") for (int m = 0; m < 4; ++m) _Pragma("unroll") for (int k = 0; k < 2; ++k) dst[m][k] = *(const PG8_LAS bf16x8*)(lds + PG8_SA(b, h) + aoff + m * 2048 + k * 1024); } while (0)
; #define PG8_LDB(dst, b, h) do { _Pragma("unroll") for (int n = 0; n < 2; ++n) _Pragma("unroll") for (int k = 0; k < 2; ++k) dst[n][k] = *(const PG8_LAS bf16x8*)(lds + PG8_SB(b, h) + boff + n * 2048 + k * 1024); } while (0)
; #define PG8_MMA(ai, bj, At, Bt) do { __builtin_amdgcn_s_setprio(1); _Pragma("unroll") for (int m = 0; m < 4; ++m) _Pragma("unroll") for (int n = 0; n < 2; ++n) _Pragma("unroll") for (int k = 0; k < 2; ++k) \
;         acc[ai][bj][m][n] = __builtin_amdgcn_mfma_f32_16x16x32_bf16(Bt[n][k], At[m][k], acc[ai][bj][m][n], 0, 0, 0); __builtin_amdgcn_s_setprio(0); } while (0)
; #define PG8_WAIT_V(n) asm volatile("s_waitcnt vmcnt(" #n ")" ::: "memory")
; #define PG8_WAIT_L(n) asm volatile("s_waitcnt lgkmcnt(" #n ")" ::: "memory")
; #define PG8_BAR __builtin_amdgcn_s_barrier()
; #define PG8_SCHED __builtin_amdgcn_sched_barrier(0)
; template <class Epi, class Sched, bool ALIGN_EPI = false, bool SP2 = false>
; __device__ __forceinline__ void gemm_phase(PG8_LAS unsigned char* lds, const Gemm g, const Sched& S, const Epi& E, int tid_in) {
;     ...
;             PG8_LDB(B0, 0, 0); PG8_LDB(B1, 0, 1); PG8_SCHED; PG8_LDA(At, 0, 0); PG8_STAGE(PG8_SA(1, 1), a1 + hstep, voffA);
;             PG8_WAIT_V(8); PG8_WAIT_L(0); PG8_BAR; PG8_MMA(0, 0, At, B0); PG8_MMA(0, 1, At, B1); PG8_BAR; PG8_SCHED;
;     ...
;             PG8_LDA(At, 1, 1); PG8_STAGE(PG8_SB(1, 0), b3, voffB); PG8_STAGE(PG8_SB(1, 1), b3 + hstepB, voffB); PG8_STAGE(PG8_SA(1, 0), a3, voffA);
;             PG8_WAIT_V(8); PG8_WAIT_L(0); PG8_BAR; PG8_MMA(1, 0, At, B0); PG8_MMA(1, 1, At, B1); PG8_BAR; PG8_SCHED;
	s_add_i32 s26, s33, s60
	s_add_i32 m0, s26, 0xffffff80
	ds_read_b128 v[188:191], v152 offset:49152
	ds_read_b128 v[192:195], v152 offset:50176
	ds_read_b128 v[196:199], v152 offset:51200
	ds_read_b128 v[200:203], v152 offset:52224
	ds_read_b128 v[204:207], v152 offset:53248
	ds_read_b128 v[212:215], v152 offset:54272
	ds_read_b128 v[216:219], v152 offset:55296
	ds_read_b128 v[220:223], v152 offset:56320
	global_load_lds_dwordx4 v130, s[54:55] offset:128
	s_add_i32 m0, s26, 0x1f80
	s_add_u32 s26, s54, 0x20080
	s_addc_u32 s27, s55, 0
	s_add_i32 s33, s77, s60
	global_load_lds_dwordx4 v134, s[54:55] offset:128
	s_mov_b32 m0, s33
	s_nop 0
	global_load_lds_dwordx4 v130, s[26:27]
	s_add_i32 m0, s33, 0x2000
	s_nop 0
	global_load_lds_dwordx4 v134, s[26:27]
	s_add_i32 m0, s66, 0xffffff80
	s_nop 0
	global_load_lds_dwordx4 v128, s[56:57] offset:128
	s_add_i32 m0, s67, 0xffffff80
	s_nop 0
	global_load_lds_dwordx4 v132, s[56:57] offset:128
	s_waitcnt vmcnt(8)
	s_waitcnt lgkmcnt(0)
	s_barrier
	s_setprio 1
	s_waitcnt lgkmcnt(0)
	v_mfma_f32_16x16x32_bf16 v[60:63], v[156:159], v[188:191], v[60:63]
	v_mfma_f32_16x16x32_bf16 v[56:59], v[164:167], v[188:191], v[56:59]
	v_mfma_f32_16x16x32_bf16 v[44:47], v[156:159], v[196:199], v[44:47]
	v_mfma_f32_16x16x32_bf16 v[40:43], v[164:167], v[196:199], v[40:43]
	v_mfma_f32_16x16x32_bf16 v[28:31], v[156:159], v[204:207], v[28:31]
	v_mfma_f32_16x16x32_bf16 v[24:27], v[164:167], v[204:207], v[24:27]
	v_mfma_f32_16x16x32_bf16 v[12:15], v[156:159], v[216:219], v[12:15]
	v_mfma_f32_16x16x32_bf16 v[8:11], v[164:167], v[216:219], v[8:11]
	v_mfma_f32_16x16x32_bf16 v[60:63], v[160:163], v[192:195], v[60:63]
	v_mfma_f32_16x16x32_bf16 v[56:59], v[168:171], v[192:195], v[56:59]
	v_mfma_f32_16x16x32_bf16 v[44:47], v[160:163], v[200:203], v[44:47]
	v_mfma_f32_16x16x32_bf16 v[40:43], v[168:171], v[200:203], v[40:43]
	v_mfma_f32_16x16x32_bf16 v[28:31], v[160:163], v[212:215], v[28:31]
	v_mfma_f32_16x16x32_bf16 v[24:27], v[168:171], v[212:215], v[24:27]
	v_mfma_f32_16x16x32_bf16 v[12:15], v[160:163], v[220:223], v[12:15]
	v_mfma_f32_16x16x32_bf16 v[8:11], v[168:171], v[220:223], v[8:11]
	s_setprio 0
	s_setprio 1
	v_mfma_f32_16x16x32_bf16 v[52:55], v[172:175], v[188:191], v[52:55]
	v_mfma_f32_16x16x32_bf16 v[48:51], v[180:183], v[188:191], v[48:51]
	v_mfma_f32_16x16x32_bf16 v[36:39], v[172:175], v[196:199], v[36:39]
	v_mfma_f32_16x16x32_bf16 v[32:35], v[180:183], v[196:199], v[32:35]
	v_mfma_f32_16x16x32_bf16 v[20:23], v[172:175], v[204:207], v[20:23]
	v_mfma_f32_16x16x32_bf16 v[16:19], v[180:183], v[204:207], v[16:19]
	v_mfma_f32_16x16x32_bf16 v[4:7], v[172:175], v[216:219], v[4:7]
	v_mfma_f32_16x16x32_bf16 v[0:3], v[180:183], v[216:219], v[0:3]
	v_mfma_f32_16x16x32_bf16 v[52:55], v[176:179], v[192:195], v[52:55]
	v_mfma_f32_16x16x32_bf16 v[48:51], v[184:187], v[192:195], v[48:51]
	v_mfma_f32_16x16x32_bf16 v[36:39], v[176:179], v[200:203], v[36:39]
	v_mfma_f32_16x16x32_bf16 v[32:35], v[184:187], v[200:203], v[32:35]
	v_mfma_f32_16x16x32_bf16 v[20:23], v[176:179], v[212:215], v[20:23]
	v_mfma_f32_16x16x32_bf16 v[16:19], v[184:187], v[212:215], v[16:19]
	v_mfma_f32_16x16x32_bf16 v[4:7], v[176:179], v[220:223], v[4:7]
	v_mfma_f32_16x16x32_bf16 v[0:3], v[184:187], v[220:223], v[0:3]
	s_setprio 0
	s_barrier
	s_add_i32 s76, s76, 2
	s_add_u32 s52, s52, 0x100
	s_addc_u32 s53, s53, 0
	s_add_u32 s74, s74, 0x100
	s_addc_u32 s75, s75, 0
	s_cmp_gt_u32 s76, 29
.LBB0_394:
	ds_read_b128 v[156:159], v150
	ds_read_b128 v[160:163], v150 offset:1024
	ds_read_b128 v[164:167], v150 offset:2048
	ds_read_b128 v[168:171], v150 offset:3072
	ds_read_b128 v[172:175], v151
	ds_read_b128 v[176:179], v151 offset:1024
	ds_read_b128 v[180:183], v151 offset:2048
	ds_read_b128 v[184:187], v151 offset:3072
	s_add_u32 s26, s52, 0xfff80080
	s_addc_u32 s27, s53, -1
	s_cmp_eq_u32 s76, 28
	s_cselect_b32 s57, s45, s27
	s_cselect_b32 s56, s72, s26
	s_cselect_b32 s55, s43, s75
	s_cselect_b32 s54, s73, s74
	s_add_i32 m0, s51, 0xc000
	ds_read_b128 v[188:191], v152
	ds_read_b128 v[192:195], v152 offset:1024
	ds_read_b128 v[196:199], v152 offset:2048
	ds_read_b128 v[200:203], v152 offset:3072
	ds_read_b128 v[204:207], v152 offset:4096
	ds_read_b128 v[212:215], v152 offset:5120
	ds_read_b128 v[216:219], v152 offset:6144
	ds_read_b128 v[220:223], v152 offset:7168
	global_load_lds_dwordx4 v138, s[52:53]
	s_add_i32 m0, s51, 0xe000
	s_nop 0
	global_load_lds_dwordx4 v140, s[52:53]
	s_waitcnt vmcnt(8)
	s_waitcnt lgkmcnt(0)
	s_barrier
; #define PG8_STAGE(bufoff, gbase, voff) do { _Pragma("unroll") for (int _i = 0; _i < 2; ++_i) \
;         __builtin_amdgcn_global_load_lds((const unsigned*)((const char*)(gbase) + (voff)[_i]), (PG8_LAS unsigned*)(lds + (bufoff) + ldsw + _i * 8192), 16, 0, 0); } while (0)
; #define PG8_LDA(dst, b, h) do { _Pragma("unroll") for (int m = 0; m < 4; ++m) _Pragma("unroll") for (int k = 0; k < 2; ++k) dst[m][k] = *(const PG8_LAS bf16x8*)(lds + PG8_SA(b, h) + aoff + m * 2048 + k * 1024); } while (0)
; #define PG8_MMA(ai, bj, At, Bt) do { __builtin_amdgcn_s_setprio(1); _Pragma("unroll") for (int m = 0; m < 4; ++m) _Pragma("unroll") for (int n = 0; n < 2; ++n) _Pragma("unroll") for (int k = 0; k < 2; ++k) \
;         acc[ai][bj][m][n] = __builtin_amdgcn_mfma_f32_16x16x32_bf16(Bt[n][k], At[m][k], acc[ai][bj][m][n], 0, 0, 0); __builtin_amdgcn_s_setprio(0); } while (0)
; #define PG8_WAIT_V(n) asm volatile("s_waitcnt vmcnt(" #n ")" ::: "memory")
; #define PG8_WAIT_L(n) asm volatile("s_waitcnt lgkmcnt(" #n ")" ::: "memory")
; #define PG8_BAR __builtin_amdgcn_s_barrier()
; #define PG8_SCHED __builtin_amdgcn_sched_barrier(0)
; template <class Epi, class Sched, bool ALIGN_EPI = false, bool SP2 = false>
; __device__ __forceinline__ void gemm_phase(PG8_LAS unsigned char* lds, const Gemm g, const Sched& S, const Epi& E, int tid_in) {
;     ...
;             PG8_WAIT_V(8); PG8_WAIT_L(0); PG8_BAR; PG8_MMA(0, 0, At, B0); PG8_MMA(0, 1, At, B1); PG8_BAR; PG8_SCHED;
;             PG8_LDA(At, 0, 1); PG8_STAGE(PG8_SB(0, 0), b2, voffB); PG8_STAGE(PG8_SB(0, 1), b2 + hstepB, voffB); PG8_STAGE(PG8_SA(0, 0), a2, voffA);
;             PG8_WAIT_V(8); PG8_WAIT_L(0); PG8_BAR; PG8_MMA(1, 0, At, B0); PG8_MMA(1, 1, At, B1); PG8_BAR; PG8_SCHED;
	s_setprio 1
	s_waitcnt lgkmcnt(0)
	v_mfma_f32_16x16x32_bf16 v[124:127], v[156:159], v[188:191], v[124:127]
	v_mfma_f32_16x16x32_bf16 v[120:123], v[164:167], v[188:191], v[120:123]
	v_mfma_f32_16x16x32_bf16 v[108:111], v[156:159], v[196:199], v[108:111]
	v_mfma_f32_16x16x32_bf16 v[104:107], v[164:167], v[196:199], v[104:107]
	v_mfma_f32_16x16x32_bf16 v[92:95], v[156:159], v[204:207], v[92:95]
	v_mfma_f32_16x16x32_bf16 v[88:91], v[164:167], v[204:207], v[88:91]
	v_mfma_f32_16x16x32_bf16 v[76:79], v[156:159], v[216:219], v[76:79]
	v_mfma_f32_16x16x32_bf16 v[72:75], v[164:167], v[216:219], v[72:75]
	v_mfma_f32_16x16x32_bf16 v[124:127], v[160:163], v[192:195], v[124:127]
	v_mfma_f32_16x16x32_bf16 v[120:123], v[168:171], v[192:195], v[120:123]
	v_mfma_f32_16x16x32_bf16 v[108:111], v[160:163], v[200:203], v[108:111]
	v_mfma_f32_16x16x32_bf16 v[104:107], v[168:171], v[200:203], v[104:107]
	v_mfma_f32_16x16x32_bf16 v[92:95], v[160:163], v[212:215], v[92:95]
	v_mfma_f32_16x16x32_bf16 v[88:91], v[168:171], v[212:215], v[88:91]
	v_mfma_f32_16x16x32_bf16 v[76:79], v[160:163], v[220:223], v[76:79]
	v_mfma_f32_16x16x32_bf16 v[72:75], v[168:171], v[220:223], v[72:75]
	s_setprio 0
	s_setprio 1
	v_mfma_f32_16x16x32_bf16 v[116:119], v[172:175], v[188:191], v[116:119]
	v_mfma_f32_16x16x32_bf16 v[112:115], v[180:183], v[188:191], v[112:115]
	v_mfma_f32_16x16x32_bf16 v[100:103], v[172:175], v[196:199], v[100:103]
	v_mfma_f32_16x16x32_bf16 v[96:99], v[180:183], v[196:199], v[96:99]
	v_mfma_f32_16x16x32_bf16 v[84:87], v[172:175], v[204:207], v[84:87]
	v_mfma_f32_16x16x32_bf16 v[80:83], v[180:183], v[204:207], v[80:83]
	v_mfma_f32_16x16x32_bf16 v[68:71], v[172:175], v[216:219], v[68:71]
	v_mfma_f32_16x16x32_bf16 v[64:67], v[180:183], v[216:219], v[64:67]
	v_mfma_f32_16x16x32_bf16 v[116:119], v[176:179], v[192:195], v[116:119]
	v_mfma_f32_16x16x32_bf16 v[112:115], v[184:187], v[192:195], v[112:115]
	v_mfma_f32_16x16x32_bf16 v[100:103], v[176:179], v[200:203], v[100:103]
	v_mfma_f32_16x16x32_bf16 v[96:99], v[184:187], v[200:203], v[96:99]
	v_mfma_f32_16x16x32_bf16 v[84:87], v[176:179], v[212:215], v[84:87]
	v_mfma_f32_16x16x32_bf16 v[80:83], v[184:187], v[212:215], v[80:83]
	v_mfma_f32_16x16x32_bf16 v[68:71], v[176:179], v[220:223], v[68:71]
	v_mfma_f32_16x16x32_bf16 v[64:67], v[184:187], v[220:223], v[64:67]
	s_setprio 0
	s_barrier
	s_add_i32 s26, s68, s60
	s_mov_b32 m0, s26
	ds_read_b128 v[188:191], v152 offset:16384
	ds_read_b128 v[192:195], v152 offset:17408
	ds_read_b128 v[196:199], v152 offset:18432
	ds_read_b128 v[200:203], v152 offset:19456
	ds_read_b128 v[204:207], v152 offset:20480
	ds_read_b128 v[212:215], v152 offset:21504
	ds_read_b128 v[216:219], v152 offset:22528
	ds_read_b128 v[220:223], v152 offset:23552
	global_load_lds_dwordx4 v130, s[54:55]
	s_add_i32 m0, s26, 0x2000
	s_add_u32 s26, s54, 0x20000
	s_addc_u32 s27, s55, 0
	s_add_i32 s33, s69, s60
	global_load_lds_dwordx4 v134, s[54:55]
	s_mov_b32 m0, s33
	s_nop 0
	global_load_lds_dwordx4 v130, s[26:27]
	s_add_i32 m0, s33, 0x2000
	s_nop 0
	global_load_lds_dwordx4 v134, s[26:27]
	s_mov_b32 m0, s51
	s_nop 0
	global_load_lds_dwordx4 v128, s[56:57]
	s_mov_b32 m0, s61
	s_nop 0
	global_load_lds_dwordx4 v132, s[56:57]
	s_waitcnt vmcnt(8)
	s_waitcnt lgkmcnt(0)
	s_barrier
	s_setprio 1
	s_waitcnt lgkmcnt(0)
	v_mfma_f32_16x16x32_bf16 v[60:63], v[156:159], v[188:191], v[60:63]
	v_mfma_f32_16x16x32_bf16 v[56:59], v[164:167], v[188:191], v[56:59]
	v_mfma_f32_16x16x32_bf16 v[44:47], v[156:159], v[196:199], v[44:47]
	v_mfma_f32_16x16x32_bf16 v[40:43], v[164:167], v[196:199], v[40:43]
	v_mfma_f32_16x16x32_bf16 v[28:31], v[156:159], v[204:207], v[28:31]
	v_mfma_f32_16x16x32_bf16 v[24:27], v[164:167], v[204:207], v[24:27]
	v_mfma_f32_16x16x32_bf16 v[12:15], v[156:159], v[216:219], v[12:15]
	v_mfma_f32_16x16x32_bf16 v[8:11], v[164:167], v[216:219], v[8:11]
	v_mfma_f32_16x16x32_bf16 v[60:63], v[160:163], v[192:195], v[60:63]
	v_mfma_f32_16x16x32_bf16 v[56:59], v[168:171], v[192:195], v[56:59]
	v_mfma_f32_16x16x32_bf16 v[44:47], v[160:163], v[200:203], v[44:47]
	v_mfma_f32_16x16x32_bf16 v[40:43], v[168:171], v[200:203], v[40:43]
	v_mfma_f32_16x16x32_bf16 v[28:31], v[160:163], v[212:215], v[28:31]
	v_mfma_f32_16x16x32_bf16 v[24:27], v[168:171], v[212:215], v[24:27]
	v_mfma_f32_16x16x32_bf16 v[12:15], v[160:163], v[220:223], v[12:15]
	v_mfma_f32_16x16x32_bf16 v[8:11], v[168:171], v[220:223], v[8:11]
	s_setprio 0
	s_setprio 1
	v_mfma_f32_16x16x32_bf16 v[52:55], v[172:175], v[188:191], v[52:55]
	v_mfma_f32_16x16x32_bf16 v[48:51], v[180:183], v[188:191], v[48:51]
	v_mfma_f32_16x16x32_bf16 v[36:39], v[172:175], v[196:199], v[36:39]
	v_mfma_f32_16x16x32_bf16 v[32:35], v[180:183], v[196:199], v[32:35]
	v_mfma_f32_16x16x32_bf16 v[20:23], v[172:175], v[204:207], v[20:23]
	v_mfma_f32_16x16x32_bf16 v[16:19], v[180:183], v[204:207], v[16:19]
	v_mfma_f32_16x16x32_bf16 v[4:7], v[172:175], v[216:219], v[4:7]
	v_mfma_f32_16x16x32_bf16 v[0:3], v[180:183], v[216:219], v[0:3]
	v_mfma_f32_16x16x32_bf16 v[52:55], v[176:179], v[192:195], v[52:55]
	v_mfma_f32_16x16x32_bf16 v[48:51], v[184:187], v[192:195], v[48:51]
	v_mfma_f32_16x16x32_bf16 v[36:39], v[176:179], v[200:203], v[36:39]
	v_mfma_f32_16x16x32_bf16 v[32:35], v[184:187], v[200:203], v[32:35]
	v_mfma_f32_16x16x32_bf16 v[20:23], v[176:179], v[212:215], v[20:23]
	v_mfma_f32_16x16x32_bf16 v[16:19], v[184:187], v[212:215], v[16:19]
	v_mfma_f32_16x16x32_bf16 v[4:7], v[176:179], v[220:223], v[4:7]
	v_mfma_f32_16x16x32_bf16 v[0:3], v[184:187], v[220:223], v[0:3]
	s_setprio 0
	s_barrier
; #define PG8_STAGE(bufoff, gbase, voff) do { _Pragma("unroll") for (int _i = 0; _i < 2; ++_i) \
;         __builtin_amdgcn_global_load_lds((const unsigned*)((const char*)(gbase) + (voff)[_i]), (PG8_LAS unsigned*)(lds + (bufoff) + ldsw + _i * 8192), 16, 0, 0); } while (0)
; #define PG8_LDA(dst, b, h) do { _Pragma("unroll") for (int m = 0; m < 4; ++m) _Pragma("unroll") for (int k = 0; k < 2; ++k) dst[m][k] = *(const PG8_LAS bf16x8*)(lds + PG8_SA(b, h) + aoff + m * 2048 + k * 1024); } while (0)
; #define PG8_LDB(dst, b, h) do { _Pragma("unroll") for (int n = 0; n < 2; ++n) _Pragma("unroll") for (int k = 0; k < 2; ++k) dst[n][k] = *(const PG8_LAS bf16x8*)(lds + PG8_SB(b, h) + boff + n * 2048 + k * 1024); } while (0)
; #define PG8_MMA(ai, bj, At, Bt) do { __builtin_amdgcn_s_setprio(1); _Pragma("unroll") for (int m = 0; m < 4; ++m) _Pragma("unroll") for (int n = 0; n < 2; ++n) _Pragma("unroll") for (int k = 0; k < 2; ++k) \
;         acc[ai][bj][m][n] = __builtin_amdgcn_mfma_f32_16x16x32_bf16(Bt[n][k], At[m][k], acc[ai][bj][m][n], 0, 0, 0); __builtin_amdgcn_s_setprio(0); } while (0)
; #define PG8_WAIT_V(n) asm volatile("s_waitcnt vmcnt(" #n ")" ::: "memory")
; #define PG8_WAIT_L(n) asm volatile("s_waitcnt lgkmcnt(" #n ")" ::: "memory")
; #define PG8_BAR __builtin_amdgcn_s_barrier()
; #define PG8_SCHED __builtin_amdgcn_sched_barrier(0)
; template <class Epi, class Sched, bool ALIGN_EPI = false, bool SP2 = false>
; __device__ __forceinline__ void gemm_phase(PG8_LAS unsigned char* lds, const Gemm g, const Sched& S, const Epi& E, int tid_in) {
;     ...
;             PG8_LDB(B0, 1, 0); PG8_LDB(B1, 1, 1); PG8_SCHED; PG8_LDA(At, 1, 0); PG8_STAGE(PG8_SA(0, 1), a2 + hstep, voffA);
;             PG8_WAIT_V(8); PG8_WAIT_L(0); PG8_BAR; PG8_MMA(0, 0, At, B0); PG8_MMA(0, 1, At, B1); PG8_BAR; PG8_SCHED;
;             PG8_LDA(At, 1, 1); PG8_STAGE(PG8_SB(1, 0), b3, voffB); PG8_STAGE(PG8_SB(1, 1), b3 + hstepB, voffB); PG8_STAGE(PG8_SA(1, 0), a3, voffA);
;             PG8_WAIT_V(8); PG8_WAIT_L(0); PG8_BAR; PG8_MMA(1, 0, At, B0); PG8_MMA(1, 1, At, B1); PG8_BAR; PG8_SCHED;
;     ...
;         if constexpr (ALIGN_EPI) { if (wr == 0) PG8_BAR; }
	s_add_i32 s33, 0, 0x18000
	v_add_u32_e32 v155, s33, v146
	s_add_i32 s77, 0, 0x1c000
	ds_read_b128 v[156:159], v155
	ds_read_b128 v[160:163], v155 offset:1024
	ds_read_b128 v[164:167], v155 offset:2048
	ds_read_b128 v[168:171], v155 offset:3072
	v_add_u32_e32 v155, s77, v146
	ds_read_b128 v[172:175], v155
	ds_read_b128 v[176:179], v155 offset:1024
	ds_read_b128 v[180:183], v155 offset:2048
	ds_read_b128 v[184:187], v155 offset:3072
	s_add_u32 s26, s56, 0x80000
	s_addc_u32 s27, s57, 0
	s_mov_b32 m0, s62
	ds_read_b128 v[188:191], v152 offset:32768
	ds_read_b128 v[192:195], v152 offset:33792
	ds_read_b128 v[196:199], v152 offset:34816
	ds_read_b128 v[200:203], v152 offset:35840
	ds_read_b128 v[204:207], v152 offset:36864
	ds_read_b128 v[212:215], v152 offset:37888
	ds_read_b128 v[216:219], v152 offset:38912
	ds_read_b128 v[220:223], v152 offset:39936
	global_load_lds_dwordx4 v128, s[26:27]
	s_mov_b32 m0, s63
	s_nop 0
	global_load_lds_dwordx4 v132, s[26:27]
	s_waitcnt vmcnt(8)
	s_waitcnt lgkmcnt(0)
	s_barrier
	s_setprio 1
	s_waitcnt lgkmcnt(0)
	v_mfma_f32_16x16x32_bf16 v[124:127], v[156:159], v[188:191], v[124:127]
	v_mfma_f32_16x16x32_bf16 v[120:123], v[164:167], v[188:191], v[120:123]
	v_mfma_f32_16x16x32_bf16 v[108:111], v[156:159], v[196:199], v[108:111]
	v_mfma_f32_16x16x32_bf16 v[104:107], v[164:167], v[196:199], v[104:107]
	v_mfma_f32_16x16x32_bf16 v[92:95], v[156:159], v[204:207], v[92:95]
	v_mfma_f32_16x16x32_bf16 v[88:91], v[164:167], v[204:207], v[88:91]
	v_mfma_f32_16x16x32_bf16 v[76:79], v[156:159], v[216:219], v[76:79]
	v_mfma_f32_16x16x32_bf16 v[72:75], v[164:167], v[216:219], v[72:75]
	v_mfma_f32_16x16x32_bf16 v[124:127], v[160:163], v[192:195], v[124:127]
	v_mfma_f32_16x16x32_bf16 v[120:123], v[168:171], v[192:195], v[120:123]
	v_mfma_f32_16x16x32_bf16 v[108:111], v[160:163], v[200:203], v[108:111]
	v_mfma_f32_16x16x32_bf16 v[104:107], v[168:171], v[200:203], v[104:107]
	v_mfma_f32_16x16x32_bf16 v[92:95], v[160:163], v[212:215], v[92:95]
	v_mfma_f32_16x16x32_bf16 v[88:91], v[168:171], v[212:215], v[88:91]
	v_mfma_f32_16x16x32_bf16 v[76:79], v[160:163], v[220:223], v[76:79]
	v_mfma_f32_16x16x32_bf16 v[72:75], v[168:171], v[220:223], v[72:75]
	s_setprio 0
	s_setprio 1
	v_mfma_f32_16x16x32_bf16 v[116:119], v[172:175], v[188:191], v[116:119]
	v_mfma_f32_16x16x32_bf16 v[112:115], v[180:183], v[188:191], v[112:115]
	v_mfma_f32_16x16x32_bf16 v[100:103], v[172:175], v[196:199], v[100:103]
	v_mfma_f32_16x16x32_bf16 v[96:99], v[180:183], v[196:199], v[96:99]
	v_mfma_f32_16x16x32_bf16 v[84:87], v[172:175], v[204:207], v[84:87]
	v_mfma_f32_16x16x32_bf16 v[80:83], v[180:183], v[204:207], v[80:83]
	v_mfma_f32_16x16x32_bf16 v[68:71], v[172:175], v[216:219], v[68:71]
	v_mfma_f32_16x16x32_bf16 v[64:67], v[180:183], v[216:219], v[64:67]
	v_mfma_f32_16x16x32_bf16 v[116:119], v[176:179], v[192:195], v[116:119]
	v_mfma_f32_16x16x32_bf16 v[112:115], v[184:187], v[192:195], v[112:115]
	v_mfma_f32_16x16x32_bf16 v[100:103], v[176:179], v[200:203], v[100:103]
	v_mfma_f32_16x16x32_bf16 v[96:99], v[184:187], v[200:203], v[96:99]
	v_mfma_f32_16x16x32_bf16 v[84:87], v[176:179], v[212:215], v[84:87]
	v_mfma_f32_16x16x32_bf16 v[80:83], v[184:187], v[212:215], v[80:83]
	v_mfma_f32_16x16x32_bf16 v[68:71], v[176:179], v[220:223], v[68:71]
	v_mfma_f32_16x16x32_bf16 v[64:67], v[184:187], v[220:223], v[64:67]
	s_setprio 0
	s_barrier
	s_add_i32 s26, s33, s60
	s_add_i32 m0, s26, 0xffffff80
	ds_read_b128 v[188:191], v152 offset:49152
	ds_read_b128 v[192:195], v152 offset:50176
	ds_read_b128 v[196:199], v152 offset:51200
	ds_read_b128 v[200:203], v152 offset:52224
	ds_read_b128 v[204:207], v152 offset:53248
	ds_read_b128 v[212:215], v152 offset:54272
	ds_read_b128 v[216:219], v152 offset:55296
	ds_read_b128 v[220:223], v152 offset:56320
	global_load_lds_dwordx4 v130, s[54:55] offset:128
	s_add_i32 m0, s26, 0x1f80
	s_add_u32 s26, s54, 0x20080
	s_addc_u32 s27, s55, 0
	s_add_i32 s33, s77, s60
	global_load_lds_dwordx4 v134, s[54:55] offset:128
	s_mov_b32 m0, s33
	s_nop 0
	global_load_lds_dwordx4 v130, s[26:27]
	s_add_i32 m0, s33, 0x2000
	s_nop 0
	global_load_lds_dwordx4 v134, s[26:27]
	s_add_i32 m0, s66, 0xffffff80
	s_nop 0
	global_load_lds_dwordx4 v128, s[56:57] offset:128
	s_add_i32 m0, s67, 0xffffff80
	s_nop 0
	global_load_lds_dwordx4 v132, s[56:57] offset:128
	s_waitcnt vmcnt(8)
	s_waitcnt lgkmcnt(0)
	s_barrier
	s_setprio 1
	s_waitcnt lgkmcnt(0)
	v_mfma_f32_16x16x32_bf16 v[60:63], v[156:159], v[188:191], v[60:63]
	v_mfma_f32_16x16x32_bf16 v[56:59], v[164:167], v[188:191], v[56:59]
	v_mfma_f32_16x16x32_bf16 v[44:47], v[156:159], v[196:199], v[44:47]
	v_mfma_f32_16x16x32_bf16 v[40:43], v[164:167], v[196:199], v[40:43]
	v_mfma_f32_16x16x32_bf16 v[28:31], v[156:159], v[204:207], v[28:31]
	v_mfma_f32_16x16x32_bf16 v[24:27], v[164:167], v[204:207], v[24:27]
	v_mfma_f32_16x16x32_bf16 v[12:15], v[156:159], v[216:219], v[12:15]
	v_mfma_f32_16x16x32_bf16 v[8:11], v[164:167], v[216:219], v[8:11]
	v_mfma_f32_16x16x32_bf16 v[60:63], v[160:163], v[192:195], v[60:63]
	v_mfma_f32_16x16x32_bf16 v[56:59], v[168:171], v[192:195], v[56:59]
	v_mfma_f32_16x16x32_bf16 v[44:47], v[160:163], v[200:203], v[44:47]
	v_mfma_f32_16x16x32_bf16 v[40:43], v[168:171], v[200:203], v[40:43]
	v_mfma_f32_16x16x32_bf16 v[28:31], v[160:163], v[212:215], v[28:31]
	v_mfma_f32_16x16x32_bf16 v[24:27], v[168:171], v[212:215], v[24:27]
	v_mfma_f32_16x16x32_bf16 v[12:15], v[160:163], v[220:223], v[12:15]
	v_mfma_f32_16x16x32_bf16 v[8:11], v[168:171], v[220:223], v[8:11]
	s_setprio 0
	s_setprio 1
	v_mfma_f32_16x16x32_bf16 v[52:55], v[172:175], v[188:191], v[52:55]
	v_mfma_f32_16x16x32_bf16 v[48:51], v[180:183], v[188:191], v[48:51]
	v_mfma_f32_16x16x32_bf16 v[36:39], v[172:175], v[196:199], v[36:39]
	v_mfma_f32_16x16x32_bf16 v[32:35], v[180:183], v[196:199], v[32:35]
	v_mfma_f32_16x16x32_bf16 v[20:23], v[172:175], v[204:207], v[20:23]
	v_mfma_f32_16x16x32_bf16 v[16:19], v[180:183], v[204:207], v[16:19]
	v_mfma_f32_16x16x32_bf16 v[4:7], v[172:175], v[216:219], v[4:7]
	v_mfma_f32_16x16x32_bf16 v[0:3], v[180:183], v[216:219], v[0:3]
	v_mfma_f32_16x16x32_bf16 v[52:55], v[176:179], v[192:195], v[52:55]
	v_mfma_f32_16x16x32_bf16 v[48:51], v[184:187], v[192:195], v[48:51]
	v_mfma_f32_16x16x32_bf16 v[36:39], v[176:179], v[200:203], v[36:39]
	v_mfma_f32_16x16x32_bf16 v[32:35], v[184:187], v[200:203], v[32:35]
	v_mfma_f32_16x16x32_bf16 v[20:23], v[176:179], v[212:215], v[20:23]
	v_mfma_f32_16x16x32_bf16 v[16:19], v[184:187], v[212:215], v[16:19]
	v_mfma_f32_16x16x32_bf16 v[4:7], v[176:179], v[220:223], v[4:7]
	v_mfma_f32_16x16x32_bf16 v[0:3], v[184:187], v[220:223], v[0:3]
	s_setprio 0
	s_barrier
	s_add_i32 s76, s76, 2
	s_add_u32 s52, s52, 0x100
	s_addc_u32 s53, s53, 0
	s_add_u32 s74, s74, 0x100
	s_addc_u32 s75, s75, 0
	s_cmp_gt_u32 s76, 29
	s_cbranch_scc0 .LBB0_394
	s_mov_b32 s99, 1
	s_and_b64 vcc, exec, s[14:15]
	s_cbranch_vccz .LBB0_397
	s_barrier

; #define PG8_STAGE(bufoff, gbase, voff) do { _Pragma("unroll") for (int _i = 0; _i < 2; ++_i) \
;         __builtin_amdgcn_global_load_lds((const unsigned*)((const char*)(gbase) + (voff)[_i]), (PG8_LAS unsigned*)(lds + (bufoff) + ldsw + _i * 8192), 16, 0, 0); } while (0)
; #define PG8_WAIT_V(n) asm volatile("s_waitcnt vmcnt(" #n ")" ::: "memory")
; #define PG8_BAR __builtin_amdgcn_s_barrier()
; template <class Epi, class Sched, bool ALIGN_EPI = false, bool SP2 = false>
; __device__ __forceinline__ void gemm_phase(PG8_LAS unsigned char* lds, const Gemm g, const Sched& S, const Epi& E, int tid_in) {
;     ...
;         PG8_STAGE(PG8_SB(0, 0), cB, voffB); PG8_STAGE(PG8_SB(0, 1), cB + hstepB, voffB); PG8_STAGE(PG8_SA(0, 0), cA, voffA); PG8_STAGE(PG8_SA(0, 1), cA + hstep, voffA);
;         if (wr == 1) PG8_BAR;
;         PG8_WAIT_V(2); PG8_BAR;
;         PG8_STAGE(PG8_SB(1, 0), cB + kstep, voffB); PG8_STAGE(PG8_SA(1, 0), cA + kstep, voffA); PG8_STAGE(PG8_SB(1, 1), cB + hstepB + kstep, voffB);
;         PG8_WAIT_V(6); PG8_BAR;
.LBB0_462:
	s_mov_b64 s[42:43], 0x80
	s_and_b32 s8, s8, 3
	s_add_i32 m0, s55, 0x18000
	v_lshl_add_u64 v[6:7], v[6:7], 0, s[42:43]
	s_lshl_b32 s26, s9, 13
	s_lshl_b32 s27, s8, 12
	s_waitcnt vmcnt(2)
	s_barrier
	global_load_lds_dwordx4 v[6:7], off
	v_lshl_add_u64 v[4:5], v[4:5], 0, s[42:43]
	s_add_i32 m0, s55, 0x1a000
	s_add_i32 s69, s55, 0x8000
	s_add_i32 s70, s55, 0xa000
	global_load_lds_dwordx4 v[4:5], off
	v_lshl_add_u64 v[0:1], v[0:1], 0, s[42:43]
	s_mov_b32 m0, s69
	s_add_u32 s12, s58, 0x80080
	global_load_lds_dwordx4 v[0:1], off
	v_lshl_add_u64 v[0:1], v[2:3], 0, s[42:43]
	s_mov_b32 m0, s70
	s_addc_u32 s13, s59, 0
	global_load_lds_dwordx4 v[0:1], off
	s_add_i32 m0, s55, 0x1c000
	v_lshl_add_u64 v[0:1], s[12:13], 0, v[130:131]
	global_load_lds_dwordx4 v[0:1], off
	v_lshl_add_u64 v[0:1], s[12:13], 0, v[134:135]
	s_add_i32 m0, s55, 0x1e000
	s_cmpk_lt_u32 s10, 0x100
	global_load_lds_dwordx4 v[0:1], off
	s_cselect_b64 s[46:47], -1, 0
	s_lshl_b32 s10, s9, 2
	v_and_b32_e32 v2, 48, v8
	v_and_b32_e32 v0, 15, v8
	v_lshlrev_b32_e32 v3, 2, v8
	s_or_b32 s10, s10, s8
	v_lshl_or_b32 v1, v0, 6, v2
	v_and_b32_e32 v3, 32, v3
	s_mulk_i32 s10, 0x900
	v_bitop3_b32 v4, v1, s26, v3 bitop3:0xde
	v_bitop3_b32 v137, v1, s27, v3 bitop3:0xde
	v_and_b32_e32 v3, 3, v8
	s_add_i32 s10, s10, 0
	v_bfe_u32 v1, v8, 2, 4
	v_lshlrev_b32_e32 v5, 3, v3
	s_add_i32 s10, s10, 0x20000
	v_lshl_or_b32 v150, s9, 6, v1
	v_lshl_or_b32 v136, s8, 6, v5
	v_lshlrev_b32_e32 v5, 5, v3
	v_cmp_eq_u32_e64 s[8:9], 0, v3
	s_movk_i32 s12, 0x90
	v_mov_b32_e32 v3, s10
	v_mad_u32_u24 v6, v0, s12, v3
	v_and_b32_e32 v0, 64, v252
	v_add_u32_e32 v0, 64, v0
	v_cmp_lt_i32_e32 vcc, v254, v0
	v_mad_u32_u24 v3, v1, s12, v3
	s_mov_b32 s10, 0x20400
	v_cndmask_b32_e32 v1, v252, v254, vcc
	v_cmp_lt_i32_e32 vcc, v253, v0
	v_lshlrev_b32_e32 v151, 2, v1
	v_lshrrev_b32_e32 v1, 1, v9
	v_cndmask_b32_e32 v0, v252, v253, vcc
	v_lshlrev_b32_e32 v152, 2, v0
	v_mul_lo_u32 v0, v11, s11
	v_mad_u64_u32 v[0:1], s[12:13], v1, s10, v[0:1]
	v_or_b32_e32 v0, v0, v10
	v_add_lshl_u32 v0, v0, v12, 1
	v_mov_b32_e32 v1, v131
	s_mov_b64 s[12:13], 0x204080
	v_lshl_add_u64 v[138:139], v[0:1], 0, s[12:13]
	v_lshrrev_b32_e32 v1, 1, v13
	v_mul_lo_u32 v0, v14, s11
	v_mad_u64_u32 v[0:1], s[10:11], v1, s10, v[0:1]
	s_waitcnt vmcnt(6)
	v_or_b32_e32 v0, v0, v15
	v_add_lshl_u32 v0, v0, v16, 1
	v_mov_b32_e32 v1, v131
	s_add_i32 s71, 0, 0x10000
	s_add_i32 s72, 0, 0x14000
	v_lshl_add_u64 v[140:141], v[0:1], 0, s[12:13]
	v_mov_b64_e32 v[142:143], 0x400
	v_mov_b64_e32 v[144:145], 0x3ff
	v_add_u32_e32 v153, s71, v137
	v_add_u32_e32 v154, s72, v137
	v_add_u32_e32 v155, 0, v4
	v_add_u32_e32 v156, v6, v2
	v_add_u32_e32 v157, v3, v5
	s_barrier
	s_mov_b32 s99, 0
	s_branch .LBB0_465

; #define PG8_STAGE(bufoff, gbase, voff) do { _Pragma("unroll") for (int _i = 0; _i < 2; ++_i) \
;         __builtin_amdgcn_global_load_lds((const unsigned*)((const char*)(gbase) + (voff)[_i]), (PG8_LAS unsigned*)(lds + (bufoff) + ldsw + _i * 8192), 16, 0, 0); } while (0)
; #define PG8_LDA(dst, b, h) do { _Pragma("unroll") for (int m = 0; m < 4; ++m) _Pragma("unroll") for (int k = 0; k < 2; ++k) dst[m][k] = *(const PG8_LAS bf16x8*)(lds + PG8_SA(b, h) + aoff + m * 2048 + k * 1024); } while (0)
; #define PG8_LDB(dst, b, h) do { _Pragma("unroll") for (int n = 0; n < 2; ++n) _Pragma("unroll") for (int k = 0; k < 2; ++k) dst[n][k] = *(const PG8_LAS bf16x8*)(lds + PG8_SB(b, h) + boff + n * 2048 + k * 1024); } while (0)
; #define PG8_MMA(ai, bj, At, Bt) do { __builtin_amdgcn_s_setprio(1); _Pragma("unroll") for (int m = 0; m < 4; ++m) _Pragma("unroll") for (int n = 0; n < 2; ++n) _Pragma("unroll") for (int k = 0; k < 2; ++k) \
;         acc[ai][bj][m][n] = __builtin_amdgcn_mfma_f32_16x16x32_bf16(Bt[n][k], At[m][k], acc[ai][bj][m][n], 0, 0, 0); __builtin_amdgcn_s_setprio(0); } while (0)
; #define PG8_WAIT_V(n) asm volatile("s_waitcnt vmcnt(" #n ")" ::: "memory")
; #define PG8_WAIT_L(n) asm volatile("s_waitcnt lgkmcnt(" #n ")" ::: "memory")
; #define PG8_BAR __builtin_amdgcn_s_barrier()
; #define PG8_SCHED __builtin_amdgcn_sched_barrier(0)
; template <class Epi, class Sched, bool ALIGN_EPI = false, bool SP2 = false>
; __device__ __forceinline__ void gemm_phase(PG8_LAS unsigned char* lds, const Gemm g, const Sched& S, const Epi& E, int tid_in) {
;     ...
;             PG8_LDB(B0, 0, 0); PG8_LDB(B1, 0, 1); PG8_SCHED; PG8_LDA(At, 0, 0); PG8_STAGE(PG8_SA(1, 1), a1 + hstep, voffA);
;             PG8_WAIT_V(8); PG8_WAIT_L(0); PG8_BAR; PG8_MMA(0, 0, At, B0); PG8_MMA(0, 1, At, B1); PG8_BAR; PG8_SCHED;
.Lkb_skip_3:
	ds_read_b128 v[146:149], v153
	ds_read_b128 v[158:161], v153 offset:1024
	ds_read_b128 v[162:165], v153 offset:2048
	ds_read_b128 v[166:169], v153 offset:3072
	ds_read_b128 v[170:173], v154
	ds_read_b128 v[174:177], v154 offset:1024
	ds_read_b128 v[178:181], v154 offset:2048
	ds_read_b128 v[182:185], v154 offset:3072
	s_add_u32 s12, s56, 0x100
	s_addc_u32 s13, s57, 0
	s_cmpk_eq_i32 s79, 0x7c
	s_cselect_b32 s61, s51, s13
	s_cselect_b32 s60, s50, s12
	s_cselect_b32 s59, s49, s77
	s_cselect_b32 s58, s75, s76
	s_add_i32 m0, s55, 0xc000
	ds_read_b128 v[186:189], v155
	ds_read_b128 v[190:193], v155 offset:1024
	ds_read_b128 v[194:197], v155 offset:2048
	ds_read_b128 v[198:201], v155 offset:3072
	ds_read_b128 v[202:205], v155 offset:4096
	ds_read_b128 v[206:209], v155 offset:5120
	ds_read_b128 v[212:215], v155 offset:6144
	ds_read_b128 v[216:219], v155 offset:7168
	global_load_lds_dwordx4 v138, s[56:57]
	s_add_i32 m0, s55, 0xe000
	s_nop 0
	global_load_lds_dwordx4 v140, s[56:57]
	s_cmp_eq_u32 s99, 0
	s_cbranch_scc1 .Lw1s_3_0
	s_waitcnt vmcnt(48)
	s_branch .Lw1d_3_0

; #define PG8_STAGE(bufoff, gbase, voff) do { _Pragma("unroll") for (int _i = 0; _i < 2; ++_i) \
;         __builtin_amdgcn_global_load_lds((const unsigned*)((const char*)(gbase) + (voff)[_i]), (PG8_LAS unsigned*)(lds + (bufoff) + ldsw + _i * 8192), 16, 0, 0); } while (0)
; #define PG8_LDA(dst, b, h) do { _Pragma("unroll") for (int m = 0; m < 4; ++m) _Pragma("unroll") for (int k = 0; k < 2; ++k) dst[m][k] = *(const PG8_LAS bf16x8*)(lds + PG8_SA(b, h) + aoff + m * 2048 + k * 1024); } while (0)
; #define PG8_MMA(ai, bj, At, Bt) do { __builtin_amdgcn_s_setprio(1); _Pragma("unroll") for (int m = 0; m < 4; ++m) _Pragma("unroll") for (int n = 0; n < 2; ++n) _Pragma("unroll") for (int k = 0; k < 2; ++k) \
;         acc[ai][bj][m][n] = __builtin_amdgcn_mfma_f32_16x16x32_bf16(Bt[n][k], At[m][k], acc[ai][bj][m][n], 0, 0, 0); __builtin_amdgcn_s_setprio(0); } while (0)
; #define PG8_WAIT_V(n) asm volatile("s_waitcnt vmcnt(" #n ")" ::: "memory")
; #define PG8_WAIT_L(n) asm volatile("s_waitcnt lgkmcnt(" #n ")" ::: "memory")
; #define PG8_BAR __builtin_amdgcn_s_barrier()
; #define PG8_SCHED __builtin_amdgcn_sched_barrier(0)
; template <class Epi, class Sched, bool ALIGN_EPI = false, bool SP2 = false>
; __device__ __forceinline__ void gemm_phase(PG8_LAS unsigned char* lds, const Gemm g, const Sched& S, const Epi& E, int tid_in) {
;     ...
;             PG8_WAIT_V(8); PG8_WAIT_L(0); PG8_BAR; PG8_MMA(0, 0, At, B0); PG8_MMA(0, 1, At, B1); PG8_BAR; PG8_SCHED;
;             PG8_LDA(At, 0, 1); PG8_STAGE(PG8_SB(0, 0), b2, voffB); PG8_STAGE(PG8_SB(0, 1), b2 + hstepB, voffB); PG8_STAGE(PG8_SA(0, 0), a2, voffA);
;             PG8_WAIT_V(8); PG8_WAIT_L(0); PG8_BAR; PG8_MMA(1, 0, At, B0); PG8_MMA(1, 1, At, B1); PG8_BAR; PG8_SCHED;
.Lw1d_3_0:
	s_waitcnt lgkmcnt(0)
	s_barrier
	s_setprio 1
	s_waitcnt lgkmcnt(0)
	v_mfma_f32_16x16x32_bf16 v[124:127], v[146:149], v[186:189], 0
	v_mfma_f32_16x16x32_bf16 v[120:123], v[162:165], v[186:189], 0
	v_mfma_f32_16x16x32_bf16 v[108:111], v[146:149], v[194:197], 0
	v_mfma_f32_16x16x32_bf16 v[104:107], v[162:165], v[194:197], 0
	v_mfma_f32_16x16x32_bf16 v[92:95], v[146:149], v[202:205], 0
	v_mfma_f32_16x16x32_bf16 v[88:91], v[162:165], v[202:205], 0
	v_mfma_f32_16x16x32_bf16 v[76:79], v[146:149], v[212:215], 0
	v_mfma_f32_16x16x32_bf16 v[72:75], v[162:165], v[212:215], 0
	v_mfma_f32_16x16x32_bf16 v[124:127], v[158:161], v[190:193], v[124:127]
	v_mfma_f32_16x16x32_bf16 v[120:123], v[166:169], v[190:193], v[120:123]
	v_mfma_f32_16x16x32_bf16 v[108:111], v[158:161], v[198:201], v[108:111]
	v_mfma_f32_16x16x32_bf16 v[104:107], v[166:169], v[198:201], v[104:107]
	v_mfma_f32_16x16x32_bf16 v[92:95], v[158:161], v[206:209], v[92:95]
	v_mfma_f32_16x16x32_bf16 v[88:91], v[166:169], v[206:209], v[88:91]
	v_mfma_f32_16x16x32_bf16 v[76:79], v[158:161], v[216:219], v[76:79]
	v_mfma_f32_16x16x32_bf16 v[72:75], v[166:169], v[216:219], v[72:75]
	s_setprio 0
	s_setprio 1
	v_mfma_f32_16x16x32_bf16 v[116:119], v[170:173], v[186:189], 0
	v_mfma_f32_16x16x32_bf16 v[112:115], v[178:181], v[186:189], 0
	v_mfma_f32_16x16x32_bf16 v[100:103], v[170:173], v[194:197], 0
	v_mfma_f32_16x16x32_bf16 v[96:99], v[178:181], v[194:197], 0
	v_mfma_f32_16x16x32_bf16 v[84:87], v[170:173], v[202:205], 0
	v_mfma_f32_16x16x32_bf16 v[80:83], v[178:181], v[202:205], 0
	v_mfma_f32_16x16x32_bf16 v[68:71], v[170:173], v[212:215], 0
	v_mfma_f32_16x16x32_bf16 v[64:67], v[178:181], v[212:215], 0
	v_mfma_f32_16x16x32_bf16 v[116:119], v[174:177], v[190:193], v[116:119]
	v_mfma_f32_16x16x32_bf16 v[112:115], v[182:185], v[190:193], v[112:115]
	v_mfma_f32_16x16x32_bf16 v[100:103], v[174:177], v[198:201], v[100:103]
	v_mfma_f32_16x16x32_bf16 v[96:99], v[182:185], v[198:201], v[96:99]
	v_mfma_f32_16x16x32_bf16 v[84:87], v[174:177], v[206:209], v[84:87]
	v_mfma_f32_16x16x32_bf16 v[80:83], v[182:185], v[206:209], v[80:83]
	v_mfma_f32_16x16x32_bf16 v[68:71], v[174:177], v[216:219], v[68:71]
	v_mfma_f32_16x16x32_bf16 v[64:67], v[182:185], v[216:219], v[64:67]
	s_setprio 0
	s_barrier
	s_add_i32 s26, s71, s64
	s_mov_b32 m0, s26
	ds_read_b128 v[186:189], v155 offset:16384
	ds_read_b128 v[190:193], v155 offset:17408
	ds_read_b128 v[194:197], v155 offset:18432
	ds_read_b128 v[198:201], v155 offset:19456
	ds_read_b128 v[202:205], v155 offset:20480
	ds_read_b128 v[206:209], v155 offset:21504
	ds_read_b128 v[212:215], v155 offset:22528
	ds_read_b128 v[216:219], v155 offset:23552
	global_load_lds_dwordx4 v130, s[58:59]
	s_add_i32 m0, s26, 0x2000
	s_add_u32 s26, s58, 0x80000
	s_addc_u32 s27, s59, 0
	s_add_i32 s33, s72, s64
	global_load_lds_dwordx4 v134, s[58:59]
	s_mov_b32 m0, s33
	s_nop 0
	global_load_lds_dwordx4 v130, s[26:27]
	s_add_i32 m0, s33, 0x2000
	s_nop 0
	global_load_lds_dwordx4 v134, s[26:27]
	s_mov_b32 m0, s55
	s_nop 0
	global_load_lds_dwordx4 v128, s[60:61]
	s_mov_b32 m0, s65
	s_nop 0
	global_load_lds_dwordx4 v132, s[60:61]
	s_cmp_eq_u32 s99, 0
	s_cbranch_scc1 .Lw1s_3_1
	s_waitcnt vmcnt(48)
	s_branch .Lw1d_3_1

; #define PG8_STAGE(bufoff, gbase, voff) do { _Pragma("unroll") for (int _i = 0; _i < 2; ++_i) \
;         __builtin_amdgcn_global_load_lds((const unsigned*)((const char*)(gbase) + (voff)[_i]), (PG8_LAS unsigned*)(lds + (bufoff) + ldsw + _i * 8192), 16, 0, 0); } while (0)
; #define PG8_LDA(dst, b, h) do { _Pragma("unroll") for (int m = 0; m < 4; ++m) _Pragma("unroll") for (int k = 0; k < 2; ++k) dst[m][k] = *(const PG8_LAS bf16x8*)(lds + PG8_SA(b, h) + aoff + m * 2048 + k * 1024); } while (0)
; #define PG8_LDB(dst, b, h) do { _Pragma("unroll") for (int n = 0; n < 2; ++n) _Pragma("unroll") for (int k = 0; k < 2; ++k) dst[n][k] = *(const PG8_LAS bf16x8*)(lds + PG8_SB(b, h) + boff + n * 2048 + k * 1024); } while (0)
; #define PG8_MMA(ai, bj, At, Bt) do { __builtin_amdgcn_s_setprio(1); _Pragma("unroll") for (int m = 0; m < 4; ++m) _Pragma("unroll") for (int n = 0; n < 2; ++n) _Pragma("unroll") for (int k = 0; k < 2; ++k) \
;         acc[ai][bj][m][n] = __builtin_amdgcn_mfma_f32_16x16x32_bf16(Bt[n][k], At[m][k], acc[ai][bj][m][n], 0, 0, 0); __builtin_amdgcn_s_setprio(0); } while (0)
; #define PG8_WAIT_V(n) asm volatile("s_waitcnt vmcnt(" #n ")" ::: "memory")
; #define PG8_WAIT_L(n) asm volatile("s_waitcnt lgkmcnt(" #n ")" ::: "memory")
; #define PG8_BAR __builtin_amdgcn_s_barrier()
; #define PG8_SCHED __builtin_amdgcn_sched_barrier(0)
; template <class Epi, class Sched, bool ALIGN_EPI = false, bool SP2 = false>
; __device__ __forceinline__ void gemm_phase(PG8_LAS unsigned char* lds, const Gemm g, const Sched& S, const Epi& E, int tid_in) {
;     ...
;             PG8_WAIT_V(8); PG8_WAIT_L(0); PG8_BAR; PG8_MMA(1, 0, At, B0); PG8_MMA(1, 1, At, B1); PG8_BAR; PG8_SCHED;
;             PG8_LDB(B0, 1, 0); PG8_LDB(B1, 1, 1); PG8_SCHED; PG8_LDA(At, 1, 0); PG8_STAGE(PG8_SA(0, 1), a2 + hstep, voffA);
;             PG8_WAIT_V(8); PG8_WAIT_L(0); PG8_BAR; PG8_MMA(0, 0, At, B0); PG8_MMA(0, 1, At, B1); PG8_BAR; PG8_SCHED;
.Lw1d_3_1:
	s_waitcnt lgkmcnt(0)
	s_barrier
	s_setprio 1
	s_waitcnt lgkmcnt(0)
	v_mfma_f32_16x16x32_bf16 v[60:63], v[146:149], v[186:189], 0
	v_mfma_f32_16x16x32_bf16 v[56:59], v[162:165], v[186:189], 0
	v_mfma_f32_16x16x32_bf16 v[44:47], v[146:149], v[194:197], 0
	v_mfma_f32_16x16x32_bf16 v[40:43], v[162:165], v[194:197], 0
	v_mfma_f32_16x16x32_bf16 v[28:31], v[146:149], v[202:205], 0
	v_mfma_f32_16x16x32_bf16 v[24:27], v[162:165], v[202:205], 0
	v_mfma_f32_16x16x32_bf16 v[12:15], v[146:149], v[212:215], 0
	v_mfma_f32_16x16x32_bf16 v[8:11], v[162:165], v[212:215], 0
	v_mfma_f32_16x16x32_bf16 v[60:63], v[158:161], v[190:193], v[60:63]
	v_mfma_f32_16x16x32_bf16 v[56:59], v[166:169], v[190:193], v[56:59]
	v_mfma_f32_16x16x32_bf16 v[44:47], v[158:161], v[198:201], v[44:47]
	v_mfma_f32_16x16x32_bf16 v[40:43], v[166:169], v[198:201], v[40:43]
	v_mfma_f32_16x16x32_bf16 v[28:31], v[158:161], v[206:209], v[28:31]
	v_mfma_f32_16x16x32_bf16 v[24:27], v[166:169], v[206:209], v[24:27]
	v_mfma_f32_16x16x32_bf16 v[12:15], v[158:161], v[216:219], v[12:15]
	v_mfma_f32_16x16x32_bf16 v[8:11], v[166:169], v[216:219], v[8:11]
	s_setprio 0
	s_setprio 1
	v_mfma_f32_16x16x32_bf16 v[52:55], v[170:173], v[186:189], 0
	v_mfma_f32_16x16x32_bf16 v[48:51], v[178:181], v[186:189], 0
	v_mfma_f32_16x16x32_bf16 v[36:39], v[170:173], v[194:197], 0
	v_mfma_f32_16x16x32_bf16 v[32:35], v[178:181], v[194:197], 0
	v_mfma_f32_16x16x32_bf16 v[20:23], v[170:173], v[202:205], 0
	v_mfma_f32_16x16x32_bf16 v[16:19], v[178:181], v[202:205], 0
	v_mfma_f32_16x16x32_bf16 v[4:7], v[170:173], v[212:215], 0
	v_mfma_f32_16x16x32_bf16 v[0:3], v[178:181], v[212:215], 0
	v_mfma_f32_16x16x32_bf16 v[52:55], v[174:177], v[190:193], v[52:55]
	v_mfma_f32_16x16x32_bf16 v[48:51], v[182:185], v[190:193], v[48:51]
	v_mfma_f32_16x16x32_bf16 v[36:39], v[174:177], v[198:201], v[36:39]
	v_mfma_f32_16x16x32_bf16 v[32:35], v[182:185], v[198:201], v[32:35]
	v_mfma_f32_16x16x32_bf16 v[20:23], v[174:177], v[206:209], v[20:23]
	v_mfma_f32_16x16x32_bf16 v[16:19], v[182:185], v[206:209], v[16:19]
	v_mfma_f32_16x16x32_bf16 v[4:7], v[174:177], v[216:219], v[4:7]
	v_mfma_f32_16x16x32_bf16 v[0:3], v[182:185], v[216:219], v[0:3]
	s_setprio 0
	s_barrier
	s_add_i32 s33, 0, 0x18000
	s_add_i32 s56, 0, 0x1c000
	v_add_u32_e32 v166, s33, v137
	v_add_u32_e32 v182, s56, v137
	ds_read_b128 v[146:149], v166
	ds_read_b128 v[158:161], v166 offset:1024
	ds_read_b128 v[162:165], v166 offset:2048
	ds_read_b128 v[166:169], v166 offset:3072
	ds_read_b128 v[170:173], v182
	ds_read_b128 v[174:177], v182 offset:1024
	ds_read_b128 v[178:181], v182 offset:2048
	ds_read_b128 v[182:185], v182 offset:3072
	s_add_u32 s26, s60, 0x204000
	s_addc_u32 s27, s61, 0
	s_mov_b32 m0, s66
	ds_read_b128 v[186:189], v155 offset:32768
	ds_read_b128 v[190:193], v155 offset:33792
	ds_read_b128 v[194:197], v155 offset:34816
	ds_read_b128 v[198:201], v155 offset:35840
	ds_read_b128 v[202:205], v155 offset:36864
	ds_read_b128 v[206:209], v155 offset:37888
	ds_read_b128 v[212:215], v155 offset:38912
	ds_read_b128 v[216:219], v155 offset:39936
	global_load_lds_dwordx4 v128, s[26:27]
	s_mov_b32 m0, s67
	s_nop 0
	global_load_lds_dwordx4 v132, s[26:27]
	s_waitcnt vmcnt(8)
	s_waitcnt lgkmcnt(0)
	s_barrier
	s_setprio 1
	s_waitcnt lgkmcnt(0)
	v_mfma_f32_16x16x32_bf16 v[124:127], v[146:149], v[186:189], v[124:127]
	v_mfma_f32_16x16x32_bf16 v[120:123], v[162:165], v[186:189], v[120:123]
	v_mfma_f32_16x16x32_bf16 v[108:111], v[146:149], v[194:197], v[108:111]
	v_mfma_f32_16x16x32_bf16 v[104:107], v[162:165], v[194:197], v[104:107]
	v_mfma_f32_16x16x32_bf16 v[92:95], v[146:149], v[202:205], v[92:95]
	v_mfma_f32_16x16x32_bf16 v[88:91], v[162:165], v[202:205], v[88:91]
	v_mfma_f32_16x16x32_bf16 v[76:79], v[146:149], v[212:215], v[76:79]
	v_mfma_f32_16x16x32_bf16 v[72:75], v[162:165], v[212:215], v[72:75]
	v_mfma_f32_16x16x32_bf16 v[124:127], v[158:161], v[190:193], v[124:127]
	v_mfma_f32_16x16x32_bf16 v[120:123], v[166:169], v[190:193], v[120:123]
	v_mfma_f32_16x16x32_bf16 v[108:111], v[158:161], v[198:201], v[108:111]
	v_mfma_f32_16x16x32_bf16 v[104:107], v[166:169], v[198:201], v[104:107]
	v_mfma_f32_16x16x32_bf16 v[92:95], v[158:161], v[206:209], v[92:95]
	v_mfma_f32_16x16x32_bf16 v[88:91], v[166:169], v[206:209], v[88:91]
	v_mfma_f32_16x16x32_bf16 v[76:79], v[158:161], v[216:219], v[76:79]
	v_mfma_f32_16x16x32_bf16 v[72:75], v[166:169], v[216:219], v[72:75]
	s_setprio 0
	s_setprio 1
	v_mfma_f32_16x16x32_bf16 v[116:119], v[170:173], v[186:189], v[116:119]
	v_mfma_f32_16x16x32_bf16 v[112:115], v[178:181], v[186:189], v[112:115]
	v_mfma_f32_16x16x32_bf16 v[100:103], v[170:173], v[194:197], v[100:103]
	v_mfma_f32_16x16x32_bf16 v[96:99], v[178:181], v[194:197], v[96:99]
	v_mfma_f32_16x16x32_bf16 v[84:87], v[170:173], v[202:205], v[84:87]
	v_mfma_f32_16x16x32_bf16 v[80:83], v[178:181], v[202:205], v[80:83]
	v_mfma_f32_16x16x32_bf16 v[68:71], v[170:173], v[212:215], v[68:71]
	v_mfma_f32_16x16x32_bf16 v[64:67], v[178:181], v[212:215], v[64:67]
	v_mfma_f32_16x16x32_bf16 v[116:119], v[174:177], v[190:193], v[116:119]
	v_mfma_f32_16x16x32_bf16 v[112:115], v[182:185], v[190:193], v[112:115]
	v_mfma_f32_16x16x32_bf16 v[100:103], v[174:177], v[198:201], v[100:103]
	v_mfma_f32_16x16x32_bf16 v[96:99], v[182:185], v[198:201], v[96:99]
	v_mfma_f32_16x16x32_bf16 v[84:87], v[174:177], v[206:209], v[84:87]
	v_mfma_f32_16x16x32_bf16 v[80:83], v[182:185], v[206:209], v[80:83]
	v_mfma_f32_16x16x32_bf16 v[68:71], v[174:177], v[216:219], v[68:71]
	v_mfma_f32_16x16x32_bf16 v[64:67], v[182:185], v[216:219], v[64:67]
	s_setprio 0
	s_barrier
; #define PG8_STAGE(bufoff, gbase, voff) do { _Pragma("unroll") for (int _i = 0; _i < 2; ++_i) \
;         __builtin_amdgcn_global_load_lds((const unsigned*)((const char*)(gbase) + (voff)[_i]), (PG8_LAS unsigned*)(lds + (bufoff) + ldsw + _i * 8192), 16, 0, 0); } while (0)
; #define PG8_LDA(dst, b, h) do { _Pragma("unroll") for (int m = 0; m < 4; ++m) _Pragma("unroll") for (int k = 0; k < 2; ++k) dst[m][k] = *(const PG8_LAS bf16x8*)(lds + PG8_SA(b, h) + aoff + m * 2048 + k * 1024); } while (0)
; #define PG8_LDB(dst, b, h) do { _Pragma("unroll") for (int n = 0; n < 2; ++n) _Pragma("unroll") for (int k = 0; k < 2; ++k) dst[n][k] = *(const PG8_LAS bf16x8*)(lds + PG8_SB(b, h) + boff + n * 2048 + k * 1024); } while (0)
; #define PG8_MMA(ai, bj, At, Bt) do { __builtin_amdgcn_s_setprio(1); _Pragma("unroll") for (int m = 0; m < 4; ++m) _Pragma("unroll") for (int n = 0; n < 2; ++n) _Pragma("unroll") for (int k = 0; k < 2; ++k) \
;         acc[ai][bj][m][n] = __builtin_amdgcn_mfma_f32_16x16x32_bf16(Bt[n][k], At[m][k], acc[ai][bj][m][n], 0, 0, 0); __builtin_amdgcn_s_setprio(0); } while (0)
; #define PG8_BAR __builtin_amdgcn_s_barrier()
; template <class Epi, class Sched, bool ALIGN_EPI = false, bool SP2 = false>
; __device__ __forceinline__ void gemm_phase(PG8_LAS unsigned char* lds, const Gemm g, const Sched& S, const Epi& E, int tid_in) {
;     ...
;             PG8_LDB(B0, 0, 0); PG8_LDB(B1, 0, 1); PG8_SCHED; PG8_LDA(At, 0, 0); PG8_STAGE(PG8_SA(1, 1), a1 + hstep, voffA);
;             PG8_WAIT_V(8); PG8_WAIT_L(0); PG8_BAR; PG8_MMA(0, 0, At, B0); PG8_MMA(0, 1, At, B1); PG8_BAR; PG8_SCHED;
;             PG8_LDA(At, 0, 1); PG8_STAGE(PG8_SB(0, 0), b2, voffB); PG8_STAGE(PG8_SB(0, 1), b2 + hstepB, voffB); PG8_STAGE(PG8_SA(0, 0), a2, voffA);
;             PG8_WAIT_V(8); PG8_WAIT_L(0); PG8_BAR; PG8_MMA(1, 0, At, B0); PG8_MMA(1, 1, At, B1); PG8_BAR; PG8_SCHED;
;             PG8_LDB(B0, 1, 0); PG8_LDB(B1, 1, 1); PG8_SCHED; PG8_LDA(At, 1, 0); PG8_STAGE(PG8_SA(0, 1), a2 + hstep, voffA);
;             PG8_WAIT_V(8); PG8_WAIT_L(0); PG8_BAR; PG8_MMA(0, 0, At, B0); PG8_MMA(0, 1, At, B1); PG8_BAR; PG8_SCHED;
;             PG8_LDA(At, 1, 1); PG8_STAGE(PG8_SB(1, 0), b3, voffB); PG8_STAGE(PG8_SB(1, 1), b3 + hstepB, voffB); PG8_STAGE(PG8_SA(1, 0), a3, voffA);
;             PG8_WAIT_V(8); PG8_WAIT_L(0); PG8_BAR; PG8_MMA(1, 0, At, B0); PG8_MMA(1, 1, At, B1); PG8_BAR; PG8_SCHED;
	s_add_i32 s26, s33, s64
	s_add_i32 m0, s26, 0xffffff80
	ds_read_b128 v[186:189], v155 offset:49152
	ds_read_b128 v[190:193], v155 offset:50176
	ds_read_b128 v[194:197], v155 offset:51200
	ds_read_b128 v[198:201], v155 offset:52224
	ds_read_b128 v[202:205], v155 offset:53248
	ds_read_b128 v[206:209], v155 offset:54272
	ds_read_b128 v[212:215], v155 offset:55296
	ds_read_b128 v[216:219], v155 offset:56320
	global_load_lds_dwordx4 v130, s[58:59] offset:128
	s_add_i32 m0, s26, 0x1f80
	s_add_u32 s26, s58, 0x80080
	s_addc_u32 s27, s59, 0
	s_add_i32 s33, s56, s64
	global_load_lds_dwordx4 v134, s[58:59] offset:128
	s_mov_b32 m0, s33
	s_nop 0
	global_load_lds_dwordx4 v130, s[26:27]
	s_add_i32 m0, s33, 0x2000
	s_nop 0
	global_load_lds_dwordx4 v134, s[26:27]
	s_add_i32 m0, s69, 0xffffff80
	s_nop 0
	global_load_lds_dwordx4 v128, s[60:61] offset:128
	s_add_i32 m0, s70, 0xffffff80
	s_nop 0
	global_load_lds_dwordx4 v132, s[60:61] offset:128
	s_waitcnt vmcnt(8)
	s_waitcnt lgkmcnt(0)
	s_barrier
	s_setprio 1
	s_waitcnt lgkmcnt(0)
	v_mfma_f32_16x16x32_bf16 v[60:63], v[146:149], v[186:189], v[60:63]
	v_mfma_f32_16x16x32_bf16 v[56:59], v[162:165], v[186:189], v[56:59]
	v_mfma_f32_16x16x32_bf16 v[44:47], v[146:149], v[194:197], v[44:47]
	v_mfma_f32_16x16x32_bf16 v[40:43], v[162:165], v[194:197], v[40:43]
	v_mfma_f32_16x16x32_bf16 v[28:31], v[146:149], v[202:205], v[28:31]
	v_mfma_f32_16x16x32_bf16 v[24:27], v[162:165], v[202:205], v[24:27]
	v_mfma_f32_16x16x32_bf16 v[12:15], v[146:149], v[212:215], v[12:15]
	v_mfma_f32_16x16x32_bf16 v[8:11], v[162:165], v[212:215], v[8:11]
	v_mfma_f32_16x16x32_bf16 v[60:63], v[158:161], v[190:193], v[60:63]
	v_mfma_f32_16x16x32_bf16 v[56:59], v[166:169], v[190:193], v[56:59]
	v_mfma_f32_16x16x32_bf16 v[44:47], v[158:161], v[198:201], v[44:47]
	v_mfma_f32_16x16x32_bf16 v[40:43], v[166:169], v[198:201], v[40:43]
	v_mfma_f32_16x16x32_bf16 v[28:31], v[158:161], v[206:209], v[28:31]
	v_mfma_f32_16x16x32_bf16 v[24:27], v[166:169], v[206:209], v[24:27]
	v_mfma_f32_16x16x32_bf16 v[12:15], v[158:161], v[216:219], v[12:15]
	v_mfma_f32_16x16x32_bf16 v[8:11], v[166:169], v[216:219], v[8:11]
	s_setprio 0
	s_setprio 1
	v_mfma_f32_16x16x32_bf16 v[52:55], v[170:173], v[186:189], v[52:55]
	v_mfma_f32_16x16x32_bf16 v[48:51], v[178:181], v[186:189], v[48:51]
	v_mfma_f32_16x16x32_bf16 v[36:39], v[170:173], v[194:197], v[36:39]
	v_mfma_f32_16x16x32_bf16 v[32:35], v[178:181], v[194:197], v[32:35]
	v_mfma_f32_16x16x32_bf16 v[20:23], v[170:173], v[202:205], v[20:23]
	v_mfma_f32_16x16x32_bf16 v[16:19], v[178:181], v[202:205], v[16:19]
	v_mfma_f32_16x16x32_bf16 v[4:7], v[170:173], v[212:215], v[4:7]
	v_mfma_f32_16x16x32_bf16 v[0:3], v[178:181], v[212:215], v[0:3]
	v_mfma_f32_16x16x32_bf16 v[52:55], v[174:177], v[190:193], v[52:55]
	v_mfma_f32_16x16x32_bf16 v[48:51], v[182:185], v[190:193], v[48:51]
	v_mfma_f32_16x16x32_bf16 v[36:39], v[174:177], v[198:201], v[36:39]
	v_mfma_f32_16x16x32_bf16 v[32:35], v[182:185], v[198:201], v[32:35]
	v_mfma_f32_16x16x32_bf16 v[20:23], v[174:177], v[206:209], v[20:23]
	v_mfma_f32_16x16x32_bf16 v[16:19], v[182:185], v[206:209], v[16:19]
	v_mfma_f32_16x16x32_bf16 v[4:7], v[174:177], v[216:219], v[4:7]
	v_mfma_f32_16x16x32_bf16 v[0:3], v[182:185], v[216:219], v[0:3]
	s_setprio 0
	s_barrier
	s_add_i32 s79, s79, 2
	s_add_u32 s76, s76, 0x100
	s_addc_u32 s77, s77, 0
	s_cmpk_gt_u32 s79, 0x7d
	s_mov_b64 s[56:57], s[12:13]
.LBB0_474:
	ds_read_b128 v[146:149], v153
	ds_read_b128 v[158:161], v153 offset:1024
	ds_read_b128 v[162:165], v153 offset:2048
	ds_read_b128 v[166:169], v153 offset:3072
	ds_read_b128 v[170:173], v154
	ds_read_b128 v[174:177], v154 offset:1024
	ds_read_b128 v[178:181], v154 offset:2048
	ds_read_b128 v[182:185], v154 offset:3072
	s_add_u32 s12, s56, 0x100
	s_addc_u32 s13, s57, 0
	s_cmpk_eq_i32 s79, 0x7c
	s_cselect_b32 s61, s51, s13
	s_cselect_b32 s60, s50, s12
	s_cselect_b32 s59, s49, s77
	s_cselect_b32 s58, s75, s76
	s_add_i32 m0, s55, 0xc000
	ds_read_b128 v[186:189], v155
	ds_read_b128 v[190:193], v155 offset:1024
	ds_read_b128 v[194:197], v155 offset:2048
	ds_read_b128 v[198:201], v155 offset:3072
	ds_read_b128 v[202:205], v155 offset:4096
	ds_read_b128 v[206:209], v155 offset:5120
	ds_read_b128 v[212:215], v155 offset:6144
	ds_read_b128 v[216:219], v155 offset:7168
	global_load_lds_dwordx4 v138, s[56:57]
	s_add_i32 m0, s55, 0xe000
	s_nop 0
	global_load_lds_dwordx4 v140, s[56:57]
	s_waitcnt vmcnt(8)
	s_waitcnt lgkmcnt(0)
	s_barrier
	s_setprio 1
	s_waitcnt lgkmcnt(0)
	v_mfma_f32_16x16x32_bf16 v[124:127], v[146:149], v[186:189], v[124:127]
	v_mfma_f32_16x16x32_bf16 v[120:123], v[162:165], v[186:189], v[120:123]
	v_mfma_f32_16x16x32_bf16 v[108:111], v[146:149], v[194:197], v[108:111]
	v_mfma_f32_16x16x32_bf16 v[104:107], v[162:165], v[194:197], v[104:107]
	v_mfma_f32_16x16x32_bf16 v[92:95], v[146:149], v[202:205], v[92:95]
	v_mfma_f32_16x16x32_bf16 v[88:91], v[162:165], v[202:205], v[88:91]
	v_mfma_f32_16x16x32_bf16 v[76:79], v[146:149], v[212:215], v[76:79]
	v_mfma_f32_16x16x32_bf16 v[72:75], v[162:165], v[212:215], v[72:75]
	v_mfma_f32_16x16x32_bf16 v[124:127], v[158:161], v[190:193], v[124:127]
	v_mfma_f32_16x16x32_bf16 v[120:123], v[166:169], v[190:193], v[120:123]
	v_mfma_f32_16x16x32_bf16 v[108:111], v[158:161], v[198:201], v[108:111]
	v_mfma_f32_16x16x32_bf16 v[104:107], v[166:169], v[198:201], v[104:107]
	v_mfma_f32_16x16x32_bf16 v[92:95], v[158:161], v[206:209], v[92:95]
	v_mfma_f32_16x16x32_bf16 v[88:91], v[166:169], v[206:209], v[88:91]
	v_mfma_f32_16x16x32_bf16 v[76:79], v[158:161], v[216:219], v[76:79]
	v_mfma_f32_16x16x32_bf16 v[72:75], v[166:169], v[216:219], v[72:75]
	s_setprio 0
	s_setprio 1
	v_mfma_f32_16x16x32_bf16 v[116:119], v[170:173], v[186:189], v[116:119]
	v_mfma_f32_16x16x32_bf16 v[112:115], v[178:181], v[186:189], v[112:115]
	v_mfma_f32_16x16x32_bf16 v[100:103], v[170:173], v[194:197], v[100:103]
	v_mfma_f32_16x16x32_bf16 v[96:99], v[178:181], v[194:197], v[96:99]
	v_mfma_f32_16x16x32_bf16 v[84:87], v[170:173], v[202:205], v[84:87]
	v_mfma_f32_16x16x32_bf16 v[80:83], v[178:181], v[202:205], v[80:83]
	v_mfma_f32_16x16x32_bf16 v[68:71], v[170:173], v[212:215], v[68:71]
	v_mfma_f32_16x16x32_bf16 v[64:67], v[178:181], v[212:215], v[64:67]
	v_mfma_f32_16x16x32_bf16 v[116:119], v[174:177], v[190:193], v[116:119]
	v_mfma_f32_16x16x32_bf16 v[112:115], v[182:185], v[190:193], v[112:115]
	v_mfma_f32_16x16x32_bf16 v[100:103], v[174:177], v[198:201], v[100:103]
	v_mfma_f32_16x16x32_bf16 v[96:99], v[182:185], v[198:201], v[96:99]
	v_mfma_f32_16x16x32_bf16 v[84:87], v[174:177], v[206:209], v[84:87]
	v_mfma_f32_16x16x32_bf16 v[80:83], v[182:185], v[206:209], v[80:83]
	v_mfma_f32_16x16x32_bf16 v[68:71], v[174:177], v[216:219], v[68:71]
	v_mfma_f32_16x16x32_bf16 v[64:67], v[182:185], v[216:219], v[64:67]
	s_setprio 0
	s_barrier
; #define PG8_STAGE(bufoff, gbase, voff) do { _Pragma("unroll") for (int _i = 0; _i < 2; ++_i) \
;         __builtin_amdgcn_global_load_lds((const unsigned*)((const char*)(gbase) + (voff)[_i]), (PG8_LAS unsigned*)(lds + (bufoff) + ldsw + _i * 8192), 16, 0, 0); } while (0)
; #define PG8_LDA(dst, b, h) do { _Pragma("unroll") for (int m = 0; m < 4; ++m) _Pragma("unroll") for (int k = 0; k < 2; ++k) dst[m][k] = *(const PG8_LAS bf16x8*)(lds + PG8_SA(b, h) + aoff + m * 2048 + k * 1024); } while (0)
; #define PG8_LDB(dst, b, h) do { _Pragma("unroll") for (int n = 0; n < 2; ++n) _Pragma("unroll") for (int k = 0; k < 2; ++k) dst[n][k] = *(const PG8_LAS bf16x8*)(lds + PG8_SB(b, h) + boff + n * 2048 + k * 1024); } while (0)
; #define PG8_MMA(ai, bj, At, Bt) do { __builtin_amdgcn_s_setprio(1); _Pragma("unroll") for (int m = 0; m < 4; ++m) _Pragma("unroll") for (int n = 0; n < 2; ++n) _Pragma("unroll") for (int k = 0; k < 2; ++k) \
;         acc[ai][bj][m][n] = __builtin_amdgcn_mfma_f32_16x16x32_bf16(Bt[n][k], At[m][k], acc[ai][bj][m][n], 0, 0, 0); __builtin_amdgcn_s_setprio(0); } while (0)
; #define PG8_WAIT_V(n) asm volatile("s_waitcnt vmcnt(" #n ")" ::: "memory")
; #define PG8_WAIT_L(n) asm volatile("s_waitcnt lgkmcnt(" #n ")" ::: "memory")
; #define PG8_BAR __builtin_amdgcn_s_barrier()
; #define PG8_SCHED __builtin_amdgcn_sched_barrier(0)
; template <class Epi, class Sched, bool ALIGN_EPI = false, bool SP2 = false>
; __device__ __forceinline__ void gemm_phase(PG8_LAS unsigned char* lds, const Gemm g, const Sched& S, const Epi& E, int tid_in) {
;     ...
;             PG8_LDA(At, 0, 1); PG8_STAGE(PG8_SB(0, 0), b2, voffB); PG8_STAGE(PG8_SB(0, 1), b2 + hstepB, voffB); PG8_STAGE(PG8_SA(0, 0), a2, voffA);
;             PG8_WAIT_V(8); PG8_WAIT_L(0); PG8_BAR; PG8_MMA(1, 0, At, B0); PG8_MMA(1, 1, At, B1); PG8_BAR; PG8_SCHED;
;             PG8_LDB(B0, 1, 0); PG8_LDB(B1, 1, 1); PG8_SCHED; PG8_LDA(At, 1, 0); PG8_STAGE(PG8_SA(0, 1), a2 + hstep, voffA);
;             PG8_WAIT_V(8); PG8_WAIT_L(0); PG8_BAR; PG8_MMA(0, 0, At, B0); PG8_MMA(0, 1, At, B1); PG8_BAR; PG8_SCHED;
	s_add_i32 s26, s71, s64
	s_mov_b32 m0, s26
	ds_read_b128 v[186:189], v155 offset:16384
	ds_read_b128 v[190:193], v155 offset:17408
	ds_read_b128 v[194:197], v155 offset:18432
	ds_read_b128 v[198:201], v155 offset:19456
	ds_read_b128 v[202:205], v155 offset:20480
	ds_read_b128 v[206:209], v155 offset:21504
	ds_read_b128 v[212:215], v155 offset:22528
	ds_read_b128 v[216:219], v155 offset:23552
	global_load_lds_dwordx4 v130, s[58:59]
	s_add_i32 m0, s26, 0x2000
	s_add_u32 s26, s58, 0x80000
	s_addc_u32 s27, s59, 0
	s_add_i32 s33, s72, s64
	global_load_lds_dwordx4 v134, s[58:59]
	s_mov_b32 m0, s33
	s_nop 0
	global_load_lds_dwordx4 v130, s[26:27]
	s_add_i32 m0, s33, 0x2000
	s_nop 0
	global_load_lds_dwordx4 v134, s[26:27]
	s_mov_b32 m0, s55
	s_nop 0
	global_load_lds_dwordx4 v128, s[60:61]
	s_mov_b32 m0, s65
	s_nop 0
	global_load_lds_dwordx4 v132, s[60:61]
	s_waitcnt vmcnt(8)
	s_waitcnt lgkmcnt(0)
	s_barrier
	s_setprio 1
	s_waitcnt lgkmcnt(0)
	v_mfma_f32_16x16x32_bf16 v[60:63], v[146:149], v[186:189], v[60:63]
	v_mfma_f32_16x16x32_bf16 v[56:59], v[162:165], v[186:189], v[56:59]
	v_mfma_f32_16x16x32_bf16 v[44:47], v[146:149], v[194:197], v[44:47]
	v_mfma_f32_16x16x32_bf16 v[40:43], v[162:165], v[194:197], v[40:43]
	v_mfma_f32_16x16x32_bf16 v[28:31], v[146:149], v[202:205], v[28:31]
	v_mfma_f32_16x16x32_bf16 v[24:27], v[162:165], v[202:205], v[24:27]
	v_mfma_f32_16x16x32_bf16 v[12:15], v[146:149], v[212:215], v[12:15]
	v_mfma_f32_16x16x32_bf16 v[8:11], v[162:165], v[212:215], v[8:11]
	v_mfma_f32_16x16x32_bf16 v[60:63], v[158:161], v[190:193], v[60:63]
	v_mfma_f32_16x16x32_bf16 v[56:59], v[166:169], v[190:193], v[56:59]
	v_mfma_f32_16x16x32_bf16 v[44:47], v[158:161], v[198:201], v[44:47]
	v_mfma_f32_16x16x32_bf16 v[40:43], v[166:169], v[198:201], v[40:43]
	v_mfma_f32_16x16x32_bf16 v[28:31], v[158:161], v[206:209], v[28:31]
	v_mfma_f32_16x16x32_bf16 v[24:27], v[166:169], v[206:209], v[24:27]
	v_mfma_f32_16x16x32_bf16 v[12:15], v[158:161], v[216:219], v[12:15]
	v_mfma_f32_16x16x32_bf16 v[8:11], v[166:169], v[216:219], v[8:11]
	s_setprio 0
	s_setprio 1
	v_mfma_f32_16x16x32_bf16 v[52:55], v[170:173], v[186:189], v[52:55]
	v_mfma_f32_16x16x32_bf16 v[48:51], v[178:181], v[186:189], v[48:51]
	v_mfma_f32_16x16x32_bf16 v[36:39], v[170:173], v[194:197], v[36:39]
	v_mfma_f32_16x16x32_bf16 v[32:35], v[178:181], v[194:197], v[32:35]
	v_mfma_f32_16x16x32_bf16 v[20:23], v[170:173], v[202:205], v[20:23]
	v_mfma_f32_16x16x32_bf16 v[16:19], v[178:181], v[202:205], v[16:19]
	v_mfma_f32_16x16x32_bf16 v[4:7], v[170:173], v[212:215], v[4:7]
	v_mfma_f32_16x16x32_bf16 v[0:3], v[178:181], v[212:215], v[0:3]
	v_mfma_f32_16x16x32_bf16 v[52:55], v[174:177], v[190:193], v[52:55]
	v_mfma_f32_16x16x32_bf16 v[48:51], v[182:185], v[190:193], v[48:51]
	v_mfma_f32_16x16x32_bf16 v[36:39], v[174:177], v[198:201], v[36:39]
	v_mfma_f32_16x16x32_bf16 v[32:35], v[182:185], v[198:201], v[32:35]
	v_mfma_f32_16x16x32_bf16 v[20:23], v[174:177], v[206:209], v[20:23]
	v_mfma_f32_16x16x32_bf16 v[16:19], v[182:185], v[206:209], v[16:19]
	v_mfma_f32_16x16x32_bf16 v[4:7], v[174:177], v[216:219], v[4:7]
	v_mfma_f32_16x16x32_bf16 v[0:3], v[182:185], v[216:219], v[0:3]
	s_setprio 0
	s_barrier
	s_add_i32 s33, 0, 0x18000
	s_add_i32 s56, 0, 0x1c000
	v_add_u32_e32 v166, s33, v137
	v_add_u32_e32 v182, s56, v137
	ds_read_b128 v[146:149], v166
	ds_read_b128 v[158:161], v166 offset:1024
	ds_read_b128 v[162:165], v166 offset:2048
	ds_read_b128 v[166:169], v166 offset:3072
	ds_read_b128 v[170:173], v182
	ds_read_b128 v[174:177], v182 offset:1024
	ds_read_b128 v[178:181], v182 offset:2048
	ds_read_b128 v[182:185], v182 offset:3072
	s_add_u32 s26, s60, 0x204000
	s_addc_u32 s27, s61, 0
	s_mov_b32 m0, s66
	ds_read_b128 v[186:189], v155 offset:32768
	ds_read_b128 v[190:193], v155 offset:33792
	ds_read_b128 v[194:197], v155 offset:34816
	ds_read_b128 v[198:201], v155 offset:35840
	ds_read_b128 v[202:205], v155 offset:36864
	ds_read_b128 v[206:209], v155 offset:37888
	ds_read_b128 v[212:215], v155 offset:38912
	ds_read_b128 v[216:219], v155 offset:39936
	global_load_lds_dwordx4 v128, s[26:27]
	s_mov_b32 m0, s67
	s_nop 0
	global_load_lds_dwordx4 v132, s[26:27]
	s_waitcnt vmcnt(8)
	s_waitcnt lgkmcnt(0)
	s_barrier
	s_setprio 1
	s_waitcnt lgkmcnt(0)
	v_mfma_f32_16x16x32_bf16 v[124:127], v[146:149], v[186:189], v[124:127]
	v_mfma_f32_16x16x32_bf16 v[120:123], v[162:165], v[186:189], v[120:123]
	v_mfma_f32_16x16x32_bf16 v[108:111], v[146:149], v[194:197], v[108:111]
	v_mfma_f32_16x16x32_bf16 v[104:107], v[162:165], v[194:197], v[104:107]
	v_mfma_f32_16x16x32_bf16 v[92:95], v[146:149], v[202:205], v[92:95]
	v_mfma_f32_16x16x32_bf16 v[88:91], v[162:165], v[202:205], v[88:91]
	v_mfma_f32_16x16x32_bf16 v[76:79], v[146:149], v[212:215], v[76:79]
	v_mfma_f32_16x16x32_bf16 v[72:75], v[162:165], v[212:215], v[72:75]
	v_mfma_f32_16x16x32_bf16 v[124:127], v[158:161], v[190:193], v[124:127]
	v_mfma_f32_16x16x32_bf16 v[120:123], v[166:169], v[190:193], v[120:123]
	v_mfma_f32_16x16x32_bf16 v[108:111], v[158:161], v[198:201], v[108:111]
	v_mfma_f32_16x16x32_bf16 v[104:107], v[166:169], v[198:201], v[104:107]
	v_mfma_f32_16x16x32_bf16 v[92:95], v[158:161], v[206:209], v[92:95]
	v_mfma_f32_16x16x32_bf16 v[88:91], v[166:169], v[206:209], v[88:91]
	v_mfma_f32_16x16x32_bf16 v[76:79], v[158:161], v[216:219], v[76:79]
	v_mfma_f32_16x16x32_bf16 v[72:75], v[166:169], v[216:219], v[72:75]
	s_setprio 0
	s_setprio 1
	v_mfma_f32_16x16x32_bf16 v[116:119], v[170:173], v[186:189], v[116:119]
	v_mfma_f32_16x16x32_bf16 v[112:115], v[178:181], v[186:189], v[112:115]
	v_mfma_f32_16x16x32_bf16 v[100:103], v[170:173], v[194:197], v[100:103]
	v_mfma_f32_16x16x32_bf16 v[96:99], v[178:181], v[194:197], v[96:99]
	v_mfma_f32_16x16x32_bf16 v[84:87], v[170:173], v[202:205], v[84:87]
	v_mfma_f32_16x16x32_bf16 v[80:83], v[178:181], v[202:205], v[80:83]
	v_mfma_f32_16x16x32_bf16 v[68:71], v[170:173], v[212:215], v[68:71]
	v_mfma_f32_16x16x32_bf16 v[64:67], v[178:181], v[212:215], v[64:67]
	v_mfma_f32_16x16x32_bf16 v[116:119], v[174:177], v[190:193], v[116:119]
	v_mfma_f32_16x16x32_bf16 v[112:115], v[182:185], v[190:193], v[112:115]
	v_mfma_f32_16x16x32_bf16 v[100:103], v[174:177], v[198:201], v[100:103]
	v_mfma_f32_16x16x32_bf16 v[96:99], v[182:185], v[198:201], v[96:99]
	v_mfma_f32_16x16x32_bf16 v[84:87], v[174:177], v[206:209], v[84:87]
	v_mfma_f32_16x16x32_bf16 v[80:83], v[182:185], v[206:209], v[80:83]
	v_mfma_f32_16x16x32_bf16 v[68:71], v[174:177], v[216:219], v[68:71]
	v_mfma_f32_16x16x32_bf16 v[64:67], v[182:185], v[216:219], v[64:67]
	s_setprio 0
	s_barrier
; #define PG8_STAGE(bufoff, gbase, voff) do { _Pragma("unroll") for (int _i = 0; _i < 2; ++_i) \
;         __builtin_amdgcn_global_load_lds((const unsigned*)((const char*)(gbase) + (voff)[_i]), (PG8_LAS unsigned*)(lds + (bufoff) + ldsw + _i * 8192), 16, 0, 0); } while (0)
; #define PG8_LDA(dst, b, h) do { _Pragma("unroll") for (int m = 0; m < 4; ++m) _Pragma("unroll") for (int k = 0; k < 2; ++k) dst[m][k] = *(const PG8_LAS bf16x8*)(lds + PG8_SA(b, h) + aoff + m * 2048 + k * 1024); } while (0)
; #define PG8_MMA(ai, bj, At, Bt) do { __builtin_amdgcn_s_setprio(1); _Pragma("unroll") for (int m = 0; m < 4; ++m) _Pragma("unroll") for (int n = 0; n < 2; ++n) _Pragma("unroll") for (int k = 0; k < 2; ++k) \
;         acc[ai][bj][m][n] = __builtin_amdgcn_mfma_f32_16x16x32_bf16(Bt[n][k], At[m][k], acc[ai][bj][m][n], 0, 0, 0); __builtin_amdgcn_s_setprio(0); } while (0)
; #define PG8_WAIT_V(n) asm volatile("s_waitcnt vmcnt(" #n ")" ::: "memory")
; #define PG8_WAIT_L(n) asm volatile("s_waitcnt lgkmcnt(" #n ")" ::: "memory")
; #define PG8_BAR __builtin_amdgcn_s_barrier()
; #define PG8_SCHED __builtin_amdgcn_sched_barrier(0)
; template <class Epi, class Sched, bool ALIGN_EPI = false, bool SP2 = false>
; __device__ __forceinline__ void gemm_phase(PG8_LAS unsigned char* lds, const Gemm g, const Sched& S, const Epi& E, int tid_in) {
;     ...
;             PG8_LDA(At, 1, 1); PG8_STAGE(PG8_SB(1, 0), b3, voffB); PG8_STAGE(PG8_SB(1, 1), b3 + hstepB, voffB); PG8_STAGE(PG8_SA(1, 0), a3, voffA);
;             PG8_WAIT_V(8); PG8_WAIT_L(0); PG8_BAR; PG8_MMA(1, 0, At, B0); PG8_MMA(1, 1, At, B1); PG8_BAR; PG8_SCHED;
;     __device__ __forceinline__ void operator()(const f32x4 (&acc)[2][2][4][2], const Unit& u, int wr, int wc, int fr, int fq) const {
;     ...
;                 const int row = u.pm * BM + ai * HALF + wr * 64 + m * 16 + r; float q = 0.f;
; #pragma unroll
;                 for (int bj = 0; bj < 2; ++bj) {
;                     const size_t off = (size_t)row * 2048 + u.pn * BM + wc * 64 + bj * 32 + 8 * p;
;                     f32x4 b0, b1;
;                     if (BASE_F32) { b0 = *(const f32x4*)((const float*)base + off); b1 = *(const f32x4*)((const float*)base + off + 4); }
;                     else { const u32x4 bb = *(const u32x4*)((const bf16_t*)base + off);
	s_add_i32 s26, s33, s64
	s_add_i32 m0, s26, 0xffffff80
	ds_read_b128 v[186:189], v155 offset:49152
	ds_read_b128 v[190:193], v155 offset:50176
	ds_read_b128 v[194:197], v155 offset:51200
	ds_read_b128 v[198:201], v155 offset:52224
	ds_read_b128 v[202:205], v155 offset:53248
	ds_read_b128 v[206:209], v155 offset:54272
	ds_read_b128 v[212:215], v155 offset:55296
	ds_read_b128 v[216:219], v155 offset:56320
	global_load_lds_dwordx4 v130, s[58:59] offset:128
	s_add_i32 m0, s26, 0x1f80
	s_add_u32 s26, s58, 0x80080
	s_addc_u32 s27, s59, 0
	s_add_i32 s33, s56, s64
	global_load_lds_dwordx4 v134, s[58:59] offset:128
	s_mov_b32 m0, s33
	s_nop 0
	global_load_lds_dwordx4 v130, s[26:27]
	s_add_i32 m0, s33, 0x2000
	s_nop 0
	global_load_lds_dwordx4 v134, s[26:27]
	s_add_i32 m0, s69, 0xffffff80
	s_nop 0
	global_load_lds_dwordx4 v128, s[60:61] offset:128
	s_add_i32 m0, s70, 0xffffff80
	s_nop 0
	global_load_lds_dwordx4 v132, s[60:61] offset:128
	s_waitcnt vmcnt(8)
	s_waitcnt lgkmcnt(0)
	s_barrier
	s_setprio 1
	s_waitcnt lgkmcnt(0)
	v_mfma_f32_16x16x32_bf16 v[60:63], v[146:149], v[186:189], v[60:63]
	v_mfma_f32_16x16x32_bf16 v[56:59], v[162:165], v[186:189], v[56:59]
	v_mfma_f32_16x16x32_bf16 v[44:47], v[146:149], v[194:197], v[44:47]
	v_mfma_f32_16x16x32_bf16 v[40:43], v[162:165], v[194:197], v[40:43]
	v_mfma_f32_16x16x32_bf16 v[28:31], v[146:149], v[202:205], v[28:31]
	v_mfma_f32_16x16x32_bf16 v[24:27], v[162:165], v[202:205], v[24:27]
	v_mfma_f32_16x16x32_bf16 v[12:15], v[146:149], v[212:215], v[12:15]
	v_mfma_f32_16x16x32_bf16 v[8:11], v[162:165], v[212:215], v[8:11]
	v_mfma_f32_16x16x32_bf16 v[60:63], v[158:161], v[190:193], v[60:63]
	v_mfma_f32_16x16x32_bf16 v[56:59], v[166:169], v[190:193], v[56:59]
	v_mfma_f32_16x16x32_bf16 v[44:47], v[158:161], v[198:201], v[44:47]
	v_mfma_f32_16x16x32_bf16 v[40:43], v[166:169], v[198:201], v[40:43]
	v_mfma_f32_16x16x32_bf16 v[28:31], v[158:161], v[206:209], v[28:31]
	v_mfma_f32_16x16x32_bf16 v[24:27], v[166:169], v[206:209], v[24:27]
	v_mfma_f32_16x16x32_bf16 v[12:15], v[158:161], v[216:219], v[12:15]
	v_mfma_f32_16x16x32_bf16 v[8:11], v[166:169], v[216:219], v[8:11]
	s_setprio 0
	s_setprio 1
	v_mfma_f32_16x16x32_bf16 v[52:55], v[170:173], v[186:189], v[52:55]
	v_mfma_f32_16x16x32_bf16 v[48:51], v[178:181], v[186:189], v[48:51]
	v_mfma_f32_16x16x32_bf16 v[36:39], v[170:173], v[194:197], v[36:39]
	v_mfma_f32_16x16x32_bf16 v[32:35], v[178:181], v[194:197], v[32:35]
	v_mfma_f32_16x16x32_bf16 v[20:23], v[170:173], v[202:205], v[20:23]
	v_mfma_f32_16x16x32_bf16 v[16:19], v[178:181], v[202:205], v[16:19]
	v_mfma_f32_16x16x32_bf16 v[4:7], v[170:173], v[212:215], v[4:7]
	v_mfma_f32_16x16x32_bf16 v[0:3], v[178:181], v[212:215], v[0:3]
	v_mfma_f32_16x16x32_bf16 v[52:55], v[174:177], v[190:193], v[52:55]
	v_mfma_f32_16x16x32_bf16 v[48:51], v[182:185], v[190:193], v[48:51]
	v_mfma_f32_16x16x32_bf16 v[36:39], v[174:177], v[198:201], v[36:39]
	v_mfma_f32_16x16x32_bf16 v[32:35], v[182:185], v[198:201], v[32:35]
	v_mfma_f32_16x16x32_bf16 v[20:23], v[174:177], v[206:209], v[20:23]
	v_mfma_f32_16x16x32_bf16 v[16:19], v[182:185], v[206:209], v[16:19]
	v_mfma_f32_16x16x32_bf16 v[4:7], v[174:177], v[216:219], v[4:7]
	v_mfma_f32_16x16x32_bf16 v[0:3], v[182:185], v[216:219], v[0:3]
	s_setprio 0
	s_barrier
	s_add_i32 s79, s79, 2
	s_add_u32 s76, s76, 0x100
	s_addc_u32 s77, s77, 0
	s_cmpk_gt_u32 s79, 0x7d
	s_mov_b64 s[56:57], s[12:13]
	s_cbranch_scc0 .LBB0_474
	s_mov_b32 s99, 1
	v_lshl_add_u32 v148, s74, 8, v150
	v_lshl_or_b32 v146, s54, 8, v136
	v_lshl_add_u32 v147, v148, 11, v146
	v_lshlrev_b32_e32 v159, 1, v147
	v_lshlrev_b32_e32 v208, 3, v148
	global_load_dwordx4 v[160:163], v159, s[38:39]
	global_load_dwordx4 v[164:167], v159, s[38:39] offset:64
	v_add_u32_e32 v149, 0x10000, v159
	global_load_dwordx4 v[168:171], v149, s[38:39]
	global_load_dwordx4 v[172:175], v149, s[38:39] offset:64
	v_add_u32_e32 v209, 0x20000, v159
	global_load_dwordx4 v[176:179], v209, s[38:39]
	global_load_dwordx4 v[180:183], v209, s[38:39] offset:64
	v_add_u32_e32 v149, 0x30000, v159
	global_load_dwordx4 v[184:187], v149, s[38:39]
	global_load_dwordx4 v[188:191], v149, s[38:39] offset:64
	v_add_u32_e32 v209, 0x80000, v159
	global_load_dwordx4 v[192:195], v209, s[38:39]
	global_load_dwordx4 v[196:199], v209, s[38:39] offset:64
	v_add_u32_e32 v149, 0x90000, v159
	global_load_dwordx4 v[200:203], v149, s[38:39]
	global_load_dwordx4 v[204:207], v149, s[38:39] offset:64
	v_add_u32_e32 v209, 0xa0000, v159
	global_load_dwordx4 v[212:215], v209, s[38:39]
	global_load_dwordx4 v[216:219], v209, s[38:39] offset:64
	v_add_u32_e32 v149, 0xb0000, v159
	global_load_dwordx4 v[220:223], v149, s[38:39]
	global_load_dwordx4 v[224:227], v149, s[38:39] offset:64
	s_and_b64 vcc, exec, s[46:47]
	s_cbranch_vccz .LBB0_477
	s_barrier

; #define PG8_STAGE(bufoff, gbase, voff) do { _Pragma("unroll") for (int _i = 0; _i < 2; ++_i) \
;         __builtin_amdgcn_global_load_lds((const unsigned*)((const char*)(gbase) + (voff)[_i]), (PG8_LAS unsigned*)(lds + (bufoff) + ldsw + _i * 8192), 16, 0, 0); } while (0)
; #define PG8_WAIT_V(n) asm volatile("s_waitcnt vmcnt(" #n ")" ::: "memory")
; #define PG8_BAR __builtin_amdgcn_s_barrier()
; template <class Epi, class Sched, bool ALIGN_EPI = false, bool SP2 = false>
; __device__ __forceinline__ void gemm_phase(PG8_LAS unsigned char* lds, const Gemm g, const Sched& S, const Epi& E, int tid_in) {
;     ...
;         PG8_STAGE(PG8_SB(0, 0), cB, voffB); PG8_STAGE(PG8_SB(0, 1), cB + hstepB, voffB); PG8_STAGE(PG8_SA(0, 0), cA, voffA); PG8_STAGE(PG8_SA(0, 1), cA + hstep, voffA);
;         if (wr == 1) PG8_BAR;
;         PG8_WAIT_V(2); PG8_BAR;
;         PG8_STAGE(PG8_SB(1, 0), cB + kstep, voffB); PG8_STAGE(PG8_SA(1, 0), cA + kstep, voffA); PG8_STAGE(PG8_SB(1, 1), cB + hstepB + kstep, voffB);
;         PG8_WAIT_V(6); PG8_BAR;
.LBB0_591:
	s_mov_b64 s[44:45], 0x80
	s_and_b32 s11, s8, 3
	s_add_i32 m0, s59, 0x18000
	v_lshl_add_u64 v[6:7], v[6:7], 0, s[44:45]
	s_lshl_b32 s73, s9, 6
	s_lshl_b32 s33, s9, 13
	s_lshl_b32 s46, s11, 12
	s_waitcnt vmcnt(2)
	s_barrier
	global_load_lds_dwordx4 v[6:7], off
	v_lshl_add_u64 v[4:5], v[4:5], 0, s[44:45]
	s_add_i32 m0, s59, 0x1a000
	s_add_i32 s74, s59, 0x8000
	s_add_i32 s75, s59, 0xa000
	global_load_lds_dwordx4 v[4:5], off
	v_lshl_add_u64 v[0:1], v[0:1], 0, s[44:45]
	s_mov_b32 m0, s74
	s_add_u32 s26, s62, 0x20080
	global_load_lds_dwordx4 v[0:1], off
	v_lshl_add_u64 v[0:1], v[2:3], 0, s[44:45]
	s_mov_b32 m0, s75
	s_addc_u32 s27, s63, 0
	global_load_lds_dwordx4 v[0:1], off
	s_add_i32 m0, s59, 0x1c000
	v_lshl_add_u64 v[0:1], s[26:27], 0, v[144:145]
	global_load_lds_dwordx4 v[0:1], off
	v_lshl_add_u64 v[0:1], s[26:27], 0, v[148:149]
	s_add_i32 m0, s59, 0x1e000
	v_and_b32_e32 v166, 15, v8
	global_load_lds_dwordx4 v[0:1], off
	v_bfe_u32 v0, v8, 4, 2
	v_lshlrev_b32_e32 v150, 4, v0
	v_lshlrev_b32_e32 v1, 2, v166
	v_lshlrev_b32_e32 v4, 3, v0
	v_lshl_or_b32 v0, v166, 6, v150
	v_and_b32_e32 v2, 32, v1
	s_cmpk_lt_u32 s48, 0x100
	v_bitop3_b32 v167, v0, s46, v2 bitop3:0xde
	s_cselect_b64 s[46:47], -1, 0
	s_lshl_b32 s26, s9, 2
	s_or_b32 s11, s26, s11
	v_bitop3_b32 v5, v0, s33, v2 bitop3:0xde
	s_bitcmp0_b32 s48, 6
	v_lshl_add_u64 v[2:3], s[18:19], 0, v[150:151]
	s_mov_b64 s[26:27], 0x300000
	s_cselect_b64 s[48:49], -1, 0
	s_lshl_b32 s9, s9, 8
	v_lshl_add_u64 v[152:153], v[2:3], 0, s[26:27]
	s_mov_b64 s[26:27], 0x200000
	s_bfe_u32 s76, s8, 0x10001
	s_add_i32 s9, s9, 0
	v_lshl_add_u64 v[154:155], v[2:3], 0, s[26:27]
	s_lshl_b32 s8, s8, 7
	v_lshlrev_b32_e32 v2, 15, v9
	s_add_i32 s9, s9, 0x24800
	s_and_b32 s8, s8, 0x80
	v_and_b32_e32 v2, 0xffff0000, v2
	s_add_u32 s8, s34, s8
	v_lshl_add_u32 v2, v10, 12, v2
	v_and_b32_e32 v3, 1, v9
	s_mulk_i32 s11, 0x900
	v_and_b32_e32 v0, 0x70, v13
	v_add_u32_e32 v170, s9, v1
	s_addc_u32 s9, s35, 0
	v_mov_b32_e32 v1, v151
	v_lshl_or_b32 v2, v3, 6, v2
	v_lshl_add_u64 v[156:157], s[8:9], 0, v[0:1]
	s_add_i32 s8, s11, 0
	v_lshl_add_u32 v158, v11, 1, v2
	v_lshlrev_b32_e32 v2, 15, v12
	s_add_i32 s8, s8, 0x20000
	v_and_b32_e32 v2, 0xffff0000, v2
	s_waitcnt vmcnt(6)
	v_bfe_u32 v168, v8, 3, 3
	s_movk_i32 s33, 0x90
	v_mov_b32_e32 v1, s8
	v_lshl_add_u32 v2, v14, 12, v2
	v_and_b32_e32 v3, 1, v12
	v_mul_u32_u24_e32 v6, 0x90, v168
	v_mad_u32_u24 v1, v166, s33, v1
	v_add_u32_e32 v0, s8, v0
	v_lshl_or_b32 v2, v3, 6, v2
	s_add_i32 s78, 0, 0x10000
	s_add_i32 s79, 0, 0x14000
	v_or_b32_e32 v169, 8, v168
	v_mov_b32_e32 v159, v151
	v_lshl_add_u32 v160, v15, 1, v2
	v_mov_b32_e32 v161, v151
	v_mov_b64_e32 v[162:163], 0x1200
	v_mov_b64_e32 v[164:165], 0x11ff
	s_movk_i32 s77, 0x241
	v_add_u32_e32 v171, s78, v167
	v_add_u32_e32 v172, s79, v167
	v_add_u32_e32 v173, 0, v5
	s_movk_i32 s84, 0x3fff
	v_add_u32_e32 v174, v1, v4
	v_add_u32_e32 v175, v0, v6
	v_mov_b32_e32 v176, 0x3fc7
	v_mov_b32_e32 v177, 0x3fcf
	v_mov_b32_e32 v178, 0x3fd7
	v_mov_b32_e32 v179, 0x3fdf
	v_mov_b32_e32 v180, 0x3fe7
	v_mov_b32_e32 v181, 0x3fef
	v_mov_b32_e32 v182, 0x3ff7
	v_mov_b32_e32 v183, 0x3fff
	s_barrier
	s_mov_b32 s99, 0
	s_branch .LBB0_594

; #define PG8_STAGE(bufoff, gbase, voff) do { _Pragma("unroll") for (int _i = 0; _i < 2; ++_i) \
;         __builtin_amdgcn_global_load_lds((const unsigned*)((const char*)(gbase) + (voff)[_i]), (PG8_LAS unsigned*)(lds + (bufoff) + ldsw + _i * 8192), 16, 0, 0); } while (0)
; #define PG8_LDA(dst, b, h) do { _Pragma("unroll") for (int m = 0; m < 4; ++m) _Pragma("unroll") for (int k = 0; k < 2; ++k) dst[m][k] = *(const PG8_LAS bf16x8*)(lds + PG8_SA(b, h) + aoff + m * 2048 + k * 1024); } while (0)
; #define PG8_LDB(dst, b, h) do { _Pragma("unroll") for (int n = 0; n < 2; ++n) _Pragma("unroll") for (int k = 0; k < 2; ++k) dst[n][k] = *(const PG8_LAS bf16x8*)(lds + PG8_SB(b, h) + boff + n * 2048 + k * 1024); } while (0)
; #define PG8_MMA(ai, bj, At, Bt) do { __builtin_amdgcn_s_setprio(1); _Pragma("unroll") for (int m = 0; m < 4; ++m) _Pragma("unroll") for (int n = 0; n < 2; ++n) _Pragma("unroll") for (int k = 0; k < 2; ++k) \
;         acc[ai][bj][m][n] = __builtin_amdgcn_mfma_f32_16x16x32_bf16(Bt[n][k], At[m][k], acc[ai][bj][m][n], 0, 0, 0); __builtin_amdgcn_s_setprio(0); } while (0)
; #define PG8_WAIT_V(n) asm volatile("s_waitcnt vmcnt(" #n ")" ::: "memory")
; #define PG8_WAIT_L(n) asm volatile("s_waitcnt lgkmcnt(" #n ")" ::: "memory")
; #define PG8_BAR __builtin_amdgcn_s_barrier()
; #define PG8_SCHED __builtin_amdgcn_sched_barrier(0)
; template <class Epi, class Sched, bool ALIGN_EPI = false, bool SP2 = false>
; __device__ __forceinline__ void gemm_phase(PG8_LAS unsigned char* lds, const Gemm g, const Sched& S, const Epi& E, int tid_in) {
;     ...
;             PG8_LDB(B0, 0, 0); PG8_LDB(B1, 0, 1); PG8_SCHED; PG8_LDA(At, 0, 0); PG8_STAGE(PG8_SA(1, 1), a1 + hstep, voffA);
;             PG8_WAIT_V(8); PG8_WAIT_L(0); PG8_BAR; PG8_MMA(0, 0, At, B0); PG8_MMA(0, 1, At, B1); PG8_BAR; PG8_SCHED;
.Lkb_skip_4:
	ds_read_b128 v[128:131], v171
	ds_read_b128 v[132:135], v171 offset:1024
	ds_read_b128 v[136:139], v171 offset:2048
	ds_read_b128 v[184:187], v171 offset:3072
	ds_read_b128 v[188:191], v172
	ds_read_b128 v[192:195], v172 offset:1024
	ds_read_b128 v[196:199], v172 offset:2048
	ds_read_b128 v[200:203], v172 offset:3072
	s_add_u32 s26, s60, 0xfff80080
	s_addc_u32 s27, s61, -1
	s_cmp_eq_u32 s88, 28
	s_cselect_b32 s65, s11, s27
	s_cselect_b32 s64, s53, s26
	s_cselect_b32 s63, s51, s87
	s_cselect_b32 s62, s85, s86
	s_add_i32 m0, s59, 0xc000
	ds_read_b128 v[204:207], v173
	ds_read_b128 v[212:215], v173 offset:1024
	ds_read_b128 v[216:219], v173 offset:2048
	ds_read_b128 v[220:223], v173 offset:3072
	ds_read_b128 v[224:227], v173 offset:4096
	ds_read_b128 v[228:231], v173 offset:5120
	ds_read_b128 v[232:235], v173 offset:6144
	ds_read_b128 v[236:239], v173 offset:7168
	global_load_lds_dwordx4 v158, s[60:61]
	s_add_i32 m0, s59, 0xe000
	s_nop 0
	global_load_lds_dwordx4 v160, s[60:61]
	s_cmp_eq_u32 s99, 0
	s_cbranch_scc1 .Lw1s_4_0
	s_waitcnt vmcnt(24)
	s_branch .Lw1d_4_0

; #define PG8_STAGE(bufoff, gbase, voff) do { _Pragma("unroll") for (int _i = 0; _i < 2; ++_i) \
;         __builtin_amdgcn_global_load_lds((const unsigned*)((const char*)(gbase) + (voff)[_i]), (PG8_LAS unsigned*)(lds + (bufoff) + ldsw + _i * 8192), 16, 0, 0); } while (0)
; #define PG8_LDA(dst, b, h) do { _Pragma("unroll") for (int m = 0; m < 4; ++m) _Pragma("unroll") for (int k = 0; k < 2; ++k) dst[m][k] = *(const PG8_LAS bf16x8*)(lds + PG8_SA(b, h) + aoff + m * 2048 + k * 1024); } while (0)
; #define PG8_MMA(ai, bj, At, Bt) do { __builtin_amdgcn_s_setprio(1); _Pragma("unroll") for (int m = 0; m < 4; ++m) _Pragma("unroll") for (int n = 0; n < 2; ++n) _Pragma("unroll") for (int k = 0; k < 2; ++k) \
;         acc[ai][bj][m][n] = __builtin_amdgcn_mfma_f32_16x16x32_bf16(Bt[n][k], At[m][k], acc[ai][bj][m][n], 0, 0, 0); __builtin_amdgcn_s_setprio(0); } while (0)
; #define PG8_WAIT_V(n) asm volatile("s_waitcnt vmcnt(" #n ")" ::: "memory")
; #define PG8_WAIT_L(n) asm volatile("s_waitcnt lgkmcnt(" #n ")" ::: "memory")
; #define PG8_BAR __builtin_amdgcn_s_barrier()
; #define PG8_SCHED __builtin_amdgcn_sched_barrier(0)
; template <class Epi, class Sched, bool ALIGN_EPI = false, bool SP2 = false>
; __device__ __forceinline__ void gemm_phase(PG8_LAS unsigned char* lds, const Gemm g, const Sched& S, const Epi& E, int tid_in) {
;     ...
;             PG8_WAIT_V(8); PG8_WAIT_L(0); PG8_BAR; PG8_MMA(0, 0, At, B0); PG8_MMA(0, 1, At, B1); PG8_BAR; PG8_SCHED;
;             PG8_LDA(At, 0, 1); PG8_STAGE(PG8_SB(0, 0), b2, voffB); PG8_STAGE(PG8_SB(0, 1), b2 + hstepB, voffB); PG8_STAGE(PG8_SA(0, 0), a2, voffA);
;             PG8_WAIT_V(8); PG8_WAIT_L(0); PG8_BAR; PG8_MMA(1, 0, At, B0); PG8_MMA(1, 1, At, B1); PG8_BAR; PG8_SCHED;
.Lw1d_4_0:
	s_waitcnt lgkmcnt(0)
	s_barrier
	s_setprio 1
	s_waitcnt lgkmcnt(0)
	v_mfma_f32_16x16x32_bf16 v[124:127], v[128:131], v[204:207], 0
	v_mfma_f32_16x16x32_bf16 v[120:123], v[136:139], v[204:207], 0
	v_mfma_f32_16x16x32_bf16 v[108:111], v[128:131], v[216:219], 0
	v_mfma_f32_16x16x32_bf16 v[104:107], v[136:139], v[216:219], 0
	v_mfma_f32_16x16x32_bf16 v[92:95], v[128:131], v[224:227], 0
	v_mfma_f32_16x16x32_bf16 v[88:91], v[136:139], v[224:227], 0
	v_mfma_f32_16x16x32_bf16 v[76:79], v[128:131], v[232:235], 0
	v_mfma_f32_16x16x32_bf16 v[72:75], v[136:139], v[232:235], 0
	v_mfma_f32_16x16x32_bf16 v[124:127], v[132:135], v[212:215], v[124:127]
	v_mfma_f32_16x16x32_bf16 v[120:123], v[184:187], v[212:215], v[120:123]
	v_mfma_f32_16x16x32_bf16 v[108:111], v[132:135], v[220:223], v[108:111]
	v_mfma_f32_16x16x32_bf16 v[104:107], v[184:187], v[220:223], v[104:107]
	v_mfma_f32_16x16x32_bf16 v[92:95], v[132:135], v[228:231], v[92:95]
	v_mfma_f32_16x16x32_bf16 v[88:91], v[184:187], v[228:231], v[88:91]
	v_mfma_f32_16x16x32_bf16 v[76:79], v[132:135], v[236:239], v[76:79]
	v_mfma_f32_16x16x32_bf16 v[72:75], v[184:187], v[236:239], v[72:75]
	s_setprio 0
	s_setprio 1
	v_mfma_f32_16x16x32_bf16 v[116:119], v[188:191], v[204:207], 0
	v_mfma_f32_16x16x32_bf16 v[112:115], v[196:199], v[204:207], 0
	v_mfma_f32_16x16x32_bf16 v[100:103], v[188:191], v[216:219], 0
	v_mfma_f32_16x16x32_bf16 v[96:99], v[196:199], v[216:219], 0
	v_mfma_f32_16x16x32_bf16 v[84:87], v[188:191], v[224:227], 0
	v_mfma_f32_16x16x32_bf16 v[80:83], v[196:199], v[224:227], 0
	v_mfma_f32_16x16x32_bf16 v[68:71], v[188:191], v[232:235], 0
	v_mfma_f32_16x16x32_bf16 v[64:67], v[196:199], v[232:235], 0
	v_mfma_f32_16x16x32_bf16 v[116:119], v[192:195], v[212:215], v[116:119]
	v_mfma_f32_16x16x32_bf16 v[112:115], v[200:203], v[212:215], v[112:115]
	v_mfma_f32_16x16x32_bf16 v[100:103], v[192:195], v[220:223], v[100:103]
	v_mfma_f32_16x16x32_bf16 v[96:99], v[200:203], v[220:223], v[96:99]
	v_mfma_f32_16x16x32_bf16 v[84:87], v[192:195], v[228:231], v[84:87]
	v_mfma_f32_16x16x32_bf16 v[80:83], v[200:203], v[228:231], v[80:83]
	v_mfma_f32_16x16x32_bf16 v[68:71], v[192:195], v[236:239], v[68:71]
	v_mfma_f32_16x16x32_bf16 v[64:67], v[200:203], v[236:239], v[64:67]
	s_setprio 0
	s_barrier
	s_add_i32 s26, s78, s68
	s_mov_b32 m0, s26
	ds_read_b128 v[204:207], v173 offset:16384
	ds_read_b128 v[212:215], v173 offset:17408
	ds_read_b128 v[216:219], v173 offset:18432
	ds_read_b128 v[220:223], v173 offset:19456
	ds_read_b128 v[224:227], v173 offset:20480
	ds_read_b128 v[228:231], v173 offset:21504
	ds_read_b128 v[232:235], v173 offset:22528
	ds_read_b128 v[236:239], v173 offset:23552
	global_load_lds_dwordx4 v144, s[62:63]
	s_add_i32 m0, s26, 0x2000
	s_add_u32 s26, s62, 0x20000
	s_addc_u32 s27, s63, 0
	s_add_i32 s33, s79, s68
	global_load_lds_dwordx4 v148, s[62:63]
	s_mov_b32 m0, s33
	s_nop 0
	global_load_lds_dwordx4 v144, s[26:27]
	s_add_i32 m0, s33, 0x2000
	s_nop 0
	global_load_lds_dwordx4 v148, s[26:27]
	s_mov_b32 m0, s59
	s_nop 0
	global_load_lds_dwordx4 v142, s[64:65]
	s_mov_b32 m0, s69
	s_nop 0
	global_load_lds_dwordx4 v146, s[64:65]
	s_cmp_eq_u32 s99, 0
	s_cbranch_scc1 .Lw1s_4_1
	s_waitcnt vmcnt(24)
	s_branch .Lw1d_4_1

; #define PG8_STAGE(bufoff, gbase, voff) do { _Pragma("unroll") for (int _i = 0; _i < 2; ++_i) \
;         __builtin_amdgcn_global_load_lds((const unsigned*)((const char*)(gbase) + (voff)[_i]), (PG8_LAS unsigned*)(lds + (bufoff) + ldsw + _i * 8192), 16, 0, 0); } while (0)
; #define PG8_LDA(dst, b, h) do { _Pragma("unroll") for (int m = 0; m < 4; ++m) _Pragma("unroll") for (int k = 0; k < 2; ++k) dst[m][k] = *(const PG8_LAS bf16x8*)(lds + PG8_SA(b, h) + aoff + m * 2048 + k * 1024); } while (0)
; #define PG8_LDB(dst, b, h) do { _Pragma("unroll") for (int n = 0; n < 2; ++n) _Pragma("unroll") for (int k = 0; k < 2; ++k) dst[n][k] = *(const PG8_LAS bf16x8*)(lds + PG8_SB(b, h) + boff + n * 2048 + k * 1024); } while (0)
; #define PG8_MMA(ai, bj, At, Bt) do { __builtin_amdgcn_s_setprio(1); _Pragma("unroll") for (int m = 0; m < 4; ++m) _Pragma("unroll") for (int n = 0; n < 2; ++n) _Pragma("unroll") for (int k = 0; k < 2; ++k) \
;         acc[ai][bj][m][n] = __builtin_amdgcn_mfma_f32_16x16x32_bf16(Bt[n][k], At[m][k], acc[ai][bj][m][n], 0, 0, 0); __builtin_amdgcn_s_setprio(0); } while (0)
; #define PG8_WAIT_V(n) asm volatile("s_waitcnt vmcnt(" #n ")" ::: "memory")
; #define PG8_WAIT_L(n) asm volatile("s_waitcnt lgkmcnt(" #n ")" ::: "memory")
; #define PG8_BAR __builtin_amdgcn_s_barrier()
; #define PG8_SCHED __builtin_amdgcn_sched_barrier(0)
; template <class Epi, class Sched, bool ALIGN_EPI = false, bool SP2 = false>
; __device__ __forceinline__ void gemm_phase(PG8_LAS unsigned char* lds, const Gemm g, const Sched& S, const Epi& E, int tid_in) {
;     ...
;             PG8_WAIT_V(8); PG8_WAIT_L(0); PG8_BAR; PG8_MMA(1, 0, At, B0); PG8_MMA(1, 1, At, B1); PG8_BAR; PG8_SCHED;
;             PG8_LDB(B0, 1, 0); PG8_LDB(B1, 1, 1); PG8_SCHED; PG8_LDA(At, 1, 0); PG8_STAGE(PG8_SA(0, 1), a2 + hstep, voffA);
;             PG8_WAIT_V(8); PG8_WAIT_L(0); PG8_BAR; PG8_MMA(0, 0, At, B0); PG8_MMA(0, 1, At, B1); PG8_BAR; PG8_SCHED;
.Lw1d_4_1:
	s_waitcnt lgkmcnt(0)
	s_barrier
	s_setprio 1
	s_waitcnt lgkmcnt(0)
	v_mfma_f32_16x16x32_bf16 v[60:63], v[128:131], v[204:207], 0
	v_mfma_f32_16x16x32_bf16 v[56:59], v[136:139], v[204:207], 0
	v_mfma_f32_16x16x32_bf16 v[44:47], v[128:131], v[216:219], 0
	v_mfma_f32_16x16x32_bf16 v[40:43], v[136:139], v[216:219], 0
	v_mfma_f32_16x16x32_bf16 v[28:31], v[128:131], v[224:227], 0
	v_mfma_f32_16x16x32_bf16 v[24:27], v[136:139], v[224:227], 0
	v_mfma_f32_16x16x32_bf16 v[12:15], v[128:131], v[232:235], 0
	v_mfma_f32_16x16x32_bf16 v[8:11], v[136:139], v[232:235], 0
	v_mfma_f32_16x16x32_bf16 v[60:63], v[132:135], v[212:215], v[60:63]
	v_mfma_f32_16x16x32_bf16 v[56:59], v[184:187], v[212:215], v[56:59]
	v_mfma_f32_16x16x32_bf16 v[44:47], v[132:135], v[220:223], v[44:47]
	v_mfma_f32_16x16x32_bf16 v[40:43], v[184:187], v[220:223], v[40:43]
	v_mfma_f32_16x16x32_bf16 v[28:31], v[132:135], v[228:231], v[28:31]
	v_mfma_f32_16x16x32_bf16 v[24:27], v[184:187], v[228:231], v[24:27]
	v_mfma_f32_16x16x32_bf16 v[12:15], v[132:135], v[236:239], v[12:15]
	v_mfma_f32_16x16x32_bf16 v[8:11], v[184:187], v[236:239], v[8:11]
	s_setprio 0
	s_setprio 1
	v_mfma_f32_16x16x32_bf16 v[52:55], v[188:191], v[204:207], 0
	v_mfma_f32_16x16x32_bf16 v[48:51], v[196:199], v[204:207], 0
	v_mfma_f32_16x16x32_bf16 v[36:39], v[188:191], v[216:219], 0
	v_mfma_f32_16x16x32_bf16 v[32:35], v[196:199], v[216:219], 0
	v_mfma_f32_16x16x32_bf16 v[20:23], v[188:191], v[224:227], 0
	v_mfma_f32_16x16x32_bf16 v[16:19], v[196:199], v[224:227], 0
	v_mfma_f32_16x16x32_bf16 v[4:7], v[188:191], v[232:235], 0
	v_mfma_f32_16x16x32_bf16 v[0:3], v[196:199], v[232:235], 0
	v_mfma_f32_16x16x32_bf16 v[52:55], v[192:195], v[212:215], v[52:55]
	v_mfma_f32_16x16x32_bf16 v[48:51], v[200:203], v[212:215], v[48:51]
	v_mfma_f32_16x16x32_bf16 v[36:39], v[192:195], v[220:223], v[36:39]
	v_mfma_f32_16x16x32_bf16 v[32:35], v[200:203], v[220:223], v[32:35]
	v_mfma_f32_16x16x32_bf16 v[20:23], v[192:195], v[228:231], v[20:23]
	v_mfma_f32_16x16x32_bf16 v[16:19], v[200:203], v[228:231], v[16:19]
	v_mfma_f32_16x16x32_bf16 v[4:7], v[192:195], v[236:239], v[4:7]
	v_mfma_f32_16x16x32_bf16 v[0:3], v[200:203], v[236:239], v[0:3]
	s_setprio 0
	s_barrier
	s_add_i32 s33, 0, 0x18000
	v_add_u32_e32 v150, s33, v167
	s_add_i32 s89, 0, 0x1c000
	ds_read_b128 v[128:131], v150
	ds_read_b128 v[132:135], v150 offset:1024
	ds_read_b128 v[136:139], v150 offset:2048
	ds_read_b128 v[184:187], v150 offset:3072
	v_add_u32_e32 v150, s89, v167
	ds_read_b128 v[188:191], v150
	ds_read_b128 v[192:195], v150 offset:1024
	ds_read_b128 v[196:199], v150 offset:2048
	ds_read_b128 v[200:203], v150 offset:3072
	s_add_u32 s26, s64, 0x80000
	s_addc_u32 s27, s65, 0
	s_mov_b32 m0, s70
	ds_read_b128 v[204:207], v173 offset:32768
	ds_read_b128 v[212:215], v173 offset:33792
	ds_read_b128 v[216:219], v173 offset:34816
	ds_read_b128 v[220:223], v173 offset:35840
	ds_read_b128 v[224:227], v173 offset:36864
	ds_read_b128 v[228:231], v173 offset:37888
	ds_read_b128 v[232:235], v173 offset:38912
	ds_read_b128 v[236:239], v173 offset:39936
	global_load_lds_dwordx4 v142, s[26:27]
	s_mov_b32 m0, s71
	s_nop 0
	global_load_lds_dwordx4 v146, s[26:27]
	s_waitcnt vmcnt(8)
	s_waitcnt lgkmcnt(0)
	s_barrier
	s_setprio 1
	s_waitcnt lgkmcnt(0)
	v_mfma_f32_16x16x32_bf16 v[124:127], v[128:131], v[204:207], v[124:127]
	v_mfma_f32_16x16x32_bf16 v[120:123], v[136:139], v[204:207], v[120:123]
	v_mfma_f32_16x16x32_bf16 v[108:111], v[128:131], v[216:219], v[108:111]
	v_mfma_f32_16x16x32_bf16 v[104:107], v[136:139], v[216:219], v[104:107]
	v_mfma_f32_16x16x32_bf16 v[92:95], v[128:131], v[224:227], v[92:95]
	v_mfma_f32_16x16x32_bf16 v[88:91], v[136:139], v[224:227], v[88:91]
	v_mfma_f32_16x16x32_bf16 v[76:79], v[128:131], v[232:235], v[76:79]
	v_mfma_f32_16x16x32_bf16 v[72:75], v[136:139], v[232:235], v[72:75]
	v_mfma_f32_16x16x32_bf16 v[124:127], v[132:135], v[212:215], v[124:127]
	v_mfma_f32_16x16x32_bf16 v[120:123], v[184:187], v[212:215], v[120:123]
	v_mfma_f32_16x16x32_bf16 v[108:111], v[132:135], v[220:223], v[108:111]
	v_mfma_f32_16x16x32_bf16 v[104:107], v[184:187], v[220:223], v[104:107]
	v_mfma_f32_16x16x32_bf16 v[92:95], v[132:135], v[228:231], v[92:95]
	v_mfma_f32_16x16x32_bf16 v[88:91], v[184:187], v[228:231], v[88:91]
	v_mfma_f32_16x16x32_bf16 v[76:79], v[132:135], v[236:239], v[76:79]
	v_mfma_f32_16x16x32_bf16 v[72:75], v[184:187], v[236:239], v[72:75]
	s_setprio 0
	s_setprio 1
	v_mfma_f32_16x16x32_bf16 v[116:119], v[188:191], v[204:207], v[116:119]
	v_mfma_f32_16x16x32_bf16 v[112:115], v[196:199], v[204:207], v[112:115]
	v_mfma_f32_16x16x32_bf16 v[100:103], v[188:191], v[216:219], v[100:103]
	v_mfma_f32_16x16x32_bf16 v[96:99], v[196:199], v[216:219], v[96:99]
	v_mfma_f32_16x16x32_bf16 v[84:87], v[188:191], v[224:227], v[84:87]
	v_mfma_f32_16x16x32_bf16 v[80:83], v[196:199], v[224:227], v[80:83]
	v_mfma_f32_16x16x32_bf16 v[68:71], v[188:191], v[232:235], v[68:71]
	v_mfma_f32_16x16x32_bf16 v[64:67], v[196:199], v[232:235], v[64:67]
	v_mfma_f32_16x16x32_bf16 v[116:119], v[192:195], v[212:215], v[116:119]
	v_mfma_f32_16x16x32_bf16 v[112:115], v[200:203], v[212:215], v[112:115]
	v_mfma_f32_16x16x32_bf16 v[100:103], v[192:195], v[220:223], v[100:103]
	v_mfma_f32_16x16x32_bf16 v[96:99], v[200:203], v[220:223], v[96:99]
	v_mfma_f32_16x16x32_bf16 v[84:87], v[192:195], v[228:231], v[84:87]
	v_mfma_f32_16x16x32_bf16 v[80:83], v[200:203], v[228:231], v[80:83]
	v_mfma_f32_16x16x32_bf16 v[68:71], v[192:195], v[236:239], v[68:71]
	v_mfma_f32_16x16x32_bf16 v[64:67], v[200:203], v[236:239], v[64:67]
	s_setprio 0
	s_barrier
; #define PG8_STAGE(bufoff, gbase, voff) do { _Pragma("unroll") for (int _i = 0; _i < 2; ++_i) \
;         __builtin_amdgcn_global_load_lds((const unsigned*)((const char*)(gbase) + (voff)[_i]), (PG8_LAS unsigned*)(lds + (bufoff) + ldsw + _i * 8192), 16, 0, 0); } while (0)
; #define PG8_LDA(dst, b, h) do { _Pragma("unroll") for (int m = 0; m < 4; ++m) _Pragma("unroll") for (int k = 0; k < 2; ++k) dst[m][k] = *(const PG8_LAS bf16x8*)(lds + PG8_SA(b, h) + aoff + m * 2048 + k * 1024); } while (0)
; #define PG8_LDB(dst, b, h) do { _Pragma("unroll") for (int n = 0; n < 2; ++n) _Pragma("unroll") for (int k = 0; k < 2; ++k) dst[n][k] = *(const PG8_LAS bf16x8*)(lds + PG8_SB(b, h) + boff + n * 2048 + k * 1024); } while (0)
; #define PG8_MMA(ai, bj, At, Bt) do { __builtin_amdgcn_s_setprio(1); _Pragma("unroll") for (int m = 0; m < 4; ++m) _Pragma("unroll") for (int n = 0; n < 2; ++n) _Pragma("unroll") for (int k = 0; k < 2; ++k) \
;         acc[ai][bj][m][n] = __builtin_amdgcn_mfma_f32_16x16x32_bf16(Bt[n][k], At[m][k], acc[ai][bj][m][n], 0, 0, 0); __builtin_amdgcn_s_setprio(0); } while (0)
; #define PG8_BAR __builtin_amdgcn_s_barrier()
; template <class Epi, class Sched, bool ALIGN_EPI = false, bool SP2 = false>
; __device__ __forceinline__ void gemm_phase(PG8_LAS unsigned char* lds, const Gemm g, const Sched& S, const Epi& E, int tid_in) {
;     ...
;             PG8_LDB(B0, 0, 0); PG8_LDB(B1, 0, 1); PG8_SCHED; PG8_LDA(At, 0, 0); PG8_STAGE(PG8_SA(1, 1), a1 + hstep, voffA);
;             PG8_WAIT_V(8); PG8_WAIT_L(0); PG8_BAR; PG8_MMA(0, 0, At, B0); PG8_MMA(0, 1, At, B1); PG8_BAR; PG8_SCHED;
;             PG8_LDA(At, 0, 1); PG8_STAGE(PG8_SB(0, 0), b2, voffB); PG8_STAGE(PG8_SB(0, 1), b2 + hstepB, voffB); PG8_STAGE(PG8_SA(0, 0), a2, voffA);
;             PG8_WAIT_V(8); PG8_WAIT_L(0); PG8_BAR; PG8_MMA(1, 0, At, B0); PG8_MMA(1, 1, At, B1); PG8_BAR; PG8_SCHED;
;             PG8_LDB(B0, 1, 0); PG8_LDB(B1, 1, 1); PG8_SCHED; PG8_LDA(At, 1, 0); PG8_STAGE(PG8_SA(0, 1), a2 + hstep, voffA);
;             PG8_WAIT_V(8); PG8_WAIT_L(0); PG8_BAR; PG8_MMA(0, 0, At, B0); PG8_MMA(0, 1, At, B1); PG8_BAR; PG8_SCHED;
;             PG8_LDA(At, 1, 1); PG8_STAGE(PG8_SB(1, 0), b3, voffB); PG8_STAGE(PG8_SB(1, 1), b3 + hstepB, voffB); PG8_STAGE(PG8_SA(1, 0), a3, voffA);
;             PG8_WAIT_V(8); PG8_WAIT_L(0); PG8_BAR; PG8_MMA(1, 0, At, B0); PG8_MMA(1, 1, At, B1); PG8_BAR; PG8_SCHED;
	s_add_i32 s26, s33, s68
	s_add_i32 m0, s26, 0xffffff80
	ds_read_b128 v[204:207], v173 offset:49152
	ds_read_b128 v[212:215], v173 offset:50176
	ds_read_b128 v[216:219], v173 offset:51200
	ds_read_b128 v[220:223], v173 offset:52224
	ds_read_b128 v[224:227], v173 offset:53248
	ds_read_b128 v[228:231], v173 offset:54272
	ds_read_b128 v[232:235], v173 offset:55296
	ds_read_b128 v[236:239], v173 offset:56320
	global_load_lds_dwordx4 v144, s[62:63] offset:128
	s_add_i32 m0, s26, 0x1f80
	s_add_u32 s26, s62, 0x20080
	s_addc_u32 s27, s63, 0
	s_add_i32 s33, s89, s68
	global_load_lds_dwordx4 v148, s[62:63] offset:128
	s_mov_b32 m0, s33
	s_nop 0
	global_load_lds_dwordx4 v144, s[26:27]
	s_add_i32 m0, s33, 0x2000
	s_nop 0
	global_load_lds_dwordx4 v148, s[26:27]
	s_add_i32 m0, s74, 0xffffff80
	s_nop 0
	global_load_lds_dwordx4 v142, s[64:65] offset:128
	s_add_i32 m0, s75, 0xffffff80
	s_nop 0
	global_load_lds_dwordx4 v146, s[64:65] offset:128
	s_waitcnt vmcnt(8)
	s_waitcnt lgkmcnt(0)
	s_barrier
	s_setprio 1
	s_waitcnt lgkmcnt(0)
	v_mfma_f32_16x16x32_bf16 v[60:63], v[128:131], v[204:207], v[60:63]
	v_mfma_f32_16x16x32_bf16 v[56:59], v[136:139], v[204:207], v[56:59]
	v_mfma_f32_16x16x32_bf16 v[44:47], v[128:131], v[216:219], v[44:47]
	v_mfma_f32_16x16x32_bf16 v[40:43], v[136:139], v[216:219], v[40:43]
	v_mfma_f32_16x16x32_bf16 v[28:31], v[128:131], v[224:227], v[28:31]
	v_mfma_f32_16x16x32_bf16 v[24:27], v[136:139], v[224:227], v[24:27]
	v_mfma_f32_16x16x32_bf16 v[12:15], v[128:131], v[232:235], v[12:15]
	v_mfma_f32_16x16x32_bf16 v[8:11], v[136:139], v[232:235], v[8:11]
	v_mfma_f32_16x16x32_bf16 v[60:63], v[132:135], v[212:215], v[60:63]
	v_mfma_f32_16x16x32_bf16 v[56:59], v[184:187], v[212:215], v[56:59]
	v_mfma_f32_16x16x32_bf16 v[44:47], v[132:135], v[220:223], v[44:47]
	v_mfma_f32_16x16x32_bf16 v[40:43], v[184:187], v[220:223], v[40:43]
	v_mfma_f32_16x16x32_bf16 v[28:31], v[132:135], v[228:231], v[28:31]
	v_mfma_f32_16x16x32_bf16 v[24:27], v[184:187], v[228:231], v[24:27]
	v_mfma_f32_16x16x32_bf16 v[12:15], v[132:135], v[236:239], v[12:15]
	v_mfma_f32_16x16x32_bf16 v[8:11], v[184:187], v[236:239], v[8:11]
	s_setprio 0
	s_setprio 1
	v_mfma_f32_16x16x32_bf16 v[52:55], v[188:191], v[204:207], v[52:55]
	v_mfma_f32_16x16x32_bf16 v[48:51], v[196:199], v[204:207], v[48:51]
	v_mfma_f32_16x16x32_bf16 v[36:39], v[188:191], v[216:219], v[36:39]
	v_mfma_f32_16x16x32_bf16 v[32:35], v[196:199], v[216:219], v[32:35]
	v_mfma_f32_16x16x32_bf16 v[20:23], v[188:191], v[224:227], v[20:23]
	v_mfma_f32_16x16x32_bf16 v[16:19], v[196:199], v[224:227], v[16:19]
	v_mfma_f32_16x16x32_bf16 v[4:7], v[188:191], v[232:235], v[4:7]
	v_mfma_f32_16x16x32_bf16 v[0:3], v[196:199], v[232:235], v[0:3]
	v_mfma_f32_16x16x32_bf16 v[52:55], v[192:195], v[212:215], v[52:55]
	v_mfma_f32_16x16x32_bf16 v[48:51], v[200:203], v[212:215], v[48:51]
	v_mfma_f32_16x16x32_bf16 v[36:39], v[192:195], v[220:223], v[36:39]
	v_mfma_f32_16x16x32_bf16 v[32:35], v[200:203], v[220:223], v[32:35]
	v_mfma_f32_16x16x32_bf16 v[20:23], v[192:195], v[228:231], v[20:23]
	v_mfma_f32_16x16x32_bf16 v[16:19], v[200:203], v[228:231], v[16:19]
	v_mfma_f32_16x16x32_bf16 v[4:7], v[192:195], v[236:239], v[4:7]
	v_mfma_f32_16x16x32_bf16 v[0:3], v[200:203], v[236:239], v[0:3]
	s_setprio 0
	s_barrier
	s_add_i32 s88, s88, 2
	s_add_u32 s60, s60, 0x100
	s_addc_u32 s61, s61, 0
	s_add_u32 s86, s86, 0x100
	s_addc_u32 s87, s87, 0
	s_cmp_gt_u32 s88, 29
.LBB0_597:
	ds_read_b128 v[128:131], v171
	ds_read_b128 v[132:135], v171 offset:1024
	ds_read_b128 v[136:139], v171 offset:2048
	ds_read_b128 v[184:187], v171 offset:3072
	ds_read_b128 v[188:191], v172
	ds_read_b128 v[192:195], v172 offset:1024
	ds_read_b128 v[196:199], v172 offset:2048
	ds_read_b128 v[200:203], v172 offset:3072
	s_add_u32 s26, s60, 0xfff80080
	s_addc_u32 s27, s61, -1
	s_cmp_eq_u32 s88, 28
	s_cselect_b32 s65, s11, s27
	s_cselect_b32 s64, s53, s26
	s_cselect_b32 s63, s51, s87
	s_cselect_b32 s62, s85, s86
	s_add_i32 m0, s59, 0xc000
	ds_read_b128 v[204:207], v173
	ds_read_b128 v[212:215], v173 offset:1024
	ds_read_b128 v[216:219], v173 offset:2048
	ds_read_b128 v[220:223], v173 offset:3072
	ds_read_b128 v[224:227], v173 offset:4096
	ds_read_b128 v[228:231], v173 offset:5120
	ds_read_b128 v[232:235], v173 offset:6144
	ds_read_b128 v[236:239], v173 offset:7168
	global_load_lds_dwordx4 v158, s[60:61]
	s_add_i32 m0, s59, 0xe000
	s_nop 0
	global_load_lds_dwordx4 v160, s[60:61]
	s_waitcnt vmcnt(8)
	s_waitcnt lgkmcnt(0)
	s_barrier
; #define PG8_STAGE(bufoff, gbase, voff) do { _Pragma("unroll") for (int _i = 0; _i < 2; ++_i) \
;         __builtin_amdgcn_global_load_lds((const unsigned*)((const char*)(gbase) + (voff)[_i]), (PG8_LAS unsigned*)(lds + (bufoff) + ldsw + _i * 8192), 16, 0, 0); } while (0)
; #define PG8_LDA(dst, b, h) do { _Pragma("unroll") for (int m = 0; m < 4; ++m) _Pragma("unroll") for (int k = 0; k < 2; ++k) dst[m][k] = *(const PG8_LAS bf16x8*)(lds + PG8_SA(b, h) + aoff + m * 2048 + k * 1024); } while (0)
; #define PG8_MMA(ai, bj, At, Bt) do { __builtin_amdgcn_s_setprio(1); _Pragma("unroll") for (int m = 0; m < 4; ++m) _Pragma("unroll") for (int n = 0; n < 2; ++n) _Pragma("unroll") for (int k = 0; k < 2; ++k) \
;         acc[ai][bj][m][n] = __builtin_amdgcn_mfma_f32_16x16x32_bf16(Bt[n][k], At[m][k], acc[ai][bj][m][n], 0, 0, 0); __builtin_amdgcn_s_setprio(0); } while (0)
; #define PG8_WAIT_V(n) asm volatile("s_waitcnt vmcnt(" #n ")" ::: "memory")
; #define PG8_WAIT_L(n) asm volatile("s_waitcnt lgkmcnt(" #n ")" ::: "memory")
; #define PG8_BAR __builtin_amdgcn_s_barrier()
; #define PG8_SCHED __builtin_amdgcn_sched_barrier(0)
; template <class Epi, class Sched, bool ALIGN_EPI = false, bool SP2 = false>
; __device__ __forceinline__ void gemm_phase(PG8_LAS unsigned char* lds, const Gemm g, const Sched& S, const Epi& E, int tid_in) {
;     ...
;             PG8_WAIT_V(8); PG8_WAIT_L(0); PG8_BAR; PG8_MMA(0, 0, At, B0); PG8_MMA(0, 1, At, B1); PG8_BAR; PG8_SCHED;
;             PG8_LDA(At, 0, 1); PG8_STAGE(PG8_SB(0, 0), b2, voffB); PG8_STAGE(PG8_SB(0, 1), b2 + hstepB, voffB); PG8_STAGE(PG8_SA(0, 0), a2, voffA);
;             PG8_WAIT_V(8); PG8_WAIT_L(0); PG8_BAR; PG8_MMA(1, 0, At, B0); PG8_MMA(1, 1, At, B1); PG8_BAR; PG8_SCHED;
	s_setprio 1
	s_waitcnt lgkmcnt(0)
	v_mfma_f32_16x16x32_bf16 v[124:127], v[128:131], v[204:207], v[124:127]
	v_mfma_f32_16x16x32_bf16 v[120:123], v[136:139], v[204:207], v[120:123]
	v_mfma_f32_16x16x32_bf16 v[108:111], v[128:131], v[216:219], v[108:111]
	v_mfma_f32_16x16x32_bf16 v[104:107], v[136:139], v[216:219], v[104:107]
	v_mfma_f32_16x16x32_bf16 v[92:95], v[128:131], v[224:227], v[92:95]
	v_mfma_f32_16x16x32_bf16 v[88:91], v[136:139], v[224:227], v[88:91]
	v_mfma_f32_16x16x32_bf16 v[76:79], v[128:131], v[232:235], v[76:79]
	v_mfma_f32_16x16x32_bf16 v[72:75], v[136:139], v[232:235], v[72:75]
	v_mfma_f32_16x16x32_bf16 v[124:127], v[132:135], v[212:215], v[124:127]
	v_mfma_f32_16x16x32_bf16 v[120:123], v[184:187], v[212:215], v[120:123]
	v_mfma_f32_16x16x32_bf16 v[108:111], v[132:135], v[220:223], v[108:111]
	v_mfma_f32_16x16x32_bf16 v[104:107], v[184:187], v[220:223], v[104:107]
	v_mfma_f32_16x16x32_bf16 v[92:95], v[132:135], v[228:231], v[92:95]
	v_mfma_f32_16x16x32_bf16 v[88:91], v[184:187], v[228:231], v[88:91]
	v_mfma_f32_16x16x32_bf16 v[76:79], v[132:135], v[236:239], v[76:79]
	v_mfma_f32_16x16x32_bf16 v[72:75], v[184:187], v[236:239], v[72:75]
	s_setprio 0
	s_setprio 1
	v_mfma_f32_16x16x32_bf16 v[116:119], v[188:191], v[204:207], v[116:119]
	v_mfma_f32_16x16x32_bf16 v[112:115], v[196:199], v[204:207], v[112:115]
	v_mfma_f32_16x16x32_bf16 v[100:103], v[188:191], v[216:219], v[100:103]
	v_mfma_f32_16x16x32_bf16 v[96:99], v[196:199], v[216:219], v[96:99]
	v_mfma_f32_16x16x32_bf16 v[84:87], v[188:191], v[224:227], v[84:87]
	v_mfma_f32_16x16x32_bf16 v[80:83], v[196:199], v[224:227], v[80:83]
	v_mfma_f32_16x16x32_bf16 v[68:71], v[188:191], v[232:235], v[68:71]
	v_mfma_f32_16x16x32_bf16 v[64:67], v[196:199], v[232:235], v[64:67]
	v_mfma_f32_16x16x32_bf16 v[116:119], v[192:195], v[212:215], v[116:119]
	v_mfma_f32_16x16x32_bf16 v[112:115], v[200:203], v[212:215], v[112:115]
	v_mfma_f32_16x16x32_bf16 v[100:103], v[192:195], v[220:223], v[100:103]
	v_mfma_f32_16x16x32_bf16 v[96:99], v[200:203], v[220:223], v[96:99]
	v_mfma_f32_16x16x32_bf16 v[84:87], v[192:195], v[228:231], v[84:87]
	v_mfma_f32_16x16x32_bf16 v[80:83], v[200:203], v[228:231], v[80:83]
	v_mfma_f32_16x16x32_bf16 v[68:71], v[192:195], v[236:239], v[68:71]
	v_mfma_f32_16x16x32_bf16 v[64:67], v[200:203], v[236:239], v[64:67]
	s_setprio 0
	s_barrier
	s_add_i32 s26, s78, s68
	s_mov_b32 m0, s26
	ds_read_b128 v[204:207], v173 offset:16384
	ds_read_b128 v[212:215], v173 offset:17408
	ds_read_b128 v[216:219], v173 offset:18432
	ds_read_b128 v[220:223], v173 offset:19456
	ds_read_b128 v[224:227], v173 offset:20480
	ds_read_b128 v[228:231], v173 offset:21504
	ds_read_b128 v[232:235], v173 offset:22528
	ds_read_b128 v[236:239], v173 offset:23552
	global_load_lds_dwordx4 v144, s[62:63]
	s_add_i32 m0, s26, 0x2000
	s_add_u32 s26, s62, 0x20000
	s_addc_u32 s27, s63, 0
	s_add_i32 s33, s79, s68
	global_load_lds_dwordx4 v148, s[62:63]
	s_mov_b32 m0, s33
	s_nop 0
	global_load_lds_dwordx4 v144, s[26:27]
	s_add_i32 m0, s33, 0x2000
	s_nop 0
	global_load_lds_dwordx4 v148, s[26:27]
	s_mov_b32 m0, s59
	s_nop 0
	global_load_lds_dwordx4 v142, s[64:65]
	s_mov_b32 m0, s69
	s_nop 0
	global_load_lds_dwordx4 v146, s[64:65]
	s_waitcnt vmcnt(8)
	s_waitcnt lgkmcnt(0)
	s_barrier
	s_setprio 1
	s_waitcnt lgkmcnt(0)
	v_mfma_f32_16x16x32_bf16 v[60:63], v[128:131], v[204:207], v[60:63]
	v_mfma_f32_16x16x32_bf16 v[56:59], v[136:139], v[204:207], v[56:59]
	v_mfma_f32_16x16x32_bf16 v[44:47], v[128:131], v[216:219], v[44:47]
	v_mfma_f32_16x16x32_bf16 v[40:43], v[136:139], v[216:219], v[40:43]
	v_mfma_f32_16x16x32_bf16 v[28:31], v[128:131], v[224:227], v[28:31]
	v_mfma_f32_16x16x32_bf16 v[24:27], v[136:139], v[224:227], v[24:27]
	v_mfma_f32_16x16x32_bf16 v[12:15], v[128:131], v[232:235], v[12:15]
	v_mfma_f32_16x16x32_bf16 v[8:11], v[136:139], v[232:235], v[8:11]
	v_mfma_f32_16x16x32_bf16 v[60:63], v[132:135], v[212:215], v[60:63]
	v_mfma_f32_16x16x32_bf16 v[56:59], v[184:187], v[212:215], v[56:59]
	v_mfma_f32_16x16x32_bf16 v[44:47], v[132:135], v[220:223], v[44:47]
	v_mfma_f32_16x16x32_bf16 v[40:43], v[184:187], v[220:223], v[40:43]
	v_mfma_f32_16x16x32_bf16 v[28:31], v[132:135], v[228:231], v[28:31]
	v_mfma_f32_16x16x32_bf16 v[24:27], v[184:187], v[228:231], v[24:27]
	v_mfma_f32_16x16x32_bf16 v[12:15], v[132:135], v[236:239], v[12:15]
	v_mfma_f32_16x16x32_bf16 v[8:11], v[184:187], v[236:239], v[8:11]
	s_setprio 0
	s_setprio 1
	v_mfma_f32_16x16x32_bf16 v[52:55], v[188:191], v[204:207], v[52:55]
	v_mfma_f32_16x16x32_bf16 v[48:51], v[196:199], v[204:207], v[48:51]
	v_mfma_f32_16x16x32_bf16 v[36:39], v[188:191], v[216:219], v[36:39]
	v_mfma_f32_16x16x32_bf16 v[32:35], v[196:199], v[216:219], v[32:35]
	v_mfma_f32_16x16x32_bf16 v[20:23], v[188:191], v[224:227], v[20:23]
	v_mfma_f32_16x16x32_bf16 v[16:19], v[196:199], v[224:227], v[16:19]
	v_mfma_f32_16x16x32_bf16 v[4:7], v[188:191], v[232:235], v[4:7]
	v_mfma_f32_16x16x32_bf16 v[0:3], v[196:199], v[232:235], v[0:3]
	v_mfma_f32_16x16x32_bf16 v[52:55], v[192:195], v[212:215], v[52:55]
	v_mfma_f32_16x16x32_bf16 v[48:51], v[200:203], v[212:215], v[48:51]
	v_mfma_f32_16x16x32_bf16 v[36:39], v[192:195], v[220:223], v[36:39]
	v_mfma_f32_16x16x32_bf16 v[32:35], v[200:203], v[220:223], v[32:35]
	v_mfma_f32_16x16x32_bf16 v[20:23], v[192:195], v[228:231], v[20:23]
	v_mfma_f32_16x16x32_bf16 v[16:19], v[200:203], v[228:231], v[16:19]
	v_mfma_f32_16x16x32_bf16 v[4:7], v[192:195], v[236:239], v[4:7]
	v_mfma_f32_16x16x32_bf16 v[0:3], v[200:203], v[236:239], v[0:3]
	s_setprio 0
	s_barrier
; #define PG8_STAGE(bufoff, gbase, voff) do { _Pragma("unroll") for (int _i = 0; _i < 2; ++_i) \
;         __builtin_amdgcn_global_load_lds((const unsigned*)((const char*)(gbase) + (voff)[_i]), (PG8_LAS unsigned*)(lds + (bufoff) + ldsw + _i * 8192), 16, 0, 0); } while (0)
; #define PG8_LDA(dst, b, h) do { _Pragma("unroll") for (int m = 0; m < 4; ++m) _Pragma("unroll") for (int k = 0; k < 2; ++k) dst[m][k] = *(const PG8_LAS bf16x8*)(lds + PG8_SA(b, h) + aoff + m * 2048 + k * 1024); } while (0)
; #define PG8_LDB(dst, b, h) do { _Pragma("unroll") for (int n = 0; n < 2; ++n) _Pragma("unroll") for (int k = 0; k < 2; ++k) dst[n][k] = *(const PG8_LAS bf16x8*)(lds + PG8_SB(b, h) + boff + n * 2048 + k * 1024); } while (0)
; #define PG8_MMA(ai, bj, At, Bt) do { __builtin_amdgcn_s_setprio(1); _Pragma("unroll") for (int m = 0; m < 4; ++m) _Pragma("unroll") for (int n = 0; n < 2; ++n) _Pragma("unroll") for (int k = 0; k < 2; ++k) \
;         acc[ai][bj][m][n] = __builtin_amdgcn_mfma_f32_16x16x32_bf16(Bt[n][k], At[m][k], acc[ai][bj][m][n], 0, 0, 0); __builtin_amdgcn_s_setprio(0); } while (0)
; #define PG8_WAIT_V(n) asm volatile("s_waitcnt vmcnt(" #n ")" ::: "memory")
; #define PG8_WAIT_L(n) asm volatile("s_waitcnt lgkmcnt(" #n ")" ::: "memory")
; #define PG8_BAR __builtin_amdgcn_s_barrier()
; #define PG8_SCHED __builtin_amdgcn_sched_barrier(0)
; template <class Epi, class Sched, bool ALIGN_EPI = false, bool SP2 = false>
; __device__ __forceinline__ void gemm_phase(PG8_LAS unsigned char* lds, const Gemm g, const Sched& S, const Epi& E, int tid_in) {
;     ...
;             PG8_LDB(B0, 1, 0); PG8_LDB(B1, 1, 1); PG8_SCHED; PG8_LDA(At, 1, 0); PG8_STAGE(PG8_SA(0, 1), a2 + hstep, voffA);
;             PG8_WAIT_V(8); PG8_WAIT_L(0); PG8_BAR; PG8_MMA(0, 0, At, B0); PG8_MMA(0, 1, At, B1); PG8_BAR; PG8_SCHED;
;             PG8_LDA(At, 1, 1); PG8_STAGE(PG8_SB(1, 0), b3, voffB); PG8_STAGE(PG8_SB(1, 1), b3 + hstepB, voffB); PG8_STAGE(PG8_SA(1, 0), a3, voffA);
;             PG8_WAIT_V(8); PG8_WAIT_L(0); PG8_BAR; PG8_MMA(1, 0, At, B0); PG8_MMA(1, 1, At, B1); PG8_BAR; PG8_SCHED;
;     ...
;         if constexpr (ALIGN_EPI) { if (wr == 0) PG8_BAR; }
	s_add_i32 s33, 0, 0x18000
	v_add_u32_e32 v150, s33, v167
	s_add_i32 s89, 0, 0x1c000
	ds_read_b128 v[128:131], v150
	ds_read_b128 v[132:135], v150 offset:1024
	ds_read_b128 v[136:139], v150 offset:2048
	ds_read_b128 v[184:187], v150 offset:3072
	v_add_u32_e32 v150, s89, v167
	ds_read_b128 v[188:191], v150
	ds_read_b128 v[192:195], v150 offset:1024
	ds_read_b128 v[196:199], v150 offset:2048
	ds_read_b128 v[200:203], v150 offset:3072
	s_add_u32 s26, s64, 0x80000
	s_addc_u32 s27, s65, 0
	s_mov_b32 m0, s70
	ds_read_b128 v[204:207], v173 offset:32768
	ds_read_b128 v[212:215], v173 offset:33792
	ds_read_b128 v[216:219], v173 offset:34816
	ds_read_b128 v[220:223], v173 offset:35840
	ds_read_b128 v[224:227], v173 offset:36864
	ds_read_b128 v[228:231], v173 offset:37888
	ds_read_b128 v[232:235], v173 offset:38912
	ds_read_b128 v[236:239], v173 offset:39936
	global_load_lds_dwordx4 v142, s[26:27]
	s_mov_b32 m0, s71
	s_nop 0
	global_load_lds_dwordx4 v146, s[26:27]
	s_waitcnt vmcnt(8)
	s_waitcnt lgkmcnt(0)
	s_barrier
	s_setprio 1
	s_waitcnt lgkmcnt(0)
	v_mfma_f32_16x16x32_bf16 v[124:127], v[128:131], v[204:207], v[124:127]
	v_mfma_f32_16x16x32_bf16 v[120:123], v[136:139], v[204:207], v[120:123]
	v_mfma_f32_16x16x32_bf16 v[108:111], v[128:131], v[216:219], v[108:111]
	v_mfma_f32_16x16x32_bf16 v[104:107], v[136:139], v[216:219], v[104:107]
	v_mfma_f32_16x16x32_bf16 v[92:95], v[128:131], v[224:227], v[92:95]
	v_mfma_f32_16x16x32_bf16 v[88:91], v[136:139], v[224:227], v[88:91]
	v_mfma_f32_16x16x32_bf16 v[76:79], v[128:131], v[232:235], v[76:79]
	v_mfma_f32_16x16x32_bf16 v[72:75], v[136:139], v[232:235], v[72:75]
	v_mfma_f32_16x16x32_bf16 v[124:127], v[132:135], v[212:215], v[124:127]
	v_mfma_f32_16x16x32_bf16 v[120:123], v[184:187], v[212:215], v[120:123]
	v_mfma_f32_16x16x32_bf16 v[108:111], v[132:135], v[220:223], v[108:111]
	v_mfma_f32_16x16x32_bf16 v[104:107], v[184:187], v[220:223], v[104:107]
	v_mfma_f32_16x16x32_bf16 v[92:95], v[132:135], v[228:231], v[92:95]
	v_mfma_f32_16x16x32_bf16 v[88:91], v[184:187], v[228:231], v[88:91]
	v_mfma_f32_16x16x32_bf16 v[76:79], v[132:135], v[236:239], v[76:79]
	v_mfma_f32_16x16x32_bf16 v[72:75], v[184:187], v[236:239], v[72:75]
	s_setprio 0
	s_setprio 1
	v_mfma_f32_16x16x32_bf16 v[116:119], v[188:191], v[204:207], v[116:119]
	v_mfma_f32_16x16x32_bf16 v[112:115], v[196:199], v[204:207], v[112:115]
	v_mfma_f32_16x16x32_bf16 v[100:103], v[188:191], v[216:219], v[100:103]
	v_mfma_f32_16x16x32_bf16 v[96:99], v[196:199], v[216:219], v[96:99]
	v_mfma_f32_16x16x32_bf16 v[84:87], v[188:191], v[224:227], v[84:87]
	v_mfma_f32_16x16x32_bf16 v[80:83], v[196:199], v[224:227], v[80:83]
	v_mfma_f32_16x16x32_bf16 v[68:71], v[188:191], v[232:235], v[68:71]
	v_mfma_f32_16x16x32_bf16 v[64:67], v[196:199], v[232:235], v[64:67]
	v_mfma_f32_16x16x32_bf16 v[116:119], v[192:195], v[212:215], v[116:119]
	v_mfma_f32_16x16x32_bf16 v[112:115], v[200:203], v[212:215], v[112:115]
	v_mfma_f32_16x16x32_bf16 v[100:103], v[192:195], v[220:223], v[100:103]
	v_mfma_f32_16x16x32_bf16 v[96:99], v[200:203], v[220:223], v[96:99]
	v_mfma_f32_16x16x32_bf16 v[84:87], v[192:195], v[228:231], v[84:87]
	v_mfma_f32_16x16x32_bf16 v[80:83], v[200:203], v[228:231], v[80:83]
	v_mfma_f32_16x16x32_bf16 v[68:71], v[192:195], v[236:239], v[68:71]
	v_mfma_f32_16x16x32_bf16 v[64:67], v[200:203], v[236:239], v[64:67]
	s_setprio 0
	s_barrier
	s_add_i32 s26, s33, s68
	s_add_i32 m0, s26, 0xffffff80
	ds_read_b128 v[204:207], v173 offset:49152
	ds_read_b128 v[212:215], v173 offset:50176
	ds_read_b128 v[216:219], v173 offset:51200
	ds_read_b128 v[220:223], v173 offset:52224
	ds_read_b128 v[224:227], v173 offset:53248
	ds_read_b128 v[228:231], v173 offset:54272
	ds_read_b128 v[232:235], v173 offset:55296
	ds_read_b128 v[236:239], v173 offset:56320
	global_load_lds_dwordx4 v144, s[62:63] offset:128
	s_add_i32 m0, s26, 0x1f80
	s_add_u32 s26, s62, 0x20080
	s_addc_u32 s27, s63, 0
	s_add_i32 s33, s89, s68
	global_load_lds_dwordx4 v148, s[62:63] offset:128
	s_mov_b32 m0, s33
	s_nop 0
	global_load_lds_dwordx4 v144, s[26:27]
	s_add_i32 m0, s33, 0x2000
	s_nop 0
	global_load_lds_dwordx4 v148, s[26:27]
	s_add_i32 m0, s74, 0xffffff80
	s_nop 0
	global_load_lds_dwordx4 v142, s[64:65] offset:128
	s_add_i32 m0, s75, 0xffffff80
	s_nop 0
	global_load_lds_dwordx4 v146, s[64:65] offset:128
	s_waitcnt vmcnt(8)
	s_waitcnt lgkmcnt(0)
	s_barrier
	s_setprio 1
	s_waitcnt lgkmcnt(0)
	v_mfma_f32_16x16x32_bf16 v[60:63], v[128:131], v[204:207], v[60:63]
	v_mfma_f32_16x16x32_bf16 v[56:59], v[136:139], v[204:207], v[56:59]
	v_mfma_f32_16x16x32_bf16 v[44:47], v[128:131], v[216:219], v[44:47]
	v_mfma_f32_16x16x32_bf16 v[40:43], v[136:139], v[216:219], v[40:43]
	v_mfma_f32_16x16x32_bf16 v[28:31], v[128:131], v[224:227], v[28:31]
	v_mfma_f32_16x16x32_bf16 v[24:27], v[136:139], v[224:227], v[24:27]
	v_mfma_f32_16x16x32_bf16 v[12:15], v[128:131], v[232:235], v[12:15]
	v_mfma_f32_16x16x32_bf16 v[8:11], v[136:139], v[232:235], v[8:11]
	v_mfma_f32_16x16x32_bf16 v[60:63], v[132:135], v[212:215], v[60:63]
	v_mfma_f32_16x16x32_bf16 v[56:59], v[184:187], v[212:215], v[56:59]
	v_mfma_f32_16x16x32_bf16 v[44:47], v[132:135], v[220:223], v[44:47]
	v_mfma_f32_16x16x32_bf16 v[40:43], v[184:187], v[220:223], v[40:43]
	v_mfma_f32_16x16x32_bf16 v[28:31], v[132:135], v[228:231], v[28:31]
	v_mfma_f32_16x16x32_bf16 v[24:27], v[184:187], v[228:231], v[24:27]
	v_mfma_f32_16x16x32_bf16 v[12:15], v[132:135], v[236:239], v[12:15]
	v_mfma_f32_16x16x32_bf16 v[8:11], v[184:187], v[236:239], v[8:11]
	s_setprio 0
	s_setprio 1
	v_mfma_f32_16x16x32_bf16 v[52:55], v[188:191], v[204:207], v[52:55]
	v_mfma_f32_16x16x32_bf16 v[48:51], v[196:199], v[204:207], v[48:51]
	v_mfma_f32_16x16x32_bf16 v[36:39], v[188:191], v[216:219], v[36:39]
	v_mfma_f32_16x16x32_bf16 v[32:35], v[196:199], v[216:219], v[32:35]
	v_mfma_f32_16x16x32_bf16 v[20:23], v[188:191], v[224:227], v[20:23]
	v_mfma_f32_16x16x32_bf16 v[16:19], v[196:199], v[224:227], v[16:19]
	v_mfma_f32_16x16x32_bf16 v[4:7], v[188:191], v[232:235], v[4:7]
	v_mfma_f32_16x16x32_bf16 v[0:3], v[196:199], v[232:235], v[0:3]
	v_mfma_f32_16x16x32_bf16 v[52:55], v[192:195], v[212:215], v[52:55]
	v_mfma_f32_16x16x32_bf16 v[48:51], v[200:203], v[212:215], v[48:51]
	v_mfma_f32_16x16x32_bf16 v[36:39], v[192:195], v[220:223], v[36:39]
	v_mfma_f32_16x16x32_bf16 v[32:35], v[200:203], v[220:223], v[32:35]
	v_mfma_f32_16x16x32_bf16 v[20:23], v[192:195], v[228:231], v[20:23]
	v_mfma_f32_16x16x32_bf16 v[16:19], v[200:203], v[228:231], v[16:19]
	v_mfma_f32_16x16x32_bf16 v[4:7], v[192:195], v[236:239], v[4:7]
	v_mfma_f32_16x16x32_bf16 v[0:3], v[200:203], v[236:239], v[0:3]
	s_setprio 0
	s_barrier
	s_add_i32 s88, s88, 2
	s_add_u32 s60, s60, 0x100
	s_addc_u32 s61, s61, 0
	s_add_u32 s86, s86, 0x100
	s_addc_u32 s87, s87, 0
	s_cmp_gt_u32 s88, 29
	s_cbranch_scc0 .LBB0_597
	s_mov_b32 s99, 1
	s_and_b64 vcc, exec, s[46:47]
	s_cbranch_vccz .LBB0_600
	s_barrier

; #define PG8_STAGE(bufoff, gbase, voff) do { _Pragma("unroll") for (int _i = 0; _i < 2; ++_i) \
;         __builtin_amdgcn_global_load_lds((const unsigned*)((const char*)(gbase) + (voff)[_i]), (PG8_LAS unsigned*)(lds + (bufoff) + ldsw + _i * 8192), 16, 0, 0); } while (0)
; #define PG8_WAIT_V(n) asm volatile("s_waitcnt vmcnt(" #n ")" ::: "memory")
; #define PG8_BAR __builtin_amdgcn_s_barrier()
; template <class Epi, class Sched, bool ALIGN_EPI = false, bool SP2 = false>
; __device__ __forceinline__ void gemm_phase(PG8_LAS unsigned char* lds, const Gemm g, const Sched& S, const Epi& E, int tid_in) {
;     ...
;         PG8_STAGE(PG8_SB(0, 0), cB, voffB); PG8_STAGE(PG8_SB(0, 1), cB + hstepB, voffB); PG8_STAGE(PG8_SA(0, 0), cA, voffA); PG8_STAGE(PG8_SA(0, 1), cA + hstep, voffA);
;         if (wr == 1) PG8_BAR;
;         PG8_WAIT_V(2); PG8_BAR;
;         PG8_STAGE(PG8_SB(1, 0), cB + kstep, voffB); PG8_STAGE(PG8_SA(1, 0), cA + kstep, voffA); PG8_STAGE(PG8_SB(1, 1), cB + hstepB + kstep, voffB);
;         PG8_WAIT_V(6); PG8_BAR;
.LBB0_757:
	s_mov_b64 s[46:47], 0x80
	s_and_b32 s8, s8, 3
	s_add_i32 m0, s61, 0x18000
	v_lshl_add_u64 v[6:7], v[6:7], 0, s[46:47]
	s_lshl_b32 s11, s9, 13
	s_lshl_b32 s33, s8, 12
	s_waitcnt vmcnt(2)
	s_barrier
	global_load_lds_dwordx4 v[6:7], off
	v_lshl_add_u64 v[4:5], v[4:5], 0, s[46:47]
	s_add_i32 m0, s61, 0x1a000
	s_add_i32 s73, s61, 0x8000
	s_add_i32 s74, s61, 0xa000
	global_load_lds_dwordx4 v[4:5], off
	v_lshl_add_u64 v[0:1], v[0:1], 0, s[46:47]
	s_mov_b32 m0, s73
	s_add_u32 s26, s64, 0x10080
	global_load_lds_dwordx4 v[0:1], off
	v_lshl_add_u64 v[0:1], v[2:3], 0, s[46:47]
	s_mov_b32 m0, s74
	s_addc_u32 s27, s65, 0
	global_load_lds_dwordx4 v[0:1], off
	s_add_i32 m0, s61, 0x1c000
	v_lshl_add_u64 v[0:1], s[26:27], 0, v[130:131]
	global_load_lds_dwordx4 v[0:1], off
	v_lshl_add_u64 v[0:1], s[26:27], 0, v[134:135]
	s_add_i32 m0, s61, 0x1e000
	s_cmpk_lt_u32 s10, 0x100
	global_load_lds_dwordx4 v[0:1], off
	s_cselect_b64 s[48:49], -1, 0
	s_lshl_b32 s10, s9, 2
	v_and_b32_e32 v0, 48, v8
	v_and_b32_e32 v1, 15, v8
	v_lshlrev_b32_e32 v3, 2, v8
	s_or_b32 s10, s10, s8
	v_lshl_or_b32 v2, v1, 6, v0
	v_and_b32_e32 v3, 32, v3
	s_mulk_i32 s10, 0x900
	v_bitop3_b32 v4, v2, s11, v3 bitop3:0xde
	v_bitop3_b32 v137, v2, s33, v3 bitop3:0xde
	v_and_b32_e32 v3, 3, v8
	s_add_i32 s10, s10, 0
	v_bfe_u32 v2, v8, 2, 4
	v_lshlrev_b32_e32 v5, 3, v3
	s_add_i32 s10, s10, 0x20000
	v_lshl_or_b32 v150, s9, 6, v2
	v_lshl_or_b32 v136, s8, 6, v5
	v_lshlrev_b32_e32 v5, 5, v3
	v_cmp_eq_u32_e64 s[8:9], 0, v3
	s_movk_i32 s11, 0x90
	v_mov_b32_e32 v3, s10
	v_mad_u32_u24 v1, v1, s11, v3
	v_mad_u32_u24 v2, v2, s11, v3
	v_and_b32_e32 v3, 64, v252
	v_add_u32_e32 v3, 64, v3
	v_cmp_lt_i32_e32 vcc, v254, v3
	s_waitcnt vmcnt(6)
	s_add_i32 s75, 0, 0x10000
	s_add_i32 s76, 0, 0x14000
	v_cndmask_b32_e32 v6, v252, v254, vcc
	v_cmp_lt_i32_e32 vcc, v253, v3
	v_lshlrev_b32_e32 v151, 2, v6
	v_and_b32_e32 v6, 1, v9
	v_cndmask_b32_e32 v3, v252, v253, vcc
	v_lshlrev_b32_e32 v152, 2, v3
	v_lshlrev_b32_e32 v3, 14, v9
	v_and_b32_e32 v3, 0xffff8000, v3
	v_lshl_add_u32 v3, v10, 11, v3
	v_lshl_or_b32 v3, v6, 6, v3
	v_lshl_add_u32 v138, v11, 1, v3
	v_lshlrev_b32_e32 v3, 14, v12
	v_and_b32_e32 v3, 0xffff8000, v3
	v_lshl_add_u32 v3, v13, 11, v3
	v_and_b32_e32 v6, 1, v12
	v_lshl_or_b32 v3, v6, 6, v3
	v_mov_b32_e32 v139, v131
	v_lshl_add_u32 v140, v14, 1, v3
	v_mov_b32_e32 v141, v131
	v_mov_b64_e32 v[142:143], 0x400
	v_mov_b64_e32 v[144:145], 0x3ff
	v_add_u32_e32 v153, s75, v137
	v_add_u32_e32 v154, s76, v137
	v_add_u32_e32 v155, 0, v4
	v_add_u32_e32 v156, v1, v0
	v_add_u32_e32 v157, v2, v5
	s_barrier
	s_mov_b32 s99, 0
	s_branch .LBB0_760

; #define PG8_STAGE(bufoff, gbase, voff) do { _Pragma("unroll") for (int _i = 0; _i < 2; ++_i) \
;         __builtin_amdgcn_global_load_lds((const unsigned*)((const char*)(gbase) + (voff)[_i]), (PG8_LAS unsigned*)(lds + (bufoff) + ldsw + _i * 8192), 16, 0, 0); } while (0)
; #define PG8_LDA(dst, b, h) do { _Pragma("unroll") for (int m = 0; m < 4; ++m) _Pragma("unroll") for (int k = 0; k < 2; ++k) dst[m][k] = *(const PG8_LAS bf16x8*)(lds + PG8_SA(b, h) + aoff + m * 2048 + k * 1024); } while (0)
; #define PG8_LDB(dst, b, h) do { _Pragma("unroll") for (int n = 0; n < 2; ++n) _Pragma("unroll") for (int k = 0; k < 2; ++k) dst[n][k] = *(const PG8_LAS bf16x8*)(lds + PG8_SB(b, h) + boff + n * 2048 + k * 1024); } while (0)
; #define PG8_MMA(ai, bj, At, Bt) do { __builtin_amdgcn_s_setprio(1); _Pragma("unroll") for (int m = 0; m < 4; ++m) _Pragma("unroll") for (int n = 0; n < 2; ++n) _Pragma("unroll") for (int k = 0; k < 2; ++k) \
;         acc[ai][bj][m][n] = __builtin_amdgcn_mfma_f32_16x16x32_bf16(Bt[n][k], At[m][k], acc[ai][bj][m][n], 0, 0, 0); __builtin_amdgcn_s_setprio(0); } while (0)
; #define PG8_WAIT_V(n) asm volatile("s_waitcnt vmcnt(" #n ")" ::: "memory")
; #define PG8_WAIT_L(n) asm volatile("s_waitcnt lgkmcnt(" #n ")" ::: "memory")
; #define PG8_BAR __builtin_amdgcn_s_barrier()
; #define PG8_SCHED __builtin_amdgcn_sched_barrier(0)
; template <class Epi, class Sched, bool ALIGN_EPI = false, bool SP2 = false>
; __device__ __forceinline__ void gemm_phase(PG8_LAS unsigned char* lds, const Gemm g, const Sched& S, const Epi& E, int tid_in) {
;     ...
;             PG8_LDB(B0, 0, 0); PG8_LDB(B1, 0, 1); PG8_SCHED; PG8_LDA(At, 0, 0); PG8_STAGE(PG8_SA(1, 1), a1 + hstep, voffA);
;             PG8_WAIT_V(8); PG8_WAIT_L(0); PG8_BAR; PG8_MMA(0, 0, At, B0); PG8_MMA(0, 1, At, B1); PG8_BAR; PG8_SCHED;
.Lkb_skip_5:
	ds_read_b128 v[146:149], v153
	ds_read_b128 v[158:161], v153 offset:1024
	ds_read_b128 v[162:165], v153 offset:2048
	ds_read_b128 v[166:169], v153 offset:3072
	ds_read_b128 v[170:173], v154
	ds_read_b128 v[174:177], v154 offset:1024
	ds_read_b128 v[178:181], v154 offset:2048
	ds_read_b128 v[182:185], v154 offset:3072
	s_add_u32 s26, s62, 0xfffc0080
	s_addc_u32 s27, s63, -1
	s_cmp_eq_u32 s83, 12
	s_cselect_b32 s67, s53, s27
	s_cselect_b32 s66, s59, s26
	s_cselect_b32 s65, s51, s79
	s_cselect_b32 s64, s77, s78
	s_add_i32 m0, s61, 0xc000
	ds_read_b128 v[186:189], v155
	ds_read_b128 v[190:193], v155 offset:1024
	ds_read_b128 v[194:197], v155 offset:2048
	ds_read_b128 v[198:201], v155 offset:3072
	ds_read_b128 v[202:205], v155 offset:4096
	ds_read_b128 v[206:209], v155 offset:5120
	ds_read_b128 v[210:213], v155 offset:6144
	ds_read_b128 v[214:217], v155 offset:7168
	global_load_lds_dwordx4 v138, s[62:63]
	s_add_i32 m0, s61, 0xe000
	s_nop 0
	global_load_lds_dwordx4 v140, s[62:63]
	s_cmp_eq_u32 s99, 0
	s_cbranch_scc1 .Lw1s_5_0
	s_waitcnt vmcnt(48)
	s_branch .Lw1d_5_0

; #define PG8_STAGE(bufoff, gbase, voff) do { _Pragma("unroll") for (int _i = 0; _i < 2; ++_i) \
;         __builtin_amdgcn_global_load_lds((const unsigned*)((const char*)(gbase) + (voff)[_i]), (PG8_LAS unsigned*)(lds + (bufoff) + ldsw + _i * 8192), 16, 0, 0); } while (0)
; #define PG8_LDA(dst, b, h) do { _Pragma("unroll") for (int m = 0; m < 4; ++m) _Pragma("unroll") for (int k = 0; k < 2; ++k) dst[m][k] = *(const PG8_LAS bf16x8*)(lds + PG8_SA(b, h) + aoff + m * 2048 + k * 1024); } while (0)
; #define PG8_MMA(ai, bj, At, Bt) do { __builtin_amdgcn_s_setprio(1); _Pragma("unroll") for (int m = 0; m < 4; ++m) _Pragma("unroll") for (int n = 0; n < 2; ++n) _Pragma("unroll") for (int k = 0; k < 2; ++k) \
;         acc[ai][bj][m][n] = __builtin_amdgcn_mfma_f32_16x16x32_bf16(Bt[n][k], At[m][k], acc[ai][bj][m][n], 0, 0, 0); __builtin_amdgcn_s_setprio(0); } while (0)
; #define PG8_WAIT_V(n) asm volatile("s_waitcnt vmcnt(" #n ")" ::: "memory")
; #define PG8_WAIT_L(n) asm volatile("s_waitcnt lgkmcnt(" #n ")" ::: "memory")
; #define PG8_BAR __builtin_amdgcn_s_barrier()
; #define PG8_SCHED __builtin_amdgcn_sched_barrier(0)
; template <class Epi, class Sched, bool ALIGN_EPI = false, bool SP2 = false>
; __device__ __forceinline__ void gemm_phase(PG8_LAS unsigned char* lds, const Gemm g, const Sched& S, const Epi& E, int tid_in) {
;     ...
;             PG8_WAIT_V(8); PG8_WAIT_L(0); PG8_BAR; PG8_MMA(0, 0, At, B0); PG8_MMA(0, 1, At, B1); PG8_BAR; PG8_SCHED;
;             PG8_LDA(At, 0, 1); PG8_STAGE(PG8_SB(0, 0), b2, voffB); PG8_STAGE(PG8_SB(0, 1), b2 + hstepB, voffB); PG8_STAGE(PG8_SA(0, 0), a2, voffA);
;             PG8_WAIT_V(8); PG8_WAIT_L(0); PG8_BAR; PG8_MMA(1, 0, At, B0); PG8_MMA(1, 1, At, B1); PG8_BAR; PG8_SCHED;
.Lw1d_5_0:
	s_waitcnt lgkmcnt(0)
	s_barrier
	s_setprio 1
	s_waitcnt lgkmcnt(0)
	v_mfma_f32_16x16x32_bf16 v[124:127], v[146:149], v[186:189], 0
	v_mfma_f32_16x16x32_bf16 v[120:123], v[162:165], v[186:189], 0
	v_mfma_f32_16x16x32_bf16 v[108:111], v[146:149], v[194:197], 0
	v_mfma_f32_16x16x32_bf16 v[104:107], v[162:165], v[194:197], 0
	v_mfma_f32_16x16x32_bf16 v[92:95], v[146:149], v[202:205], 0
	v_mfma_f32_16x16x32_bf16 v[88:91], v[162:165], v[202:205], 0
	v_mfma_f32_16x16x32_bf16 v[76:79], v[146:149], v[210:213], 0
	v_mfma_f32_16x16x32_bf16 v[72:75], v[162:165], v[210:213], 0
	v_mfma_f32_16x16x32_bf16 v[124:127], v[158:161], v[190:193], v[124:127]
	v_mfma_f32_16x16x32_bf16 v[120:123], v[166:169], v[190:193], v[120:123]
	v_mfma_f32_16x16x32_bf16 v[108:111], v[158:161], v[198:201], v[108:111]
	v_mfma_f32_16x16x32_bf16 v[104:107], v[166:169], v[198:201], v[104:107]
	v_mfma_f32_16x16x32_bf16 v[92:95], v[158:161], v[206:209], v[92:95]
	v_mfma_f32_16x16x32_bf16 v[88:91], v[166:169], v[206:209], v[88:91]
	v_mfma_f32_16x16x32_bf16 v[76:79], v[158:161], v[214:217], v[76:79]
	v_mfma_f32_16x16x32_bf16 v[72:75], v[166:169], v[214:217], v[72:75]
	s_setprio 0
	s_setprio 1
	v_mfma_f32_16x16x32_bf16 v[116:119], v[170:173], v[186:189], 0
	v_mfma_f32_16x16x32_bf16 v[112:115], v[178:181], v[186:189], 0
	v_mfma_f32_16x16x32_bf16 v[100:103], v[170:173], v[194:197], 0
	v_mfma_f32_16x16x32_bf16 v[96:99], v[178:181], v[194:197], 0
	v_mfma_f32_16x16x32_bf16 v[84:87], v[170:173], v[202:205], 0
	v_mfma_f32_16x16x32_bf16 v[80:83], v[178:181], v[202:205], 0
	v_mfma_f32_16x16x32_bf16 v[68:71], v[170:173], v[210:213], 0
	v_mfma_f32_16x16x32_bf16 v[64:67], v[178:181], v[210:213], 0
	v_mfma_f32_16x16x32_bf16 v[116:119], v[174:177], v[190:193], v[116:119]
	v_mfma_f32_16x16x32_bf16 v[112:115], v[182:185], v[190:193], v[112:115]
	v_mfma_f32_16x16x32_bf16 v[100:103], v[174:177], v[198:201], v[100:103]
	v_mfma_f32_16x16x32_bf16 v[96:99], v[182:185], v[198:201], v[96:99]
	v_mfma_f32_16x16x32_bf16 v[84:87], v[174:177], v[206:209], v[84:87]
	v_mfma_f32_16x16x32_bf16 v[80:83], v[182:185], v[206:209], v[80:83]
	v_mfma_f32_16x16x32_bf16 v[68:71], v[174:177], v[214:217], v[68:71]
	v_mfma_f32_16x16x32_bf16 v[64:67], v[182:185], v[214:217], v[64:67]
	s_setprio 0
	s_barrier
	s_add_i32 s26, s75, s68
	s_mov_b32 m0, s26
	ds_read_b128 v[186:189], v155 offset:16384
	ds_read_b128 v[190:193], v155 offset:17408
	ds_read_b128 v[194:197], v155 offset:18432
	ds_read_b128 v[198:201], v155 offset:19456
	ds_read_b128 v[202:205], v155 offset:20480
	ds_read_b128 v[206:209], v155 offset:21504
	ds_read_b128 v[210:213], v155 offset:22528
	ds_read_b128 v[214:217], v155 offset:23552
	global_load_lds_dwordx4 v130, s[64:65]
	s_add_i32 m0, s26, 0x2000
	s_add_u32 s26, s64, 0x10000
	s_addc_u32 s27, s65, 0
	s_add_i32 s33, s76, s68
	global_load_lds_dwordx4 v134, s[64:65]
	s_mov_b32 m0, s33
	s_nop 0
	global_load_lds_dwordx4 v130, s[26:27]
	s_add_i32 m0, s33, 0x2000
	s_nop 0
	global_load_lds_dwordx4 v134, s[26:27]
	s_mov_b32 m0, s61
	s_nop 0
	global_load_lds_dwordx4 v128, s[66:67]
	s_mov_b32 m0, s69
	s_nop 0
	global_load_lds_dwordx4 v132, s[66:67]
	s_cmp_eq_u32 s99, 0
	s_cbranch_scc1 .Lw1s_5_1
	s_waitcnt vmcnt(48)
	s_branch .Lw1d_5_1

; #define PG8_STAGE(bufoff, gbase, voff) do { _Pragma("unroll") for (int _i = 0; _i < 2; ++_i) \
;         __builtin_amdgcn_global_load_lds((const unsigned*)((const char*)(gbase) + (voff)[_i]), (PG8_LAS unsigned*)(lds + (bufoff) + ldsw + _i * 8192), 16, 0, 0); } while (0)
; #define PG8_LDA(dst, b, h) do { _Pragma("unroll") for (int m = 0; m < 4; ++m) _Pragma("unroll") for (int k = 0; k < 2; ++k) dst[m][k] = *(const PG8_LAS bf16x8*)(lds + PG8_SA(b, h) + aoff + m * 2048 + k * 1024); } while (0)
; #define PG8_LDB(dst, b, h) do { _Pragma("unroll") for (int n = 0; n < 2; ++n) _Pragma("unroll") for (int k = 0; k < 2; ++k) dst[n][k] = *(const PG8_LAS bf16x8*)(lds + PG8_SB(b, h) + boff + n * 2048 + k * 1024); } while (0)
; #define PG8_MMA(ai, bj, At, Bt) do { __builtin_amdgcn_s_setprio(1); _Pragma("unroll") for (int m = 0; m < 4; ++m) _Pragma("unroll") for (int n = 0; n < 2; ++n) _Pragma("unroll") for (int k = 0; k < 2; ++k) \
;         acc[ai][bj][m][n] = __builtin_amdgcn_mfma_f32_16x16x32_bf16(Bt[n][k], At[m][k], acc[ai][bj][m][n], 0, 0, 0); __builtin_amdgcn_s_setprio(0); } while (0)
; #define PG8_WAIT_V(n) asm volatile("s_waitcnt vmcnt(" #n ")" ::: "memory")
; #define PG8_WAIT_L(n) asm volatile("s_waitcnt lgkmcnt(" #n ")" ::: "memory")
; #define PG8_BAR __builtin_amdgcn_s_barrier()
; #define PG8_SCHED __builtin_amdgcn_sched_barrier(0)
; template <class Epi, class Sched, bool ALIGN_EPI = false, bool SP2 = false>
; __device__ __forceinline__ void gemm_phase(PG8_LAS unsigned char* lds, const Gemm g, const Sched& S, const Epi& E, int tid_in) {
;     ...
;             PG8_WAIT_V(8); PG8_WAIT_L(0); PG8_BAR; PG8_MMA(1, 0, At, B0); PG8_MMA(1, 1, At, B1); PG8_BAR; PG8_SCHED;
;             PG8_LDB(B0, 1, 0); PG8_LDB(B1, 1, 1); PG8_SCHED; PG8_LDA(At, 1, 0); PG8_STAGE(PG8_SA(0, 1), a2 + hstep, voffA);
;             PG8_WAIT_V(8); PG8_WAIT_L(0); PG8_BAR; PG8_MMA(0, 0, At, B0); PG8_MMA(0, 1, At, B1); PG8_BAR; PG8_SCHED;
.Lw1d_5_1:
	s_waitcnt lgkmcnt(0)
	s_barrier
	s_setprio 1
	s_waitcnt lgkmcnt(0)
	v_mfma_f32_16x16x32_bf16 v[60:63], v[146:149], v[186:189], 0
	v_mfma_f32_16x16x32_bf16 v[56:59], v[162:165], v[186:189], 0
	v_mfma_f32_16x16x32_bf16 v[44:47], v[146:149], v[194:197], 0
	v_mfma_f32_16x16x32_bf16 v[40:43], v[162:165], v[194:197], 0
	v_mfma_f32_16x16x32_bf16 v[28:31], v[146:149], v[202:205], 0
	v_mfma_f32_16x16x32_bf16 v[24:27], v[162:165], v[202:205], 0
	v_mfma_f32_16x16x32_bf16 v[12:15], v[146:149], v[210:213], 0
	v_mfma_f32_16x16x32_bf16 v[8:11], v[162:165], v[210:213], 0
	v_mfma_f32_16x16x32_bf16 v[60:63], v[158:161], v[190:193], v[60:63]
	v_mfma_f32_16x16x32_bf16 v[56:59], v[166:169], v[190:193], v[56:59]
	v_mfma_f32_16x16x32_bf16 v[44:47], v[158:161], v[198:201], v[44:47]
	v_mfma_f32_16x16x32_bf16 v[40:43], v[166:169], v[198:201], v[40:43]
	v_mfma_f32_16x16x32_bf16 v[28:31], v[158:161], v[206:209], v[28:31]
	v_mfma_f32_16x16x32_bf16 v[24:27], v[166:169], v[206:209], v[24:27]
	v_mfma_f32_16x16x32_bf16 v[12:15], v[158:161], v[214:217], v[12:15]
	v_mfma_f32_16x16x32_bf16 v[8:11], v[166:169], v[214:217], v[8:11]
	s_setprio 0
	s_setprio 1
	v_mfma_f32_16x16x32_bf16 v[52:55], v[170:173], v[186:189], 0
	v_mfma_f32_16x16x32_bf16 v[48:51], v[178:181], v[186:189], 0
	v_mfma_f32_16x16x32_bf16 v[36:39], v[170:173], v[194:197], 0
	v_mfma_f32_16x16x32_bf16 v[32:35], v[178:181], v[194:197], 0
	v_mfma_f32_16x16x32_bf16 v[20:23], v[170:173], v[202:205], 0
	v_mfma_f32_16x16x32_bf16 v[16:19], v[178:181], v[202:205], 0
	v_mfma_f32_16x16x32_bf16 v[4:7], v[170:173], v[210:213], 0
	v_mfma_f32_16x16x32_bf16 v[0:3], v[178:181], v[210:213], 0
	v_mfma_f32_16x16x32_bf16 v[52:55], v[174:177], v[190:193], v[52:55]
	v_mfma_f32_16x16x32_bf16 v[48:51], v[182:185], v[190:193], v[48:51]
	v_mfma_f32_16x16x32_bf16 v[36:39], v[174:177], v[198:201], v[36:39]
	v_mfma_f32_16x16x32_bf16 v[32:35], v[182:185], v[198:201], v[32:35]
	v_mfma_f32_16x16x32_bf16 v[20:23], v[174:177], v[206:209], v[20:23]
	v_mfma_f32_16x16x32_bf16 v[16:19], v[182:185], v[206:209], v[16:19]
	v_mfma_f32_16x16x32_bf16 v[4:7], v[174:177], v[214:217], v[4:7]
	v_mfma_f32_16x16x32_bf16 v[0:3], v[182:185], v[214:217], v[0:3]
	s_setprio 0
	s_barrier
	s_add_i32 s33, 0, 0x18000
	s_add_i32 s84, 0, 0x1c000
	v_add_u32_e32 v166, s33, v137
	v_add_u32_e32 v182, s84, v137
	ds_read_b128 v[146:149], v166
	ds_read_b128 v[158:161], v166 offset:1024
	ds_read_b128 v[162:165], v166 offset:2048
	ds_read_b128 v[166:169], v166 offset:3072
	ds_read_b128 v[170:173], v182
	ds_read_b128 v[174:177], v182 offset:1024
	ds_read_b128 v[178:181], v182 offset:2048
	ds_read_b128 v[182:185], v182 offset:3072
	s_add_u32 s26, s66, 0x40000
	s_addc_u32 s27, s67, 0
	s_mov_b32 m0, s70
	ds_read_b128 v[186:189], v155 offset:32768
	ds_read_b128 v[190:193], v155 offset:33792
	ds_read_b128 v[194:197], v155 offset:34816
	ds_read_b128 v[198:201], v155 offset:35840
	ds_read_b128 v[202:205], v155 offset:36864
	ds_read_b128 v[206:209], v155 offset:37888
	ds_read_b128 v[210:213], v155 offset:38912
	ds_read_b128 v[214:217], v155 offset:39936
	global_load_lds_dwordx4 v128, s[26:27]
	s_mov_b32 m0, s71
	s_nop 0
	global_load_lds_dwordx4 v132, s[26:27]
	s_waitcnt vmcnt(8)
	s_waitcnt lgkmcnt(0)
	s_barrier
	s_setprio 1
	s_waitcnt lgkmcnt(0)
	v_mfma_f32_16x16x32_bf16 v[124:127], v[146:149], v[186:189], v[124:127]
	v_mfma_f32_16x16x32_bf16 v[120:123], v[162:165], v[186:189], v[120:123]
	v_mfma_f32_16x16x32_bf16 v[108:111], v[146:149], v[194:197], v[108:111]
	v_mfma_f32_16x16x32_bf16 v[104:107], v[162:165], v[194:197], v[104:107]
	v_mfma_f32_16x16x32_bf16 v[92:95], v[146:149], v[202:205], v[92:95]
	v_mfma_f32_16x16x32_bf16 v[88:91], v[162:165], v[202:205], v[88:91]
	v_mfma_f32_16x16x32_bf16 v[76:79], v[146:149], v[210:213], v[76:79]
	v_mfma_f32_16x16x32_bf16 v[72:75], v[162:165], v[210:213], v[72:75]
	v_mfma_f32_16x16x32_bf16 v[124:127], v[158:161], v[190:193], v[124:127]
	v_mfma_f32_16x16x32_bf16 v[120:123], v[166:169], v[190:193], v[120:123]
	v_mfma_f32_16x16x32_bf16 v[108:111], v[158:161], v[198:201], v[108:111]
	v_mfma_f32_16x16x32_bf16 v[104:107], v[166:169], v[198:201], v[104:107]
	v_mfma_f32_16x16x32_bf16 v[92:95], v[158:161], v[206:209], v[92:95]
	v_mfma_f32_16x16x32_bf16 v[88:91], v[166:169], v[206:209], v[88:91]
	v_mfma_f32_16x16x32_bf16 v[76:79], v[158:161], v[214:217], v[76:79]
	v_mfma_f32_16x16x32_bf16 v[72:75], v[166:169], v[214:217], v[72:75]
	s_setprio 0
	s_setprio 1
	v_mfma_f32_16x16x32_bf16 v[116:119], v[170:173], v[186:189], v[116:119]
	v_mfma_f32_16x16x32_bf16 v[112:115], v[178:181], v[186:189], v[112:115]
	v_mfma_f32_16x16x32_bf16 v[100:103], v[170:173], v[194:197], v[100:103]
	v_mfma_f32_16x16x32_bf16 v[96:99], v[178:181], v[194:197], v[96:99]
	v_mfma_f32_16x16x32_bf16 v[84:87], v[170:173], v[202:205], v[84:87]
	v_mfma_f32_16x16x32_bf16 v[80:83], v[178:181], v[202:205], v[80:83]
	v_mfma_f32_16x16x32_bf16 v[68:71], v[170:173], v[210:213], v[68:71]
	v_mfma_f32_16x16x32_bf16 v[64:67], v[178:181], v[210:213], v[64:67]
	v_mfma_f32_16x16x32_bf16 v[116:119], v[174:177], v[190:193], v[116:119]
	v_mfma_f32_16x16x32_bf16 v[112:115], v[182:185], v[190:193], v[112:115]
	v_mfma_f32_16x16x32_bf16 v[100:103], v[174:177], v[198:201], v[100:103]
	v_mfma_f32_16x16x32_bf16 v[96:99], v[182:185], v[198:201], v[96:99]
	v_mfma_f32_16x16x32_bf16 v[84:87], v[174:177], v[206:209], v[84:87]
	v_mfma_f32_16x16x32_bf16 v[80:83], v[182:185], v[206:209], v[80:83]
	v_mfma_f32_16x16x32_bf16 v[68:71], v[174:177], v[214:217], v[68:71]
	v_mfma_f32_16x16x32_bf16 v[64:67], v[182:185], v[214:217], v[64:67]
	s_setprio 0
	s_barrier
; #define PG8_STAGE(bufoff, gbase, voff) do { _Pragma("unroll") for (int _i = 0; _i < 2; ++_i) \
;         __builtin_amdgcn_global_load_lds((const unsigned*)((const char*)(gbase) + (voff)[_i]), (PG8_LAS unsigned*)(lds + (bufoff) + ldsw + _i * 8192), 16, 0, 0); } while (0)
; #define PG8_LDA(dst, b, h) do { _Pragma("unroll") for (int m = 0; m < 4; ++m) _Pragma("unroll") for (int k = 0; k < 2; ++k) dst[m][k] = *(const PG8_LAS bf16x8*)(lds + PG8_SA(b, h) + aoff + m * 2048 + k * 1024); } while (0)
; #define PG8_LDB(dst, b, h) do { _Pragma("unroll") for (int n = 0; n < 2; ++n) _Pragma("unroll") for (int k = 0; k < 2; ++k) dst[n][k] = *(const PG8_LAS bf16x8*)(lds + PG8_SB(b, h) + boff + n * 2048 + k * 1024); } while (0)
; #define PG8_MMA(ai, bj, At, Bt) do { __builtin_amdgcn_s_setprio(1); _Pragma("unroll") for (int m = 0; m < 4; ++m) _Pragma("unroll") for (int n = 0; n < 2; ++n) _Pragma("unroll") for (int k = 0; k < 2; ++k) \
;         acc[ai][bj][m][n] = __builtin_amdgcn_mfma_f32_16x16x32_bf16(Bt[n][k], At[m][k], acc[ai][bj][m][n], 0, 0, 0); __builtin_amdgcn_s_setprio(0); } while (0)
; #define PG8_BAR __builtin_amdgcn_s_barrier()
; template <class Epi, class Sched, bool ALIGN_EPI = false, bool SP2 = false>
; __device__ __forceinline__ void gemm_phase(PG8_LAS unsigned char* lds, const Gemm g, const Sched& S, const Epi& E, int tid_in) {
;     ...
;             PG8_LDB(B0, 0, 0); PG8_LDB(B1, 0, 1); PG8_SCHED; PG8_LDA(At, 0, 0); PG8_STAGE(PG8_SA(1, 1), a1 + hstep, voffA);
;             PG8_WAIT_V(8); PG8_WAIT_L(0); PG8_BAR; PG8_MMA(0, 0, At, B0); PG8_MMA(0, 1, At, B1); PG8_BAR; PG8_SCHED;
;             PG8_LDA(At, 0, 1); PG8_STAGE(PG8_SB(0, 0), b2, voffB); PG8_STAGE(PG8_SB(0, 1), b2 + hstepB, voffB); PG8_STAGE(PG8_SA(0, 0), a2, voffA);
;             PG8_WAIT_V(8); PG8_WAIT_L(0); PG8_BAR; PG8_MMA(1, 0, At, B0); PG8_MMA(1, 1, At, B1); PG8_BAR; PG8_SCHED;
;             PG8_LDB(B0, 1, 0); PG8_LDB(B1, 1, 1); PG8_SCHED; PG8_LDA(At, 1, 0); PG8_STAGE(PG8_SA(0, 1), a2 + hstep, voffA);
;             PG8_WAIT_V(8); PG8_WAIT_L(0); PG8_BAR; PG8_MMA(0, 0, At, B0); PG8_MMA(0, 1, At, B1); PG8_BAR; PG8_SCHED;
;             PG8_LDA(At, 1, 1); PG8_STAGE(PG8_SB(1, 0), b3, voffB); PG8_STAGE(PG8_SB(1, 1), b3 + hstepB, voffB); PG8_STAGE(PG8_SA(1, 0), a3, voffA);
;             PG8_WAIT_V(8); PG8_WAIT_L(0); PG8_BAR; PG8_MMA(1, 0, At, B0); PG8_MMA(1, 1, At, B1); PG8_BAR; PG8_SCHED;
	s_add_i32 s26, s33, s68
	s_add_i32 m0, s26, 0xffffff80
	ds_read_b128 v[186:189], v155 offset:49152
	ds_read_b128 v[190:193], v155 offset:50176
	ds_read_b128 v[194:197], v155 offset:51200
	ds_read_b128 v[198:201], v155 offset:52224
	ds_read_b128 v[202:205], v155 offset:53248
	ds_read_b128 v[206:209], v155 offset:54272
	ds_read_b128 v[210:213], v155 offset:55296
	ds_read_b128 v[214:217], v155 offset:56320
	global_load_lds_dwordx4 v130, s[64:65] offset:128
	s_add_i32 m0, s26, 0x1f80
	s_add_u32 s26, s64, 0x10080
	s_addc_u32 s27, s65, 0
	s_add_i32 s33, s84, s68
	global_load_lds_dwordx4 v134, s[64:65] offset:128
	s_mov_b32 m0, s33
	s_nop 0
	global_load_lds_dwordx4 v130, s[26:27]
	s_add_i32 m0, s33, 0x2000
	s_nop 0
	global_load_lds_dwordx4 v134, s[26:27]
	s_add_i32 m0, s73, 0xffffff80
	s_nop 0
	global_load_lds_dwordx4 v128, s[66:67] offset:128
	s_add_i32 m0, s74, 0xffffff80
	s_nop 0
	global_load_lds_dwordx4 v132, s[66:67] offset:128
	s_waitcnt vmcnt(8)
	s_waitcnt lgkmcnt(0)
	s_barrier
	s_setprio 1
	s_waitcnt lgkmcnt(0)
	v_mfma_f32_16x16x32_bf16 v[60:63], v[146:149], v[186:189], v[60:63]
	v_mfma_f32_16x16x32_bf16 v[56:59], v[162:165], v[186:189], v[56:59]
	v_mfma_f32_16x16x32_bf16 v[44:47], v[146:149], v[194:197], v[44:47]
	v_mfma_f32_16x16x32_bf16 v[40:43], v[162:165], v[194:197], v[40:43]
	v_mfma_f32_16x16x32_bf16 v[28:31], v[146:149], v[202:205], v[28:31]
	v_mfma_f32_16x16x32_bf16 v[24:27], v[162:165], v[202:205], v[24:27]
	v_mfma_f32_16x16x32_bf16 v[12:15], v[146:149], v[210:213], v[12:15]
	v_mfma_f32_16x16x32_bf16 v[8:11], v[162:165], v[210:213], v[8:11]
	v_mfma_f32_16x16x32_bf16 v[60:63], v[158:161], v[190:193], v[60:63]
	v_mfma_f32_16x16x32_bf16 v[56:59], v[166:169], v[190:193], v[56:59]
	v_mfma_f32_16x16x32_bf16 v[44:47], v[158:161], v[198:201], v[44:47]
	v_mfma_f32_16x16x32_bf16 v[40:43], v[166:169], v[198:201], v[40:43]
	v_mfma_f32_16x16x32_bf16 v[28:31], v[158:161], v[206:209], v[28:31]
	v_mfma_f32_16x16x32_bf16 v[24:27], v[166:169], v[206:209], v[24:27]
	v_mfma_f32_16x16x32_bf16 v[12:15], v[158:161], v[214:217], v[12:15]
	v_mfma_f32_16x16x32_bf16 v[8:11], v[166:169], v[214:217], v[8:11]
	s_setprio 0
	s_setprio 1
	v_mfma_f32_16x16x32_bf16 v[52:55], v[170:173], v[186:189], v[52:55]
	v_mfma_f32_16x16x32_bf16 v[48:51], v[178:181], v[186:189], v[48:51]
	v_mfma_f32_16x16x32_bf16 v[36:39], v[170:173], v[194:197], v[36:39]
	v_mfma_f32_16x16x32_bf16 v[32:35], v[178:181], v[194:197], v[32:35]
	v_mfma_f32_16x16x32_bf16 v[20:23], v[170:173], v[202:205], v[20:23]
	v_mfma_f32_16x16x32_bf16 v[16:19], v[178:181], v[202:205], v[16:19]
	v_mfma_f32_16x16x32_bf16 v[4:7], v[170:173], v[210:213], v[4:7]
	v_mfma_f32_16x16x32_bf16 v[0:3], v[178:181], v[210:213], v[0:3]
	v_mfma_f32_16x16x32_bf16 v[52:55], v[174:177], v[190:193], v[52:55]
	v_mfma_f32_16x16x32_bf16 v[48:51], v[182:185], v[190:193], v[48:51]
	v_mfma_f32_16x16x32_bf16 v[36:39], v[174:177], v[198:201], v[36:39]
	v_mfma_f32_16x16x32_bf16 v[32:35], v[182:185], v[198:201], v[32:35]
	v_mfma_f32_16x16x32_bf16 v[20:23], v[174:177], v[206:209], v[20:23]
	v_mfma_f32_16x16x32_bf16 v[16:19], v[182:185], v[206:209], v[16:19]
	v_mfma_f32_16x16x32_bf16 v[4:7], v[174:177], v[214:217], v[4:7]
	v_mfma_f32_16x16x32_bf16 v[0:3], v[182:185], v[214:217], v[0:3]
	s_setprio 0
	s_barrier
	s_add_i32 s83, s83, 2
	s_add_u32 s62, s62, 0x100
	s_addc_u32 s63, s63, 0
	s_add_u32 s78, s78, 0x100
	s_addc_u32 s79, s79, 0
	s_cmp_gt_u32 s83, 13
.LBB0_767:
	ds_read_b128 v[146:149], v153
	ds_read_b128 v[158:161], v153 offset:1024
	ds_read_b128 v[162:165], v153 offset:2048
	ds_read_b128 v[166:169], v153 offset:3072
	ds_read_b128 v[170:173], v154
	ds_read_b128 v[174:177], v154 offset:1024
	ds_read_b128 v[178:181], v154 offset:2048
	ds_read_b128 v[182:185], v154 offset:3072
	s_add_u32 s26, s62, 0xfffc0080
	s_addc_u32 s27, s63, -1
	s_cmp_eq_u32 s83, 12
	s_cselect_b32 s67, s53, s27
	s_cselect_b32 s66, s59, s26
	s_cselect_b32 s65, s51, s79
	s_cselect_b32 s64, s77, s78
	s_add_i32 m0, s61, 0xc000
	ds_read_b128 v[186:189], v155
	ds_read_b128 v[190:193], v155 offset:1024
	ds_read_b128 v[194:197], v155 offset:2048
	ds_read_b128 v[198:201], v155 offset:3072
	ds_read_b128 v[202:205], v155 offset:4096
	ds_read_b128 v[206:209], v155 offset:5120
	ds_read_b128 v[210:213], v155 offset:6144
	ds_read_b128 v[214:217], v155 offset:7168
	global_load_lds_dwordx4 v138, s[62:63]
	s_add_i32 m0, s61, 0xe000
	s_nop 0
	global_load_lds_dwordx4 v140, s[62:63]
	s_waitcnt vmcnt(8)
	s_waitcnt lgkmcnt(0)
	s_barrier
; #define PG8_STAGE(bufoff, gbase, voff) do { _Pragma("unroll") for (int _i = 0; _i < 2; ++_i) \
;         __builtin_amdgcn_global_load_lds((const unsigned*)((const char*)(gbase) + (voff)[_i]), (PG8_LAS unsigned*)(lds + (bufoff) + ldsw + _i * 8192), 16, 0, 0); } while (0)
; #define PG8_LDA(dst, b, h) do { _Pragma("unroll") for (int m = 0; m < 4; ++m) _Pragma("unroll") for (int k = 0; k < 2; ++k) dst[m][k] = *(const PG8_LAS bf16x8*)(lds + PG8_SA(b, h) + aoff + m * 2048 + k * 1024); } while (0)
; #define PG8_MMA(ai, bj, At, Bt) do { __builtin_amdgcn_s_setprio(1); _Pragma("unroll") for (int m = 0; m < 4; ++m) _Pragma("unroll") for (int n = 0; n < 2; ++n) _Pragma("unroll") for (int k = 0; k < 2; ++k) \
;         acc[ai][bj][m][n] = __builtin_amdgcn_mfma_f32_16x16x32_bf16(Bt[n][k], At[m][k], acc[ai][bj][m][n], 0, 0, 0); __builtin_amdgcn_s_setprio(0); } while (0)
; #define PG8_WAIT_V(n) asm volatile("s_waitcnt vmcnt(" #n ")" ::: "memory")
; #define PG8_WAIT_L(n) asm volatile("s_waitcnt lgkmcnt(" #n ")" ::: "memory")
; #define PG8_BAR __builtin_amdgcn_s_barrier()
; #define PG8_SCHED __builtin_amdgcn_sched_barrier(0)
; template <class Epi, class Sched, bool ALIGN_EPI = false, bool SP2 = false>
; __device__ __forceinline__ void gemm_phase(PG8_LAS unsigned char* lds, const Gemm g, const Sched& S, const Epi& E, int tid_in) {
;     ...
;             PG8_WAIT_V(8); PG8_WAIT_L(0); PG8_BAR; PG8_MMA(0, 0, At, B0); PG8_MMA(0, 1, At, B1); PG8_BAR; PG8_SCHED;
;             PG8_LDA(At, 0, 1); PG8_STAGE(PG8_SB(0, 0), b2, voffB); PG8_STAGE(PG8_SB(0, 1), b2 + hstepB, voffB); PG8_STAGE(PG8_SA(0, 0), a2, voffA);
;             PG8_WAIT_V(8); PG8_WAIT_L(0); PG8_BAR; PG8_MMA(1, 0, At, B0); PG8_MMA(1, 1, At, B1); PG8_BAR; PG8_SCHED;
	s_setprio 1
	s_waitcnt lgkmcnt(0)
	v_mfma_f32_16x16x32_bf16 v[124:127], v[146:149], v[186:189], v[124:127]
	v_mfma_f32_16x16x32_bf16 v[120:123], v[162:165], v[186:189], v[120:123]
	v_mfma_f32_16x16x32_bf16 v[108:111], v[146:149], v[194:197], v[108:111]
	v_mfma_f32_16x16x32_bf16 v[104:107], v[162:165], v[194:197], v[104:107]
	v_mfma_f32_16x16x32_bf16 v[92:95], v[146:149], v[202:205], v[92:95]
	v_mfma_f32_16x16x32_bf16 v[88:91], v[162:165], v[202:205], v[88:91]
	v_mfma_f32_16x16x32_bf16 v[76:79], v[146:149], v[210:213], v[76:79]
	v_mfma_f32_16x16x32_bf16 v[72:75], v[162:165], v[210:213], v[72:75]
	v_mfma_f32_16x16x32_bf16 v[124:127], v[158:161], v[190:193], v[124:127]
	v_mfma_f32_16x16x32_bf16 v[120:123], v[166:169], v[190:193], v[120:123]
	v_mfma_f32_16x16x32_bf16 v[108:111], v[158:161], v[198:201], v[108:111]
	v_mfma_f32_16x16x32_bf16 v[104:107], v[166:169], v[198:201], v[104:107]
	v_mfma_f32_16x16x32_bf16 v[92:95], v[158:161], v[206:209], v[92:95]
	v_mfma_f32_16x16x32_bf16 v[88:91], v[166:169], v[206:209], v[88:91]
	v_mfma_f32_16x16x32_bf16 v[76:79], v[158:161], v[214:217], v[76:79]
	v_mfma_f32_16x16x32_bf16 v[72:75], v[166:169], v[214:217], v[72:75]
	s_setprio 0
	s_setprio 1
	v_mfma_f32_16x16x32_bf16 v[116:119], v[170:173], v[186:189], v[116:119]
	v_mfma_f32_16x16x32_bf16 v[112:115], v[178:181], v[186:189], v[112:115]
	v_mfma_f32_16x16x32_bf16 v[100:103], v[170:173], v[194:197], v[100:103]
	v_mfma_f32_16x16x32_bf16 v[96:99], v[178:181], v[194:197], v[96:99]
	v_mfma_f32_16x16x32_bf16 v[84:87], v[170:173], v[202:205], v[84:87]
	v_mfma_f32_16x16x32_bf16 v[80:83], v[178:181], v[202:205], v[80:83]
	v_mfma_f32_16x16x32_bf16 v[68:71], v[170:173], v[210:213], v[68:71]
	v_mfma_f32_16x16x32_bf16 v[64:67], v[178:181], v[210:213], v[64:67]
	v_mfma_f32_16x16x32_bf16 v[116:119], v[174:177], v[190:193], v[116:119]
	v_mfma_f32_16x16x32_bf16 v[112:115], v[182:185], v[190:193], v[112:115]
	v_mfma_f32_16x16x32_bf16 v[100:103], v[174:177], v[198:201], v[100:103]
	v_mfma_f32_16x16x32_bf16 v[96:99], v[182:185], v[198:201], v[96:99]
	v_mfma_f32_16x16x32_bf16 v[84:87], v[174:177], v[206:209], v[84:87]
	v_mfma_f32_16x16x32_bf16 v[80:83], v[182:185], v[206:209], v[80:83]
	v_mfma_f32_16x16x32_bf16 v[68:71], v[174:177], v[214:217], v[68:71]
	v_mfma_f32_16x16x32_bf16 v[64:67], v[182:185], v[214:217], v[64:67]
	s_setprio 0
	s_barrier
	s_add_i32 s26, s75, s68
	s_mov_b32 m0, s26
	ds_read_b128 v[186:189], v155 offset:16384
	ds_read_b128 v[190:193], v155 offset:17408
	ds_read_b128 v[194:197], v155 offset:18432
	ds_read_b128 v[198:201], v155 offset:19456
	ds_read_b128 v[202:205], v155 offset:20480
	ds_read_b128 v[206:209], v155 offset:21504
	ds_read_b128 v[210:213], v155 offset:22528
	ds_read_b128 v[214:217], v155 offset:23552
	global_load_lds_dwordx4 v130, s[64:65]
	s_add_i32 m0, s26, 0x2000
	s_add_u32 s26, s64, 0x10000
	s_addc_u32 s27, s65, 0
	s_add_i32 s33, s76, s68
	global_load_lds_dwordx4 v134, s[64:65]
	s_mov_b32 m0, s33
	s_nop 0
	global_load_lds_dwordx4 v130, s[26:27]
	s_add_i32 m0, s33, 0x2000
	s_nop 0
	global_load_lds_dwordx4 v134, s[26:27]
	s_mov_b32 m0, s61
	s_nop 0
	global_load_lds_dwordx4 v128, s[66:67]
	s_mov_b32 m0, s69
	s_nop 0
	global_load_lds_dwordx4 v132, s[66:67]
	s_waitcnt vmcnt(8)
	s_waitcnt lgkmcnt(0)
	s_barrier
	s_setprio 1
	s_waitcnt lgkmcnt(0)
	v_mfma_f32_16x16x32_bf16 v[60:63], v[146:149], v[186:189], v[60:63]
	v_mfma_f32_16x16x32_bf16 v[56:59], v[162:165], v[186:189], v[56:59]
	v_mfma_f32_16x16x32_bf16 v[44:47], v[146:149], v[194:197], v[44:47]
	v_mfma_f32_16x16x32_bf16 v[40:43], v[162:165], v[194:197], v[40:43]
	v_mfma_f32_16x16x32_bf16 v[28:31], v[146:149], v[202:205], v[28:31]
	v_mfma_f32_16x16x32_bf16 v[24:27], v[162:165], v[202:205], v[24:27]
	v_mfma_f32_16x16x32_bf16 v[12:15], v[146:149], v[210:213], v[12:15]
	v_mfma_f32_16x16x32_bf16 v[8:11], v[162:165], v[210:213], v[8:11]
	v_mfma_f32_16x16x32_bf16 v[60:63], v[158:161], v[190:193], v[60:63]
	v_mfma_f32_16x16x32_bf16 v[56:59], v[166:169], v[190:193], v[56:59]
	v_mfma_f32_16x16x32_bf16 v[44:47], v[158:161], v[198:201], v[44:47]
	v_mfma_f32_16x16x32_bf16 v[40:43], v[166:169], v[198:201], v[40:43]
	v_mfma_f32_16x16x32_bf16 v[28:31], v[158:161], v[206:209], v[28:31]
	v_mfma_f32_16x16x32_bf16 v[24:27], v[166:169], v[206:209], v[24:27]
	v_mfma_f32_16x16x32_bf16 v[12:15], v[158:161], v[214:217], v[12:15]
	v_mfma_f32_16x16x32_bf16 v[8:11], v[166:169], v[214:217], v[8:11]
	s_setprio 0
	s_setprio 1
	v_mfma_f32_16x16x32_bf16 v[52:55], v[170:173], v[186:189], v[52:55]
	v_mfma_f32_16x16x32_bf16 v[48:51], v[178:181], v[186:189], v[48:51]
	v_mfma_f32_16x16x32_bf16 v[36:39], v[170:173], v[194:197], v[36:39]
	v_mfma_f32_16x16x32_bf16 v[32:35], v[178:181], v[194:197], v[32:35]
	v_mfma_f32_16x16x32_bf16 v[20:23], v[170:173], v[202:205], v[20:23]
	v_mfma_f32_16x16x32_bf16 v[16:19], v[178:181], v[202:205], v[16:19]
	v_mfma_f32_16x16x32_bf16 v[4:7], v[170:173], v[210:213], v[4:7]
	v_mfma_f32_16x16x32_bf16 v[0:3], v[178:181], v[210:213], v[0:3]
	v_mfma_f32_16x16x32_bf16 v[52:55], v[174:177], v[190:193], v[52:55]
	v_mfma_f32_16x16x32_bf16 v[48:51], v[182:185], v[190:193], v[48:51]
	v_mfma_f32_16x16x32_bf16 v[36:39], v[174:177], v[198:201], v[36:39]
	v_mfma_f32_16x16x32_bf16 v[32:35], v[182:185], v[198:201], v[32:35]
	v_mfma_f32_16x16x32_bf16 v[20:23], v[174:177], v[206:209], v[20:23]
	v_mfma_f32_16x16x32_bf16 v[16:19], v[182:185], v[206:209], v[16:19]
	v_mfma_f32_16x16x32_bf16 v[4:7], v[174:177], v[214:217], v[4:7]
	v_mfma_f32_16x16x32_bf16 v[0:3], v[182:185], v[214:217], v[0:3]
	s_setprio 0
	s_barrier
; #define PG8_STAGE(bufoff, gbase, voff) do { _Pragma("unroll") for (int _i = 0; _i < 2; ++_i) \
;         __builtin_amdgcn_global_load_lds((const unsigned*)((const char*)(gbase) + (voff)[_i]), (PG8_LAS unsigned*)(lds + (bufoff) + ldsw + _i * 8192), 16, 0, 0); } while (0)
; #define PG8_LDA(dst, b, h) do { _Pragma("unroll") for (int m = 0; m < 4; ++m) _Pragma("unroll") for (int k = 0; k < 2; ++k) dst[m][k] = *(const PG8_LAS bf16x8*)(lds + PG8_SA(b, h) + aoff + m * 2048 + k * 1024); } while (0)
; #define PG8_LDB(dst, b, h) do { _Pragma("unroll") for (int n = 0; n < 2; ++n) _Pragma("unroll") for (int k = 0; k < 2; ++k) dst[n][k] = *(const PG8_LAS bf16x8*)(lds + PG8_SB(b, h) + boff + n * 2048 + k * 1024); } while (0)
; #define PG8_MMA(ai, bj, At, Bt) do { __builtin_amdgcn_s_setprio(1); _Pragma("unroll") for (int m = 0; m < 4; ++m) _Pragma("unroll") for (int n = 0; n < 2; ++n) _Pragma("unroll") for (int k = 0; k < 2; ++k) \
;         acc[ai][bj][m][n] = __builtin_amdgcn_mfma_f32_16x16x32_bf16(Bt[n][k], At[m][k], acc[ai][bj][m][n], 0, 0, 0); __builtin_amdgcn_s_setprio(0); } while (0)
; #define PG8_WAIT_V(n) asm volatile("s_waitcnt vmcnt(" #n ")" ::: "memory")
; #define PG8_WAIT_L(n) asm volatile("s_waitcnt lgkmcnt(" #n ")" ::: "memory")
; #define PG8_BAR __builtin_amdgcn_s_barrier()
; #define PG8_SCHED __builtin_amdgcn_sched_barrier(0)
; template <class Epi, class Sched, bool ALIGN_EPI = false, bool SP2 = false>
; __device__ __forceinline__ void gemm_phase(PG8_LAS unsigned char* lds, const Gemm g, const Sched& S, const Epi& E, int tid_in) {
;     ...
;             PG8_LDB(B0, 1, 0); PG8_LDB(B1, 1, 1); PG8_SCHED; PG8_LDA(At, 1, 0); PG8_STAGE(PG8_SA(0, 1), a2 + hstep, voffA);
;             PG8_WAIT_V(8); PG8_WAIT_L(0); PG8_BAR; PG8_MMA(0, 0, At, B0); PG8_MMA(0, 1, At, B1); PG8_BAR; PG8_SCHED;
;             PG8_LDA(At, 1, 1); PG8_STAGE(PG8_SB(1, 0), b3, voffB); PG8_STAGE(PG8_SB(1, 1), b3 + hstepB, voffB); PG8_STAGE(PG8_SA(1, 0), a3, voffA);
	s_add_i32 s33, 0, 0x18000
	s_add_i32 s84, 0, 0x1c000
	v_add_u32_e32 v166, s33, v137
	v_add_u32_e32 v182, s84, v137
	ds_read_b128 v[146:149], v166
	ds_read_b128 v[158:161], v166 offset:1024
	ds_read_b128 v[162:165], v166 offset:2048
	ds_read_b128 v[166:169], v166 offset:3072
	ds_read_b128 v[170:173], v182
	ds_read_b128 v[174:177], v182 offset:1024
	ds_read_b128 v[178:181], v182 offset:2048
	ds_read_b128 v[182:185], v182 offset:3072
	s_add_u32 s26, s66, 0x40000
	s_addc_u32 s27, s67, 0
	s_mov_b32 m0, s70
	ds_read_b128 v[186:189], v155 offset:32768
	ds_read_b128 v[190:193], v155 offset:33792
	ds_read_b128 v[194:197], v155 offset:34816
	ds_read_b128 v[198:201], v155 offset:35840
	ds_read_b128 v[202:205], v155 offset:36864
	ds_read_b128 v[206:209], v155 offset:37888
	ds_read_b128 v[210:213], v155 offset:38912
	ds_read_b128 v[214:217], v155 offset:39936
	global_load_lds_dwordx4 v128, s[26:27]
	s_mov_b32 m0, s71
	s_nop 0
	global_load_lds_dwordx4 v132, s[26:27]
	s_waitcnt vmcnt(8)
	s_waitcnt lgkmcnt(0)
	s_barrier
	s_setprio 1
	s_waitcnt lgkmcnt(0)
	v_mfma_f32_16x16x32_bf16 v[124:127], v[146:149], v[186:189], v[124:127]
	v_mfma_f32_16x16x32_bf16 v[120:123], v[162:165], v[186:189], v[120:123]
	v_mfma_f32_16x16x32_bf16 v[108:111], v[146:149], v[194:197], v[108:111]
	v_mfma_f32_16x16x32_bf16 v[104:107], v[162:165], v[194:197], v[104:107]
	v_mfma_f32_16x16x32_bf16 v[92:95], v[146:149], v[202:205], v[92:95]
	v_mfma_f32_16x16x32_bf16 v[88:91], v[162:165], v[202:205], v[88:91]
	v_mfma_f32_16x16x32_bf16 v[76:79], v[146:149], v[210:213], v[76:79]
	v_mfma_f32_16x16x32_bf16 v[72:75], v[162:165], v[210:213], v[72:75]
	v_mfma_f32_16x16x32_bf16 v[124:127], v[158:161], v[190:193], v[124:127]
	v_mfma_f32_16x16x32_bf16 v[120:123], v[166:169], v[190:193], v[120:123]
	v_mfma_f32_16x16x32_bf16 v[108:111], v[158:161], v[198:201], v[108:111]
	v_mfma_f32_16x16x32_bf16 v[104:107], v[166:169], v[198:201], v[104:107]
	v_mfma_f32_16x16x32_bf16 v[92:95], v[158:161], v[206:209], v[92:95]
	v_mfma_f32_16x16x32_bf16 v[88:91], v[166:169], v[206:209], v[88:91]
	v_mfma_f32_16x16x32_bf16 v[76:79], v[158:161], v[214:217], v[76:79]
	v_mfma_f32_16x16x32_bf16 v[72:75], v[166:169], v[214:217], v[72:75]
	s_setprio 0
	s_setprio 1
	v_mfma_f32_16x16x32_bf16 v[116:119], v[170:173], v[186:189], v[116:119]
	v_mfma_f32_16x16x32_bf16 v[112:115], v[178:181], v[186:189], v[112:115]
	v_mfma_f32_16x16x32_bf16 v[100:103], v[170:173], v[194:197], v[100:103]
	v_mfma_f32_16x16x32_bf16 v[96:99], v[178:181], v[194:197], v[96:99]
	v_mfma_f32_16x16x32_bf16 v[84:87], v[170:173], v[202:205], v[84:87]
	v_mfma_f32_16x16x32_bf16 v[80:83], v[178:181], v[202:205], v[80:83]
	v_mfma_f32_16x16x32_bf16 v[68:71], v[170:173], v[210:213], v[68:71]
	v_mfma_f32_16x16x32_bf16 v[64:67], v[178:181], v[210:213], v[64:67]
	v_mfma_f32_16x16x32_bf16 v[116:119], v[174:177], v[190:193], v[116:119]
	v_mfma_f32_16x16x32_bf16 v[112:115], v[182:185], v[190:193], v[112:115]
	v_mfma_f32_16x16x32_bf16 v[100:103], v[174:177], v[198:201], v[100:103]
	v_mfma_f32_16x16x32_bf16 v[96:99], v[182:185], v[198:201], v[96:99]
	v_mfma_f32_16x16x32_bf16 v[84:87], v[174:177], v[206:209], v[84:87]
	v_mfma_f32_16x16x32_bf16 v[80:83], v[182:185], v[206:209], v[80:83]
	v_mfma_f32_16x16x32_bf16 v[68:71], v[174:177], v[214:217], v[68:71]
	v_mfma_f32_16x16x32_bf16 v[64:67], v[182:185], v[214:217], v[64:67]
	s_setprio 0
	s_barrier
	s_add_i32 s26, s33, s68
	s_add_i32 m0, s26, 0xffffff80
	ds_read_b128 v[186:189], v155 offset:49152
	ds_read_b128 v[190:193], v155 offset:50176
	ds_read_b128 v[194:197], v155 offset:51200
	ds_read_b128 v[198:201], v155 offset:52224
	ds_read_b128 v[202:205], v155 offset:53248
	ds_read_b128 v[206:209], v155 offset:54272
	ds_read_b128 v[210:213], v155 offset:55296
	ds_read_b128 v[214:217], v155 offset:56320
	global_load_lds_dwordx4 v130, s[64:65] offset:128
	s_add_i32 m0, s26, 0x1f80
	s_add_u32 s26, s64, 0x10080
	s_addc_u32 s27, s65, 0
	s_add_i32 s33, s84, s68
	global_load_lds_dwordx4 v134, s[64:65] offset:128
	s_mov_b32 m0, s33
	s_nop 0
	global_load_lds_dwordx4 v130, s[26:27]
	s_add_i32 m0, s33, 0x2000
	s_nop 0
	global_load_lds_dwordx4 v134, s[26:27]
	s_add_i32 m0, s73, 0xffffff80
	s_nop 0
	global_load_lds_dwordx4 v128, s[66:67] offset:128
	s_add_i32 m0, s74, 0xffffff80
	s_nop 0
	global_load_lds_dwordx4 v132, s[66:67] offset:128
	s_waitcnt vmcnt(8)
	s_waitcnt lgkmcnt(0)
	s_barrier
; #define PG8_STAGE(bufoff, gbase, voff) do { _Pragma("unroll") for (int _i = 0; _i < 2; ++_i) \
;         __builtin_amdgcn_global_load_lds((const unsigned*)((const char*)(gbase) + (voff)[_i]), (PG8_LAS unsigned*)(lds + (bufoff) + ldsw + _i * 8192), 16, 0, 0); } while (0)
; #define PG8_LDA(dst, b, h) do { _Pragma("unroll") for (int m = 0; m < 4; ++m) _Pragma("unroll") for (int k = 0; k < 2; ++k) dst[m][k] = *(const PG8_LAS bf16x8*)(lds + PG8_SA(b, h) + aoff + m * 2048 + k * 1024); } while (0)
; #define PG8_MMA(ai, bj, At, Bt) do { __builtin_amdgcn_s_setprio(1); _Pragma("unroll") for (int m = 0; m < 4; ++m) _Pragma("unroll") for (int n = 0; n < 2; ++n) _Pragma("unroll") for (int k = 0; k < 2; ++k) \
;         acc[ai][bj][m][n] = __builtin_amdgcn_mfma_f32_16x16x32_bf16(Bt[n][k], At[m][k], acc[ai][bj][m][n], 0, 0, 0); __builtin_amdgcn_s_setprio(0); } while (0)
; #define PG8_WAIT_V(n) asm volatile("s_waitcnt vmcnt(" #n ")" ::: "memory")
; #define PG8_WAIT_L(n) asm volatile("s_waitcnt lgkmcnt(" #n ")" ::: "memory")
; #define PG8_BAR __builtin_amdgcn_s_barrier()
; #define PG8_SCHED __builtin_amdgcn_sched_barrier(0)
; template <class Epi, class Sched, bool ALIGN_EPI = false, bool SP2 = false>
; __device__ __forceinline__ void gemm_phase(PG8_LAS unsigned char* lds, const Gemm g, const Sched& S, const Epi& E, int tid_in) {
;     ...
;             PG8_LDA(At, 1, 1); PG8_STAGE(PG8_SB(1, 0), b3, voffB); PG8_STAGE(PG8_SB(1, 1), b3 + hstepB, voffB); PG8_STAGE(PG8_SA(1, 0), a3, voffA);
;             PG8_WAIT_V(8); PG8_WAIT_L(0); PG8_BAR; PG8_MMA(1, 0, At, B0); PG8_MMA(1, 1, At, B1); PG8_BAR; PG8_SCHED;
;     __device__ __forceinline__ void operator()(const f32x4 (&acc)[2][2][4][2], const Unit& u, int wr, int wc, int fr, int fq) const {
;     ...
;                 const int row = u.pm * BM + ai * HALF + wr * 64 + m * 16 + r; float q = 0.f;
; #pragma unroll
;                 for (int bj = 0; bj < 2; ++bj) {
;                     const size_t off = (size_t)row * 2048 + u.pn * BM + wc * 64 + bj * 32 + 8 * p;
;                     f32x4 b0, b1;
;                     if (BASE_F32) { b0 = *(const f32x4*)((const float*)base + off); b1 = *(const f32x4*)((const float*)base + off + 4); }
;                     else { const u32x4 bb = *(const u32x4*)((const bf16_t*)base + off);
	s_setprio 1
	s_waitcnt lgkmcnt(0)
	v_mfma_f32_16x16x32_bf16 v[60:63], v[146:149], v[186:189], v[60:63]
	v_mfma_f32_16x16x32_bf16 v[56:59], v[162:165], v[186:189], v[56:59]
	v_mfma_f32_16x16x32_bf16 v[44:47], v[146:149], v[194:197], v[44:47]
	v_mfma_f32_16x16x32_bf16 v[40:43], v[162:165], v[194:197], v[40:43]
	v_mfma_f32_16x16x32_bf16 v[28:31], v[146:149], v[202:205], v[28:31]
	v_mfma_f32_16x16x32_bf16 v[24:27], v[162:165], v[202:205], v[24:27]
	v_mfma_f32_16x16x32_bf16 v[12:15], v[146:149], v[210:213], v[12:15]
	v_mfma_f32_16x16x32_bf16 v[8:11], v[162:165], v[210:213], v[8:11]
	v_mfma_f32_16x16x32_bf16 v[60:63], v[158:161], v[190:193], v[60:63]
	v_mfma_f32_16x16x32_bf16 v[56:59], v[166:169], v[190:193], v[56:59]
	v_mfma_f32_16x16x32_bf16 v[44:47], v[158:161], v[198:201], v[44:47]
	v_mfma_f32_16x16x32_bf16 v[40:43], v[166:169], v[198:201], v[40:43]
	v_mfma_f32_16x16x32_bf16 v[28:31], v[158:161], v[206:209], v[28:31]
	v_mfma_f32_16x16x32_bf16 v[24:27], v[166:169], v[206:209], v[24:27]
	v_mfma_f32_16x16x32_bf16 v[12:15], v[158:161], v[214:217], v[12:15]
	v_mfma_f32_16x16x32_bf16 v[8:11], v[166:169], v[214:217], v[8:11]
	s_setprio 0
	s_setprio 1
	v_mfma_f32_16x16x32_bf16 v[52:55], v[170:173], v[186:189], v[52:55]
	v_mfma_f32_16x16x32_bf16 v[48:51], v[178:181], v[186:189], v[48:51]
	v_mfma_f32_16x16x32_bf16 v[36:39], v[170:173], v[194:197], v[36:39]
	v_mfma_f32_16x16x32_bf16 v[32:35], v[178:181], v[194:197], v[32:35]
	v_mfma_f32_16x16x32_bf16 v[20:23], v[170:173], v[202:205], v[20:23]
	v_mfma_f32_16x16x32_bf16 v[16:19], v[178:181], v[202:205], v[16:19]
	v_mfma_f32_16x16x32_bf16 v[4:7], v[170:173], v[210:213], v[4:7]
	v_mfma_f32_16x16x32_bf16 v[0:3], v[178:181], v[210:213], v[0:3]
	v_mfma_f32_16x16x32_bf16 v[52:55], v[174:177], v[190:193], v[52:55]
	v_mfma_f32_16x16x32_bf16 v[48:51], v[182:185], v[190:193], v[48:51]
	v_mfma_f32_16x16x32_bf16 v[36:39], v[174:177], v[198:201], v[36:39]
	v_mfma_f32_16x16x32_bf16 v[32:35], v[182:185], v[198:201], v[32:35]
	v_mfma_f32_16x16x32_bf16 v[20:23], v[174:177], v[206:209], v[20:23]
	v_mfma_f32_16x16x32_bf16 v[16:19], v[182:185], v[206:209], v[16:19]
	v_mfma_f32_16x16x32_bf16 v[4:7], v[174:177], v[214:217], v[4:7]
	v_mfma_f32_16x16x32_bf16 v[0:3], v[182:185], v[214:217], v[0:3]
	s_setprio 0
	s_barrier
	s_add_i32 s83, s83, 2
	s_add_u32 s62, s62, 0x100
	s_addc_u32 s63, s63, 0
	s_add_u32 s78, s78, 0x100
	s_addc_u32 s79, s79, 0
	s_cmp_gt_u32 s83, 13
	s_cbranch_scc0 .LBB0_767
	s_mov_b32 s99, 1
	v_lshl_add_u32 v148, s58, 8, v150
	v_lshl_or_b32 v146, s60, 8, v136
	v_lshl_add_u32 v147, v148, 11, v146
	v_lshlrev_b32_e32 v159, 1, v147
	v_lshlrev_b32_e32 v208, 3, v148
	global_load_dwordx4 v[160:163], v159, s[28:29]
	global_load_dwordx4 v[164:167], v159, s[28:29] offset:64
	v_add_u32_e32 v149, 0x10000, v159
	global_load_dwordx4 v[168:171], v149, s[28:29]
	global_load_dwordx4 v[172:175], v149, s[28:29] offset:64
	v_add_u32_e32 v209, 0x20000, v159
	global_load_dwordx4 v[176:179], v209, s[28:29]
	global_load_dwordx4 v[180:183], v209, s[28:29] offset:64
	v_add_u32_e32 v149, 0x30000, v159
	global_load_dwordx4 v[184:187], v149, s[28:29]
	global_load_dwordx4 v[188:191], v149, s[28:29] offset:64
	v_add_u32_e32 v209, 0x80000, v159
	global_load_dwordx4 v[192:195], v209, s[28:29]
	global_load_dwordx4 v[196:199], v209, s[28:29] offset:64
	v_add_u32_e32 v149, 0x90000, v159
	global_load_dwordx4 v[200:203], v149, s[28:29]
	global_load_dwordx4 v[204:207], v149, s[28:29] offset:64
	v_add_u32_e32 v209, 0xa0000, v159
	global_load_dwordx4 v[212:215], v209, s[28:29]
	global_load_dwordx4 v[216:219], v209, s[28:29] offset:64
	v_add_u32_e32 v149, 0xb0000, v159
	global_load_dwordx4 v[220:223], v149, s[28:29]
	global_load_dwordx4 v[224:227], v149, s[28:29] offset:64
	s_and_b64 vcc, exec, s[48:49]
	s_cbranch_vccz .LBB0_770
	s_barrier

; #define PG8_STAGE(bufoff, gbase, voff) do { _Pragma("unroll") for (int _i = 0; _i < 2; ++_i) \
;         __builtin_amdgcn_global_load_lds((const unsigned*)((const char*)(gbase) + (voff)[_i]), (PG8_LAS unsigned*)(lds + (bufoff) + ldsw + _i * 8192), 16, 0, 0); } while (0)
; #define PG8_LDA(dst, b, h) do { _Pragma("unroll") for (int m = 0; m < 4; ++m) _Pragma("unroll") for (int k = 0; k < 2; ++k) dst[m][k] = *(const PG8_LAS bf16x8*)(lds + PG8_SA(b, h) + aoff + m * 2048 + k * 1024); } while (0)
; #define PG8_LDB(dst, b, h) do { _Pragma("unroll") for (int n = 0; n < 2; ++n) _Pragma("unroll") for (int k = 0; k < 2; ++k) dst[n][k] = *(const PG8_LAS bf16x8*)(lds + PG8_SB(b, h) + boff + n * 2048 + k * 1024); } while (0)
; #define PG8_MMA(ai, bj, At, Bt) do { __builtin_amdgcn_s_setprio(1); _Pragma("unroll") for (int m = 0; m < 4; ++m) _Pragma("unroll") for (int n = 0; n < 2; ++n) _Pragma("unroll") for (int k = 0; k < 2; ++k) \
;         acc[ai][bj][m][n] = __builtin_amdgcn_mfma_f32_16x16x32_bf16(Bt[n][k], At[m][k], acc[ai][bj][m][n], 0, 0, 0); __builtin_amdgcn_s_setprio(0); } while (0)
; #define PG8_WAIT_V(n) asm volatile("s_waitcnt vmcnt(" #n ")" ::: "memory")
; #define PG8_WAIT_L(n) asm volatile("s_waitcnt lgkmcnt(" #n ")" ::: "memory")
; #define PG8_BAR __builtin_amdgcn_s_barrier()
; #define PG8_SCHED __builtin_amdgcn_sched_barrier(0)
; template <class Epi, class Sched, bool ALIGN_EPI = false, bool SP2 = false>
; __device__ __forceinline__ void gemm_phase(PG8_LAS unsigned char* lds, const Gemm g, const Sched& S, const Epi& E, int tid_in) {
;     ...
;             PG8_LDB(B0, 0, 0); PG8_LDB(B1, 0, 1); PG8_SCHED; PG8_LDA(At, 0, 0); PG8_STAGE(PG8_SA(1, 1), a1 + hstep, voffA);
;             PG8_WAIT_V(8); PG8_WAIT_L(0); PG8_BAR; PG8_MMA(0, 0, At, B0); PG8_MMA(0, 1, At, B1); PG8_BAR; PG8_SCHED;
.Lkb_skip_6:
	ds_read_b128 v[156:159], v150
	ds_read_b128 v[160:163], v150 offset:1024
	ds_read_b128 v[164:167], v150 offset:2048
	ds_read_b128 v[168:171], v150 offset:3072
	ds_read_b128 v[172:175], v151
	ds_read_b128 v[176:179], v151 offset:1024
	ds_read_b128 v[180:183], v151 offset:2048
	ds_read_b128 v[184:187], v151 offset:3072
	s_add_u32 s26, s50, 0xfff80080
	s_addc_u32 s27, s51, -1
	s_cmp_eq_u32 s72, 28
	s_cselect_b32 s55, s41, s27
	s_cselect_b32 s54, s68, s26
	s_cselect_b32 s53, s39, s71
	s_cselect_b32 s52, s69, s70
	s_add_i32 m0, s49, 0xc000
	ds_read_b128 v[188:191], v152
	ds_read_b128 v[192:195], v152 offset:1024
	ds_read_b128 v[196:199], v152 offset:2048
	ds_read_b128 v[200:203], v152 offset:3072
	ds_read_b128 v[204:207], v152 offset:4096
	ds_read_b128 v[208:211], v152 offset:5120
	ds_read_b128 v[212:215], v152 offset:6144
	ds_read_b128 v[216:219], v152 offset:7168
	global_load_lds_dwordx4 v138, s[50:51]
	s_add_i32 m0, s49, 0xe000
	s_nop 0
	global_load_lds_dwordx4 v140, s[50:51]
	s_cmp_eq_u32 s99, 0
	s_cbranch_scc1 .Lw1s_6_0
	s_waitcnt vmcnt(24)
	s_branch .Lw1d_6_0

; #define PG8_STAGE(bufoff, gbase, voff) do { _Pragma("unroll") for (int _i = 0; _i < 2; ++_i) \
;         __builtin_amdgcn_global_load_lds((const unsigned*)((const char*)(gbase) + (voff)[_i]), (PG8_LAS unsigned*)(lds + (bufoff) + ldsw + _i * 8192), 16, 0, 0); } while (0)
; #define PG8_LDA(dst, b, h) do { _Pragma("unroll") for (int m = 0; m < 4; ++m) _Pragma("unroll") for (int k = 0; k < 2; ++k) dst[m][k] = *(const PG8_LAS bf16x8*)(lds + PG8_SA(b, h) + aoff + m * 2048 + k * 1024); } while (0)
; #define PG8_MMA(ai, bj, At, Bt) do { __builtin_amdgcn_s_setprio(1); _Pragma("unroll") for (int m = 0; m < 4; ++m) _Pragma("unroll") for (int n = 0; n < 2; ++n) _Pragma("unroll") for (int k = 0; k < 2; ++k) \
;         acc[ai][bj][m][n] = __builtin_amdgcn_mfma_f32_16x16x32_bf16(Bt[n][k], At[m][k], acc[ai][bj][m][n], 0, 0, 0); __builtin_amdgcn_s_setprio(0); } while (0)
; #define PG8_WAIT_V(n) asm volatile("s_waitcnt vmcnt(" #n ")" ::: "memory")
; #define PG8_WAIT_L(n) asm volatile("s_waitcnt lgkmcnt(" #n ")" ::: "memory")
; #define PG8_BAR __builtin_amdgcn_s_barrier()
; #define PG8_SCHED __builtin_amdgcn_sched_barrier(0)
; template <class Epi, class Sched, bool ALIGN_EPI = false, bool SP2 = false>
; __device__ __forceinline__ void gemm_phase(PG8_LAS unsigned char* lds, const Gemm g, const Sched& S, const Epi& E, int tid_in) {
;     ...
;             PG8_WAIT_V(8); PG8_WAIT_L(0); PG8_BAR; PG8_MMA(0, 0, At, B0); PG8_MMA(0, 1, At, B1); PG8_BAR; PG8_SCHED;
;             PG8_LDA(At, 0, 1); PG8_STAGE(PG8_SB(0, 0), b2, voffB); PG8_STAGE(PG8_SB(0, 1), b2 + hstepB, voffB); PG8_STAGE(PG8_SA(0, 0), a2, voffA);
;             PG8_WAIT_V(8); PG8_WAIT_L(0); PG8_BAR; PG8_MMA(1, 0, At, B0); PG8_MMA(1, 1, At, B1); PG8_BAR; PG8_SCHED;
.Lw1d_6_0:
	s_waitcnt lgkmcnt(0)
	s_barrier
	s_setprio 1
	s_waitcnt lgkmcnt(0)
	v_mfma_f32_16x16x32_bf16 v[124:127], v[156:159], v[188:191], 0
	v_mfma_f32_16x16x32_bf16 v[120:123], v[164:167], v[188:191], 0
	v_mfma_f32_16x16x32_bf16 v[108:111], v[156:159], v[196:199], 0
	v_mfma_f32_16x16x32_bf16 v[104:107], v[164:167], v[196:199], 0
	v_mfma_f32_16x16x32_bf16 v[92:95], v[156:159], v[204:207], 0
	v_mfma_f32_16x16x32_bf16 v[88:91], v[164:167], v[204:207], 0
	v_mfma_f32_16x16x32_bf16 v[76:79], v[156:159], v[212:215], 0
	v_mfma_f32_16x16x32_bf16 v[72:75], v[164:167], v[212:215], 0
	v_mfma_f32_16x16x32_bf16 v[124:127], v[160:163], v[192:195], v[124:127]
	v_mfma_f32_16x16x32_bf16 v[120:123], v[168:171], v[192:195], v[120:123]
	v_mfma_f32_16x16x32_bf16 v[108:111], v[160:163], v[200:203], v[108:111]
	v_mfma_f32_16x16x32_bf16 v[104:107], v[168:171], v[200:203], v[104:107]
	v_mfma_f32_16x16x32_bf16 v[92:95], v[160:163], v[208:211], v[92:95]
	v_mfma_f32_16x16x32_bf16 v[88:91], v[168:171], v[208:211], v[88:91]
	v_mfma_f32_16x16x32_bf16 v[76:79], v[160:163], v[216:219], v[76:79]
	v_mfma_f32_16x16x32_bf16 v[72:75], v[168:171], v[216:219], v[72:75]
	s_setprio 0
	s_setprio 1
	v_mfma_f32_16x16x32_bf16 v[116:119], v[172:175], v[188:191], 0
	v_mfma_f32_16x16x32_bf16 v[112:115], v[180:183], v[188:191], 0
	v_mfma_f32_16x16x32_bf16 v[100:103], v[172:175], v[196:199], 0
	v_mfma_f32_16x16x32_bf16 v[96:99], v[180:183], v[196:199], 0
	v_mfma_f32_16x16x32_bf16 v[84:87], v[172:175], v[204:207], 0
	v_mfma_f32_16x16x32_bf16 v[80:83], v[180:183], v[204:207], 0
	v_mfma_f32_16x16x32_bf16 v[68:71], v[172:175], v[212:215], 0
	v_mfma_f32_16x16x32_bf16 v[64:67], v[180:183], v[212:215], 0
	v_mfma_f32_16x16x32_bf16 v[116:119], v[176:179], v[192:195], v[116:119]
	v_mfma_f32_16x16x32_bf16 v[112:115], v[184:187], v[192:195], v[112:115]
	v_mfma_f32_16x16x32_bf16 v[100:103], v[176:179], v[200:203], v[100:103]
	v_mfma_f32_16x16x32_bf16 v[96:99], v[184:187], v[200:203], v[96:99]
	v_mfma_f32_16x16x32_bf16 v[84:87], v[176:179], v[208:211], v[84:87]
	v_mfma_f32_16x16x32_bf16 v[80:83], v[184:187], v[208:211], v[80:83]
	v_mfma_f32_16x16x32_bf16 v[68:71], v[176:179], v[216:219], v[68:71]
	v_mfma_f32_16x16x32_bf16 v[64:67], v[184:187], v[216:219], v[64:67]
	s_setprio 0
	s_barrier
	s_add_i32 s26, s64, s56
	s_mov_b32 m0, s26
	ds_read_b128 v[188:191], v152 offset:16384
	ds_read_b128 v[192:195], v152 offset:17408
	ds_read_b128 v[196:199], v152 offset:18432
	ds_read_b128 v[200:203], v152 offset:19456
	ds_read_b128 v[204:207], v152 offset:20480
	ds_read_b128 v[208:211], v152 offset:21504
	ds_read_b128 v[212:215], v152 offset:22528
	ds_read_b128 v[216:219], v152 offset:23552
	global_load_lds_dwordx4 v130, s[52:53]
	s_add_i32 m0, s26, 0x2000
	s_add_u32 s26, s52, 0x20000
	s_addc_u32 s27, s53, 0
	s_add_i32 s33, s65, s56
	global_load_lds_dwordx4 v134, s[52:53]
	s_mov_b32 m0, s33
	s_nop 0
	global_load_lds_dwordx4 v130, s[26:27]
	s_add_i32 m0, s33, 0x2000
	s_nop 0
	global_load_lds_dwordx4 v134, s[26:27]
	s_mov_b32 m0, s49
	s_nop 0
	global_load_lds_dwordx4 v128, s[54:55]
	s_mov_b32 m0, s57
	s_nop 0
	global_load_lds_dwordx4 v132, s[54:55]
	s_cmp_eq_u32 s99, 0
	s_cbranch_scc1 .Lw1s_6_1
	s_waitcnt vmcnt(24)
	s_branch .Lw1d_6_1

; #define PG8_STAGE(bufoff, gbase, voff) do { _Pragma("unroll") for (int _i = 0; _i < 2; ++_i) \
;         __builtin_amdgcn_global_load_lds((const unsigned*)((const char*)(gbase) + (voff)[_i]), (PG8_LAS unsigned*)(lds + (bufoff) + ldsw + _i * 8192), 16, 0, 0); } while (0)
; #define PG8_LDA(dst, b, h) do { _Pragma("unroll") for (int m = 0; m < 4; ++m) _Pragma("unroll") for (int k = 0; k < 2; ++k) dst[m][k] = *(const PG8_LAS bf16x8*)(lds + PG8_SA(b, h) + aoff + m * 2048 + k * 1024); } while (0)
; #define PG8_LDB(dst, b, h) do { _Pragma("unroll") for (int n = 0; n < 2; ++n) _Pragma("unroll") for (int k = 0; k < 2; ++k) dst[n][k] = *(const PG8_LAS bf16x8*)(lds + PG8_SB(b, h) + boff + n * 2048 + k * 1024); } while (0)
; #define PG8_MMA(ai, bj, At, Bt) do { __builtin_amdgcn_s_setprio(1); _Pragma("unroll") for (int m = 0; m < 4; ++m) _Pragma("unroll") for (int n = 0; n < 2; ++n) _Pragma("unroll") for (int k = 0; k < 2; ++k) \
;         acc[ai][bj][m][n] = __builtin_amdgcn_mfma_f32_16x16x32_bf16(Bt[n][k], At[m][k], acc[ai][bj][m][n], 0, 0, 0); __builtin_amdgcn_s_setprio(0); } while (0)
; #define PG8_WAIT_V(n) asm volatile("s_waitcnt vmcnt(" #n ")" ::: "memory")
; #define PG8_WAIT_L(n) asm volatile("s_waitcnt lgkmcnt(" #n ")" ::: "memory")
; #define PG8_BAR __builtin_amdgcn_s_barrier()
; #define PG8_SCHED __builtin_amdgcn_sched_barrier(0)
; template <class Epi, class Sched, bool ALIGN_EPI = false, bool SP2 = false>
; __device__ __forceinline__ void gemm_phase(PG8_LAS unsigned char* lds, const Gemm g, const Sched& S, const Epi& E, int tid_in) {
;     ...
;             PG8_WAIT_V(8); PG8_WAIT_L(0); PG8_BAR; PG8_MMA(1, 0, At, B0); PG8_MMA(1, 1, At, B1); PG8_BAR; PG8_SCHED;
;             PG8_LDB(B0, 1, 0); PG8_LDB(B1, 1, 1); PG8_SCHED; PG8_LDA(At, 1, 0); PG8_STAGE(PG8_SA(0, 1), a2 + hstep, voffA);
;             PG8_WAIT_V(8); PG8_WAIT_L(0); PG8_BAR; PG8_MMA(0, 0, At, B0); PG8_MMA(0, 1, At, B1); PG8_BAR; PG8_SCHED;
.Lw1d_6_1:
	s_waitcnt lgkmcnt(0)
	s_barrier
	s_setprio 1
	s_waitcnt lgkmcnt(0)
	v_mfma_f32_16x16x32_bf16 v[60:63], v[156:159], v[188:191], 0
	v_mfma_f32_16x16x32_bf16 v[56:59], v[164:167], v[188:191], 0
	v_mfma_f32_16x16x32_bf16 v[44:47], v[156:159], v[196:199], 0
	v_mfma_f32_16x16x32_bf16 v[40:43], v[164:167], v[196:199], 0
	v_mfma_f32_16x16x32_bf16 v[28:31], v[156:159], v[204:207], 0
	v_mfma_f32_16x16x32_bf16 v[24:27], v[164:167], v[204:207], 0
	v_mfma_f32_16x16x32_bf16 v[12:15], v[156:159], v[212:215], 0
	v_mfma_f32_16x16x32_bf16 v[8:11], v[164:167], v[212:215], 0
	v_mfma_f32_16x16x32_bf16 v[60:63], v[160:163], v[192:195], v[60:63]
	v_mfma_f32_16x16x32_bf16 v[56:59], v[168:171], v[192:195], v[56:59]
	v_mfma_f32_16x16x32_bf16 v[44:47], v[160:163], v[200:203], v[44:47]
	v_mfma_f32_16x16x32_bf16 v[40:43], v[168:171], v[200:203], v[40:43]
	v_mfma_f32_16x16x32_bf16 v[28:31], v[160:163], v[208:211], v[28:31]
	v_mfma_f32_16x16x32_bf16 v[24:27], v[168:171], v[208:211], v[24:27]
	v_mfma_f32_16x16x32_bf16 v[12:15], v[160:163], v[216:219], v[12:15]
	v_mfma_f32_16x16x32_bf16 v[8:11], v[168:171], v[216:219], v[8:11]
	s_setprio 0
	s_setprio 1
	v_mfma_f32_16x16x32_bf16 v[52:55], v[172:175], v[188:191], 0
	v_mfma_f32_16x16x32_bf16 v[48:51], v[180:183], v[188:191], 0
	v_mfma_f32_16x16x32_bf16 v[36:39], v[172:175], v[196:199], 0
	v_mfma_f32_16x16x32_bf16 v[32:35], v[180:183], v[196:199], 0
	v_mfma_f32_16x16x32_bf16 v[20:23], v[172:175], v[204:207], 0
	v_mfma_f32_16x16x32_bf16 v[16:19], v[180:183], v[204:207], 0
	v_mfma_f32_16x16x32_bf16 v[4:7], v[172:175], v[212:215], 0
	v_mfma_f32_16x16x32_bf16 v[0:3], v[180:183], v[212:215], 0
	v_mfma_f32_16x16x32_bf16 v[52:55], v[176:179], v[192:195], v[52:55]
	v_mfma_f32_16x16x32_bf16 v[48:51], v[184:187], v[192:195], v[48:51]
	v_mfma_f32_16x16x32_bf16 v[36:39], v[176:179], v[200:203], v[36:39]
	v_mfma_f32_16x16x32_bf16 v[32:35], v[184:187], v[200:203], v[32:35]
	v_mfma_f32_16x16x32_bf16 v[20:23], v[176:179], v[208:211], v[20:23]
	v_mfma_f32_16x16x32_bf16 v[16:19], v[184:187], v[208:211], v[16:19]
	v_mfma_f32_16x16x32_bf16 v[4:7], v[176:179], v[216:219], v[4:7]
	v_mfma_f32_16x16x32_bf16 v[0:3], v[184:187], v[216:219], v[0:3]
	s_setprio 0
	s_barrier
	s_add_i32 s33, 0, 0x18000
	v_add_u32_e32 v155, s33, v146
	s_add_i32 s73, 0, 0x1c000
	ds_read_b128 v[156:159], v155
	ds_read_b128 v[160:163], v155 offset:1024
	ds_read_b128 v[164:167], v155 offset:2048
	ds_read_b128 v[168:171], v155 offset:3072
	v_add_u32_e32 v155, s73, v146
	ds_read_b128 v[172:175], v155
	ds_read_b128 v[176:179], v155 offset:1024
	ds_read_b128 v[180:183], v155 offset:2048
	ds_read_b128 v[184:187], v155 offset:3072
	s_add_u32 s26, s54, 0x80000
	s_addc_u32 s27, s55, 0
	s_mov_b32 m0, s58
	ds_read_b128 v[188:191], v152 offset:32768
	ds_read_b128 v[192:195], v152 offset:33792
	ds_read_b128 v[196:199], v152 offset:34816
	ds_read_b128 v[200:203], v152 offset:35840
	ds_read_b128 v[204:207], v152 offset:36864
	ds_read_b128 v[208:211], v152 offset:37888
	ds_read_b128 v[212:215], v152 offset:38912
	ds_read_b128 v[216:219], v152 offset:39936
	global_load_lds_dwordx4 v128, s[26:27]
	s_mov_b32 m0, s59
	s_nop 0
	global_load_lds_dwordx4 v132, s[26:27]
	s_waitcnt vmcnt(8)
	s_waitcnt lgkmcnt(0)
	s_barrier
	s_setprio 1
	s_waitcnt lgkmcnt(0)
	v_mfma_f32_16x16x32_bf16 v[124:127], v[156:159], v[188:191], v[124:127]
	v_mfma_f32_16x16x32_bf16 v[120:123], v[164:167], v[188:191], v[120:123]
	v_mfma_f32_16x16x32_bf16 v[108:111], v[156:159], v[196:199], v[108:111]
	v_mfma_f32_16x16x32_bf16 v[104:107], v[164:167], v[196:199], v[104:107]
	v_mfma_f32_16x16x32_bf16 v[92:95], v[156:159], v[204:207], v[92:95]
	v_mfma_f32_16x16x32_bf16 v[88:91], v[164:167], v[204:207], v[88:91]
	v_mfma_f32_16x16x32_bf16 v[76:79], v[156:159], v[212:215], v[76:79]
	v_mfma_f32_16x16x32_bf16 v[72:75], v[164:167], v[212:215], v[72:75]
	v_mfma_f32_16x16x32_bf16 v[124:127], v[160:163], v[192:195], v[124:127]
	v_mfma_f32_16x16x32_bf16 v[120:123], v[168:171], v[192:195], v[120:123]
	v_mfma_f32_16x16x32_bf16 v[108:111], v[160:163], v[200:203], v[108:111]
	v_mfma_f32_16x16x32_bf16 v[104:107], v[168:171], v[200:203], v[104:107]
	v_mfma_f32_16x16x32_bf16 v[92:95], v[160:163], v[208:211], v[92:95]
	v_mfma_f32_16x16x32_bf16 v[88:91], v[168:171], v[208:211], v[88:91]
	v_mfma_f32_16x16x32_bf16 v[76:79], v[160:163], v[216:219], v[76:79]
	v_mfma_f32_16x16x32_bf16 v[72:75], v[168:171], v[216:219], v[72:75]
	s_setprio 0
	s_setprio 1
	v_mfma_f32_16x16x32_bf16 v[116:119], v[172:175], v[188:191], v[116:119]
	v_mfma_f32_16x16x32_bf16 v[112:115], v[180:183], v[188:191], v[112:115]
	v_mfma_f32_16x16x32_bf16 v[100:103], v[172:175], v[196:199], v[100:103]
	v_mfma_f32_16x16x32_bf16 v[96:99], v[180:183], v[196:199], v[96:99]
	v_mfma_f32_16x16x32_bf16 v[84:87], v[172:175], v[204:207], v[84:87]
	v_mfma_f32_16x16x32_bf16 v[80:83], v[180:183], v[204:207], v[80:83]
	v_mfma_f32_16x16x32_bf16 v[68:71], v[172:175], v[212:215], v[68:71]
	v_mfma_f32_16x16x32_bf16 v[64:67], v[180:183], v[212:215], v[64:67]
	v_mfma_f32_16x16x32_bf16 v[116:119], v[176:179], v[192:195], v[116:119]
	v_mfma_f32_16x16x32_bf16 v[112:115], v[184:187], v[192:195], v[112:115]
	v_mfma_f32_16x16x32_bf16 v[100:103], v[176:179], v[200:203], v[100:103]
	v_mfma_f32_16x16x32_bf16 v[96:99], v[184:187], v[200:203], v[96:99]
	v_mfma_f32_16x16x32_bf16 v[84:87], v[176:179], v[208:211], v[84:87]
	v_mfma_f32_16x16x32_bf16 v[80:83], v[184:187], v[208:211], v[80:83]
	v_mfma_f32_16x16x32_bf16 v[68:71], v[176:179], v[216:219], v[68:71]
	v_mfma_f32_16x16x32_bf16 v[64:67], v[184:187], v[216:219], v[64:67]
	s_setprio 0
	s_barrier
; #define PG8_STAGE(bufoff, gbase, voff) do { _Pragma("unroll") for (int _i = 0; _i < 2; ++_i) \
;         __builtin_amdgcn_global_load_lds((const unsigned*)((const char*)(gbase) + (voff)[_i]), (PG8_LAS unsigned*)(lds + (bufoff) + ldsw + _i * 8192), 16, 0, 0); } while (0)
; #define PG8_LDA(dst, b, h) do { _Pragma("unroll") for (int m = 0; m < 4; ++m) _Pragma("unroll") for (int k = 0; k < 2; ++k) dst[m][k] = *(const PG8_LAS bf16x8*)(lds + PG8_SA(b, h) + aoff + m * 2048 + k * 1024); } while (0)
; #define PG8_LDB(dst, b, h) do { _Pragma("unroll") for (int n = 0; n < 2; ++n) _Pragma("unroll") for (int k = 0; k < 2; ++k) dst[n][k] = *(const PG8_LAS bf16x8*)(lds + PG8_SB(b, h) + boff + n * 2048 + k * 1024); } while (0)
; #define PG8_MMA(ai, bj, At, Bt) do { __builtin_amdgcn_s_setprio(1); _Pragma("unroll") for (int m = 0; m < 4; ++m) _Pragma("unroll") for (int n = 0; n < 2; ++n) _Pragma("unroll") for (int k = 0; k < 2; ++k) \
;         acc[ai][bj][m][n] = __builtin_amdgcn_mfma_f32_16x16x32_bf16(Bt[n][k], At[m][k], acc[ai][bj][m][n], 0, 0, 0); __builtin_amdgcn_s_setprio(0); } while (0)
; #define PG8_BAR __builtin_amdgcn_s_barrier()
; template <class Epi, class Sched, bool ALIGN_EPI = false, bool SP2 = false>
; __device__ __forceinline__ void gemm_phase(PG8_LAS unsigned char* lds, const Gemm g, const Sched& S, const Epi& E, int tid_in) {
;     ...
;             PG8_LDB(B0, 0, 0); PG8_LDB(B1, 0, 1); PG8_SCHED; PG8_LDA(At, 0, 0); PG8_STAGE(PG8_SA(1, 1), a1 + hstep, voffA);
;             PG8_WAIT_V(8); PG8_WAIT_L(0); PG8_BAR; PG8_MMA(0, 0, At, B0); PG8_MMA(0, 1, At, B1); PG8_BAR; PG8_SCHED;
;             PG8_LDA(At, 0, 1); PG8_STAGE(PG8_SB(0, 0), b2, voffB); PG8_STAGE(PG8_SB(0, 1), b2 + hstepB, voffB); PG8_STAGE(PG8_SA(0, 0), a2, voffA);
;             PG8_WAIT_V(8); PG8_WAIT_L(0); PG8_BAR; PG8_MMA(1, 0, At, B0); PG8_MMA(1, 1, At, B1); PG8_BAR; PG8_SCHED;
;             PG8_LDB(B0, 1, 0); PG8_LDB(B1, 1, 1); PG8_SCHED; PG8_LDA(At, 1, 0); PG8_STAGE(PG8_SA(0, 1), a2 + hstep, voffA);
;             PG8_WAIT_V(8); PG8_WAIT_L(0); PG8_BAR; PG8_MMA(0, 0, At, B0); PG8_MMA(0, 1, At, B1); PG8_BAR; PG8_SCHED;
;             PG8_LDA(At, 1, 1); PG8_STAGE(PG8_SB(1, 0), b3, voffB); PG8_STAGE(PG8_SB(1, 1), b3 + hstepB, voffB); PG8_STAGE(PG8_SA(1, 0), a3, voffA);
;             PG8_WAIT_V(8); PG8_WAIT_L(0); PG8_BAR; PG8_MMA(1, 0, At, B0); PG8_MMA(1, 1, At, B1); PG8_BAR; PG8_SCHED;
	s_add_i32 s26, s33, s56
	s_add_i32 m0, s26, 0xffffff80
	ds_read_b128 v[188:191], v152 offset:49152
	ds_read_b128 v[192:195], v152 offset:50176
	ds_read_b128 v[196:199], v152 offset:51200
	ds_read_b128 v[200:203], v152 offset:52224
	ds_read_b128 v[204:207], v152 offset:53248
	ds_read_b128 v[208:211], v152 offset:54272
	ds_read_b128 v[212:215], v152 offset:55296
	ds_read_b128 v[216:219], v152 offset:56320
	global_load_lds_dwordx4 v130, s[52:53] offset:128
	s_add_i32 m0, s26, 0x1f80
	s_add_u32 s26, s52, 0x20080
	s_addc_u32 s27, s53, 0
	s_add_i32 s33, s73, s56
	global_load_lds_dwordx4 v134, s[52:53] offset:128
	s_mov_b32 m0, s33
	s_nop 0
	global_load_lds_dwordx4 v130, s[26:27]
	s_add_i32 m0, s33, 0x2000
	s_nop 0
	global_load_lds_dwordx4 v134, s[26:27]
	s_add_i32 m0, s62, 0xffffff80
	s_nop 0
	global_load_lds_dwordx4 v128, s[54:55] offset:128
	s_add_i32 m0, s63, 0xffffff80
	s_nop 0
	global_load_lds_dwordx4 v132, s[54:55] offset:128
	s_waitcnt vmcnt(8)
	s_waitcnt lgkmcnt(0)
	s_barrier
	s_setprio 1
	s_waitcnt lgkmcnt(0)
	v_mfma_f32_16x16x32_bf16 v[60:63], v[156:159], v[188:191], v[60:63]
	v_mfma_f32_16x16x32_bf16 v[56:59], v[164:167], v[188:191], v[56:59]
	v_mfma_f32_16x16x32_bf16 v[44:47], v[156:159], v[196:199], v[44:47]
	v_mfma_f32_16x16x32_bf16 v[40:43], v[164:167], v[196:199], v[40:43]
	v_mfma_f32_16x16x32_bf16 v[28:31], v[156:159], v[204:207], v[28:31]
	v_mfma_f32_16x16x32_bf16 v[24:27], v[164:167], v[204:207], v[24:27]
	v_mfma_f32_16x16x32_bf16 v[12:15], v[156:159], v[212:215], v[12:15]
	v_mfma_f32_16x16x32_bf16 v[8:11], v[164:167], v[212:215], v[8:11]
	v_mfma_f32_16x16x32_bf16 v[60:63], v[160:163], v[192:195], v[60:63]
	v_mfma_f32_16x16x32_bf16 v[56:59], v[168:171], v[192:195], v[56:59]
	v_mfma_f32_16x16x32_bf16 v[44:47], v[160:163], v[200:203], v[44:47]
	v_mfma_f32_16x16x32_bf16 v[40:43], v[168:171], v[200:203], v[40:43]
	v_mfma_f32_16x16x32_bf16 v[28:31], v[160:163], v[208:211], v[28:31]
	v_mfma_f32_16x16x32_bf16 v[24:27], v[168:171], v[208:211], v[24:27]
	v_mfma_f32_16x16x32_bf16 v[12:15], v[160:163], v[216:219], v[12:15]
	v_mfma_f32_16x16x32_bf16 v[8:11], v[168:171], v[216:219], v[8:11]
	s_setprio 0
	s_setprio 1
	v_mfma_f32_16x16x32_bf16 v[52:55], v[172:175], v[188:191], v[52:55]
	v_mfma_f32_16x16x32_bf16 v[48:51], v[180:183], v[188:191], v[48:51]
	v_mfma_f32_16x16x32_bf16 v[36:39], v[172:175], v[196:199], v[36:39]
	v_mfma_f32_16x16x32_bf16 v[32:35], v[180:183], v[196:199], v[32:35]
	v_mfma_f32_16x16x32_bf16 v[20:23], v[172:175], v[204:207], v[20:23]
	v_mfma_f32_16x16x32_bf16 v[16:19], v[180:183], v[204:207], v[16:19]
	v_mfma_f32_16x16x32_bf16 v[4:7], v[172:175], v[212:215], v[4:7]
	v_mfma_f32_16x16x32_bf16 v[0:3], v[180:183], v[212:215], v[0:3]
	v_mfma_f32_16x16x32_bf16 v[52:55], v[176:179], v[192:195], v[52:55]
	v_mfma_f32_16x16x32_bf16 v[48:51], v[184:187], v[192:195], v[48:51]
	v_mfma_f32_16x16x32_bf16 v[36:39], v[176:179], v[200:203], v[36:39]
	v_mfma_f32_16x16x32_bf16 v[32:35], v[184:187], v[200:203], v[32:35]
	v_mfma_f32_16x16x32_bf16 v[20:23], v[176:179], v[208:211], v[20:23]
	v_mfma_f32_16x16x32_bf16 v[16:19], v[184:187], v[208:211], v[16:19]
	v_mfma_f32_16x16x32_bf16 v[4:7], v[176:179], v[216:219], v[4:7]
	v_mfma_f32_16x16x32_bf16 v[0:3], v[184:187], v[216:219], v[0:3]
	s_setprio 0
	s_barrier
	s_add_i32 s72, s72, 2
	s_add_u32 s50, s50, 0x100
	s_addc_u32 s51, s51, 0
	s_add_u32 s70, s70, 0x100
	s_addc_u32 s71, s71, 0
	s_cmp_gt_u32 s72, 29
.LBB0_869:
	ds_read_b128 v[156:159], v150
	ds_read_b128 v[160:163], v150 offset:1024
	ds_read_b128 v[164:167], v150 offset:2048
	ds_read_b128 v[168:171], v150 offset:3072
	ds_read_b128 v[172:175], v151
	ds_read_b128 v[176:179], v151 offset:1024
	ds_read_b128 v[180:183], v151 offset:2048
	ds_read_b128 v[184:187], v151 offset:3072
	s_add_u32 s26, s50, 0xfff80080
	s_addc_u32 s27, s51, -1
	s_cmp_eq_u32 s72, 28
	s_cselect_b32 s55, s41, s27
	s_cselect_b32 s54, s68, s26
	s_cselect_b32 s53, s39, s71
	s_cselect_b32 s52, s69, s70
	s_add_i32 m0, s49, 0xc000
	ds_read_b128 v[188:191], v152
	ds_read_b128 v[192:195], v152 offset:1024
	ds_read_b128 v[196:199], v152 offset:2048
	ds_read_b128 v[200:203], v152 offset:3072
	ds_read_b128 v[204:207], v152 offset:4096
	ds_read_b128 v[208:211], v152 offset:5120
	ds_read_b128 v[212:215], v152 offset:6144
	ds_read_b128 v[216:219], v152 offset:7168
	global_load_lds_dwordx4 v138, s[50:51]
	s_add_i32 m0, s49, 0xe000
	s_nop 0
	global_load_lds_dwordx4 v140, s[50:51]
	s_waitcnt vmcnt(8)
	s_waitcnt lgkmcnt(0)
	s_barrier
; #define PG8_STAGE(bufoff, gbase, voff) do { _Pragma("unroll") for (int _i = 0; _i < 2; ++_i) \
;         __builtin_amdgcn_global_load_lds((const unsigned*)((const char*)(gbase) + (voff)[_i]), (PG8_LAS unsigned*)(lds + (bufoff) + ldsw + _i * 8192), 16, 0, 0); } while (0)
; #define PG8_LDA(dst, b, h) do { _Pragma("unroll") for (int m = 0; m < 4; ++m) _Pragma("unroll") for (int k = 0; k < 2; ++k) dst[m][k] = *(const PG8_LAS bf16x8*)(lds + PG8_SA(b, h) + aoff + m * 2048 + k * 1024); } while (0)
; #define PG8_MMA(ai, bj, At, Bt) do { __builtin_amdgcn_s_setprio(1); _Pragma("unroll") for (int m = 0; m < 4; ++m) _Pragma("unroll") for (int n = 0; n < 2; ++n) _Pragma("unroll") for (int k = 0; k < 2; ++k) \
;         acc[ai][bj][m][n] = __builtin_amdgcn_mfma_f32_16x16x32_bf16(Bt[n][k], At[m][k], acc[ai][bj][m][n], 0, 0, 0); __builtin_amdgcn_s_setprio(0); } while (0)
; #define PG8_WAIT_V(n) asm volatile("s_waitcnt vmcnt(" #n ")" ::: "memory")
; #define PG8_WAIT_L(n) asm volatile("s_waitcnt lgkmcnt(" #n ")" ::: "memory")
; #define PG8_BAR __builtin_amdgcn_s_barrier()
; #define PG8_SCHED __builtin_amdgcn_sched_barrier(0)
; template <class Epi, class Sched, bool ALIGN_EPI = false, bool SP2 = false>
; __device__ __forceinline__ void gemm_phase(PG8_LAS unsigned char* lds, const Gemm g, const Sched& S, const Epi& E, int tid_in) {
;     ...
;             PG8_WAIT_V(8); PG8_WAIT_L(0); PG8_BAR; PG8_MMA(0, 0, At, B0); PG8_MMA(0, 1, At, B1); PG8_BAR; PG8_SCHED;
;             PG8_LDA(At, 0, 1); PG8_STAGE(PG8_SB(0, 0), b2, voffB); PG8_STAGE(PG8_SB(0, 1), b2 + hstepB, voffB); PG8_STAGE(PG8_SA(0, 0), a2, voffA);
;             PG8_WAIT_V(8); PG8_WAIT_L(0); PG8_BAR; PG8_MMA(1, 0, At, B0); PG8_MMA(1, 1, At, B1); PG8_BAR; PG8_SCHED;
	s_setprio 1
	s_waitcnt lgkmcnt(0)
	v_mfma_f32_16x16x32_bf16 v[124:127], v[156:159], v[188:191], v[124:127]
	v_mfma_f32_16x16x32_bf16 v[120:123], v[164:167], v[188:191], v[120:123]
	v_mfma_f32_16x16x32_bf16 v[108:111], v[156:159], v[196:199], v[108:111]
	v_mfma_f32_16x16x32_bf16 v[104:107], v[164:167], v[196:199], v[104:107]
	v_mfma_f32_16x16x32_bf16 v[92:95], v[156:159], v[204:207], v[92:95]
	v_mfma_f32_16x16x32_bf16 v[88:91], v[164:167], v[204:207], v[88:91]
	v_mfma_f32_16x16x32_bf16 v[76:79], v[156:159], v[212:215], v[76:79]
	v_mfma_f32_16x16x32_bf16 v[72:75], v[164:167], v[212:215], v[72:75]
	v_mfma_f32_16x16x32_bf16 v[124:127], v[160:163], v[192:195], v[124:127]
	v_mfma_f32_16x16x32_bf16 v[120:123], v[168:171], v[192:195], v[120:123]
	v_mfma_f32_16x16x32_bf16 v[108:111], v[160:163], v[200:203], v[108:111]
	v_mfma_f32_16x16x32_bf16 v[104:107], v[168:171], v[200:203], v[104:107]
	v_mfma_f32_16x16x32_bf16 v[92:95], v[160:163], v[208:211], v[92:95]
	v_mfma_f32_16x16x32_bf16 v[88:91], v[168:171], v[208:211], v[88:91]
	v_mfma_f32_16x16x32_bf16 v[76:79], v[160:163], v[216:219], v[76:79]
	v_mfma_f32_16x16x32_bf16 v[72:75], v[168:171], v[216:219], v[72:75]
	s_setprio 0
	s_setprio 1
	v_mfma_f32_16x16x32_bf16 v[116:119], v[172:175], v[188:191], v[116:119]
	v_mfma_f32_16x16x32_bf16 v[112:115], v[180:183], v[188:191], v[112:115]
	v_mfma_f32_16x16x32_bf16 v[100:103], v[172:175], v[196:199], v[100:103]
	v_mfma_f32_16x16x32_bf16 v[96:99], v[180:183], v[196:199], v[96:99]
	v_mfma_f32_16x16x32_bf16 v[84:87], v[172:175], v[204:207], v[84:87]
	v_mfma_f32_16x16x32_bf16 v[80:83], v[180:183], v[204:207], v[80:83]
	v_mfma_f32_16x16x32_bf16 v[68:71], v[172:175], v[212:215], v[68:71]
	v_mfma_f32_16x16x32_bf16 v[64:67], v[180:183], v[212:215], v[64:67]
	v_mfma_f32_16x16x32_bf16 v[116:119], v[176:179], v[192:195], v[116:119]
	v_mfma_f32_16x16x32_bf16 v[112:115], v[184:187], v[192:195], v[112:115]
	v_mfma_f32_16x16x32_bf16 v[100:103], v[176:179], v[200:203], v[100:103]
	v_mfma_f32_16x16x32_bf16 v[96:99], v[184:187], v[200:203], v[96:99]
	v_mfma_f32_16x16x32_bf16 v[84:87], v[176:179], v[208:211], v[84:87]
	v_mfma_f32_16x16x32_bf16 v[80:83], v[184:187], v[208:211], v[80:83]
	v_mfma_f32_16x16x32_bf16 v[68:71], v[176:179], v[216:219], v[68:71]
	v_mfma_f32_16x16x32_bf16 v[64:67], v[184:187], v[216:219], v[64:67]
	s_setprio 0
	s_barrier
	s_add_i32 s26, s64, s56
	s_mov_b32 m0, s26
	ds_read_b128 v[188:191], v152 offset:16384
	ds_read_b128 v[192:195], v152 offset:17408
	ds_read_b128 v[196:199], v152 offset:18432
	ds_read_b128 v[200:203], v152 offset:19456
	ds_read_b128 v[204:207], v152 offset:20480
	ds_read_b128 v[208:211], v152 offset:21504
	ds_read_b128 v[212:215], v152 offset:22528
	ds_read_b128 v[216:219], v152 offset:23552
	global_load_lds_dwordx4 v130, s[52:53]
	s_add_i32 m0, s26, 0x2000
	s_add_u32 s26, s52, 0x20000
	s_addc_u32 s27, s53, 0
	s_add_i32 s33, s65, s56
	global_load_lds_dwordx4 v134, s[52:53]
	s_mov_b32 m0, s33
	s_nop 0
	global_load_lds_dwordx4 v130, s[26:27]
	s_add_i32 m0, s33, 0x2000
	s_nop 0
	global_load_lds_dwordx4 v134, s[26:27]
	s_mov_b32 m0, s49
	s_nop 0
	global_load_lds_dwordx4 v128, s[54:55]
	s_mov_b32 m0, s57
	s_nop 0
	global_load_lds_dwordx4 v132, s[54:55]
	s_waitcnt vmcnt(8)
	s_waitcnt lgkmcnt(0)
	s_barrier
	s_setprio 1
	s_waitcnt lgkmcnt(0)
	v_mfma_f32_16x16x32_bf16 v[60:63], v[156:159], v[188:191], v[60:63]
	v_mfma_f32_16x16x32_bf16 v[56:59], v[164:167], v[188:191], v[56:59]
	v_mfma_f32_16x16x32_bf16 v[44:47], v[156:159], v[196:199], v[44:47]
	v_mfma_f32_16x16x32_bf16 v[40:43], v[164:167], v[196:199], v[40:43]
	v_mfma_f32_16x16x32_bf16 v[28:31], v[156:159], v[204:207], v[28:31]
	v_mfma_f32_16x16x32_bf16 v[24:27], v[164:167], v[204:207], v[24:27]
	v_mfma_f32_16x16x32_bf16 v[12:15], v[156:159], v[212:215], v[12:15]
	v_mfma_f32_16x16x32_bf16 v[8:11], v[164:167], v[212:215], v[8:11]
	v_mfma_f32_16x16x32_bf16 v[60:63], v[160:163], v[192:195], v[60:63]
	v_mfma_f32_16x16x32_bf16 v[56:59], v[168:171], v[192:195], v[56:59]
	v_mfma_f32_16x16x32_bf16 v[44:47], v[160:163], v[200:203], v[44:47]
	v_mfma_f32_16x16x32_bf16 v[40:43], v[168:171], v[200:203], v[40:43]
	v_mfma_f32_16x16x32_bf16 v[28:31], v[160:163], v[208:211], v[28:31]
	v_mfma_f32_16x16x32_bf16 v[24:27], v[168:171], v[208:211], v[24:27]
	v_mfma_f32_16x16x32_bf16 v[12:15], v[160:163], v[216:219], v[12:15]
	v_mfma_f32_16x16x32_bf16 v[8:11], v[168:171], v[216:219], v[8:11]
	s_setprio 0
	s_setprio 1
	v_mfma_f32_16x16x32_bf16 v[52:55], v[172:175], v[188:191], v[52:55]
	v_mfma_f32_16x16x32_bf16 v[48:51], v[180:183], v[188:191], v[48:51]
	v_mfma_f32_16x16x32_bf16 v[36:39], v[172:175], v[196:199], v[36:39]
	v_mfma_f32_16x16x32_bf16 v[32:35], v[180:183], v[196:199], v[32:35]
	v_mfma_f32_16x16x32_bf16 v[20:23], v[172:175], v[204:207], v[20:23]
	v_mfma_f32_16x16x32_bf16 v[16:19], v[180:183], v[204:207], v[16:19]
	v_mfma_f32_16x16x32_bf16 v[4:7], v[172:175], v[212:215], v[4:7]
	v_mfma_f32_16x16x32_bf16 v[0:3], v[180:183], v[212:215], v[0:3]
	v_mfma_f32_16x16x32_bf16 v[52:55], v[176:179], v[192:195], v[52:55]
	v_mfma_f32_16x16x32_bf16 v[48:51], v[184:187], v[192:195], v[48:51]
	v_mfma_f32_16x16x32_bf16 v[36:39], v[176:179], v[200:203], v[36:39]
	v_mfma_f32_16x16x32_bf16 v[32:35], v[184:187], v[200:203], v[32:35]
	v_mfma_f32_16x16x32_bf16 v[20:23], v[176:179], v[208:211], v[20:23]
	v_mfma_f32_16x16x32_bf16 v[16:19], v[184:187], v[208:211], v[16:19]
	v_mfma_f32_16x16x32_bf16 v[4:7], v[176:179], v[216:219], v[4:7]
	v_mfma_f32_16x16x32_bf16 v[0:3], v[184:187], v[216:219], v[0:3]
	s_setprio 0
	s_barrier
; #define PG8_STAGE(bufoff, gbase, voff) do { _Pragma("unroll") for (int _i = 0; _i < 2; ++_i) \
;         __builtin_amdgcn_global_load_lds((const unsigned*)((const char*)(gbase) + (voff)[_i]), (PG8_LAS unsigned*)(lds + (bufoff) + ldsw + _i * 8192), 16, 0, 0); } while (0)
; #define PG8_LDA(dst, b, h) do { _Pragma("unroll") for (int m = 0; m < 4; ++m) _Pragma("unroll") for (int k = 0; k < 2; ++k) dst[m][k] = *(const PG8_LAS bf16x8*)(lds + PG8_SA(b, h) + aoff + m * 2048 + k * 1024); } while (0)
; #define PG8_LDB(dst, b, h) do { _Pragma("unroll") for (int n = 0; n < 2; ++n) _Pragma("unroll") for (int k = 0; k < 2; ++k) dst[n][k] = *(const PG8_LAS bf16x8*)(lds + PG8_SB(b, h) + boff + n * 2048 + k * 1024); } while (0)
; #define PG8_MMA(ai, bj, At, Bt) do { __builtin_amdgcn_s_setprio(1); _Pragma("unroll") for (int m = 0; m < 4; ++m) _Pragma("unroll") for (int n = 0; n < 2; ++n) _Pragma("unroll") for (int k = 0; k < 2; ++k) \
;         acc[ai][bj][m][n] = __builtin_amdgcn_mfma_f32_16x16x32_bf16(Bt[n][k], At[m][k], acc[ai][bj][m][n], 0, 0, 0); __builtin_amdgcn_s_setprio(0); } while (0)
; #define PG8_BAR __builtin_amdgcn_s_barrier()
; template <class Epi, class Sched, bool ALIGN_EPI = false, bool SP2 = false>
; __device__ __forceinline__ void gemm_phase(PG8_LAS unsigned char* lds, const Gemm g, const Sched& S, const Epi& E, int tid_in) {
;     ...
;             PG8_LDB(B0, 0, 0); PG8_LDB(B1, 0, 1); PG8_SCHED; PG8_LDA(At, 0, 0); PG8_STAGE(PG8_SA(1, 1), a1 + hstep, voffA);
;             PG8_WAIT_V(8); PG8_WAIT_L(0); PG8_BAR; PG8_MMA(0, 0, At, B0); PG8_MMA(0, 1, At, B1); PG8_BAR; PG8_SCHED;
;             PG8_LDA(At, 0, 1); PG8_STAGE(PG8_SB(0, 0), b2, voffB); PG8_STAGE(PG8_SB(0, 1), b2 + hstepB, voffB); PG8_STAGE(PG8_SA(0, 0), a2, voffA);
;             PG8_WAIT_V(8); PG8_WAIT_L(0); PG8_BAR; PG8_MMA(1, 0, At, B0); PG8_MMA(1, 1, At, B1); PG8_BAR; PG8_SCHED;
;             PG8_LDB(B0, 1, 0); PG8_LDB(B1, 1, 1); PG8_SCHED; PG8_LDA(At, 1, 0); PG8_STAGE(PG8_SA(0, 1), a2 + hstep, voffA);
;             PG8_WAIT_V(8); PG8_WAIT_L(0); PG8_BAR; PG8_MMA(0, 0, At, B0); PG8_MMA(0, 1, At, B1); PG8_BAR; PG8_SCHED;
;             PG8_LDA(At, 1, 1); PG8_STAGE(PG8_SB(1, 0), b3, voffB); PG8_STAGE(PG8_SB(1, 1), b3 + hstepB, voffB); PG8_STAGE(PG8_SA(1, 0), a3, voffA);
;             PG8_WAIT_V(8); PG8_WAIT_L(0); PG8_BAR; PG8_MMA(1, 0, At, B0); PG8_MMA(1, 1, At, B1); PG8_BAR; PG8_SCHED;
	s_add_i32 s33, 0, 0x18000
	v_add_u32_e32 v155, s33, v146
	s_add_i32 s73, 0, 0x1c000
	ds_read_b128 v[156:159], v155
	ds_read_b128 v[160:163], v155 offset:1024
	ds_read_b128 v[164:167], v155 offset:2048
	ds_read_b128 v[168:171], v155 offset:3072
	v_add_u32_e32 v155, s73, v146
	ds_read_b128 v[172:175], v155
	ds_read_b128 v[176:179], v155 offset:1024
	ds_read_b128 v[180:183], v155 offset:2048
	ds_read_b128 v[184:187], v155 offset:3072
	s_add_u32 s26, s54, 0x80000
	s_addc_u32 s27, s55, 0
	s_mov_b32 m0, s58
	ds_read_b128 v[188:191], v152 offset:32768
	ds_read_b128 v[192:195], v152 offset:33792
	ds_read_b128 v[196:199], v152 offset:34816
	ds_read_b128 v[200:203], v152 offset:35840
	ds_read_b128 v[204:207], v152 offset:36864
	ds_read_b128 v[208:211], v152 offset:37888
	ds_read_b128 v[212:215], v152 offset:38912
	ds_read_b128 v[216:219], v152 offset:39936
	global_load_lds_dwordx4 v128, s[26:27]
	s_mov_b32 m0, s59
	s_nop 0
	global_load_lds_dwordx4 v132, s[26:27]
	s_waitcnt vmcnt(8)
	s_waitcnt lgkmcnt(0)
	s_barrier
	s_setprio 1
	s_waitcnt lgkmcnt(0)
	v_mfma_f32_16x16x32_bf16 v[124:127], v[156:159], v[188:191], v[124:127]
	v_mfma_f32_16x16x32_bf16 v[120:123], v[164:167], v[188:191], v[120:123]
	v_mfma_f32_16x16x32_bf16 v[108:111], v[156:159], v[196:199], v[108:111]
	v_mfma_f32_16x16x32_bf16 v[104:107], v[164:167], v[196:199], v[104:107]
	v_mfma_f32_16x16x32_bf16 v[92:95], v[156:159], v[204:207], v[92:95]
	v_mfma_f32_16x16x32_bf16 v[88:91], v[164:167], v[204:207], v[88:91]
	v_mfma_f32_16x16x32_bf16 v[76:79], v[156:159], v[212:215], v[76:79]
	v_mfma_f32_16x16x32_bf16 v[72:75], v[164:167], v[212:215], v[72:75]
	v_mfma_f32_16x16x32_bf16 v[124:127], v[160:163], v[192:195], v[124:127]
	v_mfma_f32_16x16x32_bf16 v[120:123], v[168:171], v[192:195], v[120:123]
	v_mfma_f32_16x16x32_bf16 v[108:111], v[160:163], v[200:203], v[108:111]
	v_mfma_f32_16x16x32_bf16 v[104:107], v[168:171], v[200:203], v[104:107]
	v_mfma_f32_16x16x32_bf16 v[92:95], v[160:163], v[208:211], v[92:95]
	v_mfma_f32_16x16x32_bf16 v[88:91], v[168:171], v[208:211], v[88:91]
	v_mfma_f32_16x16x32_bf16 v[76:79], v[160:163], v[216:219], v[76:79]
	v_mfma_f32_16x16x32_bf16 v[72:75], v[168:171], v[216:219], v[72:75]
	s_setprio 0
	s_setprio 1
	v_mfma_f32_16x16x32_bf16 v[116:119], v[172:175], v[188:191], v[116:119]
	v_mfma_f32_16x16x32_bf16 v[112:115], v[180:183], v[188:191], v[112:115]
	v_mfma_f32_16x16x32_bf16 v[100:103], v[172:175], v[196:199], v[100:103]
	v_mfma_f32_16x16x32_bf16 v[96:99], v[180:183], v[196:199], v[96:99]
	v_mfma_f32_16x16x32_bf16 v[84:87], v[172:175], v[204:207], v[84:87]
	v_mfma_f32_16x16x32_bf16 v[80:83], v[180:183], v[204:207], v[80:83]
	v_mfma_f32_16x16x32_bf16 v[68:71], v[172:175], v[212:215], v[68:71]
	v_mfma_f32_16x16x32_bf16 v[64:67], v[180:183], v[212:215], v[64:67]
	v_mfma_f32_16x16x32_bf16 v[116:119], v[176:179], v[192:195], v[116:119]
	v_mfma_f32_16x16x32_bf16 v[112:115], v[184:187], v[192:195], v[112:115]
	v_mfma_f32_16x16x32_bf16 v[100:103], v[176:179], v[200:203], v[100:103]
	v_mfma_f32_16x16x32_bf16 v[96:99], v[184:187], v[200:203], v[96:99]
	v_mfma_f32_16x16x32_bf16 v[84:87], v[176:179], v[208:211], v[84:87]
	v_mfma_f32_16x16x32_bf16 v[80:83], v[184:187], v[208:211], v[80:83]
	v_mfma_f32_16x16x32_bf16 v[68:71], v[176:179], v[216:219], v[68:71]
	v_mfma_f32_16x16x32_bf16 v[64:67], v[184:187], v[216:219], v[64:67]
	s_setprio 0
	s_barrier
	s_add_i32 s26, s33, s56
	s_add_i32 m0, s26, 0xffffff80
	ds_read_b128 v[188:191], v152 offset:49152
	ds_read_b128 v[192:195], v152 offset:50176
	ds_read_b128 v[196:199], v152 offset:51200
	ds_read_b128 v[200:203], v152 offset:52224
	ds_read_b128 v[204:207], v152 offset:53248
	ds_read_b128 v[208:211], v152 offset:54272
	ds_read_b128 v[212:215], v152 offset:55296
	ds_read_b128 v[216:219], v152 offset:56320
	global_load_lds_dwordx4 v130, s[52:53] offset:128
	s_add_i32 m0, s26, 0x1f80
	s_add_u32 s26, s52, 0x20080
	s_addc_u32 s27, s53, 0
	s_add_i32 s33, s73, s56
	global_load_lds_dwordx4 v134, s[52:53] offset:128
	s_mov_b32 m0, s33
	s_nop 0
	global_load_lds_dwordx4 v130, s[26:27]
	s_add_i32 m0, s33, 0x2000
	s_nop 0
	global_load_lds_dwordx4 v134, s[26:27]
	s_add_i32 m0, s62, 0xffffff80
	s_nop 0
	global_load_lds_dwordx4 v128, s[54:55] offset:128
	s_add_i32 m0, s63, 0xffffff80
	s_nop 0
	global_load_lds_dwordx4 v132, s[54:55] offset:128
	s_waitcnt vmcnt(8)
	s_waitcnt lgkmcnt(0)
	s_barrier
	s_setprio 1
	s_waitcnt lgkmcnt(0)
	v_mfma_f32_16x16x32_bf16 v[60:63], v[156:159], v[188:191], v[60:63]
	v_mfma_f32_16x16x32_bf16 v[56:59], v[164:167], v[188:191], v[56:59]
	v_mfma_f32_16x16x32_bf16 v[44:47], v[156:159], v[196:199], v[44:47]
	v_mfma_f32_16x16x32_bf16 v[40:43], v[164:167], v[196:199], v[40:43]
	v_mfma_f32_16x16x32_bf16 v[28:31], v[156:159], v[204:207], v[28:31]
	v_mfma_f32_16x16x32_bf16 v[24:27], v[164:167], v[204:207], v[24:27]
	v_mfma_f32_16x16x32_bf16 v[12:15], v[156:159], v[212:215], v[12:15]
	v_mfma_f32_16x16x32_bf16 v[8:11], v[164:167], v[212:215], v[8:11]
	v_mfma_f32_16x16x32_bf16 v[60:63], v[160:163], v[192:195], v[60:63]
	v_mfma_f32_16x16x32_bf16 v[56:59], v[168:171], v[192:195], v[56:59]
	v_mfma_f32_16x16x32_bf16 v[44:47], v[160:163], v[200:203], v[44:47]
	v_mfma_f32_16x16x32_bf16 v[40:43], v[168:171], v[200:203], v[40:43]
	v_mfma_f32_16x16x32_bf16 v[28:31], v[160:163], v[208:211], v[28:31]
	v_mfma_f32_16x16x32_bf16 v[24:27], v[168:171], v[208:211], v[24:27]
	v_mfma_f32_16x16x32_bf16 v[12:15], v[160:163], v[216:219], v[12:15]
	v_mfma_f32_16x16x32_bf16 v[8:11], v[168:171], v[216:219], v[8:11]
	s_setprio 0
	s_setprio 1
	v_mfma_f32_16x16x32_bf16 v[52:55], v[172:175], v[188:191], v[52:55]
	v_mfma_f32_16x16x32_bf16 v[48:51], v[180:183], v[188:191], v[48:51]
	v_mfma_f32_16x16x32_bf16 v[36:39], v[172:175], v[196:199], v[36:39]
	v_mfma_f32_16x16x32_bf16 v[32:35], v[180:183], v[196:199], v[32:35]
	v_mfma_f32_16x16x32_bf16 v[20:23], v[172:175], v[204:207], v[20:23]
	v_mfma_f32_16x16x32_bf16 v[16:19], v[180:183], v[204:207], v[16:19]
	v_mfma_f32_16x16x32_bf16 v[4:7], v[172:175], v[212:215], v[4:7]
	v_mfma_f32_16x16x32_bf16 v[0:3], v[180:183], v[212:215], v[0:3]
	v_mfma_f32_16x16x32_bf16 v[52:55], v[176:179], v[192:195], v[52:55]
	v_mfma_f32_16x16x32_bf16 v[48:51], v[184:187], v[192:195], v[48:51]
	v_mfma_f32_16x16x32_bf16 v[36:39], v[176:179], v[200:203], v[36:39]
	v_mfma_f32_16x16x32_bf16 v[32:35], v[184:187], v[200:203], v[32:35]
	v_mfma_f32_16x16x32_bf16 v[20:23], v[176:179], v[208:211], v[20:23]
	v_mfma_f32_16x16x32_bf16 v[16:19], v[184:187], v[208:211], v[16:19]
	v_mfma_f32_16x16x32_bf16 v[4:7], v[176:179], v[216:219], v[4:7]
	v_mfma_f32_16x16x32_bf16 v[0:3], v[184:187], v[216:219], v[0:3]
	s_setprio 0
	s_barrier
	s_add_i32 s72, s72, 2
	s_add_u32 s50, s50, 0x100
	s_addc_u32 s51, s51, 0
	s_add_u32 s70, s70, 0x100
	s_addc_u32 s71, s71, 0
	s_cmp_gt_u32 s72, 29
	s_cbranch_scc0 .LBB0_869
	s_mov_b32 s99, 1
	s_and_b64 vcc, exec, s[36:37]
	s_cbranch_vccz .LBB0_872
	s_barrier

; #define PG8_STAGE(bufoff, gbase, voff) do { _Pragma("unroll") for (int _i = 0; _i < 2; ++_i) \
;         __builtin_amdgcn_global_load_lds((const unsigned*)((const char*)(gbase) + (voff)[_i]), (PG8_LAS unsigned*)(lds + (bufoff) + ldsw + _i * 8192), 16, 0, 0); } while (0)
; #define PG8_WAIT_V(n) asm volatile("s_waitcnt vmcnt(" #n ")" ::: "memory")
; #define PG8_BAR __builtin_amdgcn_s_barrier()
; template <class Epi, class Sched, bool ALIGN_EPI = false, bool SP2 = false>
; __device__ __forceinline__ void gemm_phase(PG8_LAS unsigned char* lds, const Gemm g, const Sched& S, const Epi& E, int tid_in) {
;     ...
;     const char* cA = (const char*)g.A + (size_t)cur.pm * tstep; const char* cB = (const char*)g.Bt + (size_t)cur.pn * tstepB;
;     S.a_ready(cur);
;     if constexpr (SP2) {
;         PG8_STAGE(PG8_SB(0, 0), cB, voffB); PG8_STAGE(PG8_SB(0, 1), cB + hstepB, voffB); PG8_STAGE(PG8_SA(0, 0), cA, voffA); PG8_STAGE(PG8_SA(0, 1), cA + hstep, voffA);
;         if (wr == 1) PG8_BAR;
;         PG8_WAIT_V(2); PG8_BAR;
;         PG8_STAGE(PG8_SB(1, 0), cB + kstep, voffB); PG8_STAGE(PG8_SA(1, 0), cA + kstep, voffA); PG8_STAGE(PG8_SB(1, 1), cB + hstepB + kstep, voffB);
;         PG8_WAIT_V(6); PG8_BAR;
.LBB0_937:
	s_mov_b64 s[38:39], 0x80
	s_and_b32 s6, s6, 3
	s_add_i32 m0, s49, 0x18000
	v_lshl_add_u64 v[6:7], v[6:7], 0, s[38:39]
	s_lshl_b32 s9, s7, 13
	s_lshl_b32 s11, s6, 12
	s_waitcnt vmcnt(2)
	s_barrier
	global_load_lds_dwordx4 v[6:7], off
	v_lshl_add_u64 v[4:5], v[4:5], 0, s[38:39]
	s_add_i32 m0, s49, 0x1a000
	s_add_i32 s61, s49, 0x8000
	s_add_i32 s62, s49, 0xa000
	global_load_lds_dwordx4 v[4:5], off
	v_lshl_add_u64 v[0:1], v[0:1], 0, s[38:39]
	s_mov_b32 m0, s61
	s_add_u32 s26, s52, 0x80080
	global_load_lds_dwordx4 v[0:1], off
	v_lshl_add_u64 v[0:1], v[2:3], 0, s[38:39]
	s_mov_b32 m0, s62
	s_addc_u32 s27, s53, 0
	global_load_lds_dwordx4 v[0:1], off
	s_add_i32 m0, s49, 0x1c000
	v_lshl_add_u64 v[0:1], s[26:27], 0, v[130:131]
	global_load_lds_dwordx4 v[0:1], off
	v_lshl_add_u64 v[0:1], s[26:27], 0, v[134:135]
	s_add_i32 m0, s49, 0x1e000
	v_and_b32_e32 v2, 48, v8
	global_load_lds_dwordx4 v[0:1], off
	v_and_b32_e32 v0, 15, v8
	v_lshlrev_b32_e32 v3, 2, v8
	v_lshl_or_b32 v1, v0, 6, v2
	v_and_b32_e32 v3, 32, v3
	s_cmpk_lt_u32 s10, 0x100
	v_bitop3_b32 v4, v1, s9, v3 bitop3:0xde
	s_cselect_b64 s[40:41], -1, 0
	s_lshl_b32 s9, s7, 2
	s_or_b32 s9, s9, s6
	s_mulk_i32 s9, 0x900
	v_bitop3_b32 v137, v1, s11, v3 bitop3:0xde
	v_and_b32_e32 v3, 3, v8
	s_add_i32 s9, s9, 0
	v_bfe_u32 v1, v8, 2, 4
	v_lshlrev_b32_e32 v5, 3, v3
	s_add_i32 s9, s9, 0x20000
	v_lshl_or_b32 v150, s7, 6, v1
	v_lshl_or_b32 v136, s6, 6, v5
	v_lshlrev_b32_e32 v5, 5, v3
	v_cmp_eq_u32_e64 s[6:7], 0, v3
	s_movk_i32 s10, 0x90
	v_mov_b32_e32 v3, s9
	v_mad_u32_u24 v6, v0, s10, v3
	v_and_b32_e32 v0, 64, v252
	v_add_u32_e32 v0, 64, v0
	v_cmp_lt_i32_e32 vcc, v254, v0
	v_mad_u32_u24 v3, v1, s10, v3
	s_mov_b32 s9, 0x20400
	v_cndmask_b32_e32 v1, v252, v254, vcc
	v_cmp_lt_i32_e32 vcc, v253, v0
	v_lshlrev_b32_e32 v151, 2, v1
	v_lshrrev_b32_e32 v1, 1, v9
	v_cndmask_b32_e32 v0, v252, v253, vcc
	v_lshlrev_b32_e32 v152, 2, v0
	v_mul_lo_u32 v0, v11, s8
	v_mad_u64_u32 v[0:1], s[10:11], v1, s9, v[0:1]
	v_or_b32_e32 v0, v0, v10
	v_add_lshl_u32 v0, v0, v12, 1
	v_mov_b32_e32 v1, v131
	s_mov_b64 s[10:11], 0x204080
	v_lshl_add_u64 v[138:139], v[0:1], 0, s[10:11]
	v_lshrrev_b32_e32 v1, 1, v13
	v_mul_lo_u32 v0, v14, s8
	v_mad_u64_u32 v[0:1], s[8:9], v1, s9, v[0:1]
	s_waitcnt vmcnt(6)
	v_or_b32_e32 v0, v0, v15
	v_add_lshl_u32 v0, v0, v16, 1
	v_mov_b32_e32 v1, v131
	s_add_i32 s63, 0, 0x10000
	s_add_i32 s64, 0, 0x14000
	v_lshl_add_u64 v[140:141], v[0:1], 0, s[10:11]
	v_mov_b64_e32 v[142:143], 0x400
	v_mov_b64_e32 v[144:145], 0x3ff
	v_add_u32_e32 v153, s63, v137
	v_add_u32_e32 v154, s64, v137
	v_add_u32_e32 v155, 0, v4
	v_add_u32_e32 v156, v6, v2
	v_add_u32_e32 v157, v3, v5
	s_barrier
	s_mov_b32 s99, 0
	s_branch .LBB0_940

; #define PG8_STAGE(bufoff, gbase, voff) do { _Pragma("unroll") for (int _i = 0; _i < 2; ++_i) \
;         __builtin_amdgcn_global_load_lds((const unsigned*)((const char*)(gbase) + (voff)[_i]), (PG8_LAS unsigned*)(lds + (bufoff) + ldsw + _i * 8192), 16, 0, 0); } while (0)
; #define PG8_LDA(dst, b, h) do { _Pragma("unroll") for (int m = 0; m < 4; ++m) _Pragma("unroll") for (int k = 0; k < 2; ++k) dst[m][k] = *(const PG8_LAS bf16x8*)(lds + PG8_SA(b, h) + aoff + m * 2048 + k * 1024); } while (0)
; #define PG8_LDB(dst, b, h) do { _Pragma("unroll") for (int n = 0; n < 2; ++n) _Pragma("unroll") for (int k = 0; k < 2; ++k) dst[n][k] = *(const PG8_LAS bf16x8*)(lds + PG8_SB(b, h) + boff + n * 2048 + k * 1024); } while (0)
; #define PG8_SCHED __builtin_amdgcn_sched_barrier(0)
; template <class Epi, class Sched, bool ALIGN_EPI = false, bool SP2 = false>
; __device__ __forceinline__ void gemm_phase(PG8_LAS unsigned char* lds, const Gemm g, const Sched& S, const Epi& E, int tid_in) {
;     ...
;         const char* nA = has_next ? (const char*)g.A + (size_t)nxt.pm * tstep : cA; const char* nB = has_next ? (const char*)g.Bt + (size_t)nxt.pn * tstepB : cB;
;         for (int t = 0; t < nt; t += 2) {
;             const bool last = (t == nt - 2);
;             const char* a1 = cA + (size_t)(t + 1) * kstep;
;             const char* a2 = last ? nA : cA + (size_t)(t + 2) * kstep; const char* b2 = last ? nB : cB + (size_t)(t + 2) * kstep;
;             const char* a3 = a2 + kstep; const char* b3 = b2 + kstep;
;             if (last && has_next) S.a_ready(nxt);
;             if constexpr (SP2) {
;             PG8_LDB(B0, 0, 0); PG8_LDB(B1, 0, 1); PG8_SCHED; PG8_LDA(At, 0, 0); PG8_STAGE(PG8_SA(1, 1), a1 + hstep, voffA);
.Lkb_skip_7:
	ds_read_b128 v[146:149], v153
	ds_read_b128 v[158:161], v153 offset:1024
	ds_read_b128 v[162:165], v153 offset:2048
	ds_read_b128 v[166:169], v153 offset:3072
	ds_read_b128 v[170:173], v154
	ds_read_b128 v[174:177], v154 offset:1024
	ds_read_b128 v[178:181], v154 offset:2048
	ds_read_b128 v[182:185], v154 offset:3072
	s_add_u32 s10, s50, 0x100
	s_addc_u32 s11, s51, 0
	s_cmpk_eq_i32 s70, 0x7c
	s_cselect_b32 s55, s45, s11
	s_cselect_b32 s54, s44, s10
	s_cselect_b32 s53, s43, s69
	s_cselect_b32 s52, s67, s68
	s_add_i32 m0, s49, 0xc000
	ds_read_b128 v[186:189], v155
	ds_read_b128 v[190:193], v155 offset:1024
	ds_read_b128 v[194:197], v155 offset:2048
	ds_read_b128 v[198:201], v155 offset:3072
	ds_read_b128 v[202:205], v155 offset:4096
	ds_read_b128 v[206:209], v155 offset:5120
	ds_read_b128 v[210:213], v155 offset:6144
	ds_read_b128 v[214:217], v155 offset:7168
	global_load_lds_dwordx4 v138, s[50:51]
	s_add_i32 m0, s49, 0xe000
	s_nop 0
	global_load_lds_dwordx4 v140, s[50:51]
	s_cmp_eq_u32 s99, 0
	s_cbranch_scc1 .Lw1s_7_0
	s_waitcnt vmcnt(48)
	s_branch .Lw1d_7_0

; #define PG8_STAGE(bufoff, gbase, voff) do { _Pragma("unroll") for (int _i = 0; _i < 2; ++_i) \
;         __builtin_amdgcn_global_load_lds((const unsigned*)((const char*)(gbase) + (voff)[_i]), (PG8_LAS unsigned*)(lds + (bufoff) + ldsw + _i * 8192), 16, 0, 0); } while (0)
; #define PG8_LDA(dst, b, h) do { _Pragma("unroll") for (int m = 0; m < 4; ++m) _Pragma("unroll") for (int k = 0; k < 2; ++k) dst[m][k] = *(const PG8_LAS bf16x8*)(lds + PG8_SA(b, h) + aoff + m * 2048 + k * 1024); } while (0)
; #define PG8_MMA(ai, bj, At, Bt) do { __builtin_amdgcn_s_setprio(1); _Pragma("unroll") for (int m = 0; m < 4; ++m) _Pragma("unroll") for (int n = 0; n < 2; ++n) _Pragma("unroll") for (int k = 0; k < 2; ++k) \
;         acc[ai][bj][m][n] = __builtin_amdgcn_mfma_f32_16x16x32_bf16(Bt[n][k], At[m][k], acc[ai][bj][m][n], 0, 0, 0); __builtin_amdgcn_s_setprio(0); } while (0)
; #define PG8_WAIT_V(n) asm volatile("s_waitcnt vmcnt(" #n ")" ::: "memory")
; #define PG8_WAIT_L(n) asm volatile("s_waitcnt lgkmcnt(" #n ")" ::: "memory")
; #define PG8_BAR __builtin_amdgcn_s_barrier()
; #define PG8_SCHED __builtin_amdgcn_sched_barrier(0)
; template <class Epi, class Sched, bool ALIGN_EPI = false, bool SP2 = false>
; __device__ __forceinline__ void gemm_phase(PG8_LAS unsigned char* lds, const Gemm g, const Sched& S, const Epi& E, int tid_in) {
;     ...
;             PG8_WAIT_V(8); PG8_WAIT_L(0); PG8_BAR; PG8_MMA(0, 0, At, B0); PG8_MMA(0, 1, At, B1); PG8_BAR; PG8_SCHED;
;             PG8_LDA(At, 0, 1); PG8_STAGE(PG8_SB(0, 0), b2, voffB); PG8_STAGE(PG8_SB(0, 1), b2 + hstepB, voffB); PG8_STAGE(PG8_SA(0, 0), a2, voffA);
;             PG8_WAIT_V(8); PG8_WAIT_L(0); PG8_BAR; PG8_MMA(1, 0, At, B0); PG8_MMA(1, 1, At, B1); PG8_BAR; PG8_SCHED;
.Lw1d_7_0:
	s_waitcnt lgkmcnt(0)
	s_barrier
	s_setprio 1
	s_waitcnt lgkmcnt(0)
	v_mfma_f32_16x16x32_bf16 v[124:127], v[146:149], v[186:189], 0
	v_mfma_f32_16x16x32_bf16 v[120:123], v[162:165], v[186:189], 0
	v_mfma_f32_16x16x32_bf16 v[108:111], v[146:149], v[194:197], 0
	v_mfma_f32_16x16x32_bf16 v[104:107], v[162:165], v[194:197], 0
	v_mfma_f32_16x16x32_bf16 v[92:95], v[146:149], v[202:205], 0
	v_mfma_f32_16x16x32_bf16 v[88:91], v[162:165], v[202:205], 0
	v_mfma_f32_16x16x32_bf16 v[76:79], v[146:149], v[210:213], 0
	v_mfma_f32_16x16x32_bf16 v[72:75], v[162:165], v[210:213], 0
	v_mfma_f32_16x16x32_bf16 v[124:127], v[158:161], v[190:193], v[124:127]
	v_mfma_f32_16x16x32_bf16 v[120:123], v[166:169], v[190:193], v[120:123]
	v_mfma_f32_16x16x32_bf16 v[108:111], v[158:161], v[198:201], v[108:111]
	v_mfma_f32_16x16x32_bf16 v[104:107], v[166:169], v[198:201], v[104:107]
	v_mfma_f32_16x16x32_bf16 v[92:95], v[158:161], v[206:209], v[92:95]
	v_mfma_f32_16x16x32_bf16 v[88:91], v[166:169], v[206:209], v[88:91]
	v_mfma_f32_16x16x32_bf16 v[76:79], v[158:161], v[214:217], v[76:79]
	v_mfma_f32_16x16x32_bf16 v[72:75], v[166:169], v[214:217], v[72:75]
	s_setprio 0
	s_setprio 1
	v_mfma_f32_16x16x32_bf16 v[116:119], v[170:173], v[186:189], 0
	v_mfma_f32_16x16x32_bf16 v[112:115], v[178:181], v[186:189], 0
	v_mfma_f32_16x16x32_bf16 v[100:103], v[170:173], v[194:197], 0
	v_mfma_f32_16x16x32_bf16 v[96:99], v[178:181], v[194:197], 0
	v_mfma_f32_16x16x32_bf16 v[84:87], v[170:173], v[202:205], 0
	v_mfma_f32_16x16x32_bf16 v[80:83], v[178:181], v[202:205], 0
	v_mfma_f32_16x16x32_bf16 v[68:71], v[170:173], v[210:213], 0
	v_mfma_f32_16x16x32_bf16 v[64:67], v[178:181], v[210:213], 0
	v_mfma_f32_16x16x32_bf16 v[116:119], v[174:177], v[190:193], v[116:119]
	v_mfma_f32_16x16x32_bf16 v[112:115], v[182:185], v[190:193], v[112:115]
	v_mfma_f32_16x16x32_bf16 v[100:103], v[174:177], v[198:201], v[100:103]
	v_mfma_f32_16x16x32_bf16 v[96:99], v[182:185], v[198:201], v[96:99]
	v_mfma_f32_16x16x32_bf16 v[84:87], v[174:177], v[206:209], v[84:87]
	v_mfma_f32_16x16x32_bf16 v[80:83], v[182:185], v[206:209], v[80:83]
	v_mfma_f32_16x16x32_bf16 v[68:71], v[174:177], v[214:217], v[68:71]
	v_mfma_f32_16x16x32_bf16 v[64:67], v[182:185], v[214:217], v[64:67]
	s_setprio 0
	s_barrier
	s_add_i32 s26, s63, s56
	s_mov_b32 m0, s26
	ds_read_b128 v[186:189], v155 offset:16384
	ds_read_b128 v[190:193], v155 offset:17408
	ds_read_b128 v[194:197], v155 offset:18432
	ds_read_b128 v[198:201], v155 offset:19456
	ds_read_b128 v[202:205], v155 offset:20480
	ds_read_b128 v[206:209], v155 offset:21504
	ds_read_b128 v[210:213], v155 offset:22528
	ds_read_b128 v[214:217], v155 offset:23552
	global_load_lds_dwordx4 v130, s[52:53]
	s_add_i32 m0, s26, 0x2000
	s_add_u32 s26, s52, 0x80000
	s_addc_u32 s27, s53, 0
	s_add_i32 s33, s64, s56
	global_load_lds_dwordx4 v134, s[52:53]
	s_mov_b32 m0, s33
	s_nop 0
	global_load_lds_dwordx4 v130, s[26:27]
	s_add_i32 m0, s33, 0x2000
	s_nop 0
	global_load_lds_dwordx4 v134, s[26:27]
	s_mov_b32 m0, s49
	s_nop 0
	global_load_lds_dwordx4 v128, s[54:55]
	s_mov_b32 m0, s57
	s_nop 0
	global_load_lds_dwordx4 v132, s[54:55]
	s_cmp_eq_u32 s99, 0
	s_cbranch_scc1 .Lw1s_7_1
	s_waitcnt vmcnt(48)
	s_branch .Lw1d_7_1

; #define PG8_STAGE(bufoff, gbase, voff) do { _Pragma("unroll") for (int _i = 0; _i < 2; ++_i) \
;         __builtin_amdgcn_global_load_lds((const unsigned*)((const char*)(gbase) + (voff)[_i]), (PG8_LAS unsigned*)(lds + (bufoff) + ldsw + _i * 8192), 16, 0, 0); } while (0)
; #define PG8_LDA(dst, b, h) do { _Pragma("unroll") for (int m = 0; m < 4; ++m) _Pragma("unroll") for (int k = 0; k < 2; ++k) dst[m][k] = *(const PG8_LAS bf16x8*)(lds + PG8_SA(b, h) + aoff + m * 2048 + k * 1024); } while (0)
; #define PG8_LDB(dst, b, h) do { _Pragma("unroll") for (int n = 0; n < 2; ++n) _Pragma("unroll") for (int k = 0; k < 2; ++k) dst[n][k] = *(const PG8_LAS bf16x8*)(lds + PG8_SB(b, h) + boff + n * 2048 + k * 1024); } while (0)
; #define PG8_MMA(ai, bj, At, Bt) do { __builtin_amdgcn_s_setprio(1); _Pragma("unroll") for (int m = 0; m < 4; ++m) _Pragma("unroll") for (int n = 0; n < 2; ++n) _Pragma("unroll") for (int k = 0; k < 2; ++k) \
;         acc[ai][bj][m][n] = __builtin_amdgcn_mfma_f32_16x16x32_bf16(Bt[n][k], At[m][k], acc[ai][bj][m][n], 0, 0, 0); __builtin_amdgcn_s_setprio(0); } while (0)
; #define PG8_WAIT_V(n) asm volatile("s_waitcnt vmcnt(" #n ")" ::: "memory")
; #define PG8_WAIT_L(n) asm volatile("s_waitcnt lgkmcnt(" #n ")" ::: "memory")
; #define PG8_BAR __builtin_amdgcn_s_barrier()
; #define PG8_SCHED __builtin_amdgcn_sched_barrier(0)
; template <class Epi, class Sched, bool ALIGN_EPI = false, bool SP2 = false>
; __device__ __forceinline__ void gemm_phase(PG8_LAS unsigned char* lds, const Gemm g, const Sched& S, const Epi& E, int tid_in) {
;     ...
;             PG8_WAIT_V(8); PG8_WAIT_L(0); PG8_BAR; PG8_MMA(1, 0, At, B0); PG8_MMA(1, 1, At, B1); PG8_BAR; PG8_SCHED;
;             PG8_LDB(B0, 1, 0); PG8_LDB(B1, 1, 1); PG8_SCHED; PG8_LDA(At, 1, 0); PG8_STAGE(PG8_SA(0, 1), a2 + hstep, voffA);
;             PG8_WAIT_V(8); PG8_WAIT_L(0); PG8_BAR; PG8_MMA(0, 0, At, B0); PG8_MMA(0, 1, At, B1); PG8_BAR; PG8_SCHED;
;             PG8_LDA(At, 1, 1); PG8_STAGE(PG8_SB(1, 0), b3, voffB); PG8_STAGE(PG8_SB(1, 1), b3 + hstepB, voffB); PG8_STAGE(PG8_SA(1, 0), a3, voffA);
.Lw1d_7_1:
	s_waitcnt lgkmcnt(0)
	s_barrier
	s_setprio 1
	s_waitcnt lgkmcnt(0)
	v_mfma_f32_16x16x32_bf16 v[60:63], v[146:149], v[186:189], 0
	v_mfma_f32_16x16x32_bf16 v[56:59], v[162:165], v[186:189], 0
	v_mfma_f32_16x16x32_bf16 v[44:47], v[146:149], v[194:197], 0
	v_mfma_f32_16x16x32_bf16 v[40:43], v[162:165], v[194:197], 0
	v_mfma_f32_16x16x32_bf16 v[28:31], v[146:149], v[202:205], 0
	v_mfma_f32_16x16x32_bf16 v[24:27], v[162:165], v[202:205], 0
	v_mfma_f32_16x16x32_bf16 v[12:15], v[146:149], v[210:213], 0
	v_mfma_f32_16x16x32_bf16 v[8:11], v[162:165], v[210:213], 0
	v_mfma_f32_16x16x32_bf16 v[60:63], v[158:161], v[190:193], v[60:63]
	v_mfma_f32_16x16x32_bf16 v[56:59], v[166:169], v[190:193], v[56:59]
	v_mfma_f32_16x16x32_bf16 v[44:47], v[158:161], v[198:201], v[44:47]
	v_mfma_f32_16x16x32_bf16 v[40:43], v[166:169], v[198:201], v[40:43]
	v_mfma_f32_16x16x32_bf16 v[28:31], v[158:161], v[206:209], v[28:31]
	v_mfma_f32_16x16x32_bf16 v[24:27], v[166:169], v[206:209], v[24:27]
	v_mfma_f32_16x16x32_bf16 v[12:15], v[158:161], v[214:217], v[12:15]
	v_mfma_f32_16x16x32_bf16 v[8:11], v[166:169], v[214:217], v[8:11]
	s_setprio 0
	s_setprio 1
	v_mfma_f32_16x16x32_bf16 v[52:55], v[170:173], v[186:189], 0
	v_mfma_f32_16x16x32_bf16 v[48:51], v[178:181], v[186:189], 0
	v_mfma_f32_16x16x32_bf16 v[36:39], v[170:173], v[194:197], 0
	v_mfma_f32_16x16x32_bf16 v[32:35], v[178:181], v[194:197], 0
	v_mfma_f32_16x16x32_bf16 v[20:23], v[170:173], v[202:205], 0
	v_mfma_f32_16x16x32_bf16 v[16:19], v[178:181], v[202:205], 0
	v_mfma_f32_16x16x32_bf16 v[4:7], v[170:173], v[210:213], 0
	v_mfma_f32_16x16x32_bf16 v[0:3], v[178:181], v[210:213], 0
	v_mfma_f32_16x16x32_bf16 v[52:55], v[174:177], v[190:193], v[52:55]
	v_mfma_f32_16x16x32_bf16 v[48:51], v[182:185], v[190:193], v[48:51]
	v_mfma_f32_16x16x32_bf16 v[36:39], v[174:177], v[198:201], v[36:39]
	v_mfma_f32_16x16x32_bf16 v[32:35], v[182:185], v[198:201], v[32:35]
	v_mfma_f32_16x16x32_bf16 v[20:23], v[174:177], v[206:209], v[20:23]
	v_mfma_f32_16x16x32_bf16 v[16:19], v[182:185], v[206:209], v[16:19]
	v_mfma_f32_16x16x32_bf16 v[4:7], v[174:177], v[214:217], v[4:7]
	v_mfma_f32_16x16x32_bf16 v[0:3], v[182:185], v[214:217], v[0:3]
	s_setprio 0
	s_barrier
	s_add_i32 s33, 0, 0x18000
	s_add_i32 s50, 0, 0x1c000
	v_add_u32_e32 v166, s33, v137
	v_add_u32_e32 v182, s50, v137
	ds_read_b128 v[146:149], v166
	ds_read_b128 v[158:161], v166 offset:1024
	ds_read_b128 v[162:165], v166 offset:2048
	ds_read_b128 v[166:169], v166 offset:3072
	ds_read_b128 v[170:173], v182
	ds_read_b128 v[174:177], v182 offset:1024
	ds_read_b128 v[178:181], v182 offset:2048
	ds_read_b128 v[182:185], v182 offset:3072
	s_add_u32 s26, s54, 0x204000
	s_addc_u32 s27, s55, 0
	s_mov_b32 m0, s58
	ds_read_b128 v[186:189], v155 offset:32768
	ds_read_b128 v[190:193], v155 offset:33792
	ds_read_b128 v[194:197], v155 offset:34816
	ds_read_b128 v[198:201], v155 offset:35840
	ds_read_b128 v[202:205], v155 offset:36864
	ds_read_b128 v[206:209], v155 offset:37888
	ds_read_b128 v[210:213], v155 offset:38912
	ds_read_b128 v[214:217], v155 offset:39936
	global_load_lds_dwordx4 v128, s[26:27]
	s_mov_b32 m0, s59
	s_nop 0
	global_load_lds_dwordx4 v132, s[26:27]
	s_waitcnt vmcnt(8)
	s_waitcnt lgkmcnt(0)
	s_barrier
	s_setprio 1
	s_waitcnt lgkmcnt(0)
	v_mfma_f32_16x16x32_bf16 v[124:127], v[146:149], v[186:189], v[124:127]
	v_mfma_f32_16x16x32_bf16 v[120:123], v[162:165], v[186:189], v[120:123]
	v_mfma_f32_16x16x32_bf16 v[108:111], v[146:149], v[194:197], v[108:111]
	v_mfma_f32_16x16x32_bf16 v[104:107], v[162:165], v[194:197], v[104:107]
	v_mfma_f32_16x16x32_bf16 v[92:95], v[146:149], v[202:205], v[92:95]
	v_mfma_f32_16x16x32_bf16 v[88:91], v[162:165], v[202:205], v[88:91]
	v_mfma_f32_16x16x32_bf16 v[76:79], v[146:149], v[210:213], v[76:79]
	v_mfma_f32_16x16x32_bf16 v[72:75], v[162:165], v[210:213], v[72:75]
	v_mfma_f32_16x16x32_bf16 v[124:127], v[158:161], v[190:193], v[124:127]
	v_mfma_f32_16x16x32_bf16 v[120:123], v[166:169], v[190:193], v[120:123]
	v_mfma_f32_16x16x32_bf16 v[108:111], v[158:161], v[198:201], v[108:111]
	v_mfma_f32_16x16x32_bf16 v[104:107], v[166:169], v[198:201], v[104:107]
	v_mfma_f32_16x16x32_bf16 v[92:95], v[158:161], v[206:209], v[92:95]
	v_mfma_f32_16x16x32_bf16 v[88:91], v[166:169], v[206:209], v[88:91]
	v_mfma_f32_16x16x32_bf16 v[76:79], v[158:161], v[214:217], v[76:79]
	v_mfma_f32_16x16x32_bf16 v[72:75], v[166:169], v[214:217], v[72:75]
	s_setprio 0
	s_setprio 1
	v_mfma_f32_16x16x32_bf16 v[116:119], v[170:173], v[186:189], v[116:119]
	v_mfma_f32_16x16x32_bf16 v[112:115], v[178:181], v[186:189], v[112:115]
	v_mfma_f32_16x16x32_bf16 v[100:103], v[170:173], v[194:197], v[100:103]
	v_mfma_f32_16x16x32_bf16 v[96:99], v[178:181], v[194:197], v[96:99]
	v_mfma_f32_16x16x32_bf16 v[84:87], v[170:173], v[202:205], v[84:87]
	v_mfma_f32_16x16x32_bf16 v[80:83], v[178:181], v[202:205], v[80:83]
	v_mfma_f32_16x16x32_bf16 v[68:71], v[170:173], v[210:213], v[68:71]
	v_mfma_f32_16x16x32_bf16 v[64:67], v[178:181], v[210:213], v[64:67]
	v_mfma_f32_16x16x32_bf16 v[116:119], v[174:177], v[190:193], v[116:119]
	v_mfma_f32_16x16x32_bf16 v[112:115], v[182:185], v[190:193], v[112:115]
	v_mfma_f32_16x16x32_bf16 v[100:103], v[174:177], v[198:201], v[100:103]
	v_mfma_f32_16x16x32_bf16 v[96:99], v[182:185], v[198:201], v[96:99]
	v_mfma_f32_16x16x32_bf16 v[84:87], v[174:177], v[206:209], v[84:87]
	v_mfma_f32_16x16x32_bf16 v[80:83], v[182:185], v[206:209], v[80:83]
	v_mfma_f32_16x16x32_bf16 v[68:71], v[174:177], v[214:217], v[68:71]
	v_mfma_f32_16x16x32_bf16 v[64:67], v[182:185], v[214:217], v[64:67]
	s_setprio 0
	s_barrier
; #define PG8_STAGE(bufoff, gbase, voff) do { _Pragma("unroll") for (int _i = 0; _i < 2; ++_i) \
;         __builtin_amdgcn_global_load_lds((const unsigned*)((const char*)(gbase) + (voff)[_i]), (PG8_LAS unsigned*)(lds + (bufoff) + ldsw + _i * 8192), 16, 0, 0); } while (0)
; #define PG8_LDA(dst, b, h) do { _Pragma("unroll") for (int m = 0; m < 4; ++m) _Pragma("unroll") for (int k = 0; k < 2; ++k) dst[m][k] = *(const PG8_LAS bf16x8*)(lds + PG8_SA(b, h) + aoff + m * 2048 + k * 1024); } while (0)
; #define PG8_LDB(dst, b, h) do { _Pragma("unroll") for (int n = 0; n < 2; ++n) _Pragma("unroll") for (int k = 0; k < 2; ++k) dst[n][k] = *(const PG8_LAS bf16x8*)(lds + PG8_SB(b, h) + boff + n * 2048 + k * 1024); } while (0)
; #define PG8_MMA(ai, bj, At, Bt) do { __builtin_amdgcn_s_setprio(1); _Pragma("unroll") for (int m = 0; m < 4; ++m) _Pragma("unroll") for (int n = 0; n < 2; ++n) _Pragma("unroll") for (int k = 0; k < 2; ++k) \
;         acc[ai][bj][m][n] = __builtin_amdgcn_mfma_f32_16x16x32_bf16(Bt[n][k], At[m][k], acc[ai][bj][m][n], 0, 0, 0); __builtin_amdgcn_s_setprio(0); } while (0)
; #define PG8_BAR __builtin_amdgcn_s_barrier()
; template <class Epi, class Sched, bool ALIGN_EPI = false, bool SP2 = false>
; __device__ __forceinline__ void gemm_phase(PG8_LAS unsigned char* lds, const Gemm g, const Sched& S, const Epi& E, int tid_in) {
;     ...
;             PG8_LDB(B0, 0, 0); PG8_LDB(B1, 0, 1); PG8_SCHED; PG8_LDA(At, 0, 0); PG8_STAGE(PG8_SA(1, 1), a1 + hstep, voffA);
;             PG8_WAIT_V(8); PG8_WAIT_L(0); PG8_BAR; PG8_MMA(0, 0, At, B0); PG8_MMA(0, 1, At, B1); PG8_BAR; PG8_SCHED;
;             PG8_LDA(At, 0, 1); PG8_STAGE(PG8_SB(0, 0), b2, voffB); PG8_STAGE(PG8_SB(0, 1), b2 + hstepB, voffB); PG8_STAGE(PG8_SA(0, 0), a2, voffA);
;             PG8_WAIT_V(8); PG8_WAIT_L(0); PG8_BAR; PG8_MMA(1, 0, At, B0); PG8_MMA(1, 1, At, B1); PG8_BAR; PG8_SCHED;
;             PG8_LDB(B0, 1, 0); PG8_LDB(B1, 1, 1); PG8_SCHED; PG8_LDA(At, 1, 0); PG8_STAGE(PG8_SA(0, 1), a2 + hstep, voffA);
;             PG8_WAIT_V(8); PG8_WAIT_L(0); PG8_BAR; PG8_MMA(0, 0, At, B0); PG8_MMA(0, 1, At, B1); PG8_BAR; PG8_SCHED;
;             PG8_LDA(At, 1, 1); PG8_STAGE(PG8_SB(1, 0), b3, voffB); PG8_STAGE(PG8_SB(1, 1), b3 + hstepB, voffB); PG8_STAGE(PG8_SA(1, 0), a3, voffA);
;             PG8_WAIT_V(8); PG8_WAIT_L(0); PG8_BAR; PG8_MMA(1, 0, At, B0); PG8_MMA(1, 1, At, B1); PG8_BAR; PG8_SCHED;
	s_add_i32 s26, s33, s56
	s_add_i32 m0, s26, 0xffffff80
	ds_read_b128 v[186:189], v155 offset:49152
	ds_read_b128 v[190:193], v155 offset:50176
	ds_read_b128 v[194:197], v155 offset:51200
	ds_read_b128 v[198:201], v155 offset:52224
	ds_read_b128 v[202:205], v155 offset:53248
	ds_read_b128 v[206:209], v155 offset:54272
	ds_read_b128 v[210:213], v155 offset:55296
	ds_read_b128 v[214:217], v155 offset:56320
	global_load_lds_dwordx4 v130, s[52:53] offset:128
	s_add_i32 m0, s26, 0x1f80
	s_add_u32 s26, s52, 0x80080
	s_addc_u32 s27, s53, 0
	s_add_i32 s33, s50, s56
	global_load_lds_dwordx4 v134, s[52:53] offset:128
	s_mov_b32 m0, s33
	s_nop 0
	global_load_lds_dwordx4 v130, s[26:27]
	s_add_i32 m0, s33, 0x2000
	s_nop 0
	global_load_lds_dwordx4 v134, s[26:27]
	s_add_i32 m0, s61, 0xffffff80
	s_nop 0
	global_load_lds_dwordx4 v128, s[54:55] offset:128
	s_add_i32 m0, s62, 0xffffff80
	s_nop 0
	global_load_lds_dwordx4 v132, s[54:55] offset:128
	s_waitcnt vmcnt(8)
	s_waitcnt lgkmcnt(0)
	s_barrier
	s_setprio 1
	s_waitcnt lgkmcnt(0)
	v_mfma_f32_16x16x32_bf16 v[60:63], v[146:149], v[186:189], v[60:63]
	v_mfma_f32_16x16x32_bf16 v[56:59], v[162:165], v[186:189], v[56:59]
	v_mfma_f32_16x16x32_bf16 v[44:47], v[146:149], v[194:197], v[44:47]
	v_mfma_f32_16x16x32_bf16 v[40:43], v[162:165], v[194:197], v[40:43]
	v_mfma_f32_16x16x32_bf16 v[28:31], v[146:149], v[202:205], v[28:31]
	v_mfma_f32_16x16x32_bf16 v[24:27], v[162:165], v[202:205], v[24:27]
	v_mfma_f32_16x16x32_bf16 v[12:15], v[146:149], v[210:213], v[12:15]
	v_mfma_f32_16x16x32_bf16 v[8:11], v[162:165], v[210:213], v[8:11]
	v_mfma_f32_16x16x32_bf16 v[60:63], v[158:161], v[190:193], v[60:63]
	v_mfma_f32_16x16x32_bf16 v[56:59], v[166:169], v[190:193], v[56:59]
	v_mfma_f32_16x16x32_bf16 v[44:47], v[158:161], v[198:201], v[44:47]
	v_mfma_f32_16x16x32_bf16 v[40:43], v[166:169], v[198:201], v[40:43]
	v_mfma_f32_16x16x32_bf16 v[28:31], v[158:161], v[206:209], v[28:31]
	v_mfma_f32_16x16x32_bf16 v[24:27], v[166:169], v[206:209], v[24:27]
	v_mfma_f32_16x16x32_bf16 v[12:15], v[158:161], v[214:217], v[12:15]
	v_mfma_f32_16x16x32_bf16 v[8:11], v[166:169], v[214:217], v[8:11]
	s_setprio 0
	s_setprio 1
	v_mfma_f32_16x16x32_bf16 v[52:55], v[170:173], v[186:189], v[52:55]
	v_mfma_f32_16x16x32_bf16 v[48:51], v[178:181], v[186:189], v[48:51]
	v_mfma_f32_16x16x32_bf16 v[36:39], v[170:173], v[194:197], v[36:39]
	v_mfma_f32_16x16x32_bf16 v[32:35], v[178:181], v[194:197], v[32:35]
	v_mfma_f32_16x16x32_bf16 v[20:23], v[170:173], v[202:205], v[20:23]
	v_mfma_f32_16x16x32_bf16 v[16:19], v[178:181], v[202:205], v[16:19]
	v_mfma_f32_16x16x32_bf16 v[4:7], v[170:173], v[210:213], v[4:7]
	v_mfma_f32_16x16x32_bf16 v[0:3], v[178:181], v[210:213], v[0:3]
	v_mfma_f32_16x16x32_bf16 v[52:55], v[174:177], v[190:193], v[52:55]
	v_mfma_f32_16x16x32_bf16 v[48:51], v[182:185], v[190:193], v[48:51]
	v_mfma_f32_16x16x32_bf16 v[36:39], v[174:177], v[198:201], v[36:39]
	v_mfma_f32_16x16x32_bf16 v[32:35], v[182:185], v[198:201], v[32:35]
	v_mfma_f32_16x16x32_bf16 v[20:23], v[174:177], v[206:209], v[20:23]
	v_mfma_f32_16x16x32_bf16 v[16:19], v[182:185], v[206:209], v[16:19]
	v_mfma_f32_16x16x32_bf16 v[4:7], v[174:177], v[214:217], v[4:7]
	v_mfma_f32_16x16x32_bf16 v[0:3], v[182:185], v[214:217], v[0:3]
	s_setprio 0
	s_barrier
	s_add_i32 s70, s70, 2
	s_add_u32 s68, s68, 0x100
	s_addc_u32 s69, s69, 0
	s_cmpk_gt_u32 s70, 0x7d
	s_mov_b64 s[50:51], s[10:11]
.LBB0_949:
	ds_read_b128 v[146:149], v153
	ds_read_b128 v[158:161], v153 offset:1024
	ds_read_b128 v[162:165], v153 offset:2048
	ds_read_b128 v[166:169], v153 offset:3072
	ds_read_b128 v[170:173], v154
	ds_read_b128 v[174:177], v154 offset:1024
	ds_read_b128 v[178:181], v154 offset:2048
	ds_read_b128 v[182:185], v154 offset:3072
	s_add_u32 s10, s50, 0x100
	s_addc_u32 s11, s51, 0
	s_cmpk_eq_i32 s70, 0x7c
	s_cselect_b32 s55, s45, s11
	s_cselect_b32 s54, s44, s10
	s_cselect_b32 s53, s43, s69
	s_cselect_b32 s52, s67, s68
	s_add_i32 m0, s49, 0xc000
	ds_read_b128 v[186:189], v155
	ds_read_b128 v[190:193], v155 offset:1024
	ds_read_b128 v[194:197], v155 offset:2048
	ds_read_b128 v[198:201], v155 offset:3072
	ds_read_b128 v[202:205], v155 offset:4096
	ds_read_b128 v[206:209], v155 offset:5120
	ds_read_b128 v[210:213], v155 offset:6144
	ds_read_b128 v[214:217], v155 offset:7168
	global_load_lds_dwordx4 v138, s[50:51]
	s_add_i32 m0, s49, 0xe000
	s_nop 0
	global_load_lds_dwordx4 v140, s[50:51]
	s_waitcnt vmcnt(8)
	s_waitcnt lgkmcnt(0)
	s_barrier
	s_setprio 1
	s_waitcnt lgkmcnt(0)
	v_mfma_f32_16x16x32_bf16 v[124:127], v[146:149], v[186:189], v[124:127]
	v_mfma_f32_16x16x32_bf16 v[120:123], v[162:165], v[186:189], v[120:123]
	v_mfma_f32_16x16x32_bf16 v[108:111], v[146:149], v[194:197], v[108:111]
	v_mfma_f32_16x16x32_bf16 v[104:107], v[162:165], v[194:197], v[104:107]
	v_mfma_f32_16x16x32_bf16 v[92:95], v[146:149], v[202:205], v[92:95]
	v_mfma_f32_16x16x32_bf16 v[88:91], v[162:165], v[202:205], v[88:91]
	v_mfma_f32_16x16x32_bf16 v[76:79], v[146:149], v[210:213], v[76:79]
	v_mfma_f32_16x16x32_bf16 v[72:75], v[162:165], v[210:213], v[72:75]
	v_mfma_f32_16x16x32_bf16 v[124:127], v[158:161], v[190:193], v[124:127]
	v_mfma_f32_16x16x32_bf16 v[120:123], v[166:169], v[190:193], v[120:123]
	v_mfma_f32_16x16x32_bf16 v[108:111], v[158:161], v[198:201], v[108:111]
	v_mfma_f32_16x16x32_bf16 v[104:107], v[166:169], v[198:201], v[104:107]
	v_mfma_f32_16x16x32_bf16 v[92:95], v[158:161], v[206:209], v[92:95]
	v_mfma_f32_16x16x32_bf16 v[88:91], v[166:169], v[206:209], v[88:91]
	v_mfma_f32_16x16x32_bf16 v[76:79], v[158:161], v[214:217], v[76:79]
	v_mfma_f32_16x16x32_bf16 v[72:75], v[166:169], v[214:217], v[72:75]
	s_setprio 0
	s_setprio 1
	v_mfma_f32_16x16x32_bf16 v[116:119], v[170:173], v[186:189], v[116:119]
	v_mfma_f32_16x16x32_bf16 v[112:115], v[178:181], v[186:189], v[112:115]
	v_mfma_f32_16x16x32_bf16 v[100:103], v[170:173], v[194:197], v[100:103]
	v_mfma_f32_16x16x32_bf16 v[96:99], v[178:181], v[194:197], v[96:99]
	v_mfma_f32_16x16x32_bf16 v[84:87], v[170:173], v[202:205], v[84:87]
	v_mfma_f32_16x16x32_bf16 v[80:83], v[178:181], v[202:205], v[80:83]
	v_mfma_f32_16x16x32_bf16 v[68:71], v[170:173], v[210:213], v[68:71]
	v_mfma_f32_16x16x32_bf16 v[64:67], v[178:181], v[210:213], v[64:67]
	v_mfma_f32_16x16x32_bf16 v[116:119], v[174:177], v[190:193], v[116:119]
	v_mfma_f32_16x16x32_bf16 v[112:115], v[182:185], v[190:193], v[112:115]
	v_mfma_f32_16x16x32_bf16 v[100:103], v[174:177], v[198:201], v[100:103]
	v_mfma_f32_16x16x32_bf16 v[96:99], v[182:185], v[198:201], v[96:99]
	v_mfma_f32_16x16x32_bf16 v[84:87], v[174:177], v[206:209], v[84:87]
	v_mfma_f32_16x16x32_bf16 v[80:83], v[182:185], v[206:209], v[80:83]
	v_mfma_f32_16x16x32_bf16 v[68:71], v[174:177], v[214:217], v[68:71]
	v_mfma_f32_16x16x32_bf16 v[64:67], v[182:185], v[214:217], v[64:67]
	s_setprio 0
	s_barrier
; #define PG8_STAGE(bufoff, gbase, voff) do { _Pragma("unroll") for (int _i = 0; _i < 2; ++_i) \
;         __builtin_amdgcn_global_load_lds((const unsigned*)((const char*)(gbase) + (voff)[_i]), (PG8_LAS unsigned*)(lds + (bufoff) + ldsw + _i * 8192), 16, 0, 0); } while (0)
; #define PG8_LDA(dst, b, h) do { _Pragma("unroll") for (int m = 0; m < 4; ++m) _Pragma("unroll") for (int k = 0; k < 2; ++k) dst[m][k] = *(const PG8_LAS bf16x8*)(lds + PG8_SA(b, h) + aoff + m * 2048 + k * 1024); } while (0)
; #define PG8_LDB(dst, b, h) do { _Pragma("unroll") for (int n = 0; n < 2; ++n) _Pragma("unroll") for (int k = 0; k < 2; ++k) dst[n][k] = *(const PG8_LAS bf16x8*)(lds + PG8_SB(b, h) + boff + n * 2048 + k * 1024); } while (0)
; #define PG8_MMA(ai, bj, At, Bt) do { __builtin_amdgcn_s_setprio(1); _Pragma("unroll") for (int m = 0; m < 4; ++m) _Pragma("unroll") for (int n = 0; n < 2; ++n) _Pragma("unroll") for (int k = 0; k < 2; ++k) \
;         acc[ai][bj][m][n] = __builtin_amdgcn_mfma_f32_16x16x32_bf16(Bt[n][k], At[m][k], acc[ai][bj][m][n], 0, 0, 0); __builtin_amdgcn_s_setprio(0); } while (0)
; #define PG8_WAIT_V(n) asm volatile("s_waitcnt vmcnt(" #n ")" ::: "memory")
; #define PG8_WAIT_L(n) asm volatile("s_waitcnt lgkmcnt(" #n ")" ::: "memory")
; #define PG8_BAR __builtin_amdgcn_s_barrier()
; #define PG8_SCHED __builtin_amdgcn_sched_barrier(0)
; template <class Epi, class Sched, bool ALIGN_EPI = false, bool SP2 = false>
; __device__ __forceinline__ void gemm_phase(PG8_LAS unsigned char* lds, const Gemm g, const Sched& S, const Epi& E, int tid_in) {
;     ...
;             PG8_LDA(At, 0, 1); PG8_STAGE(PG8_SB(0, 0), b2, voffB); PG8_STAGE(PG8_SB(0, 1), b2 + hstepB, voffB); PG8_STAGE(PG8_SA(0, 0), a2, voffA);
;             PG8_WAIT_V(8); PG8_WAIT_L(0); PG8_BAR; PG8_MMA(1, 0, At, B0); PG8_MMA(1, 1, At, B1); PG8_BAR; PG8_SCHED;
;             PG8_LDB(B0, 1, 0); PG8_LDB(B1, 1, 1); PG8_SCHED; PG8_LDA(At, 1, 0); PG8_STAGE(PG8_SA(0, 1), a2 + hstep, voffA);
;             PG8_WAIT_V(8); PG8_WAIT_L(0); PG8_BAR; PG8_MMA(0, 0, At, B0); PG8_MMA(0, 1, At, B1); PG8_BAR; PG8_SCHED;
;             PG8_LDA(At, 1, 1); PG8_STAGE(PG8_SB(1, 0), b3, voffB); PG8_STAGE(PG8_SB(1, 1), b3 + hstepB, voffB); PG8_STAGE(PG8_SA(1, 0), a3, voffA);
	s_add_i32 s26, s63, s56
	s_mov_b32 m0, s26
	ds_read_b128 v[186:189], v155 offset:16384
	ds_read_b128 v[190:193], v155 offset:17408
	ds_read_b128 v[194:197], v155 offset:18432
	ds_read_b128 v[198:201], v155 offset:19456
	ds_read_b128 v[202:205], v155 offset:20480
	ds_read_b128 v[206:209], v155 offset:21504
	ds_read_b128 v[210:213], v155 offset:22528
	ds_read_b128 v[214:217], v155 offset:23552
	global_load_lds_dwordx4 v130, s[52:53]
	s_add_i32 m0, s26, 0x2000
	s_add_u32 s26, s52, 0x80000
	s_addc_u32 s27, s53, 0
	s_add_i32 s33, s64, s56
	global_load_lds_dwordx4 v134, s[52:53]
	s_mov_b32 m0, s33
	s_nop 0
	global_load_lds_dwordx4 v130, s[26:27]
	s_add_i32 m0, s33, 0x2000
	s_nop 0
	global_load_lds_dwordx4 v134, s[26:27]
	s_mov_b32 m0, s49
	s_nop 0
	global_load_lds_dwordx4 v128, s[54:55]
	s_mov_b32 m0, s57
	s_nop 0
	global_load_lds_dwordx4 v132, s[54:55]
	s_waitcnt vmcnt(8)
	s_waitcnt lgkmcnt(0)
	s_barrier
	s_setprio 1
	s_waitcnt lgkmcnt(0)
	v_mfma_f32_16x16x32_bf16 v[60:63], v[146:149], v[186:189], v[60:63]
	v_mfma_f32_16x16x32_bf16 v[56:59], v[162:165], v[186:189], v[56:59]
	v_mfma_f32_16x16x32_bf16 v[44:47], v[146:149], v[194:197], v[44:47]
	v_mfma_f32_16x16x32_bf16 v[40:43], v[162:165], v[194:197], v[40:43]
	v_mfma_f32_16x16x32_bf16 v[28:31], v[146:149], v[202:205], v[28:31]
	v_mfma_f32_16x16x32_bf16 v[24:27], v[162:165], v[202:205], v[24:27]
	v_mfma_f32_16x16x32_bf16 v[12:15], v[146:149], v[210:213], v[12:15]
	v_mfma_f32_16x16x32_bf16 v[8:11], v[162:165], v[210:213], v[8:11]
	v_mfma_f32_16x16x32_bf16 v[60:63], v[158:161], v[190:193], v[60:63]
	v_mfma_f32_16x16x32_bf16 v[56:59], v[166:169], v[190:193], v[56:59]
	v_mfma_f32_16x16x32_bf16 v[44:47], v[158:161], v[198:201], v[44:47]
	v_mfma_f32_16x16x32_bf16 v[40:43], v[166:169], v[198:201], v[40:43]
	v_mfma_f32_16x16x32_bf16 v[28:31], v[158:161], v[206:209], v[28:31]
	v_mfma_f32_16x16x32_bf16 v[24:27], v[166:169], v[206:209], v[24:27]
	v_mfma_f32_16x16x32_bf16 v[12:15], v[158:161], v[214:217], v[12:15]
	v_mfma_f32_16x16x32_bf16 v[8:11], v[166:169], v[214:217], v[8:11]
	s_setprio 0
	s_setprio 1
	v_mfma_f32_16x16x32_bf16 v[52:55], v[170:173], v[186:189], v[52:55]
	v_mfma_f32_16x16x32_bf16 v[48:51], v[178:181], v[186:189], v[48:51]
	v_mfma_f32_16x16x32_bf16 v[36:39], v[170:173], v[194:197], v[36:39]
	v_mfma_f32_16x16x32_bf16 v[32:35], v[178:181], v[194:197], v[32:35]
	v_mfma_f32_16x16x32_bf16 v[20:23], v[170:173], v[202:205], v[20:23]
	v_mfma_f32_16x16x32_bf16 v[16:19], v[178:181], v[202:205], v[16:19]
	v_mfma_f32_16x16x32_bf16 v[4:7], v[170:173], v[210:213], v[4:7]
	v_mfma_f32_16x16x32_bf16 v[0:3], v[178:181], v[210:213], v[0:3]
	v_mfma_f32_16x16x32_bf16 v[52:55], v[174:177], v[190:193], v[52:55]
	v_mfma_f32_16x16x32_bf16 v[48:51], v[182:185], v[190:193], v[48:51]
	v_mfma_f32_16x16x32_bf16 v[36:39], v[174:177], v[198:201], v[36:39]
	v_mfma_f32_16x16x32_bf16 v[32:35], v[182:185], v[198:201], v[32:35]
	v_mfma_f32_16x16x32_bf16 v[20:23], v[174:177], v[206:209], v[20:23]
	v_mfma_f32_16x16x32_bf16 v[16:19], v[182:185], v[206:209], v[16:19]
	v_mfma_f32_16x16x32_bf16 v[4:7], v[174:177], v[214:217], v[4:7]
	v_mfma_f32_16x16x32_bf16 v[0:3], v[182:185], v[214:217], v[0:3]
	s_setprio 0
	s_barrier
	s_add_i32 s33, 0, 0x18000
	s_add_i32 s50, 0, 0x1c000
	v_add_u32_e32 v166, s33, v137
	v_add_u32_e32 v182, s50, v137
	ds_read_b128 v[146:149], v166
	ds_read_b128 v[158:161], v166 offset:1024
	ds_read_b128 v[162:165], v166 offset:2048
	ds_read_b128 v[166:169], v166 offset:3072
	ds_read_b128 v[170:173], v182
	ds_read_b128 v[174:177], v182 offset:1024
	ds_read_b128 v[178:181], v182 offset:2048
	ds_read_b128 v[182:185], v182 offset:3072
	s_add_u32 s26, s54, 0x204000
	s_addc_u32 s27, s55, 0
	s_mov_b32 m0, s58
	ds_read_b128 v[186:189], v155 offset:32768
	ds_read_b128 v[190:193], v155 offset:33792
	ds_read_b128 v[194:197], v155 offset:34816
	ds_read_b128 v[198:201], v155 offset:35840
	ds_read_b128 v[202:205], v155 offset:36864
	ds_read_b128 v[206:209], v155 offset:37888
	ds_read_b128 v[210:213], v155 offset:38912
	ds_read_b128 v[214:217], v155 offset:39936
	global_load_lds_dwordx4 v128, s[26:27]
	s_mov_b32 m0, s59
	s_nop 0
	global_load_lds_dwordx4 v132, s[26:27]
	s_waitcnt vmcnt(8)
	s_waitcnt lgkmcnt(0)
	s_barrier
	s_setprio 1
	s_waitcnt lgkmcnt(0)
	v_mfma_f32_16x16x32_bf16 v[124:127], v[146:149], v[186:189], v[124:127]
	v_mfma_f32_16x16x32_bf16 v[120:123], v[162:165], v[186:189], v[120:123]
	v_mfma_f32_16x16x32_bf16 v[108:111], v[146:149], v[194:197], v[108:111]
	v_mfma_f32_16x16x32_bf16 v[104:107], v[162:165], v[194:197], v[104:107]
	v_mfma_f32_16x16x32_bf16 v[92:95], v[146:149], v[202:205], v[92:95]
	v_mfma_f32_16x16x32_bf16 v[88:91], v[162:165], v[202:205], v[88:91]
	v_mfma_f32_16x16x32_bf16 v[76:79], v[146:149], v[210:213], v[76:79]
	v_mfma_f32_16x16x32_bf16 v[72:75], v[162:165], v[210:213], v[72:75]
	v_mfma_f32_16x16x32_bf16 v[124:127], v[158:161], v[190:193], v[124:127]
	v_mfma_f32_16x16x32_bf16 v[120:123], v[166:169], v[190:193], v[120:123]
	v_mfma_f32_16x16x32_bf16 v[108:111], v[158:161], v[198:201], v[108:111]
	v_mfma_f32_16x16x32_bf16 v[104:107], v[166:169], v[198:201], v[104:107]
	v_mfma_f32_16x16x32_bf16 v[92:95], v[158:161], v[206:209], v[92:95]
	v_mfma_f32_16x16x32_bf16 v[88:91], v[166:169], v[206:209], v[88:91]
	v_mfma_f32_16x16x32_bf16 v[76:79], v[158:161], v[214:217], v[76:79]
	v_mfma_f32_16x16x32_bf16 v[72:75], v[166:169], v[214:217], v[72:75]
	s_setprio 0
	s_setprio 1
	v_mfma_f32_16x16x32_bf16 v[116:119], v[170:173], v[186:189], v[116:119]
	v_mfma_f32_16x16x32_bf16 v[112:115], v[178:181], v[186:189], v[112:115]
	v_mfma_f32_16x16x32_bf16 v[100:103], v[170:173], v[194:197], v[100:103]
	v_mfma_f32_16x16x32_bf16 v[96:99], v[178:181], v[194:197], v[96:99]
	v_mfma_f32_16x16x32_bf16 v[84:87], v[170:173], v[202:205], v[84:87]
	v_mfma_f32_16x16x32_bf16 v[80:83], v[178:181], v[202:205], v[80:83]
	v_mfma_f32_16x16x32_bf16 v[68:71], v[170:173], v[210:213], v[68:71]
	v_mfma_f32_16x16x32_bf16 v[64:67], v[178:181], v[210:213], v[64:67]
	v_mfma_f32_16x16x32_bf16 v[116:119], v[174:177], v[190:193], v[116:119]
	v_mfma_f32_16x16x32_bf16 v[112:115], v[182:185], v[190:193], v[112:115]
	v_mfma_f32_16x16x32_bf16 v[100:103], v[174:177], v[198:201], v[100:103]
	v_mfma_f32_16x16x32_bf16 v[96:99], v[182:185], v[198:201], v[96:99]
	v_mfma_f32_16x16x32_bf16 v[84:87], v[174:177], v[206:209], v[84:87]
	v_mfma_f32_16x16x32_bf16 v[80:83], v[182:185], v[206:209], v[80:83]
	v_mfma_f32_16x16x32_bf16 v[68:71], v[174:177], v[214:217], v[68:71]
	v_mfma_f32_16x16x32_bf16 v[64:67], v[182:185], v[214:217], v[64:67]
	s_setprio 0
	s_barrier
; #define PG8_STAGE(bufoff, gbase, voff) do { _Pragma("unroll") for (int _i = 0; _i < 2; ++_i) \
;         __builtin_amdgcn_global_load_lds((const unsigned*)((const char*)(gbase) + (voff)[_i]), (PG8_LAS unsigned*)(lds + (bufoff) + ldsw + _i * 8192), 16, 0, 0); } while (0)
; #define PG8_LDA(dst, b, h) do { _Pragma("unroll") for (int m = 0; m < 4; ++m) _Pragma("unroll") for (int k = 0; k < 2; ++k) dst[m][k] = *(const PG8_LAS bf16x8*)(lds + PG8_SA(b, h) + aoff + m * 2048 + k * 1024); } while (0)
; #define PG8_MMA(ai, bj, At, Bt) do { __builtin_amdgcn_s_setprio(1); _Pragma("unroll") for (int m = 0; m < 4; ++m) _Pragma("unroll") for (int n = 0; n < 2; ++n) _Pragma("unroll") for (int k = 0; k < 2; ++k) \
;         acc[ai][bj][m][n] = __builtin_amdgcn_mfma_f32_16x16x32_bf16(Bt[n][k], At[m][k], acc[ai][bj][m][n], 0, 0, 0); __builtin_amdgcn_s_setprio(0); } while (0)
; template <class Epi, class Sched, bool ALIGN_EPI = false, bool SP2 = false>
; __device__ __forceinline__ void gemm_phase(PG8_LAS unsigned char* lds, const Gemm g, const Sched& S, const Epi& E, int tid_in) {
;     ...
;             PG8_LDA(At, 1, 1); PG8_STAGE(PG8_SB(1, 0), b3, voffB); PG8_STAGE(PG8_SB(1, 1), b3 + hstepB, voffB); PG8_STAGE(PG8_SA(1, 0), a3, voffA);
;             PG8_WAIT_V(8); PG8_WAIT_L(0); PG8_BAR; PG8_MMA(1, 0, At, B0); PG8_MMA(1, 1, At, B1); PG8_BAR; PG8_SCHED;
;     __device__ __forceinline__ void operator()(const f32x4 (&acc)[2][2][4][2], const Unit& u, int wr, int wc, int fr, int fq) const {
;     ...
;                 const int row = u.pm * BM + ai * HALF + wr * 64 + m * 16 + r; float q = 0.f;
; #pragma unroll
;                 for (int bj = 0; bj < 2; ++bj) {
;                     const size_t off = (size_t)row * 2048 + u.pn * BM + wc * 64 + bj * 32 + 8 * p;
;                     f32x4 b0, b1;
;                     if (BASE_F32) { b0 = *(const f32x4*)((const float*)base + off); b1 = *(const f32x4*)((const float*)base + off + 4); }
;                     else { const u32x4 bb = *(const u32x4*)((const bf16_t*)base + off);
;                         b0 = (f32x4){__uint_as_float(bb.x << 16), __uint_as_float(bb.x & 0xffff0000u), __uint_as_float(bb.y << 16), __uint_as_float(bb.y & 0xffff0000u)};
;                         b1 = (f32x4){__uint_as_float(bb.z << 16), __uint_as_float(bb.z & 0xffff0000u), __uint_as_float(bb.w << 16), __uint_as_float(bb.w & 0xffff0000u)}; }
	s_add_i32 s26, s33, s56
	s_add_i32 m0, s26, 0xffffff80
	ds_read_b128 v[186:189], v155 offset:49152
	ds_read_b128 v[190:193], v155 offset:50176
	ds_read_b128 v[194:197], v155 offset:51200
	ds_read_b128 v[198:201], v155 offset:52224
	ds_read_b128 v[202:205], v155 offset:53248
	ds_read_b128 v[206:209], v155 offset:54272
	ds_read_b128 v[210:213], v155 offset:55296
	ds_read_b128 v[214:217], v155 offset:56320
	global_load_lds_dwordx4 v130, s[52:53] offset:128
	s_add_i32 m0, s26, 0x1f80
	s_add_u32 s26, s52, 0x80080
	s_addc_u32 s27, s53, 0
	s_add_i32 s33, s50, s56
	global_load_lds_dwordx4 v134, s[52:53] offset:128
	s_mov_b32 m0, s33
	s_nop 0
	global_load_lds_dwordx4 v130, s[26:27]
	s_add_i32 m0, s33, 0x2000
	s_nop 0
	global_load_lds_dwordx4 v134, s[26:27]
	s_add_i32 m0, s61, 0xffffff80
	s_nop 0
	global_load_lds_dwordx4 v128, s[54:55] offset:128
	s_add_i32 m0, s62, 0xffffff80
	s_nop 0
	global_load_lds_dwordx4 v132, s[54:55] offset:128
	s_waitcnt vmcnt(8)
	s_waitcnt lgkmcnt(0)
	s_barrier
	s_setprio 1
	s_waitcnt lgkmcnt(0)
	v_mfma_f32_16x16x32_bf16 v[60:63], v[146:149], v[186:189], v[60:63]
	v_mfma_f32_16x16x32_bf16 v[56:59], v[162:165], v[186:189], v[56:59]
	v_mfma_f32_16x16x32_bf16 v[44:47], v[146:149], v[194:197], v[44:47]
	v_mfma_f32_16x16x32_bf16 v[40:43], v[162:165], v[194:197], v[40:43]
	v_mfma_f32_16x16x32_bf16 v[28:31], v[146:149], v[202:205], v[28:31]
	v_mfma_f32_16x16x32_bf16 v[24:27], v[162:165], v[202:205], v[24:27]
	v_mfma_f32_16x16x32_bf16 v[12:15], v[146:149], v[210:213], v[12:15]
	v_mfma_f32_16x16x32_bf16 v[8:11], v[162:165], v[210:213], v[8:11]
	v_mfma_f32_16x16x32_bf16 v[60:63], v[158:161], v[190:193], v[60:63]
	v_mfma_f32_16x16x32_bf16 v[56:59], v[166:169], v[190:193], v[56:59]
	v_mfma_f32_16x16x32_bf16 v[44:47], v[158:161], v[198:201], v[44:47]
	v_mfma_f32_16x16x32_bf16 v[40:43], v[166:169], v[198:201], v[40:43]
	v_mfma_f32_16x16x32_bf16 v[28:31], v[158:161], v[206:209], v[28:31]
	v_mfma_f32_16x16x32_bf16 v[24:27], v[166:169], v[206:209], v[24:27]
	v_mfma_f32_16x16x32_bf16 v[12:15], v[158:161], v[214:217], v[12:15]
	v_mfma_f32_16x16x32_bf16 v[8:11], v[166:169], v[214:217], v[8:11]
	s_setprio 0
	s_setprio 1
	v_mfma_f32_16x16x32_bf16 v[52:55], v[170:173], v[186:189], v[52:55]
	v_mfma_f32_16x16x32_bf16 v[48:51], v[178:181], v[186:189], v[48:51]
	v_mfma_f32_16x16x32_bf16 v[36:39], v[170:173], v[194:197], v[36:39]
	v_mfma_f32_16x16x32_bf16 v[32:35], v[178:181], v[194:197], v[32:35]
	v_mfma_f32_16x16x32_bf16 v[20:23], v[170:173], v[202:205], v[20:23]
	v_mfma_f32_16x16x32_bf16 v[16:19], v[178:181], v[202:205], v[16:19]
	v_mfma_f32_16x16x32_bf16 v[4:7], v[170:173], v[210:213], v[4:7]
	v_mfma_f32_16x16x32_bf16 v[0:3], v[178:181], v[210:213], v[0:3]
	v_mfma_f32_16x16x32_bf16 v[52:55], v[174:177], v[190:193], v[52:55]
	v_mfma_f32_16x16x32_bf16 v[48:51], v[182:185], v[190:193], v[48:51]
	v_mfma_f32_16x16x32_bf16 v[36:39], v[174:177], v[198:201], v[36:39]
	v_mfma_f32_16x16x32_bf16 v[32:35], v[182:185], v[198:201], v[32:35]
	v_mfma_f32_16x16x32_bf16 v[20:23], v[174:177], v[206:209], v[20:23]
	v_mfma_f32_16x16x32_bf16 v[16:19], v[182:185], v[206:209], v[16:19]
	v_mfma_f32_16x16x32_bf16 v[4:7], v[174:177], v[214:217], v[4:7]
	v_mfma_f32_16x16x32_bf16 v[0:3], v[182:185], v[214:217], v[0:3]
	s_setprio 0
	s_barrier
	s_add_i32 s70, s70, 2
	s_add_u32 s68, s68, 0x100
	s_addc_u32 s69, s69, 0
	s_cmpk_gt_u32 s70, 0x7d
	s_mov_b64 s[50:51], s[10:11]
	s_cbranch_scc0 .LBB0_949
	s_mov_b32 s99, 1
	v_lshl_add_u32 v148, s66, 8, v150
	v_lshl_or_b32 v146, s48, 8, v136
	v_lshl_add_u32 v147, v148, 11, v146
	v_lshlrev_b32_e32 v159, 1, v147
	v_lshlrev_b32_e32 v208, 3, v148
	global_load_dwordx4 v[160:163], v159, s[28:29]
	global_load_dwordx4 v[164:167], v159, s[28:29] offset:64
	v_add_u32_e32 v149, 0x10000, v159
	global_load_dwordx4 v[168:171], v149, s[28:29]
	global_load_dwordx4 v[172:175], v149, s[28:29] offset:64
	v_add_u32_e32 v209, 0x20000, v159
	global_load_dwordx4 v[176:179], v209, s[28:29]
	global_load_dwordx4 v[180:183], v209, s[28:29] offset:64
	v_add_u32_e32 v149, 0x30000, v159
	global_load_dwordx4 v[184:187], v149, s[28:29]
	global_load_dwordx4 v[188:191], v149, s[28:29] offset:64
	v_add_u32_e32 v209, 0x80000, v159
	global_load_dwordx4 v[192:195], v209, s[28:29]
	global_load_dwordx4 v[196:199], v209, s[28:29] offset:64
	v_add_u32_e32 v149, 0x90000, v159
	global_load_dwordx4 v[200:203], v149, s[28:29]
	global_load_dwordx4 v[204:207], v149, s[28:29] offset:64
	v_add_u32_e32 v209, 0xa0000, v159
	global_load_dwordx4 v[212:215], v209, s[28:29]
	global_load_dwordx4 v[216:219], v209, s[28:29] offset:64
	v_add_u32_e32 v149, 0xb0000, v159
	global_load_dwordx4 v[220:223], v149, s[28:29]
	global_load_dwordx4 v[224:227], v149, s[28:29] offset:64
	s_and_b64 vcc, exec, s[40:41]
	s_cbranch_vccz .LBB0_952
	s_barrier
